# K-loop MMA heads: lgkmcnt wait and s_setprio 1 moved ahead of the pre-MMA barrier so the first MFMA issues right after release
# speedup vs baseline: 1.0177x; 1.0106x over previous
; #define PG8_STAGE(bufoff, gbase, voff) do { _Pragma("unroll") for (int _i = 0; _i < 2; ++_i) \
;         __builtin_amdgcn_global_load_lds((const unsigned*)((const char*)(gbase) + (voff)[_i]), (LAS unsigned*)(lds + (bufoff) + ldsw + _i * 8192), 16, 0, 0); } while (0)
; #define PG8_LDA(dst, b, h) do { _Pragma("unroll") for (int m = 0; m < 4; ++m) _Pragma("unroll") for (int k = 0; k < 2; ++k) dst[m][k] = *(const LAS bf16x8*)(lds + PG8_SA(b, h) + aoff + m * 2048 + k * 1024); } while (0)
; #define PG8_LDB(dst, b, h) do { _Pragma("unroll") for (int n = 0; n < 2; ++n) _Pragma("unroll") for (int k = 0; k < 2; ++k) dst[n][k] = *(const LAS bf16x8*)(lds + PG8_SB(b, h) + boff + n * 2048 + k * 1024); } while (0)
; #define PG8_MMA(ai, bj, At, Bt) do { __builtin_amdgcn_s_setprio(1); _Pragma("unroll") for (int m = 0; m < 4; ++m) _Pragma("unroll") for (int n = 0; n < 2; ++n) _Pragma("unroll") for (int k = 0; k < 2; ++k) \
;         acc[ai][bj][m][n] = __builtin_amdgcn_mfma_f32_16x16x32_bf16(Bt[n][k], At[m][k], acc[ai][bj][m][n], 0, 0, 0); __builtin_amdgcn_s_setprio(0); } while (0)
; #define PG8_WAIT_L(n) asm volatile("s_waitcnt lgkmcnt(" #n ")" ::: "memory")
; #define PG8_BAR __builtin_amdgcn_s_barrier()
; #define PG8_SCHED __builtin_amdgcn_sched_barrier(0)
; template <class Epi>
; __device__ __forceinline__ void gemm_phase(LAS unsigned char* lds, const Gemm g, const StaticOrder& S, const Epi& E) {
;     ...
;             PG8_LDB(B0, 0, 0); PG8_SCHED; PG8_LDA(At, 0, 0); PG8_STAGE(PG8_SA(1, 1), a1 + hstep, voffA);
;             PG8_WAIT_L(8); PG8_BAR; PG8_WAIT_L(0); PG8_MMA(0, 0, At, B0); PG8_BAR; PG8_SCHED;
.LBB0_259:
	ds_read_b128 v[160:163], v148
	ds_read_b128 v[166:169], v148 offset:1024
	ds_read_b128 v[170:173], v148 offset:2048
	ds_read_b128 v[174:177], v148 offset:3072
	s_add_u32 s18, s16, 0xfff80080
	s_addc_u32 s19, s17, -1
	s_cmp_eq_u32 s67, 28
	s_cselect_b32 s21, s9, s19
	s_cselect_b32 s20, s63, s18
	s_cselect_b32 s19, s7, s66
	s_cselect_b32 s18, s64, s65
	v_lshl_add_u64 v[212:213], s[16:17], 0, v[136:137]
	s_add_i32 m0, s35, 0xc000
	ds_read_b128 v[180:183], v149
	ds_read_b128 v[184:187], v149 offset:1024
	ds_read_b128 v[188:191], v149 offset:2048
	ds_read_b128 v[192:195], v149 offset:3072
	ds_read_b128 v[196:199], v149 offset:4096
	ds_read_b128 v[200:203], v149 offset:5120
	ds_read_b128 v[204:207], v149 offset:6144
	ds_read_b128 v[208:211], v149 offset:7168
	global_load_lds_dwordx4 v[212:213], off
	v_lshl_add_u64 v[212:213], s[16:17], 0, v[138:139]
	s_add_i32 m0, s35, 0xe000
	s_nop 0
	global_load_lds_dwordx4 v[212:213], off
	s_waitcnt lgkmcnt(8)
	s_setprio 1
	s_barrier
	s_waitcnt lgkmcnt(0)


; #define PG8_STAGE(bufoff, gbase, voff) do { _Pragma("unroll") for (int _i = 0; _i < 2; ++_i) \
;         __builtin_amdgcn_global_load_lds((const unsigned*)((const char*)(gbase) + (voff)[_i]), (LAS unsigned*)(lds + (bufoff) + ldsw + _i * 8192), 16, 0, 0); } while (0)
; #define PG8_LDB(dst, b, h) do { _Pragma("unroll") for (int n = 0; n < 2; ++n) _Pragma("unroll") for (int k = 0; k < 2; ++k) dst[n][k] = *(const LAS bf16x8*)(lds + PG8_SB(b, h) + boff + n * 2048 + k * 1024); } while (0)
; #define PG8_MMA(ai, bj, At, Bt) do { __builtin_amdgcn_s_setprio(1); _Pragma("unroll") for (int m = 0; m < 4; ++m) _Pragma("unroll") for (int n = 0; n < 2; ++n) _Pragma("unroll") for (int k = 0; k < 2; ++k) \
;         acc[ai][bj][m][n] = __builtin_amdgcn_mfma_f32_16x16x32_bf16(Bt[n][k], At[m][k], acc[ai][bj][m][n], 0, 0, 0); __builtin_amdgcn_s_setprio(0); } while (0)
; #define PG8_WAIT_L(n) asm volatile("s_waitcnt lgkmcnt(" #n ")" ::: "memory")
; #define PG8_BAR __builtin_amdgcn_s_barrier()
; #define PG8_SCHED __builtin_amdgcn_sched_barrier(0)
; template <class Epi>
; __device__ __forceinline__ void gemm_phase(LAS unsigned char* lds, const Gemm g, const StaticOrder& S, const Epi& E) {
;     ...
;             PG8_WAIT_L(8); PG8_BAR; PG8_WAIT_L(0); PG8_MMA(0, 0, At, B0); PG8_BAR; PG8_SCHED;
;             PG8_LDB(B1, 0, 1); PG8_STAGE(PG8_SB(0, 0), b2, voffB);
;             PG8_BAR; PG8_WAIT_L(0); PG8_MMA(0, 1, At, B1); PG8_BAR;
	v_mfma_f32_16x16x32_bf16 v[124:127], v[160:163], v[180:183], v[124:127]
	v_mfma_f32_16x16x32_bf16 v[116:119], v[170:173], v[180:183], v[116:119]
	v_mfma_f32_16x16x32_bf16 v[108:111], v[160:163], v[188:191], v[108:111]
	v_mfma_f32_16x16x32_bf16 v[100:103], v[170:173], v[188:191], v[100:103]
	v_mfma_f32_16x16x32_bf16 v[92:95], v[160:163], v[196:199], v[92:95]
	v_mfma_f32_16x16x32_bf16 v[84:87], v[170:173], v[196:199], v[84:87]
	v_mfma_f32_16x16x32_bf16 v[76:79], v[160:163], v[204:207], v[76:79]
	v_mfma_f32_16x16x32_bf16 v[68:71], v[170:173], v[204:207], v[68:71]
	v_mfma_f32_16x16x32_bf16 v[124:127], v[166:169], v[184:187], v[124:127]
	v_mfma_f32_16x16x32_bf16 v[116:119], v[174:177], v[184:187], v[116:119]
	v_mfma_f32_16x16x32_bf16 v[108:111], v[166:169], v[192:195], v[108:111]
	v_mfma_f32_16x16x32_bf16 v[100:103], v[174:177], v[192:195], v[100:103]
	v_mfma_f32_16x16x32_bf16 v[92:95], v[166:169], v[200:203], v[92:95]
	v_mfma_f32_16x16x32_bf16 v[84:87], v[174:177], v[200:203], v[84:87]
	v_mfma_f32_16x16x32_bf16 v[76:79], v[166:169], v[208:211], v[76:79]
	v_mfma_f32_16x16x32_bf16 v[68:71], v[174:177], v[208:211], v[68:71]
	s_setprio 0
	s_barrier
	s_add_i32 s68, s60, s31
	v_lshl_add_u64 v[228:229], s[18:19], 0, v[132:133]
	s_mov_b32 m0, s68
	ds_read_b128 v[212:215], v150
	ds_read_b128 v[216:219], v150 offset:1024
	ds_read_b128 v[220:223], v150 offset:2048
	ds_read_b128 v[224:227], v150 offset:3072
	global_load_lds_dwordx4 v[228:229], off
	v_lshl_add_u64 v[230:231], s[18:19], 0, v[128:129]
	s_add_i32 m0, s68, 0x2000
	s_nop 0
	global_load_lds_dwordx4 v[230:231], off
	s_waitcnt lgkmcnt(0)
	s_setprio 1
	s_barrier


; #define PG8_STAGE(bufoff, gbase, voff) do { _Pragma("unroll") for (int _i = 0; _i < 2; ++_i) \
;         __builtin_amdgcn_global_load_lds((const unsigned*)((const char*)(gbase) + (voff)[_i]), (LAS unsigned*)(lds + (bufoff) + ldsw + _i * 8192), 16, 0, 0); } while (0)
; #define PG8_LDA(dst, b, h) do { _Pragma("unroll") for (int m = 0; m < 4; ++m) _Pragma("unroll") for (int k = 0; k < 2; ++k) dst[m][k] = *(const LAS bf16x8*)(lds + PG8_SA(b, h) + aoff + m * 2048 + k * 1024); } while (0)
; #define PG8_MMA(ai, bj, At, Bt) do { __builtin_amdgcn_s_setprio(1); _Pragma("unroll") for (int m = 0; m < 4; ++m) _Pragma("unroll") for (int n = 0; n < 2; ++n) _Pragma("unroll") for (int k = 0; k < 2; ++k) \
;         acc[ai][bj][m][n] = __builtin_amdgcn_mfma_f32_16x16x32_bf16(Bt[n][k], At[m][k], acc[ai][bj][m][n], 0, 0, 0); __builtin_amdgcn_s_setprio(0); } while (0)
; #define PG8_WAIT_L(n) asm volatile("s_waitcnt lgkmcnt(" #n ")" ::: "memory")
; #define PG8_BAR __builtin_amdgcn_s_barrier()
; #define PG8_SCHED __builtin_amdgcn_sched_barrier(0)
; template <class Epi>
; __device__ __forceinline__ void gemm_phase(LAS unsigned char* lds, const Gemm g, const StaticOrder& S, const Epi& E) {
;     ...
;             PG8_BAR; PG8_WAIT_L(0); PG8_MMA(0, 1, At, B1); PG8_BAR;
;             PG8_LDA(At, 0, 1); PG8_STAGE(PG8_SA(0, 0), a2, voffA);
;             PG8_BAR; PG8_WAIT_L(0); PG8_MMA(1, 0, At, B0); PG8_BAR; PG8_SCHED;
	v_mfma_f32_16x16x32_bf16 v[120:123], v[212:215], v[180:183], v[120:123]
	v_mfma_f32_16x16x32_bf16 v[112:115], v[220:223], v[180:183], v[112:115]
	v_mfma_f32_16x16x32_bf16 v[104:107], v[212:215], v[188:191], v[104:107]
	v_mfma_f32_16x16x32_bf16 v[96:99], v[220:223], v[188:191], v[96:99]
	v_mfma_f32_16x16x32_bf16 v[88:91], v[212:215], v[196:199], v[88:91]
	v_mfma_f32_16x16x32_bf16 v[80:83], v[220:223], v[196:199], v[80:83]
	v_mfma_f32_16x16x32_bf16 v[72:75], v[212:215], v[204:207], v[72:75]
	v_mfma_f32_16x16x32_bf16 v[64:67], v[220:223], v[204:207], v[64:67]
	v_mfma_f32_16x16x32_bf16 v[120:123], v[216:219], v[184:187], v[120:123]
	v_mfma_f32_16x16x32_bf16 v[112:115], v[224:227], v[184:187], v[112:115]
	v_mfma_f32_16x16x32_bf16 v[104:107], v[216:219], v[192:195], v[104:107]
	v_mfma_f32_16x16x32_bf16 v[96:99], v[224:227], v[192:195], v[96:99]
	v_mfma_f32_16x16x32_bf16 v[88:91], v[216:219], v[200:203], v[88:91]
	v_mfma_f32_16x16x32_bf16 v[80:83], v[224:227], v[200:203], v[80:83]
	v_mfma_f32_16x16x32_bf16 v[72:75], v[216:219], v[208:211], v[72:75]
	v_mfma_f32_16x16x32_bf16 v[64:67], v[224:227], v[208:211], v[64:67]
	s_setprio 0
	s_mov_b32 m0, s35
	v_lshl_add_u64 v[232:233], s[20:21], 0, v[134:135]
	s_barrier
	ds_read_b128 v[180:183], v149 offset:16384
	ds_read_b128 v[184:187], v149 offset:17408
	ds_read_b128 v[188:191], v149 offset:18432
	ds_read_b128 v[192:195], v149 offset:19456
	ds_read_b128 v[196:199], v149 offset:20480
	ds_read_b128 v[200:203], v149 offset:21504
	ds_read_b128 v[204:207], v149 offset:22528
	ds_read_b128 v[208:211], v149 offset:23552
	global_load_lds_dwordx4 v[232:233], off
	v_lshl_add_u64 v[234:235], s[20:21], 0, v[130:131]
	s_mov_b32 m0, s38
	s_nop 0
	global_load_lds_dwordx4 v[234:235], off
	s_waitcnt lgkmcnt(0)
	s_setprio 1
	s_barrier


; #define PG8_STAGE(bufoff, gbase, voff) do { _Pragma("unroll") for (int _i = 0; _i < 2; ++_i) \
;         __builtin_amdgcn_global_load_lds((const unsigned*)((const char*)(gbase) + (voff)[_i]), (LAS unsigned*)(lds + (bufoff) + ldsw + _i * 8192), 16, 0, 0); } while (0)
; #define PG8_MMA(ai, bj, At, Bt) do { __builtin_amdgcn_s_setprio(1); _Pragma("unroll") for (int m = 0; m < 4; ++m) _Pragma("unroll") for (int n = 0; n < 2; ++n) _Pragma("unroll") for (int k = 0; k < 2; ++k) \
;         acc[ai][bj][m][n] = __builtin_amdgcn_mfma_f32_16x16x32_bf16(Bt[n][k], At[m][k], acc[ai][bj][m][n], 0, 0, 0); __builtin_amdgcn_s_setprio(0); } while (0)
; #define PG8_WAIT_V(n) asm volatile("s_waitcnt vmcnt(" #n ")" ::: "memory")
; #define PG8_WAIT_L(n) asm volatile("s_waitcnt lgkmcnt(" #n ")" ::: "memory")
; #define PG8_BAR __builtin_amdgcn_s_barrier()
; #define PG8_SCHED __builtin_amdgcn_sched_barrier(0)
; template <class Epi>
; __device__ __forceinline__ void gemm_phase(LAS unsigned char* lds, const Gemm g, const StaticOrder& S, const Epi& E) {
;     ...
;             PG8_BAR; PG8_WAIT_L(0); PG8_MMA(1, 0, At, B0); PG8_BAR; PG8_SCHED;
;             PG8_STAGE(PG8_SB(0, 1), b2 + hstep, voffB);
;             PG8_WAIT_V(6); PG8_BAR; PG8_MMA(1, 1, At, B1); PG8_BAR;
	v_mfma_f32_16x16x32_bf16 v[60:63], v[160:163], v[180:183], v[60:63]
	v_mfma_f32_16x16x32_bf16 v[52:55], v[170:173], v[180:183], v[52:55]
	v_mfma_f32_16x16x32_bf16 v[44:47], v[160:163], v[188:191], v[44:47]
	v_mfma_f32_16x16x32_bf16 v[36:39], v[170:173], v[188:191], v[36:39]
	v_mfma_f32_16x16x32_bf16 v[28:31], v[160:163], v[196:199], v[28:31]
	v_mfma_f32_16x16x32_bf16 v[20:23], v[170:173], v[196:199], v[20:23]
	v_mfma_f32_16x16x32_bf16 v[12:15], v[160:163], v[204:207], v[12:15]
	v_mfma_f32_16x16x32_bf16 v[4:7], v[170:173], v[204:207], v[4:7]
	v_mfma_f32_16x16x32_bf16 v[60:63], v[166:169], v[184:187], v[60:63]
	v_mfma_f32_16x16x32_bf16 v[52:55], v[174:177], v[184:187], v[52:55]
	v_mfma_f32_16x16x32_bf16 v[44:47], v[166:169], v[192:195], v[44:47]
	v_mfma_f32_16x16x32_bf16 v[36:39], v[174:177], v[192:195], v[36:39]
	v_mfma_f32_16x16x32_bf16 v[28:31], v[166:169], v[200:203], v[28:31]
	v_mfma_f32_16x16x32_bf16 v[20:23], v[174:177], v[200:203], v[20:23]
	v_mfma_f32_16x16x32_bf16 v[12:15], v[166:169], v[208:211], v[12:15]
	v_mfma_f32_16x16x32_bf16 v[4:7], v[174:177], v[208:211], v[4:7]
	s_setprio 0
	s_barrier
	s_add_u32 s68, s18, 0x80000
	s_addc_u32 s69, s19, 0
	s_add_i32 s70, s61, s31
	v_lshl_add_u64 v[160:161], s[68:69], 0, v[132:133]
	s_mov_b32 m0, s70
	s_nop 0
	global_load_lds_dwordx4 v[160:161], off
	v_lshl_add_u64 v[160:161], s[68:69], 0, v[128:129]
	s_add_i32 m0, s70, 0x2000
	s_nop 0
	global_load_lds_dwordx4 v[160:161], off
	s_waitcnt vmcnt(6)
	s_setprio 1
	s_barrier

; #define PG8_STAGE(bufoff, gbase, voff) do { _Pragma("unroll") for (int _i = 0; _i < 2; ++_i) \
;         __builtin_amdgcn_global_load_lds((const unsigned*)((const char*)(gbase) + (voff)[_i]), (LAS unsigned*)(lds + (bufoff) + ldsw + _i * 8192), 16, 0, 0); } while (0)
; #define PG8_LDA(dst, b, h) do { _Pragma("unroll") for (int m = 0; m < 4; ++m) _Pragma("unroll") for (int k = 0; k < 2; ++k) dst[m][k] = *(const LAS bf16x8*)(lds + PG8_SA(b, h) + aoff + m * 2048 + k * 1024); } while (0)
; #define PG8_LDB(dst, b, h) do { _Pragma("unroll") for (int n = 0; n < 2; ++n) _Pragma("unroll") for (int k = 0; k < 2; ++k) dst[n][k] = *(const LAS bf16x8*)(lds + PG8_SB(b, h) + boff + n * 2048 + k * 1024); } while (0)
; #define PG8_MMA(ai, bj, At, Bt) do { __builtin_amdgcn_s_setprio(1); _Pragma("unroll") for (int m = 0; m < 4; ++m) _Pragma("unroll") for (int n = 0; n < 2; ++n) _Pragma("unroll") for (int k = 0; k < 2; ++k) \
;         acc[ai][bj][m][n] = __builtin_amdgcn_mfma_f32_16x16x32_bf16(Bt[n][k], At[m][k], acc[ai][bj][m][n], 0, 0, 0); __builtin_amdgcn_s_setprio(0); } while (0)
; #define PG8_WAIT_V(n) asm volatile("s_waitcnt vmcnt(" #n ")" ::: "memory")
; #define PG8_WAIT_L(n) asm volatile("s_waitcnt lgkmcnt(" #n ")" ::: "memory")
; #define PG8_BAR __builtin_amdgcn_s_barrier()
; #define PG8_SCHED __builtin_amdgcn_sched_barrier(0)
; template <class Epi>
; __device__ __forceinline__ void gemm_phase(LAS unsigned char* lds, const Gemm g, const StaticOrder& S, const Epi& E) {
;     ...
;             PG8_WAIT_V(6); PG8_BAR; PG8_MMA(1, 1, At, B1); PG8_BAR;
;             PG8_LDB(B0, 1, 0); PG8_SCHED; PG8_LDA(At, 1, 0); PG8_STAGE(PG8_SA(0, 1), a2 + hstep, voffA);
;             PG8_WAIT_L(8); PG8_BAR; PG8_WAIT_L(0); PG8_MMA(0, 0, At, B0); PG8_BAR; PG8_SCHED;
	v_mfma_f32_16x16x32_bf16 v[56:59], v[212:215], v[180:183], v[56:59]
	v_mfma_f32_16x16x32_bf16 v[48:51], v[220:223], v[180:183], v[48:51]
	v_mfma_f32_16x16x32_bf16 v[40:43], v[212:215], v[188:191], v[40:43]
	v_mfma_f32_16x16x32_bf16 v[32:35], v[220:223], v[188:191], v[32:35]
	v_mfma_f32_16x16x32_bf16 v[24:27], v[212:215], v[196:199], v[24:27]
	v_mfma_f32_16x16x32_bf16 v[16:19], v[220:223], v[196:199], v[16:19]
	v_mfma_f32_16x16x32_bf16 v[8:11], v[212:215], v[204:207], v[8:11]
	v_mfma_f32_16x16x32_bf16 v[0:3], v[220:223], v[204:207], v[0:3]
	v_mfma_f32_16x16x32_bf16 v[56:59], v[216:219], v[184:187], v[56:59]
	v_mfma_f32_16x16x32_bf16 v[48:51], v[224:227], v[184:187], v[48:51]
	v_mfma_f32_16x16x32_bf16 v[40:43], v[216:219], v[192:195], v[40:43]
	v_mfma_f32_16x16x32_bf16 v[32:35], v[224:227], v[192:195], v[32:35]
	v_mfma_f32_16x16x32_bf16 v[24:27], v[216:219], v[200:203], v[24:27]
	v_mfma_f32_16x16x32_bf16 v[16:19], v[224:227], v[200:203], v[16:19]
	v_mfma_f32_16x16x32_bf16 v[8:11], v[216:219], v[208:211], v[8:11]
	v_mfma_f32_16x16x32_bf16 v[0:3], v[224:227], v[208:211], v[0:3]
	s_setprio 0
	s_add_i32 s68, 0, 0x18000
	v_add_u32_e32 v165, s68, v146
	s_barrier
	ds_read_b128 v[160:163], v165
	ds_read_b128 v[166:169], v165 offset:1024
	ds_read_b128 v[170:173], v165 offset:2048
	ds_read_b128 v[174:177], v165 offset:3072
	s_add_u32 s20, s20, 0x80000
	s_addc_u32 s21, s21, 0
	s_mov_b32 m0, s39
	v_lshl_add_u64 v[212:213], s[20:21], 0, v[134:135]
	ds_read_b128 v[180:183], v149 offset:32768
	ds_read_b128 v[184:187], v149 offset:33792
	ds_read_b128 v[188:191], v149 offset:34816
	ds_read_b128 v[192:195], v149 offset:35840
	ds_read_b128 v[196:199], v149 offset:36864
	ds_read_b128 v[200:203], v149 offset:37888
	ds_read_b128 v[204:207], v149 offset:38912
	ds_read_b128 v[208:211], v149 offset:39936
	global_load_lds_dwordx4 v[212:213], off
	v_lshl_add_u64 v[212:213], s[20:21], 0, v[130:131]
	s_mov_b32 m0, s42
	s_nop 0
	global_load_lds_dwordx4 v[212:213], off
	s_waitcnt lgkmcnt(8)
	s_setprio 1
	s_barrier
	s_waitcnt lgkmcnt(0)


; #define PG8_STAGE(bufoff, gbase, voff) do { _Pragma("unroll") for (int _i = 0; _i < 2; ++_i) \
;         __builtin_amdgcn_global_load_lds((const unsigned*)((const char*)(gbase) + (voff)[_i]), (LAS unsigned*)(lds + (bufoff) + ldsw + _i * 8192), 16, 0, 0); } while (0)
; #define PG8_LDB(dst, b, h) do { _Pragma("unroll") for (int n = 0; n < 2; ++n) _Pragma("unroll") for (int k = 0; k < 2; ++k) dst[n][k] = *(const LAS bf16x8*)(lds + PG8_SB(b, h) + boff + n * 2048 + k * 1024); } while (0)
; #define PG8_MMA(ai, bj, At, Bt) do { __builtin_amdgcn_s_setprio(1); _Pragma("unroll") for (int m = 0; m < 4; ++m) _Pragma("unroll") for (int n = 0; n < 2; ++n) _Pragma("unroll") for (int k = 0; k < 2; ++k) \
;         acc[ai][bj][m][n] = __builtin_amdgcn_mfma_f32_16x16x32_bf16(Bt[n][k], At[m][k], acc[ai][bj][m][n], 0, 0, 0); __builtin_amdgcn_s_setprio(0); } while (0)
; #define PG8_WAIT_L(n) asm volatile("s_waitcnt lgkmcnt(" #n ")" ::: "memory")
; #define PG8_BAR __builtin_amdgcn_s_barrier()
; #define PG8_SCHED __builtin_amdgcn_sched_barrier(0)
; template <class Epi>
; __device__ __forceinline__ void gemm_phase(LAS unsigned char* lds, const Gemm g, const StaticOrder& S, const Epi& E) {
;     ...
;             PG8_WAIT_L(8); PG8_BAR; PG8_WAIT_L(0); PG8_MMA(0, 0, At, B0); PG8_BAR; PG8_SCHED;
;             PG8_LDB(B1, 1, 1); PG8_STAGE(PG8_SB(1, 0), b3, voffB);
;             PG8_BAR; PG8_WAIT_L(0); PG8_MMA(0, 1, At, B1); PG8_BAR;
	v_mfma_f32_16x16x32_bf16 v[124:127], v[160:163], v[180:183], v[124:127]
	v_mfma_f32_16x16x32_bf16 v[116:119], v[170:173], v[180:183], v[116:119]
	v_mfma_f32_16x16x32_bf16 v[108:111], v[160:163], v[188:191], v[108:111]
	v_mfma_f32_16x16x32_bf16 v[100:103], v[170:173], v[188:191], v[100:103]
	v_mfma_f32_16x16x32_bf16 v[92:95], v[160:163], v[196:199], v[92:95]
	v_mfma_f32_16x16x32_bf16 v[84:87], v[170:173], v[196:199], v[84:87]
	v_mfma_f32_16x16x32_bf16 v[76:79], v[160:163], v[204:207], v[76:79]
	v_mfma_f32_16x16x32_bf16 v[68:71], v[170:173], v[204:207], v[68:71]
	v_mfma_f32_16x16x32_bf16 v[124:127], v[166:169], v[184:187], v[124:127]
	v_mfma_f32_16x16x32_bf16 v[116:119], v[174:177], v[184:187], v[116:119]
	v_mfma_f32_16x16x32_bf16 v[108:111], v[166:169], v[192:195], v[108:111]
	v_mfma_f32_16x16x32_bf16 v[100:103], v[174:177], v[192:195], v[100:103]
	v_mfma_f32_16x16x32_bf16 v[92:95], v[166:169], v[200:203], v[92:95]
	v_mfma_f32_16x16x32_bf16 v[84:87], v[174:177], v[200:203], v[84:87]
	v_mfma_f32_16x16x32_bf16 v[76:79], v[166:169], v[208:211], v[76:79]
	v_mfma_f32_16x16x32_bf16 v[68:71], v[174:177], v[208:211], v[68:71]
	s_setprio 0
	s_barrier
	s_add_i32 s20, 0, 0x1c000
	s_add_i32 s21, s68, s31
	v_add_u32_e32 v165, s20, v146
	v_lshl_add_u64 v[228:229], v[228:229], 0, s[4:5]
	s_mov_b32 m0, s21
	ds_read_b128 v[212:215], v165
	ds_read_b128 v[216:219], v165 offset:1024
	ds_read_b128 v[220:223], v165 offset:2048
	ds_read_b128 v[224:227], v165 offset:3072
	global_load_lds_dwordx4 v[228:229], off
	v_lshl_add_u64 v[228:229], v[230:231], 0, s[4:5]
	s_add_i32 m0, s21, 0x2000
	s_nop 0
	global_load_lds_dwordx4 v[228:229], off
	s_waitcnt lgkmcnt(0)
	s_setprio 1
	s_barrier


; #define PG8_STAGE(bufoff, gbase, voff) do { _Pragma("unroll") for (int _i = 0; _i < 2; ++_i) \
;         __builtin_amdgcn_global_load_lds((const unsigned*)((const char*)(gbase) + (voff)[_i]), (LAS unsigned*)(lds + (bufoff) + ldsw + _i * 8192), 16, 0, 0); } while (0)
; #define PG8_LDA(dst, b, h) do { _Pragma("unroll") for (int m = 0; m < 4; ++m) _Pragma("unroll") for (int k = 0; k < 2; ++k) dst[m][k] = *(const LAS bf16x8*)(lds + PG8_SA(b, h) + aoff + m * 2048 + k * 1024); } while (0)
; #define PG8_MMA(ai, bj, At, Bt) do { __builtin_amdgcn_s_setprio(1); _Pragma("unroll") for (int m = 0; m < 4; ++m) _Pragma("unroll") for (int n = 0; n < 2; ++n) _Pragma("unroll") for (int k = 0; k < 2; ++k) \
;         acc[ai][bj][m][n] = __builtin_amdgcn_mfma_f32_16x16x32_bf16(Bt[n][k], At[m][k], acc[ai][bj][m][n], 0, 0, 0); __builtin_amdgcn_s_setprio(0); } while (0)
; #define PG8_WAIT_L(n) asm volatile("s_waitcnt lgkmcnt(" #n ")" ::: "memory")
; #define PG8_BAR __builtin_amdgcn_s_barrier()
; #define PG8_SCHED __builtin_amdgcn_sched_barrier(0)
; template <class Epi>
; __device__ __forceinline__ void gemm_phase(LAS unsigned char* lds, const Gemm g, const StaticOrder& S, const Epi& E) {
;     ...
;             PG8_BAR; PG8_WAIT_L(0); PG8_MMA(0, 1, At, B1); PG8_BAR;
;             PG8_LDA(At, 1, 1); PG8_STAGE(PG8_SA(1, 0), a3, voffA);
;             PG8_BAR; PG8_WAIT_L(0); PG8_MMA(1, 0, At, B0); PG8_BAR; PG8_SCHED;
	v_mfma_f32_16x16x32_bf16 v[120:123], v[212:215], v[180:183], v[120:123]
	v_mfma_f32_16x16x32_bf16 v[112:115], v[220:223], v[180:183], v[112:115]
	v_mfma_f32_16x16x32_bf16 v[104:107], v[212:215], v[188:191], v[104:107]
	v_mfma_f32_16x16x32_bf16 v[96:99], v[220:223], v[188:191], v[96:99]
	v_mfma_f32_16x16x32_bf16 v[88:91], v[212:215], v[196:199], v[88:91]
	v_mfma_f32_16x16x32_bf16 v[80:83], v[220:223], v[196:199], v[80:83]
	v_mfma_f32_16x16x32_bf16 v[72:75], v[212:215], v[204:207], v[72:75]
	v_mfma_f32_16x16x32_bf16 v[64:67], v[220:223], v[204:207], v[64:67]
	v_mfma_f32_16x16x32_bf16 v[120:123], v[216:219], v[184:187], v[120:123]
	v_mfma_f32_16x16x32_bf16 v[112:115], v[224:227], v[184:187], v[112:115]
	v_mfma_f32_16x16x32_bf16 v[104:107], v[216:219], v[192:195], v[104:107]
	v_mfma_f32_16x16x32_bf16 v[96:99], v[224:227], v[192:195], v[96:99]
	v_mfma_f32_16x16x32_bf16 v[88:91], v[216:219], v[200:203], v[88:91]
	v_mfma_f32_16x16x32_bf16 v[80:83], v[224:227], v[200:203], v[80:83]
	v_mfma_f32_16x16x32_bf16 v[72:75], v[216:219], v[208:211], v[72:75]
	v_mfma_f32_16x16x32_bf16 v[64:67], v[224:227], v[208:211], v[64:67]
	s_setprio 0
	s_mov_b32 m0, s56
	v_lshl_add_u64 v[228:229], v[232:233], 0, s[4:5]
	s_barrier
	ds_read_b128 v[180:183], v149 offset:49152
	ds_read_b128 v[184:187], v149 offset:50176
	ds_read_b128 v[188:191], v149 offset:51200
	ds_read_b128 v[192:195], v149 offset:52224
	ds_read_b128 v[196:199], v149 offset:53248
	ds_read_b128 v[200:203], v149 offset:54272
	ds_read_b128 v[204:207], v149 offset:55296
	ds_read_b128 v[208:211], v149 offset:56320
	global_load_lds_dwordx4 v[228:229], off
	v_lshl_add_u64 v[228:229], v[234:235], 0, s[4:5]
	s_mov_b32 m0, s57
	s_nop 0
	global_load_lds_dwordx4 v[228:229], off
	s_waitcnt lgkmcnt(0)
	s_setprio 1
	s_barrier


; #define PG8_STAGE(bufoff, gbase, voff) do { _Pragma("unroll") for (int _i = 0; _i < 2; ++_i) \
;         __builtin_amdgcn_global_load_lds((const unsigned*)((const char*)(gbase) + (voff)[_i]), (LAS unsigned*)(lds + (bufoff) + ldsw + _i * 8192), 16, 0, 0); } while (0)
; #define PG8_MMA(ai, bj, At, Bt) do { __builtin_amdgcn_s_setprio(1); _Pragma("unroll") for (int m = 0; m < 4; ++m) _Pragma("unroll") for (int n = 0; n < 2; ++n) _Pragma("unroll") for (int k = 0; k < 2; ++k) \
;         acc[ai][bj][m][n] = __builtin_amdgcn_mfma_f32_16x16x32_bf16(Bt[n][k], At[m][k], acc[ai][bj][m][n], 0, 0, 0); __builtin_amdgcn_s_setprio(0); } while (0)
; #define PG8_WAIT_V(n) asm volatile("s_waitcnt vmcnt(" #n ")" ::: "memory")
; #define PG8_WAIT_L(n) asm volatile("s_waitcnt lgkmcnt(" #n ")" ::: "memory")
; #define PG8_BAR __builtin_amdgcn_s_barrier()
; #define PG8_SCHED __builtin_amdgcn_sched_barrier(0)
; template <class Epi>
; __device__ __forceinline__ void gemm_phase(LAS unsigned char* lds, const Gemm g, const StaticOrder& S, const Epi& E) {
;     ...
;             PG8_BAR; PG8_WAIT_L(0); PG8_MMA(1, 0, At, B0); PG8_BAR; PG8_SCHED;
;             PG8_STAGE(PG8_SB(1, 1), b3 + hstep, voffB);
;             PG8_WAIT_V(6); PG8_BAR; PG8_MMA(1, 1, At, B1); PG8_BAR;
	v_mfma_f32_16x16x32_bf16 v[60:63], v[160:163], v[180:183], v[60:63]
	v_mfma_f32_16x16x32_bf16 v[52:55], v[170:173], v[180:183], v[52:55]
	v_mfma_f32_16x16x32_bf16 v[44:47], v[160:163], v[188:191], v[44:47]
	v_mfma_f32_16x16x32_bf16 v[36:39], v[170:173], v[188:191], v[36:39]
	v_mfma_f32_16x16x32_bf16 v[28:31], v[160:163], v[196:199], v[28:31]
	v_mfma_f32_16x16x32_bf16 v[20:23], v[170:173], v[196:199], v[20:23]
	v_mfma_f32_16x16x32_bf16 v[12:15], v[160:163], v[204:207], v[12:15]
	v_mfma_f32_16x16x32_bf16 v[4:7], v[170:173], v[204:207], v[4:7]
	v_mfma_f32_16x16x32_bf16 v[60:63], v[166:169], v[184:187], v[60:63]
	v_mfma_f32_16x16x32_bf16 v[52:55], v[174:177], v[184:187], v[52:55]
	v_mfma_f32_16x16x32_bf16 v[44:47], v[166:169], v[192:195], v[44:47]
	v_mfma_f32_16x16x32_bf16 v[36:39], v[174:177], v[192:195], v[36:39]
	v_mfma_f32_16x16x32_bf16 v[28:31], v[166:169], v[200:203], v[28:31]
	v_mfma_f32_16x16x32_bf16 v[20:23], v[174:177], v[200:203], v[20:23]
	v_mfma_f32_16x16x32_bf16 v[12:15], v[166:169], v[208:211], v[12:15]
	v_mfma_f32_16x16x32_bf16 v[4:7], v[174:177], v[208:211], v[4:7]
	s_setprio 0
	s_barrier
	s_add_u32 s18, s18, 0x80080
	s_addc_u32 s19, s19, 0
	s_add_i32 s20, s20, s31
	v_lshl_add_u64 v[160:161], s[18:19], 0, v[132:133]
	s_mov_b32 m0, s20
	s_nop 0
	global_load_lds_dwordx4 v[160:161], off
	v_lshl_add_u64 v[160:161], s[18:19], 0, v[128:129]
	s_add_i32 m0, s20, 0x2000
	s_nop 0
	global_load_lds_dwordx4 v[160:161], off
	s_waitcnt vmcnt(6)
	s_setprio 1
	s_barrier

; __device__ __forceinline__ float sigmoidf_(float x) { return __builtin_amdgcn_rcpf(1.0f + fexp(-x)); }
; #define PG8_MMA(ai, bj, At, Bt) do { __builtin_amdgcn_s_setprio(1); _Pragma("unroll") for (int m = 0; m < 4; ++m) _Pragma("unroll") for (int n = 0; n < 2; ++n) _Pragma("unroll") for (int k = 0; k < 2; ++k) \
;         acc[ai][bj][m][n] = __builtin_amdgcn_mfma_f32_16x16x32_bf16(Bt[n][k], At[m][k], acc[ai][bj][m][n], 0, 0, 0); __builtin_amdgcn_s_setprio(0); } while (0)
; #define PG8_WAIT_V(n) asm volatile("s_waitcnt vmcnt(" #n ")" ::: "memory")
; #define PG8_BAR __builtin_amdgcn_s_barrier()
; template <class Epi>
; __device__ __forceinline__ void gemm_phase(LAS unsigned char* lds, const Gemm g, const StaticOrder& S, const Epi& E) {
;     ...
;             PG8_WAIT_V(6); PG8_BAR; PG8_MMA(1, 1, At, B1); PG8_BAR;
;         }
;     __device__ __forceinline__ void operator()(const f32x4 (&acc)[2][2][4][2], const Unit& u, int wr, int wc, int fr, int fq, const Pre& P) const {
;         const int row0 = ROW_X + u.pm * BM + wr * 64 + fr, col0 = u.pn * HALF + wc * 32 + 8 * fq;
; #pragma unroll
;         for (int ai = 0; ai < 2; ++ai)
; #pragma unroll
;             for (int m = 0; m < 4; ++m) { const int r = row0 + ai * HALF + m * 16; const float rs = __builtin_amdgcn_rsqf(P.rs[ai * 4 + m] * (1.0f / DM) + RMS_EPS);
;                 float y[8];
; #pragma unroll
;                 for (int n = 0; n < 2; ++n)
; #pragma unroll
;                     for (int j = 0; j < 4; ++j) { const float a = acc[ai][0][m][n][j] * rs, b = acc[ai][1][m][n][j] * rs; y[n * 4 + j] = a * b * sigmoidf_(a); }
;                 u32x4 w; w.x = cvtpk(y[0], y[1]); w.y = cvtpk(y[2], y[3]); w.z = cvtpk(y[4], y[5]); w.w = cvtpk(y[6], y[7]);
;                 *(u32x4*)(O + (size_t)r * FF + col0) = w; }
	v_mfma_f32_16x16x32_bf16 v[56:59], v[212:215], v[180:183], v[56:59]
	v_mfma_f32_16x16x32_bf16 v[48:51], v[220:223], v[180:183], v[48:51]
	v_mfma_f32_16x16x32_bf16 v[40:43], v[212:215], v[188:191], v[40:43]
	v_mfma_f32_16x16x32_bf16 v[32:35], v[220:223], v[188:191], v[32:35]
	v_mfma_f32_16x16x32_bf16 v[24:27], v[212:215], v[196:199], v[24:27]
	v_mfma_f32_16x16x32_bf16 v[16:19], v[220:223], v[196:199], v[16:19]
	v_mfma_f32_16x16x32_bf16 v[8:11], v[212:215], v[204:207], v[8:11]
	v_mfma_f32_16x16x32_bf16 v[0:3], v[220:223], v[204:207], v[0:3]
	v_mfma_f32_16x16x32_bf16 v[56:59], v[216:219], v[184:187], v[56:59]
	v_mfma_f32_16x16x32_bf16 v[48:51], v[224:227], v[184:187], v[48:51]
	v_mfma_f32_16x16x32_bf16 v[40:43], v[216:219], v[192:195], v[40:43]
	v_mfma_f32_16x16x32_bf16 v[32:35], v[224:227], v[192:195], v[32:35]
	v_mfma_f32_16x16x32_bf16 v[24:27], v[216:219], v[200:203], v[24:27]
	v_mfma_f32_16x16x32_bf16 v[16:19], v[224:227], v[200:203], v[16:19]
	v_mfma_f32_16x16x32_bf16 v[8:11], v[216:219], v[208:211], v[8:11]
	v_mfma_f32_16x16x32_bf16 v[0:3], v[224:227], v[208:211], v[0:3]
	s_setprio 0
	s_add_i32 s67, s67, 2
	s_add_u32 s16, s16, 0x100
	s_addc_u32 s17, s17, 0
	s_add_u32 s65, s65, 0x100
	s_addc_u32 s66, s66, 0
	s_cmp_gt_u32 s67, 29
	s_barrier
	s_cbranch_scc0 .LBB0_259
	s_waitcnt vmcnt(0)
	v_fmamk_f32 v159, v159, 0x3a000000, v151
	v_rsq_f32_e32 v166, v159
	v_lshl_or_b32 v162, s15, 7, v147
	v_lshl_add_u32 v160, s14, 8, v145
	v_ashrrev_i32_e32 v163, 31, v162
	v_pk_mul_f32 v[124:125], v[166:167], v[124:125] op_sel_hi:[0,1]
	v_pk_mul_f32 v[120:121], v[166:167], v[120:121] op_sel_hi:[0,1]
	v_mul_f32_e32 v159, 0xbfb8aa3b, v124
	v_pk_mul_f32 v[120:121], v[124:125], v[120:121]
	v_mul_f32_e32 v124, 0xbfb8aa3b, v125
	v_exp_f32_e32 v159, v159
	v_exp_f32_e32 v124, v124
	v_pk_mul_f32 v[122:123], v[166:167], v[122:123] op_sel_hi:[0,1]
	v_pk_mul_f32 v[116:117], v[166:167], v[116:117] op_sel_hi:[0,1]
	v_add_f32_e32 v159, 1.0, v159
	v_add_f32_e32 v124, 1.0, v124
	v_rcp_f32_e32 v168, v159
	v_rcp_f32_e32 v169, v124
	v_pk_mul_f32 v[124:125], v[166:167], v[126:127] op_sel_hi:[0,1]
	v_pk_mul_f32 v[122:123], v[124:125], v[122:123]
	v_pk_mul_f32 v[112:113], v[166:167], v[112:113] op_sel_hi:[0,1]
	v_pk_mul_f32 v[120:121], v[168:169], v[120:121]
	v_pk_mul_f32 v[112:113], v[116:117], v[112:113]
	v_cvt_pk_bf16_f32 v120, v120, v121
	v_mul_f32_e32 v121, 0xbfb8aa3b, v124
	v_exp_f32_e32 v121, v121
	v_pk_mul_f32 v[114:115], v[166:167], v[114:115] op_sel_hi:[0,1]
	s_and_b64 vcc, vcc, exec
	v_add_f32_e32 v121, 1.0, v121
	v_rcp_f32_e32 v126, v121
	v_mul_f32_e32 v121, 0xbfb8aa3b, v125
	v_exp_f32_e32 v121, v121
	s_nop 0
	v_add_f32_e32 v121, 1.0, v121
	v_rcp_f32_e32 v127, v121
	s_nop 0
	v_pk_mul_f32 v[122:123], v[126:127], v[122:123]
	s_nop 0
	v_cvt_pk_bf16_f32 v121, v122, v123
	v_mul_f32_e32 v122, 0xbfb8aa3b, v116
	v_mul_f32_e32 v116, 0xbfb8aa3b, v117
	v_exp_f32_e32 v122, v122
	v_exp_f32_e32 v116, v116
	v_add_f32_e32 v122, 1.0, v122
	v_add_f32_e32 v116, 1.0, v116
	v_rcp_f32_e32 v122, v122
	v_rcp_f32_e32 v123, v116
	s_nop 0
	v_pk_mul_f32 v[112:113], v[122:123], v[112:113]
	s_nop 0
	v_cvt_pk_bf16_f32 v122, v112, v113
	v_pk_mul_f32 v[112:113], v[166:167], v[118:119] op_sel_hi:[0,1]
	v_mul_f32_e32 v116, 0xbfb8aa3b, v112
	v_pk_mul_f32 v[114:115], v[112:113], v[114:115]
	v_mul_f32_e32 v112, 0xbfb8aa3b, v113
	v_exp_f32_e32 v116, v116
	v_exp_f32_e32 v112, v112
	v_add_f32_e32 v116, 1.0, v116
	v_add_f32_e32 v112, 1.0, v112
	v_rcp_f32_e32 v116, v116
	v_rcp_f32_e32 v117, v112
	s_nop 0
	v_pk_mul_f32 v[112:113], v[116:117], v[114:115]
	s_nop 0
	v_cvt_pk_bf16_f32 v123, v112, v113
	v_mov_b64_e32 v[112:113], s[0:1]
	v_mad_i64_i32 v[116:117], s[14:15], v160, s62, v[112:113]
	v_lshlrev_b64 v[114:115], 1, v[162:163]
	v_lshl_add_u64 v[116:117], v[116:117], 0, v[114:115]
	global_store_dwordx4 v[116:117], v[120:123], off
	v_fmamk_f32 v116, v158, 0x3a000000, v151
	v_rsq_f32_e32 v116, v116
	v_or_b32_e32 v117, 16, v160
	v_pk_mul_f32 v[108:109], v[116:117], v[108:109] op_sel_hi:[0,1]
	v_pk_mul_f32 v[104:105], v[116:117], v[104:105] op_sel_hi:[0,1]
	v_mul_f32_e32 v118, 0xbfb8aa3b, v108
	v_pk_mul_f32 v[104:105], v[108:109], v[104:105]
	v_mul_f32_e32 v108, 0xbfb8aa3b, v109
	v_exp_f32_e32 v118, v118
	v_exp_f32_e32 v108, v108
	v_pk_mul_f32 v[106:107], v[116:117], v[106:107] op_sel_hi:[0,1]
	v_pk_mul_f32 v[100:101], v[116:117], v[100:101] op_sel_hi:[0,1]
	v_add_f32_e32 v118, 1.0, v118
	v_add_f32_e32 v108, 1.0, v108
	v_rcp_f32_e32 v118, v118
	v_rcp_f32_e32 v119, v108
	v_pk_mul_f32 v[108:109], v[116:117], v[110:111] op_sel_hi:[0,1]
	v_pk_mul_f32 v[106:107], v[108:109], v[106:107]
	v_pk_mul_f32 v[96:97], v[116:117], v[96:97] op_sel_hi:[0,1]
	v_pk_mul_f32 v[104:105], v[118:119], v[104:105]
	v_pk_mul_f32 v[96:97], v[100:101], v[96:97]
	v_cvt_pk_bf16_f32 v104, v104, v105
	v_mul_f32_e32 v105, 0xbfb8aa3b, v108
	v_exp_f32_e32 v105, v105
	v_pk_mul_f32 v[98:99], v[116:117], v[98:99] op_sel_hi:[0,1]
	v_add_f32_e32 v105, 1.0, v105
	v_rcp_f32_e32 v110, v105
	v_mul_f32_e32 v105, 0xbfb8aa3b, v109
	v_exp_f32_e32 v105, v105
	s_nop 0
	v_add_f32_e32 v105, 1.0, v105
	v_rcp_f32_e32 v111, v105
	s_nop 0
	v_pk_mul_f32 v[106:107], v[110:111], v[106:107]
	s_nop 0
	v_cvt_pk_bf16_f32 v105, v106, v107
	v_mul_f32_e32 v106, 0xbfb8aa3b, v100
	v_mul_f32_e32 v100, 0xbfb8aa3b, v101
	v_exp_f32_e32 v106, v106
	v_exp_f32_e32 v100, v100
	v_add_f32_e32 v106, 1.0, v106
	v_add_f32_e32 v100, 1.0, v100
	v_rcp_f32_e32 v106, v106
	v_rcp_f32_e32 v107, v100
	s_nop 0
	v_pk_mul_f32 v[96:97], v[106:107], v[96:97]
	s_nop 0
	v_cvt_pk_bf16_f32 v106, v96, v97
	v_pk_mul_f32 v[96:97], v[116:117], v[102:103] op_sel_hi:[0,1]
	v_mul_f32_e32 v100, 0xbfb8aa3b, v96
; __device__ __forceinline__ float sigmoidf_(float x) { return __builtin_amdgcn_rcpf(1.0f + fexp(-x)); }
;     __device__ __forceinline__ void operator()(const f32x4 (&acc)[2][2][4][2], const Unit& u, int wr, int wc, int fr, int fq, const Pre& P) const {
;         const int row0 = ROW_X + u.pm * BM + wr * 64 + fr, col0 = u.pn * HALF + wc * 32 + 8 * fq;
; #pragma unroll
;         for (int ai = 0; ai < 2; ++ai)
; #pragma unroll
;             for (int m = 0; m < 4; ++m) { const int r = row0 + ai * HALF + m * 16; const float rs = __builtin_amdgcn_rsqf(P.rs[ai * 4 + m] * (1.0f / DM) + RMS_EPS);
;                 float y[8];
; #pragma unroll
;                 for (int n = 0; n < 2; ++n)
; #pragma unroll
;                     for (int j = 0; j < 4; ++j) { const float a = acc[ai][0][m][n][j] * rs, b = acc[ai][1][m][n][j] * rs; y[n * 4 + j] = a * b * sigmoidf_(a); }
;                 u32x4 w; w.x = cvtpk(y[0], y[1]); w.y = cvtpk(y[2], y[3]); w.z = cvtpk(y[4], y[5]); w.w = cvtpk(y[6], y[7]);
;                 *(u32x4*)(O + (size_t)r * FF + col0) = w; }
	v_pk_mul_f32 v[98:99], v[96:97], v[98:99]
	v_mul_f32_e32 v96, 0xbfb8aa3b, v97
	v_exp_f32_e32 v100, v100
	v_exp_f32_e32 v96, v96
	v_add_f32_e32 v100, 1.0, v100
	v_add_f32_e32 v96, 1.0, v96
	v_rcp_f32_e32 v100, v100
	v_rcp_f32_e32 v101, v96
	s_nop 0
	v_pk_mul_f32 v[96:97], v[100:101], v[98:99]
	s_nop 0
	v_cvt_pk_bf16_f32 v107, v96, v97
	v_mad_i64_i32 v[96:97], s[14:15], v117, s62, v[112:113]
	v_lshl_add_u64 v[96:97], v[96:97], 0, v[114:115]
	global_store_dwordx4 v[96:97], v[104:107], off
	v_fmamk_f32 v96, v157, 0x3a000000, v151
	v_rsq_f32_e32 v96, v96
	v_or_b32_e32 v97, 32, v160
	v_pk_mul_f32 v[92:93], v[96:97], v[92:93] op_sel_hi:[0,1]
	v_pk_mul_f32 v[88:89], v[96:97], v[88:89] op_sel_hi:[0,1]
	v_mul_f32_e32 v98, 0xbfb8aa3b, v92
	v_pk_mul_f32 v[88:89], v[92:93], v[88:89]
	v_mul_f32_e32 v92, 0xbfb8aa3b, v93
	v_exp_f32_e32 v98, v98
	v_exp_f32_e32 v92, v92
	v_pk_mul_f32 v[90:91], v[96:97], v[90:91] op_sel_hi:[0,1]
	v_pk_mul_f32 v[84:85], v[96:97], v[84:85] op_sel_hi:[0,1]
	v_add_f32_e32 v98, 1.0, v98
	v_add_f32_e32 v92, 1.0, v92
	v_rcp_f32_e32 v98, v98
	v_rcp_f32_e32 v99, v92
	v_pk_mul_f32 v[92:93], v[96:97], v[94:95] op_sel_hi:[0,1]
	v_pk_mul_f32 v[90:91], v[92:93], v[90:91]
	v_pk_mul_f32 v[80:81], v[96:97], v[80:81] op_sel_hi:[0,1]
	v_pk_mul_f32 v[88:89], v[98:99], v[88:89]
	v_pk_mul_f32 v[80:81], v[84:85], v[80:81]
	v_cvt_pk_bf16_f32 v88, v88, v89
	v_mul_f32_e32 v89, 0xbfb8aa3b, v92
	v_exp_f32_e32 v89, v89
	v_pk_mul_f32 v[82:83], v[96:97], v[82:83] op_sel_hi:[0,1]
	v_add_f32_e32 v89, 1.0, v89
	v_rcp_f32_e32 v94, v89
	v_mul_f32_e32 v89, 0xbfb8aa3b, v93
	v_exp_f32_e32 v89, v89
	s_nop 0
	v_add_f32_e32 v89, 1.0, v89
	v_rcp_f32_e32 v95, v89
	s_nop 0
	v_pk_mul_f32 v[90:91], v[94:95], v[90:91]
	s_nop 0
	v_cvt_pk_bf16_f32 v89, v90, v91
	v_mul_f32_e32 v90, 0xbfb8aa3b, v84
	v_mul_f32_e32 v84, 0xbfb8aa3b, v85
	v_exp_f32_e32 v90, v90
	v_exp_f32_e32 v84, v84
	v_add_f32_e32 v90, 1.0, v90
	v_add_f32_e32 v84, 1.0, v84
	v_rcp_f32_e32 v90, v90
	v_rcp_f32_e32 v91, v84
	s_nop 0
	v_pk_mul_f32 v[80:81], v[90:91], v[80:81]
	s_nop 0
	v_cvt_pk_bf16_f32 v90, v80, v81
	v_pk_mul_f32 v[80:81], v[96:97], v[86:87] op_sel_hi:[0,1]
	v_mul_f32_e32 v84, 0xbfb8aa3b, v80
	v_pk_mul_f32 v[82:83], v[80:81], v[82:83]
	v_mul_f32_e32 v80, 0xbfb8aa3b, v81
	v_exp_f32_e32 v84, v84
	v_exp_f32_e32 v80, v80
	v_add_f32_e32 v84, 1.0, v84
	v_add_f32_e32 v80, 1.0, v80
	v_rcp_f32_e32 v84, v84
	v_rcp_f32_e32 v85, v80
	s_nop 0
	v_pk_mul_f32 v[80:81], v[84:85], v[82:83]
	s_nop 0
	v_cvt_pk_bf16_f32 v91, v80, v81
	v_mad_i64_i32 v[80:81], s[14:15], v97, s62, v[112:113]
	v_lshl_add_u64 v[80:81], v[80:81], 0, v[114:115]
	global_store_dwordx4 v[80:81], v[88:91], off
	v_fmamk_f32 v80, v156, 0x3a000000, v151
	v_rsq_f32_e32 v80, v80
	v_or_b32_e32 v81, 48, v160
	v_pk_mul_f32 v[76:77], v[80:81], v[76:77] op_sel_hi:[0,1]
	v_pk_mul_f32 v[72:73], v[80:81], v[72:73] op_sel_hi:[0,1]
	v_mul_f32_e32 v82, 0xbfb8aa3b, v76
	v_pk_mul_f32 v[72:73], v[76:77], v[72:73]
	v_mul_f32_e32 v76, 0xbfb8aa3b, v77
	v_exp_f32_e32 v82, v82
	v_exp_f32_e32 v76, v76
	v_pk_mul_f32 v[74:75], v[80:81], v[74:75] op_sel_hi:[0,1]
	v_pk_mul_f32 v[68:69], v[80:81], v[68:69] op_sel_hi:[0,1]
	v_add_f32_e32 v82, 1.0, v82
	v_add_f32_e32 v76, 1.0, v76
	v_rcp_f32_e32 v82, v82
	v_rcp_f32_e32 v83, v76
	v_pk_mul_f32 v[76:77], v[80:81], v[78:79] op_sel_hi:[0,1]
	v_pk_mul_f32 v[74:75], v[76:77], v[74:75]
	v_pk_mul_f32 v[64:65], v[80:81], v[64:65] op_sel_hi:[0,1]
	v_pk_mul_f32 v[72:73], v[82:83], v[72:73]
	v_pk_mul_f32 v[64:65], v[68:69], v[64:65]
	v_cvt_pk_bf16_f32 v72, v72, v73
	v_mul_f32_e32 v73, 0xbfb8aa3b, v76
	v_exp_f32_e32 v73, v73
	v_pk_mul_f32 v[66:67], v[80:81], v[66:67] op_sel_hi:[0,1]
	v_add_f32_e32 v73, 1.0, v73
	v_rcp_f32_e32 v78, v73
	v_mul_f32_e32 v73, 0xbfb8aa3b, v77
	v_exp_f32_e32 v73, v73
	s_nop 0
	v_add_f32_e32 v73, 1.0, v73
	v_rcp_f32_e32 v79, v73
	s_nop 0
	v_pk_mul_f32 v[74:75], v[78:79], v[74:75]
	s_nop 0
	v_cvt_pk_bf16_f32 v73, v74, v75
	v_mul_f32_e32 v74, 0xbfb8aa3b, v68
	v_mul_f32_e32 v68, 0xbfb8aa3b, v69
	v_exp_f32_e32 v74, v74
	v_exp_f32_e32 v68, v68
	v_add_f32_e32 v74, 1.0, v74
	v_add_f32_e32 v68, 1.0, v68
	v_rcp_f32_e32 v74, v74
	v_rcp_f32_e32 v75, v68
	s_nop 0
	v_pk_mul_f32 v[64:65], v[74:75], v[64:65]
	s_nop 0
	v_cvt_pk_bf16_f32 v74, v64, v65
	v_pk_mul_f32 v[64:65], v[80:81], v[70:71] op_sel_hi:[0,1]
	v_mul_f32_e32 v68, 0xbfb8aa3b, v64
	v_pk_mul_f32 v[66:67], v[64:65], v[66:67]
	v_mul_f32_e32 v64, 0xbfb8aa3b, v65
	v_exp_f32_e32 v68, v68
	v_exp_f32_e32 v64, v64
	v_add_f32_e32 v68, 1.0, v68
	v_add_f32_e32 v64, 1.0, v64
	v_rcp_f32_e32 v68, v68
	v_rcp_f32_e32 v69, v64
	s_nop 0
	v_pk_mul_f32 v[64:65], v[68:69], v[66:67]
	s_nop 0
	v_cvt_pk_bf16_f32 v75, v64, v65
	v_mad_i64_i32 v[64:65], s[14:15], v81, s62, v[112:113]
	v_lshl_add_u64 v[64:65], v[64:65], 0, v[114:115]
	global_store_dwordx4 v[64:65], v[72:75], off
	v_fmamk_f32 v64, v155, 0x3a000000, v151
	v_rsq_f32_e32 v64, v64
	v_add_u32_e32 v65, 0x80, v160
	v_pk_mul_f32 v[60:61], v[64:65], v[60:61] op_sel_hi:[0,1]
	v_pk_mul_f32 v[56:57], v[64:65], v[56:57] op_sel_hi:[0,1]
	v_mul_f32_e32 v66, 0xbfb8aa3b, v60
	v_pk_mul_f32 v[56:57], v[60:61], v[56:57]
	v_mul_f32_e32 v60, 0xbfb8aa3b, v61
	v_exp_f32_e32 v66, v66
	v_exp_f32_e32 v60, v60
	v_pk_mul_f32 v[58:59], v[64:65], v[58:59] op_sel_hi:[0,1]
	v_pk_mul_f32 v[52:53], v[64:65], v[52:53] op_sel_hi:[0,1]
	v_add_f32_e32 v66, 1.0, v66
	v_add_f32_e32 v60, 1.0, v60
	v_rcp_f32_e32 v66, v66
	v_rcp_f32_e32 v67, v60
	v_pk_mul_f32 v[60:61], v[64:65], v[62:63] op_sel_hi:[0,1]
	v_pk_mul_f32 v[58:59], v[60:61], v[58:59]
	v_pk_mul_f32 v[48:49], v[64:65], v[48:49] op_sel_hi:[0,1]
	v_pk_mul_f32 v[56:57], v[66:67], v[56:57]
	v_pk_mul_f32 v[48:49], v[52:53], v[48:49]
; __device__ __forceinline__ float sigmoidf_(float x) { return __builtin_amdgcn_rcpf(1.0f + fexp(-x)); }
;     __device__ __forceinline__ void operator()(const f32x4 (&acc)[2][2][4][2], const Unit& u, int wr, int wc, int fr, int fq, const Pre& P) const {
;         const int row0 = ROW_X + u.pm * BM + wr * 64 + fr, col0 = u.pn * HALF + wc * 32 + 8 * fq;
; #pragma unroll
;         for (int ai = 0; ai < 2; ++ai)
; #pragma unroll
;             for (int m = 0; m < 4; ++m) { const int r = row0 + ai * HALF + m * 16; const float rs = __builtin_amdgcn_rsqf(P.rs[ai * 4 + m] * (1.0f / DM) + RMS_EPS);
;                 float y[8];
; #pragma unroll
;                 for (int n = 0; n < 2; ++n)
; #pragma unroll
;                     for (int j = 0; j < 4; ++j) { const float a = acc[ai][0][m][n][j] * rs, b = acc[ai][1][m][n][j] * rs; y[n * 4 + j] = a * b * sigmoidf_(a); }
;                 u32x4 w; w.x = cvtpk(y[0], y[1]); w.y = cvtpk(y[2], y[3]); w.z = cvtpk(y[4], y[5]); w.w = cvtpk(y[6], y[7]);
;                 *(u32x4*)(O + (size_t)r * FF + col0) = w; }
	v_cvt_pk_bf16_f32 v56, v56, v57
	v_mul_f32_e32 v57, 0xbfb8aa3b, v60
	v_exp_f32_e32 v57, v57
	v_pk_mul_f32 v[50:51], v[64:65], v[50:51] op_sel_hi:[0,1]
	v_add_f32_e32 v57, 1.0, v57
	v_rcp_f32_e32 v62, v57
	v_mul_f32_e32 v57, 0xbfb8aa3b, v61
	v_exp_f32_e32 v57, v57
	s_nop 0
	v_add_f32_e32 v57, 1.0, v57
	v_rcp_f32_e32 v63, v57
	s_nop 0
	v_pk_mul_f32 v[58:59], v[62:63], v[58:59]
	s_nop 0
	v_cvt_pk_bf16_f32 v57, v58, v59
	v_mul_f32_e32 v58, 0xbfb8aa3b, v52
	v_mul_f32_e32 v52, 0xbfb8aa3b, v53
	v_exp_f32_e32 v58, v58
	v_exp_f32_e32 v52, v52
	v_add_f32_e32 v58, 1.0, v58
	v_add_f32_e32 v52, 1.0, v52
	v_rcp_f32_e32 v58, v58
	v_rcp_f32_e32 v59, v52
	s_nop 0
	v_pk_mul_f32 v[48:49], v[58:59], v[48:49]
	s_nop 0
	v_cvt_pk_bf16_f32 v58, v48, v49
	v_pk_mul_f32 v[48:49], v[64:65], v[54:55] op_sel_hi:[0,1]
	v_mul_f32_e32 v52, 0xbfb8aa3b, v48
	v_pk_mul_f32 v[50:51], v[48:49], v[50:51]
	v_mul_f32_e32 v48, 0xbfb8aa3b, v49
	v_exp_f32_e32 v52, v52
	v_exp_f32_e32 v48, v48
	v_add_f32_e32 v52, 1.0, v52
	v_add_f32_e32 v48, 1.0, v48
	v_rcp_f32_e32 v52, v52
	v_rcp_f32_e32 v53, v48
	s_nop 0
	v_pk_mul_f32 v[48:49], v[52:53], v[50:51]
	s_nop 0
	v_cvt_pk_bf16_f32 v59, v48, v49
	v_mad_i64_i32 v[48:49], s[14:15], v65, s62, v[112:113]
	v_lshl_add_u64 v[48:49], v[48:49], 0, v[114:115]
	global_store_dwordx4 v[48:49], v[56:59], off
	v_fmamk_f32 v48, v154, 0x3a000000, v151
	v_rsq_f32_e32 v48, v48
	v_add_u32_e32 v49, 0x90, v160
	v_pk_mul_f32 v[44:45], v[48:49], v[44:45] op_sel_hi:[0,1]
	v_pk_mul_f32 v[40:41], v[48:49], v[40:41] op_sel_hi:[0,1]
	v_mul_f32_e32 v50, 0xbfb8aa3b, v44
	v_pk_mul_f32 v[40:41], v[44:45], v[40:41]
	v_mul_f32_e32 v44, 0xbfb8aa3b, v45
	v_exp_f32_e32 v50, v50
	v_exp_f32_e32 v44, v44
	v_pk_mul_f32 v[42:43], v[48:49], v[42:43] op_sel_hi:[0,1]
	v_pk_mul_f32 v[36:37], v[48:49], v[36:37] op_sel_hi:[0,1]
	v_add_f32_e32 v50, 1.0, v50
	v_add_f32_e32 v44, 1.0, v44
	v_rcp_f32_e32 v50, v50
	v_rcp_f32_e32 v51, v44
	v_pk_mul_f32 v[44:45], v[48:49], v[46:47] op_sel_hi:[0,1]
	v_pk_mul_f32 v[42:43], v[44:45], v[42:43]
	v_pk_mul_f32 v[32:33], v[48:49], v[32:33] op_sel_hi:[0,1]
	v_pk_mul_f32 v[40:41], v[50:51], v[40:41]
	v_pk_mul_f32 v[32:33], v[36:37], v[32:33]
	v_cvt_pk_bf16_f32 v40, v40, v41
	v_mul_f32_e32 v41, 0xbfb8aa3b, v44
	v_exp_f32_e32 v41, v41
	v_pk_mul_f32 v[34:35], v[48:49], v[34:35] op_sel_hi:[0,1]
	v_add_f32_e32 v41, 1.0, v41
	v_rcp_f32_e32 v46, v41
	v_mul_f32_e32 v41, 0xbfb8aa3b, v45
	v_exp_f32_e32 v41, v41
	s_nop 0
	v_add_f32_e32 v41, 1.0, v41
	v_rcp_f32_e32 v47, v41
	s_nop 0
	v_pk_mul_f32 v[42:43], v[46:47], v[42:43]
	s_nop 0
	v_cvt_pk_bf16_f32 v41, v42, v43
	v_mul_f32_e32 v42, 0xbfb8aa3b, v36
	v_mul_f32_e32 v36, 0xbfb8aa3b, v37
	v_exp_f32_e32 v42, v42
	v_exp_f32_e32 v36, v36
	v_add_f32_e32 v42, 1.0, v42
	v_add_f32_e32 v36, 1.0, v36
	v_rcp_f32_e32 v42, v42
	v_rcp_f32_e32 v43, v36
	s_nop 0
	v_pk_mul_f32 v[32:33], v[42:43], v[32:33]
	s_nop 0
	v_cvt_pk_bf16_f32 v42, v32, v33
	v_pk_mul_f32 v[32:33], v[48:49], v[38:39] op_sel_hi:[0,1]
	v_mul_f32_e32 v36, 0xbfb8aa3b, v32
	v_pk_mul_f32 v[34:35], v[32:33], v[34:35]
	v_mul_f32_e32 v32, 0xbfb8aa3b, v33
	v_exp_f32_e32 v36, v36
	v_exp_f32_e32 v32, v32
	v_add_f32_e32 v36, 1.0, v36
	v_add_f32_e32 v32, 1.0, v32
	v_rcp_f32_e32 v36, v36
	v_rcp_f32_e32 v37, v32
	s_nop 0
	v_pk_mul_f32 v[32:33], v[36:37], v[34:35]
	s_nop 0
	v_cvt_pk_bf16_f32 v43, v32, v33
	v_mad_i64_i32 v[32:33], s[14:15], v49, s62, v[112:113]
	v_lshl_add_u64 v[32:33], v[32:33], 0, v[114:115]
	global_store_dwordx4 v[32:33], v[40:43], off
	v_fmamk_f32 v32, v153, 0x3a000000, v151
	v_rsq_f32_e32 v32, v32
	v_add_u32_e32 v33, 0xa0, v160
	v_pk_mul_f32 v[28:29], v[32:33], v[28:29] op_sel_hi:[0,1]
	v_pk_mul_f32 v[24:25], v[32:33], v[24:25] op_sel_hi:[0,1]
	v_mul_f32_e32 v34, 0xbfb8aa3b, v28
	v_pk_mul_f32 v[24:25], v[28:29], v[24:25]
	v_mul_f32_e32 v28, 0xbfb8aa3b, v29
	v_exp_f32_e32 v34, v34
	v_exp_f32_e32 v28, v28
	v_pk_mul_f32 v[26:27], v[32:33], v[26:27] op_sel_hi:[0,1]
	v_pk_mul_f32 v[20:21], v[32:33], v[20:21] op_sel_hi:[0,1]
	v_add_f32_e32 v34, 1.0, v34
	v_add_f32_e32 v28, 1.0, v28
	v_rcp_f32_e32 v34, v34
	v_rcp_f32_e32 v35, v28
	v_pk_mul_f32 v[28:29], v[32:33], v[30:31] op_sel_hi:[0,1]
	v_pk_mul_f32 v[26:27], v[28:29], v[26:27]
	v_pk_mul_f32 v[16:17], v[32:33], v[16:17] op_sel_hi:[0,1]
	v_pk_mul_f32 v[24:25], v[34:35], v[24:25]
	v_pk_mul_f32 v[16:17], v[20:21], v[16:17]
; __device__ __forceinline__ float sigmoidf_(float x) { return __builtin_amdgcn_rcpf(1.0f + fexp(-x)); }
; __device__ __forceinline__ PreRs load_rs(const float* ssq, int pm, int wr, int fr) { PreRs p;
; #pragma unroll
;     for (int ai = 0; ai < 2; ++ai)
; #pragma unroll
;         for (int m = 0; m < 4; ++m) p.rs[ai * 4 + m] = ssq[ROW_X + pm * BM + ai * HALF + wr * 64 + m * 16 + fr];
;     return p; }
;     __device__ __forceinline__ void operator()(const f32x4 (&acc)[2][2][4][2], const Unit& u, int wr, int wc, int fr, int fq, const Pre& P) const {
;     ...
;             for (int m = 0; m < 4; ++m) { const int r = row0 + ai * HALF + m * 16; const float rs = __builtin_amdgcn_rsqf(P.rs[ai * 4 + m] * (1.0f / DM) + RMS_EPS);
;                 float y[8];
; #pragma unroll
;                 for (int n = 0; n < 2; ++n)
; #pragma unroll
;                     for (int j = 0; j < 4; ++j) { const float a = acc[ai][0][m][n][j] * rs, b = acc[ai][1][m][n][j] * rs; y[n * 4 + j] = a * b * sigmoidf_(a); }
;                 u32x4 w; w.x = cvtpk(y[0], y[1]); w.y = cvtpk(y[2], y[3]); w.z = cvtpk(y[4], y[5]); w.w = cvtpk(y[6], y[7]);
;                 *(u32x4*)(O + (size_t)r * FF + col0) = w; }
	v_cvt_pk_bf16_f32 v24, v24, v25
	v_mul_f32_e32 v25, 0xbfb8aa3b, v28
	v_exp_f32_e32 v25, v25
	v_pk_mul_f32 v[18:19], v[32:33], v[18:19] op_sel_hi:[0,1]
	v_add_f32_e32 v25, 1.0, v25
	v_rcp_f32_e32 v30, v25
	v_mul_f32_e32 v25, 0xbfb8aa3b, v29
	v_exp_f32_e32 v25, v25
	s_nop 0
	v_add_f32_e32 v25, 1.0, v25
	v_rcp_f32_e32 v31, v25
	s_nop 0
	v_pk_mul_f32 v[26:27], v[30:31], v[26:27]
	s_nop 0
	v_cvt_pk_bf16_f32 v25, v26, v27
	v_mul_f32_e32 v26, 0xbfb8aa3b, v20
	v_mul_f32_e32 v20, 0xbfb8aa3b, v21
	v_exp_f32_e32 v26, v26
	v_exp_f32_e32 v20, v20
	v_add_f32_e32 v26, 1.0, v26
	v_add_f32_e32 v20, 1.0, v20
	v_rcp_f32_e32 v26, v26
	v_rcp_f32_e32 v27, v20
	s_nop 0
	v_pk_mul_f32 v[16:17], v[26:27], v[16:17]
	s_nop 0
	v_cvt_pk_bf16_f32 v26, v16, v17
	v_pk_mul_f32 v[16:17], v[32:33], v[22:23] op_sel_hi:[0,1]
	v_mul_f32_e32 v20, 0xbfb8aa3b, v16
	v_pk_mul_f32 v[18:19], v[16:17], v[18:19]
	v_mul_f32_e32 v16, 0xbfb8aa3b, v17
	v_exp_f32_e32 v20, v20
	v_exp_f32_e32 v16, v16
	v_add_f32_e32 v20, 1.0, v20
	v_add_f32_e32 v16, 1.0, v16
	v_rcp_f32_e32 v20, v20
	v_rcp_f32_e32 v21, v16
	s_nop 0
	v_pk_mul_f32 v[16:17], v[20:21], v[18:19]
	s_nop 0
	v_cvt_pk_bf16_f32 v27, v16, v17
	v_mad_i64_i32 v[16:17], s[14:15], v33, s62, v[112:113]
	v_lshl_add_u64 v[16:17], v[16:17], 0, v[114:115]
	global_store_dwordx4 v[16:17], v[24:27], off
	v_fmamk_f32 v16, v152, 0x3a000000, v151
	v_rsq_f32_e32 v16, v16
	v_add_u32_e32 v17, 0xb0, v160
	v_pk_mul_f32 v[12:13], v[16:17], v[12:13] op_sel_hi:[0,1]
	v_pk_mul_f32 v[8:9], v[16:17], v[8:9] op_sel_hi:[0,1]
	v_mul_f32_e32 v18, 0xbfb8aa3b, v12
	v_pk_mul_f32 v[8:9], v[12:13], v[8:9]
	v_mul_f32_e32 v12, 0xbfb8aa3b, v13
	v_exp_f32_e32 v18, v18
	v_exp_f32_e32 v12, v12
	v_pk_mul_f32 v[10:11], v[16:17], v[10:11] op_sel_hi:[0,1]
	v_pk_mul_f32 v[4:5], v[16:17], v[4:5] op_sel_hi:[0,1]
	v_add_f32_e32 v18, 1.0, v18
	v_add_f32_e32 v12, 1.0, v12
	v_rcp_f32_e32 v18, v18
	v_rcp_f32_e32 v19, v12
	v_pk_mul_f32 v[12:13], v[16:17], v[14:15] op_sel_hi:[0,1]
	v_pk_mul_f32 v[10:11], v[12:13], v[10:11]
	v_pk_mul_f32 v[0:1], v[16:17], v[0:1] op_sel_hi:[0,1]
	v_pk_mul_f32 v[8:9], v[18:19], v[8:9]
	v_pk_mul_f32 v[0:1], v[4:5], v[0:1]
	v_cvt_pk_bf16_f32 v8, v8, v9
	v_mul_f32_e32 v9, 0xbfb8aa3b, v12
	v_exp_f32_e32 v9, v9
	v_pk_mul_f32 v[2:3], v[16:17], v[2:3] op_sel_hi:[0,1]
	v_add_f32_e32 v9, 1.0, v9
	v_rcp_f32_e32 v14, v9
	v_mul_f32_e32 v9, 0xbfb8aa3b, v13
	v_exp_f32_e32 v9, v9
	s_nop 0
	v_add_f32_e32 v9, 1.0, v9
	v_rcp_f32_e32 v15, v9
	s_nop 0
	v_pk_mul_f32 v[10:11], v[14:15], v[10:11]
	s_nop 0
	v_cvt_pk_bf16_f32 v9, v10, v11
	v_mul_f32_e32 v10, 0xbfb8aa3b, v4
	v_mul_f32_e32 v4, 0xbfb8aa3b, v5
	v_exp_f32_e32 v10, v10
	v_exp_f32_e32 v4, v4
	v_add_f32_e32 v10, 1.0, v10
	v_add_f32_e32 v4, 1.0, v4
	v_rcp_f32_e32 v10, v10
	v_rcp_f32_e32 v11, v4
	s_nop 0
	v_pk_mul_f32 v[0:1], v[10:11], v[0:1]
	s_nop 0
	v_cvt_pk_bf16_f32 v10, v0, v1
	v_pk_mul_f32 v[0:1], v[16:17], v[6:7] op_sel_hi:[0,1]
	v_mul_f32_e32 v4, 0xbfb8aa3b, v0
	v_pk_mul_f32 v[2:3], v[0:1], v[2:3]
	v_mul_f32_e32 v0, 0xbfb8aa3b, v1
	v_exp_f32_e32 v4, v4
	v_exp_f32_e32 v0, v0
	v_add_f32_e32 v4, 1.0, v4
	v_add_f32_e32 v0, 1.0, v0
	v_rcp_f32_e32 v4, v4
	v_rcp_f32_e32 v5, v0
	s_nop 0
	v_pk_mul_f32 v[0:1], v[4:5], v[2:3]
	s_nop 0
	v_cvt_pk_bf16_f32 v11, v0, v1
	v_mad_i64_i32 v[0:1], s[14:15], v17, s62, v[112:113]
	v_lshl_add_u64 v[0:1], v[0:1], 0, v[114:115]
	s_mov_b64 s[14:15], -1
	global_store_dwordx4 v[0:1], v[8:11], off
	s_cbranch_vccz .LBB0_255
	v_lshl_add_u32 v0, s8, 8, v145
	v_ashrrev_i32_e32 v1, 31, v0
	v_lshl_add_u64 v[2:3], v[0:1], 2, s[2:3]
	v_add_u32_e32 v4, 0x80, v0
	v_add_u32_e32 v6, 0x90, v0
	v_add_u32_e32 v8, 0xa0, v0
	v_add_u32_e32 v0, 0xb0, v0
	v_ashrrev_i32_e32 v5, 31, v4
	v_ashrrev_i32_e32 v7, 31, v6
	v_ashrrev_i32_e32 v9, 31, v8
	v_ashrrev_i32_e32 v1, 31, v0
	v_lshl_add_u64 v[4:5], v[4:5], 2, s[2:3]
	v_lshl_add_u64 v[6:7], v[6:7], 2, s[2:3]
	v_lshl_add_u64 v[8:9], v[8:9], 2, s[2:3]
	v_lshl_add_u64 v[0:1], v[0:1], 2, s[2:3]
	global_load_dword v159, v[2:3], off
	global_load_dword v158, v[2:3], off offset:64
	global_load_dword v157, v[2:3], off offset:128
	global_load_dword v156, v[2:3], off offset:192
	global_load_dword v155, v[4:5], off
	global_load_dword v154, v[6:7], off
	global_load_dword v153, v[8:9], off
	global_load_dword v152, v[0:1], off
	s_mov_b64 s[14:15], 0
	s_branch .LBB0_255

; #define PG8_STAGE(bufoff, gbase, voff) do { _Pragma("unroll") for (int _i = 0; _i < 2; ++_i) \
;         __builtin_amdgcn_global_load_lds((const unsigned*)((const char*)(gbase) + (voff)[_i]), (LAS unsigned*)(lds + (bufoff) + ldsw + _i * 8192), 16, 0, 0); } while (0)
; #define PG8_LDA(dst, b, h) do { _Pragma("unroll") for (int m = 0; m < 4; ++m) _Pragma("unroll") for (int k = 0; k < 2; ++k) dst[m][k] = *(const LAS bf16x8*)(lds + PG8_SA(b, h) + aoff + m * 2048 + k * 1024); } while (0)
; #define PG8_LDB(dst, b, h) do { _Pragma("unroll") for (int n = 0; n < 2; ++n) _Pragma("unroll") for (int k = 0; k < 2; ++k) dst[n][k] = *(const LAS bf16x8*)(lds + PG8_SB(b, h) + boff + n * 2048 + k * 1024); } while (0)
; #define PG8_MMA(ai, bj, At, Bt) do { __builtin_amdgcn_s_setprio(1); _Pragma("unroll") for (int m = 0; m < 4; ++m) _Pragma("unroll") for (int n = 0; n < 2; ++n) _Pragma("unroll") for (int k = 0; k < 2; ++k) \
;         acc[ai][bj][m][n] = __builtin_amdgcn_mfma_f32_16x16x32_bf16(Bt[n][k], At[m][k], acc[ai][bj][m][n], 0, 0, 0); __builtin_amdgcn_s_setprio(0); } while (0)
; #define PG8_WAIT_L(n) asm volatile("s_waitcnt lgkmcnt(" #n ")" ::: "memory")
; #define PG8_BAR __builtin_amdgcn_s_barrier()
; #define PG8_SCHED __builtin_amdgcn_sched_barrier(0)
; template <class Epi>
; __device__ __forceinline__ void gemm_phase(LAS unsigned char* lds, const Gemm g, const StaticOrder& S, const Epi& E) {
;     ...
;             PG8_LDB(B0, 0, 0); PG8_SCHED; PG8_LDA(At, 0, 0); PG8_STAGE(PG8_SA(1, 1), a1 + hstep, voffA);
;             PG8_WAIT_L(8); PG8_BAR; PG8_WAIT_L(0); PG8_MMA(0, 0, At, B0); PG8_BAR; PG8_SCHED;
.LBB0_364:
	ds_read_b128 v[128:131], v161
	ds_read_b128 v[132:135], v161 offset:1024
	ds_read_b128 v[152:155], v161 offset:2048
	ds_read_b128 v[166:169], v161 offset:3072
	s_add_u32 s16, s14, 0xffea8080
	s_addc_u32 s17, s15, -1
	s_cmpk_eq_i32 s65, 0x52
	s_cselect_b32 s19, s1, s17
	s_cselect_b32 s18, s0, s16
	s_cselect_b32 s17, s7, s64
	s_cselect_b32 s16, s6, s63
	v_lshl_add_u64 v[156:157], s[14:15], 0, v[144:145]
	s_add_i32 m0, s30, 0xc000
	ds_read_b128 v[170:173], v162
	ds_read_b128 v[174:177], v162 offset:1024
	ds_read_b128 v[180:183], v162 offset:2048
	ds_read_b128 v[184:187], v162 offset:3072
	ds_read_b128 v[188:191], v162 offset:4096
	ds_read_b128 v[192:195], v162 offset:5120
	ds_read_b128 v[196:199], v162 offset:6144
	ds_read_b128 v[200:203], v162 offset:7168
	global_load_lds_dwordx4 v[156:157], off
	v_lshl_add_u64 v[156:157], s[14:15], 0, v[146:147]
	s_add_i32 m0, s30, 0xe000
	s_nop 0
	global_load_lds_dwordx4 v[156:157], off
	s_waitcnt lgkmcnt(8)
	s_setprio 1
	s_barrier
	s_waitcnt lgkmcnt(0)


; #define PG8_STAGE(bufoff, gbase, voff) do { _Pragma("unroll") for (int _i = 0; _i < 2; ++_i) \
;         __builtin_amdgcn_global_load_lds((const unsigned*)((const char*)(gbase) + (voff)[_i]), (LAS unsigned*)(lds + (bufoff) + ldsw + _i * 8192), 16, 0, 0); } while (0)
; #define PG8_LDB(dst, b, h) do { _Pragma("unroll") for (int n = 0; n < 2; ++n) _Pragma("unroll") for (int k = 0; k < 2; ++k) dst[n][k] = *(const LAS bf16x8*)(lds + PG8_SB(b, h) + boff + n * 2048 + k * 1024); } while (0)
; #define PG8_MMA(ai, bj, At, Bt) do { __builtin_amdgcn_s_setprio(1); _Pragma("unroll") for (int m = 0; m < 4; ++m) _Pragma("unroll") for (int n = 0; n < 2; ++n) _Pragma("unroll") for (int k = 0; k < 2; ++k) \
;         acc[ai][bj][m][n] = __builtin_amdgcn_mfma_f32_16x16x32_bf16(Bt[n][k], At[m][k], acc[ai][bj][m][n], 0, 0, 0); __builtin_amdgcn_s_setprio(0); } while (0)
; #define PG8_WAIT_L(n) asm volatile("s_waitcnt lgkmcnt(" #n ")" ::: "memory")
; #define PG8_BAR __builtin_amdgcn_s_barrier()
; #define PG8_SCHED __builtin_amdgcn_sched_barrier(0)
; template <class Epi>
; __device__ __forceinline__ void gemm_phase(LAS unsigned char* lds, const Gemm g, const StaticOrder& S, const Epi& E) {
;     ...
;             PG8_WAIT_L(8); PG8_BAR; PG8_WAIT_L(0); PG8_MMA(0, 0, At, B0); PG8_BAR; PG8_SCHED;
;             PG8_LDB(B1, 0, 1); PG8_STAGE(PG8_SB(0, 0), b2, voffB);
;             PG8_BAR; PG8_WAIT_L(0); PG8_MMA(0, 1, At, B1); PG8_BAR;
	v_mfma_f32_16x16x32_bf16 v[124:127], v[128:131], v[170:173], v[124:127]
	v_mfma_f32_16x16x32_bf16 v[120:123], v[152:155], v[170:173], v[120:123]
	v_mfma_f32_16x16x32_bf16 v[108:111], v[128:131], v[180:183], v[108:111]
	v_mfma_f32_16x16x32_bf16 v[104:107], v[152:155], v[180:183], v[104:107]
	v_mfma_f32_16x16x32_bf16 v[92:95], v[128:131], v[188:191], v[92:95]
	v_mfma_f32_16x16x32_bf16 v[88:91], v[152:155], v[188:191], v[88:91]
	v_mfma_f32_16x16x32_bf16 v[76:79], v[128:131], v[196:199], v[76:79]
	v_mfma_f32_16x16x32_bf16 v[72:75], v[152:155], v[196:199], v[72:75]
	v_mfma_f32_16x16x32_bf16 v[124:127], v[132:135], v[174:177], v[124:127]
	v_mfma_f32_16x16x32_bf16 v[120:123], v[166:169], v[174:177], v[120:123]
	v_mfma_f32_16x16x32_bf16 v[108:111], v[132:135], v[184:187], v[108:111]
	v_mfma_f32_16x16x32_bf16 v[104:107], v[166:169], v[184:187], v[104:107]
	v_mfma_f32_16x16x32_bf16 v[92:95], v[132:135], v[192:195], v[92:95]
	v_mfma_f32_16x16x32_bf16 v[88:91], v[166:169], v[192:195], v[88:91]
	v_mfma_f32_16x16x32_bf16 v[76:79], v[132:135], v[200:203], v[76:79]
	v_mfma_f32_16x16x32_bf16 v[72:75], v[166:169], v[200:203], v[72:75]
	s_setprio 0
	s_barrier
	s_add_i32 s66, s57, s21
	v_lshl_add_u64 v[156:157], s[16:17], 0, v[138:139]
	s_mov_b32 m0, s66
	ds_read_b128 v[204:207], v163
	ds_read_b128 v[208:211], v163 offset:1024
	ds_read_b128 v[212:215], v163 offset:2048
	ds_read_b128 v[216:219], v163 offset:3072
	global_load_lds_dwordx4 v[156:157], off
	v_lshl_add_u64 v[220:221], s[16:17], 0, v[142:143]
	s_add_i32 m0, s66, 0x2000
	s_nop 0
	global_load_lds_dwordx4 v[220:221], off
	s_waitcnt lgkmcnt(0)
	s_setprio 1
	s_barrier


; #define PG8_STAGE(bufoff, gbase, voff) do { _Pragma("unroll") for (int _i = 0; _i < 2; ++_i) \
;         __builtin_amdgcn_global_load_lds((const unsigned*)((const char*)(gbase) + (voff)[_i]), (LAS unsigned*)(lds + (bufoff) + ldsw + _i * 8192), 16, 0, 0); } while (0)
; #define PG8_LDA(dst, b, h) do { _Pragma("unroll") for (int m = 0; m < 4; ++m) _Pragma("unroll") for (int k = 0; k < 2; ++k) dst[m][k] = *(const LAS bf16x8*)(lds + PG8_SA(b, h) + aoff + m * 2048 + k * 1024); } while (0)
; #define PG8_MMA(ai, bj, At, Bt) do { __builtin_amdgcn_s_setprio(1); _Pragma("unroll") for (int m = 0; m < 4; ++m) _Pragma("unroll") for (int n = 0; n < 2; ++n) _Pragma("unroll") for (int k = 0; k < 2; ++k) \
;         acc[ai][bj][m][n] = __builtin_amdgcn_mfma_f32_16x16x32_bf16(Bt[n][k], At[m][k], acc[ai][bj][m][n], 0, 0, 0); __builtin_amdgcn_s_setprio(0); } while (0)
; #define PG8_WAIT_L(n) asm volatile("s_waitcnt lgkmcnt(" #n ")" ::: "memory")
; #define PG8_BAR __builtin_amdgcn_s_barrier()
; #define PG8_SCHED __builtin_amdgcn_sched_barrier(0)
; template <class Epi>
; __device__ __forceinline__ void gemm_phase(LAS unsigned char* lds, const Gemm g, const StaticOrder& S, const Epi& E) {
;     ...
;             PG8_BAR; PG8_WAIT_L(0); PG8_MMA(0, 1, At, B1); PG8_BAR;
;             PG8_LDA(At, 0, 1); PG8_STAGE(PG8_SA(0, 0), a2, voffA);
;             PG8_BAR; PG8_WAIT_L(0); PG8_MMA(1, 0, At, B0); PG8_BAR; PG8_SCHED;
	v_mfma_f32_16x16x32_bf16 v[116:119], v[204:207], v[170:173], v[116:119]
	v_mfma_f32_16x16x32_bf16 v[112:115], v[212:215], v[170:173], v[112:115]
	v_mfma_f32_16x16x32_bf16 v[100:103], v[204:207], v[180:183], v[100:103]
	v_mfma_f32_16x16x32_bf16 v[96:99], v[212:215], v[180:183], v[96:99]
	v_mfma_f32_16x16x32_bf16 v[84:87], v[204:207], v[188:191], v[84:87]
	v_mfma_f32_16x16x32_bf16 v[80:83], v[212:215], v[188:191], v[80:83]
	v_mfma_f32_16x16x32_bf16 v[68:71], v[204:207], v[196:199], v[68:71]
	v_mfma_f32_16x16x32_bf16 v[64:67], v[212:215], v[196:199], v[64:67]
	v_mfma_f32_16x16x32_bf16 v[116:119], v[208:211], v[174:177], v[116:119]
	v_mfma_f32_16x16x32_bf16 v[112:115], v[216:219], v[174:177], v[112:115]
	v_mfma_f32_16x16x32_bf16 v[100:103], v[208:211], v[184:187], v[100:103]
	v_mfma_f32_16x16x32_bf16 v[96:99], v[216:219], v[184:187], v[96:99]
	v_mfma_f32_16x16x32_bf16 v[84:87], v[208:211], v[192:195], v[84:87]
	v_mfma_f32_16x16x32_bf16 v[80:83], v[216:219], v[192:195], v[80:83]
	v_mfma_f32_16x16x32_bf16 v[68:71], v[208:211], v[200:203], v[68:71]
	v_mfma_f32_16x16x32_bf16 v[64:67], v[216:219], v[200:203], v[64:67]
	s_setprio 0
	s_mov_b32 m0, s30
	v_lshl_add_u64 v[222:223], s[18:19], 0, v[136:137]
	s_barrier
	ds_read_b128 v[170:173], v162 offset:16384
	ds_read_b128 v[174:177], v162 offset:17408
	ds_read_b128 v[180:183], v162 offset:18432
	ds_read_b128 v[184:187], v162 offset:19456
	ds_read_b128 v[188:191], v162 offset:20480
	ds_read_b128 v[192:195], v162 offset:21504
	ds_read_b128 v[196:199], v162 offset:22528
	ds_read_b128 v[200:203], v162 offset:23552
	global_load_lds_dwordx4 v[222:223], off
	v_lshl_add_u64 v[224:225], s[18:19], 0, v[140:141]
	s_mov_b32 m0, s31
	s_nop 0
	global_load_lds_dwordx4 v[224:225], off
	s_waitcnt lgkmcnt(0)
	s_setprio 1
	s_barrier


; #define PG8_STAGE(bufoff, gbase, voff) do { _Pragma("unroll") for (int _i = 0; _i < 2; ++_i) \
;         __builtin_amdgcn_global_load_lds((const unsigned*)((const char*)(gbase) + (voff)[_i]), (LAS unsigned*)(lds + (bufoff) + ldsw + _i * 8192), 16, 0, 0); } while (0)
; #define PG8_MMA(ai, bj, At, Bt) do { __builtin_amdgcn_s_setprio(1); _Pragma("unroll") for (int m = 0; m < 4; ++m) _Pragma("unroll") for (int n = 0; n < 2; ++n) _Pragma("unroll") for (int k = 0; k < 2; ++k) \
;         acc[ai][bj][m][n] = __builtin_amdgcn_mfma_f32_16x16x32_bf16(Bt[n][k], At[m][k], acc[ai][bj][m][n], 0, 0, 0); __builtin_amdgcn_s_setprio(0); } while (0)
; #define PG8_WAIT_V(n) asm volatile("s_waitcnt vmcnt(" #n ")" ::: "memory")
; #define PG8_WAIT_L(n) asm volatile("s_waitcnt lgkmcnt(" #n ")" ::: "memory")
; #define PG8_BAR __builtin_amdgcn_s_barrier()
; #define PG8_SCHED __builtin_amdgcn_sched_barrier(0)
; template <class Epi>
; __device__ __forceinline__ void gemm_phase(LAS unsigned char* lds, const Gemm g, const StaticOrder& S, const Epi& E) {
;     ...
;             PG8_BAR; PG8_WAIT_L(0); PG8_MMA(1, 0, At, B0); PG8_BAR; PG8_SCHED;
;             PG8_STAGE(PG8_SB(0, 1), b2 + hstep, voffB);
;             PG8_WAIT_V(6); PG8_BAR; PG8_MMA(1, 1, At, B1); PG8_BAR;
	v_mfma_f32_16x16x32_bf16 v[60:63], v[128:131], v[170:173], v[60:63]
	v_mfma_f32_16x16x32_bf16 v[56:59], v[152:155], v[170:173], v[56:59]
	v_mfma_f32_16x16x32_bf16 v[44:47], v[128:131], v[180:183], v[44:47]
	v_mfma_f32_16x16x32_bf16 v[40:43], v[152:155], v[180:183], v[40:43]
	v_mfma_f32_16x16x32_bf16 v[28:31], v[128:131], v[188:191], v[28:31]
	v_mfma_f32_16x16x32_bf16 v[24:27], v[152:155], v[188:191], v[24:27]
	v_mfma_f32_16x16x32_bf16 v[12:15], v[128:131], v[196:199], v[12:15]
	v_mfma_f32_16x16x32_bf16 v[8:11], v[152:155], v[196:199], v[8:11]
	v_mfma_f32_16x16x32_bf16 v[60:63], v[132:135], v[174:177], v[60:63]
	v_mfma_f32_16x16x32_bf16 v[56:59], v[166:169], v[174:177], v[56:59]
	v_mfma_f32_16x16x32_bf16 v[44:47], v[132:135], v[184:187], v[44:47]
	v_mfma_f32_16x16x32_bf16 v[40:43], v[166:169], v[184:187], v[40:43]
	v_mfma_f32_16x16x32_bf16 v[28:31], v[132:135], v[192:195], v[28:31]
	v_mfma_f32_16x16x32_bf16 v[24:27], v[166:169], v[192:195], v[24:27]
	v_mfma_f32_16x16x32_bf16 v[12:15], v[132:135], v[200:203], v[12:15]
	v_mfma_f32_16x16x32_bf16 v[8:11], v[166:169], v[200:203], v[8:11]
	s_setprio 0
	s_barrier
	s_add_u32 s66, s16, 0x158000
	s_addc_u32 s67, s17, 0
	s_add_i32 s68, s58, s21
	v_lshl_add_u64 v[128:129], s[66:67], 0, v[138:139]
	s_mov_b32 m0, s68
	s_nop 0
	global_load_lds_dwordx4 v[128:129], off
	v_lshl_add_u64 v[128:129], s[66:67], 0, v[142:143]
	s_add_i32 m0, s68, 0x2000
	s_nop 0
	global_load_lds_dwordx4 v[128:129], off
	s_waitcnt vmcnt(6)
	s_setprio 1
	s_barrier

; #define PG8_STAGE(bufoff, gbase, voff) do { _Pragma("unroll") for (int _i = 0; _i < 2; ++_i) \
;         __builtin_amdgcn_global_load_lds((const unsigned*)((const char*)(gbase) + (voff)[_i]), (LAS unsigned*)(lds + (bufoff) + ldsw + _i * 8192), 16, 0, 0); } while (0)
; #define PG8_LDA(dst, b, h) do { _Pragma("unroll") for (int m = 0; m < 4; ++m) _Pragma("unroll") for (int k = 0; k < 2; ++k) dst[m][k] = *(const LAS bf16x8*)(lds + PG8_SA(b, h) + aoff + m * 2048 + k * 1024); } while (0)
; #define PG8_LDB(dst, b, h) do { _Pragma("unroll") for (int n = 0; n < 2; ++n) _Pragma("unroll") for (int k = 0; k < 2; ++k) dst[n][k] = *(const LAS bf16x8*)(lds + PG8_SB(b, h) + boff + n * 2048 + k * 1024); } while (0)
; #define PG8_MMA(ai, bj, At, Bt) do { __builtin_amdgcn_s_setprio(1); _Pragma("unroll") for (int m = 0; m < 4; ++m) _Pragma("unroll") for (int n = 0; n < 2; ++n) _Pragma("unroll") for (int k = 0; k < 2; ++k) \
;         acc[ai][bj][m][n] = __builtin_amdgcn_mfma_f32_16x16x32_bf16(Bt[n][k], At[m][k], acc[ai][bj][m][n], 0, 0, 0); __builtin_amdgcn_s_setprio(0); } while (0)
; #define PG8_WAIT_V(n) asm volatile("s_waitcnt vmcnt(" #n ")" ::: "memory")
; #define PG8_WAIT_L(n) asm volatile("s_waitcnt lgkmcnt(" #n ")" ::: "memory")
; #define PG8_BAR __builtin_amdgcn_s_barrier()
; #define PG8_SCHED __builtin_amdgcn_sched_barrier(0)
; template <class Epi>
; __device__ __forceinline__ void gemm_phase(LAS unsigned char* lds, const Gemm g, const StaticOrder& S, const Epi& E) {
;     ...
;             PG8_WAIT_V(6); PG8_BAR; PG8_MMA(1, 1, At, B1); PG8_BAR;
;             PG8_LDB(B0, 1, 0); PG8_SCHED; PG8_LDA(At, 1, 0); PG8_STAGE(PG8_SA(0, 1), a2 + hstep, voffA);
;             PG8_WAIT_L(8); PG8_BAR; PG8_WAIT_L(0); PG8_MMA(0, 0, At, B0); PG8_BAR; PG8_SCHED;
	v_mfma_f32_16x16x32_bf16 v[52:55], v[204:207], v[170:173], v[52:55]
	v_mfma_f32_16x16x32_bf16 v[48:51], v[212:215], v[170:173], v[48:51]
	v_mfma_f32_16x16x32_bf16 v[36:39], v[204:207], v[180:183], v[36:39]
	v_mfma_f32_16x16x32_bf16 v[32:35], v[212:215], v[180:183], v[32:35]
	v_mfma_f32_16x16x32_bf16 v[20:23], v[204:207], v[188:191], v[20:23]
	v_mfma_f32_16x16x32_bf16 v[16:19], v[212:215], v[188:191], v[16:19]
	v_mfma_f32_16x16x32_bf16 v[4:7], v[204:207], v[196:199], v[4:7]
	v_mfma_f32_16x16x32_bf16 v[0:3], v[212:215], v[196:199], v[0:3]
	v_mfma_f32_16x16x32_bf16 v[52:55], v[208:211], v[174:177], v[52:55]
	v_mfma_f32_16x16x32_bf16 v[48:51], v[216:219], v[174:177], v[48:51]
	v_mfma_f32_16x16x32_bf16 v[36:39], v[208:211], v[184:187], v[36:39]
	v_mfma_f32_16x16x32_bf16 v[32:35], v[216:219], v[184:187], v[32:35]
	v_mfma_f32_16x16x32_bf16 v[20:23], v[208:211], v[192:195], v[20:23]
	v_mfma_f32_16x16x32_bf16 v[16:19], v[216:219], v[192:195], v[16:19]
	v_mfma_f32_16x16x32_bf16 v[4:7], v[208:211], v[200:203], v[4:7]
	v_mfma_f32_16x16x32_bf16 v[0:3], v[216:219], v[200:203], v[0:3]
	s_setprio 0
	s_add_i32 s66, 0, 0x18000
	v_add_u32_e32 v166, s66, v158
	s_barrier
	ds_read_b128 v[128:131], v166
	ds_read_b128 v[132:135], v166 offset:1024
	ds_read_b128 v[152:155], v166 offset:2048
	ds_read_b128 v[166:169], v166 offset:3072
	s_add_u32 s18, s18, 0x158000
	s_addc_u32 s19, s19, 0
	s_mov_b32 m0, s33
	v_lshl_add_u64 v[204:205], s[18:19], 0, v[136:137]
	ds_read_b128 v[170:173], v162 offset:32768
	ds_read_b128 v[174:177], v162 offset:33792
	ds_read_b128 v[180:183], v162 offset:34816
	ds_read_b128 v[184:187], v162 offset:35840
	ds_read_b128 v[188:191], v162 offset:36864
	ds_read_b128 v[192:195], v162 offset:37888
	ds_read_b128 v[196:199], v162 offset:38912
	ds_read_b128 v[200:203], v162 offset:39936
	global_load_lds_dwordx4 v[204:205], off
	v_lshl_add_u64 v[204:205], s[18:19], 0, v[140:141]
	s_mov_b32 m0, s34
	s_nop 0
	global_load_lds_dwordx4 v[204:205], off
	s_waitcnt lgkmcnt(8)
	s_setprio 1
	s_barrier
	s_waitcnt lgkmcnt(0)


; #define PG8_STAGE(bufoff, gbase, voff) do { _Pragma("unroll") for (int _i = 0; _i < 2; ++_i) \
;         __builtin_amdgcn_global_load_lds((const unsigned*)((const char*)(gbase) + (voff)[_i]), (LAS unsigned*)(lds + (bufoff) + ldsw + _i * 8192), 16, 0, 0); } while (0)
; #define PG8_LDB(dst, b, h) do { _Pragma("unroll") for (int n = 0; n < 2; ++n) _Pragma("unroll") for (int k = 0; k < 2; ++k) dst[n][k] = *(const LAS bf16x8*)(lds + PG8_SB(b, h) + boff + n * 2048 + k * 1024); } while (0)
; #define PG8_MMA(ai, bj, At, Bt) do { __builtin_amdgcn_s_setprio(1); _Pragma("unroll") for (int m = 0; m < 4; ++m) _Pragma("unroll") for (int n = 0; n < 2; ++n) _Pragma("unroll") for (int k = 0; k < 2; ++k) \
;         acc[ai][bj][m][n] = __builtin_amdgcn_mfma_f32_16x16x32_bf16(Bt[n][k], At[m][k], acc[ai][bj][m][n], 0, 0, 0); __builtin_amdgcn_s_setprio(0); } while (0)
; #define PG8_WAIT_L(n) asm volatile("s_waitcnt lgkmcnt(" #n ")" ::: "memory")
; #define PG8_BAR __builtin_amdgcn_s_barrier()
; #define PG8_SCHED __builtin_amdgcn_sched_barrier(0)
; template <class Epi>
; __device__ __forceinline__ void gemm_phase(LAS unsigned char* lds, const Gemm g, const StaticOrder& S, const Epi& E) {
;     ...
;             PG8_WAIT_L(8); PG8_BAR; PG8_WAIT_L(0); PG8_MMA(0, 0, At, B0); PG8_BAR; PG8_SCHED;
;             PG8_LDB(B1, 1, 1); PG8_STAGE(PG8_SB(1, 0), b3, voffB);
;             PG8_BAR; PG8_WAIT_L(0); PG8_MMA(0, 1, At, B1); PG8_BAR;
	v_mfma_f32_16x16x32_bf16 v[124:127], v[128:131], v[170:173], v[124:127]
	v_mfma_f32_16x16x32_bf16 v[120:123], v[152:155], v[170:173], v[120:123]
	v_mfma_f32_16x16x32_bf16 v[108:111], v[128:131], v[180:183], v[108:111]
	v_mfma_f32_16x16x32_bf16 v[104:107], v[152:155], v[180:183], v[104:107]
	v_mfma_f32_16x16x32_bf16 v[92:95], v[128:131], v[188:191], v[92:95]
	v_mfma_f32_16x16x32_bf16 v[88:91], v[152:155], v[188:191], v[88:91]
	v_mfma_f32_16x16x32_bf16 v[76:79], v[128:131], v[196:199], v[76:79]
	v_mfma_f32_16x16x32_bf16 v[72:75], v[152:155], v[196:199], v[72:75]
	v_mfma_f32_16x16x32_bf16 v[124:127], v[132:135], v[174:177], v[124:127]
	v_mfma_f32_16x16x32_bf16 v[120:123], v[166:169], v[174:177], v[120:123]
	v_mfma_f32_16x16x32_bf16 v[108:111], v[132:135], v[184:187], v[108:111]
	v_mfma_f32_16x16x32_bf16 v[104:107], v[166:169], v[184:187], v[104:107]
	v_mfma_f32_16x16x32_bf16 v[92:95], v[132:135], v[192:195], v[92:95]
	v_mfma_f32_16x16x32_bf16 v[88:91], v[166:169], v[192:195], v[88:91]
	v_mfma_f32_16x16x32_bf16 v[76:79], v[132:135], v[200:203], v[76:79]
	v_mfma_f32_16x16x32_bf16 v[72:75], v[166:169], v[200:203], v[72:75]
	s_setprio 0
	s_barrier
	s_add_i32 s18, 0, 0x1c000
	s_add_i32 s19, s66, s21
	v_add_u32_e32 v179, s18, v158
	v_lshl_add_u64 v[156:157], v[156:157], 0, s[12:13]
	s_mov_b32 m0, s19
	ds_read_b128 v[204:207], v179
	ds_read_b128 v[208:211], v179 offset:1024
	ds_read_b128 v[212:215], v179 offset:2048
	ds_read_b128 v[216:219], v179 offset:3072
	global_load_lds_dwordx4 v[156:157], off
	v_lshl_add_u64 v[156:157], v[220:221], 0, s[12:13]
	s_add_i32 m0, s19, 0x2000
	s_nop 0
	global_load_lds_dwordx4 v[156:157], off
	s_waitcnt lgkmcnt(0)
	s_setprio 1
	s_barrier


; #define PG8_STAGE(bufoff, gbase, voff) do { _Pragma("unroll") for (int _i = 0; _i < 2; ++_i) \
;         __builtin_amdgcn_global_load_lds((const unsigned*)((const char*)(gbase) + (voff)[_i]), (LAS unsigned*)(lds + (bufoff) + ldsw + _i * 8192), 16, 0, 0); } while (0)
; #define PG8_LDA(dst, b, h) do { _Pragma("unroll") for (int m = 0; m < 4; ++m) _Pragma("unroll") for (int k = 0; k < 2; ++k) dst[m][k] = *(const LAS bf16x8*)(lds + PG8_SA(b, h) + aoff + m * 2048 + k * 1024); } while (0)
; #define PG8_MMA(ai, bj, At, Bt) do { __builtin_amdgcn_s_setprio(1); _Pragma("unroll") for (int m = 0; m < 4; ++m) _Pragma("unroll") for (int n = 0; n < 2; ++n) _Pragma("unroll") for (int k = 0; k < 2; ++k) \
;         acc[ai][bj][m][n] = __builtin_amdgcn_mfma_f32_16x16x32_bf16(Bt[n][k], At[m][k], acc[ai][bj][m][n], 0, 0, 0); __builtin_amdgcn_s_setprio(0); } while (0)
; #define PG8_WAIT_L(n) asm volatile("s_waitcnt lgkmcnt(" #n ")" ::: "memory")
; #define PG8_BAR __builtin_amdgcn_s_barrier()
; #define PG8_SCHED __builtin_amdgcn_sched_barrier(0)
; template <class Epi>
; __device__ __forceinline__ void gemm_phase(LAS unsigned char* lds, const Gemm g, const StaticOrder& S, const Epi& E) {
;     ...
;             PG8_BAR; PG8_WAIT_L(0); PG8_MMA(0, 1, At, B1); PG8_BAR;
;             PG8_LDA(At, 1, 1); PG8_STAGE(PG8_SA(1, 0), a3, voffA);
;             PG8_BAR; PG8_WAIT_L(0); PG8_MMA(1, 0, At, B0); PG8_BAR; PG8_SCHED;
	v_mfma_f32_16x16x32_bf16 v[116:119], v[204:207], v[170:173], v[116:119]
	v_mfma_f32_16x16x32_bf16 v[112:115], v[212:215], v[170:173], v[112:115]
	v_mfma_f32_16x16x32_bf16 v[100:103], v[204:207], v[180:183], v[100:103]
	v_mfma_f32_16x16x32_bf16 v[96:99], v[212:215], v[180:183], v[96:99]
	v_mfma_f32_16x16x32_bf16 v[84:87], v[204:207], v[188:191], v[84:87]
	v_mfma_f32_16x16x32_bf16 v[80:83], v[212:215], v[188:191], v[80:83]
	v_mfma_f32_16x16x32_bf16 v[68:71], v[204:207], v[196:199], v[68:71]
	v_mfma_f32_16x16x32_bf16 v[64:67], v[212:215], v[196:199], v[64:67]
	v_mfma_f32_16x16x32_bf16 v[116:119], v[208:211], v[174:177], v[116:119]
	v_mfma_f32_16x16x32_bf16 v[112:115], v[216:219], v[174:177], v[112:115]
	v_mfma_f32_16x16x32_bf16 v[100:103], v[208:211], v[184:187], v[100:103]
	v_mfma_f32_16x16x32_bf16 v[96:99], v[216:219], v[184:187], v[96:99]
	v_mfma_f32_16x16x32_bf16 v[84:87], v[208:211], v[192:195], v[84:87]
	v_mfma_f32_16x16x32_bf16 v[80:83], v[216:219], v[192:195], v[80:83]
	v_mfma_f32_16x16x32_bf16 v[68:71], v[208:211], v[200:203], v[68:71]
	v_mfma_f32_16x16x32_bf16 v[64:67], v[216:219], v[200:203], v[64:67]
	s_setprio 0
	s_mov_b32 m0, s38
	v_lshl_add_u64 v[156:157], v[222:223], 0, s[12:13]
	s_barrier
	ds_read_b128 v[170:173], v162 offset:49152
	ds_read_b128 v[174:177], v162 offset:50176
	ds_read_b128 v[180:183], v162 offset:51200
	ds_read_b128 v[184:187], v162 offset:52224
	ds_read_b128 v[188:191], v162 offset:53248
	ds_read_b128 v[192:195], v162 offset:54272
	ds_read_b128 v[196:199], v162 offset:55296
	ds_read_b128 v[200:203], v162 offset:56320
	global_load_lds_dwordx4 v[156:157], off
	v_lshl_add_u64 v[156:157], v[224:225], 0, s[12:13]
	s_mov_b32 m0, s39
	s_nop 0
	global_load_lds_dwordx4 v[156:157], off
	s_waitcnt lgkmcnt(0)
	s_setprio 1
	s_barrier


; #define PG8_STAGE(bufoff, gbase, voff) do { _Pragma("unroll") for (int _i = 0; _i < 2; ++_i) \
;         __builtin_amdgcn_global_load_lds((const unsigned*)((const char*)(gbase) + (voff)[_i]), (LAS unsigned*)(lds + (bufoff) + ldsw + _i * 8192), 16, 0, 0); } while (0)
; #define PG8_MMA(ai, bj, At, Bt) do { __builtin_amdgcn_s_setprio(1); _Pragma("unroll") for (int m = 0; m < 4; ++m) _Pragma("unroll") for (int n = 0; n < 2; ++n) _Pragma("unroll") for (int k = 0; k < 2; ++k) \
;         acc[ai][bj][m][n] = __builtin_amdgcn_mfma_f32_16x16x32_bf16(Bt[n][k], At[m][k], acc[ai][bj][m][n], 0, 0, 0); __builtin_amdgcn_s_setprio(0); } while (0)
; #define PG8_WAIT_V(n) asm volatile("s_waitcnt vmcnt(" #n ")" ::: "memory")
; #define PG8_WAIT_L(n) asm volatile("s_waitcnt lgkmcnt(" #n ")" ::: "memory")
; #define PG8_BAR __builtin_amdgcn_s_barrier()
; #define PG8_SCHED __builtin_amdgcn_sched_barrier(0)
; template <class Epi>
; __device__ __forceinline__ void gemm_phase(LAS unsigned char* lds, const Gemm g, const StaticOrder& S, const Epi& E) {
;     ...
;             PG8_BAR; PG8_WAIT_L(0); PG8_MMA(1, 0, At, B0); PG8_BAR; PG8_SCHED;
;             PG8_STAGE(PG8_SB(1, 1), b3 + hstep, voffB);
;             PG8_WAIT_V(6); PG8_BAR; PG8_MMA(1, 1, At, B1); PG8_BAR;
	v_mfma_f32_16x16x32_bf16 v[60:63], v[128:131], v[170:173], v[60:63]
	v_mfma_f32_16x16x32_bf16 v[56:59], v[152:155], v[170:173], v[56:59]
	v_mfma_f32_16x16x32_bf16 v[44:47], v[128:131], v[180:183], v[44:47]
	v_mfma_f32_16x16x32_bf16 v[40:43], v[152:155], v[180:183], v[40:43]
	v_mfma_f32_16x16x32_bf16 v[28:31], v[128:131], v[188:191], v[28:31]
	v_mfma_f32_16x16x32_bf16 v[24:27], v[152:155], v[188:191], v[24:27]
	v_mfma_f32_16x16x32_bf16 v[12:15], v[128:131], v[196:199], v[12:15]
	v_mfma_f32_16x16x32_bf16 v[8:11], v[152:155], v[196:199], v[8:11]
	v_mfma_f32_16x16x32_bf16 v[60:63], v[132:135], v[174:177], v[60:63]
	v_mfma_f32_16x16x32_bf16 v[56:59], v[166:169], v[174:177], v[56:59]
	v_mfma_f32_16x16x32_bf16 v[44:47], v[132:135], v[184:187], v[44:47]
	v_mfma_f32_16x16x32_bf16 v[40:43], v[166:169], v[184:187], v[40:43]
	v_mfma_f32_16x16x32_bf16 v[28:31], v[132:135], v[192:195], v[28:31]
	v_mfma_f32_16x16x32_bf16 v[24:27], v[166:169], v[192:195], v[24:27]
	v_mfma_f32_16x16x32_bf16 v[12:15], v[132:135], v[200:203], v[12:15]
	v_mfma_f32_16x16x32_bf16 v[8:11], v[166:169], v[200:203], v[8:11]
	s_setprio 0
	s_barrier
	s_add_u32 s16, s16, 0x158080
	s_addc_u32 s17, s17, 0
	s_add_i32 s18, s18, s21
	v_lshl_add_u64 v[128:129], s[16:17], 0, v[138:139]
	s_mov_b32 m0, s18
	s_nop 0
	global_load_lds_dwordx4 v[128:129], off
	v_lshl_add_u64 v[128:129], s[16:17], 0, v[142:143]
	s_add_i32 m0, s18, 0x2000
	s_nop 0
	global_load_lds_dwordx4 v[128:129], off
	s_waitcnt vmcnt(6)
	s_setprio 1
	s_barrier

; __device__ __forceinline__ float bflo(unsigned w) { return __uint_as_float(w << 16); }
; __device__ __forceinline__ float bfhi(unsigned w) { return __uint_as_float(w & 0xffff0000u); }
; #define PG8_WAIT_V(n) asm volatile("s_waitcnt vmcnt(" #n ")" ::: "memory")
; #define PG8_BAR __builtin_amdgcn_s_barrier()
; template <class Epi>
; __device__ __forceinline__ void gemm_phase(LAS unsigned char* lds, const Gemm g, const StaticOrder& S, const Epi& E) {
;     ...
;             PG8_WAIT_V(6); PG8_BAR; PG8_MMA(1, 1, At, B1); PG8_BAR;
;         }
;     __device__ __forceinline__ void operator()(const f32x4 (&acc)[2][2][4][2], const Unit& u, int wr, int wc, int fr, int fq, const Pre&) const {
;         const int row0 = ROW_X + u.pm * BM + wr * 64 + fr, col0 = u.pn * BM + wc * 32 + 8 * fq;
;         u32x4 hv[2][2]; float sprev = 0.f;
;     ...
;         ER_LOAD(0, 0);
; #pragma unroll
;         for (int g = 0; g < 8; ++g) { const int ai = g >> 2, m = g & 3; const int r = row0 + ai * HALF + m * 16; const size_t off = (size_t)r * DM + col0; float s = 0.f;
;             if (g + 1 < 8) ER_LOAD(g + 1, (g + 1) & 1);
; #pragma unroll
;             for (int bj = 0; bj < 2; ++bj) { const u32x4 w = hv[g & 1][bj];
;                 const f32x4 h0 = {bflo(w.x), bfhi(w.x), bflo(w.y), bfhi(w.y)}, h1 = {bflo(w.z), bfhi(w.z), bflo(w.w), bfhi(w.w)};
;                 const f32x4 o0 = h0 + acc[ai][bj][m][0] * alpha, o1 = h1 + acc[ai][bj][m][1] * alpha;
;                 if (FINAL) { float* op = OUT + (size_t)(r - ROW_X) * DM + col0 + bj * HALF; *(f32x4*)op = o0; *(f32x4*)(op + 4) = o1; }
;                 else { u32x4 q; q.x = cvtpk(o0[0], o0[1]); q.y = cvtpk(o0[2], o0[3]); q.z = cvtpk(o1[0], o1[1]); q.w = cvtpk(o1[2], o1[3]); *(u32x4*)(HB + off + bj * HALF) = q;
;                        s += ((o0[0] * o0[0] + o0[1] * o0[1]) + (o0[2] * o0[2] + o0[3] * o0[3])) + ((o1[0] * o1[0] + o1[1] * o1[1]) + (o1[2] * o1[2] + o1[3] * o1[3])); } }
;             if (!FINAL) { if (g > 0) { float t = sprev; t += __shfl_xor(t, 16); t += __shfl_xor(t, 32);
;                     if (fq == 0) __hip_atomic_fetch_add(ssq_out + row0 + ((g - 1) >> 2) * HALF + ((g - 1) & 3) * 16, t, __ATOMIC_RELAXED, __HIP_MEMORY_SCOPE_AGENT); }
;                 sprev = s; } }
	v_mfma_f32_16x16x32_bf16 v[52:55], v[204:207], v[170:173], v[52:55]
	v_mfma_f32_16x16x32_bf16 v[48:51], v[212:215], v[170:173], v[48:51]
	v_mfma_f32_16x16x32_bf16 v[36:39], v[204:207], v[180:183], v[36:39]
	v_mfma_f32_16x16x32_bf16 v[32:35], v[212:215], v[180:183], v[32:35]
	v_mfma_f32_16x16x32_bf16 v[20:23], v[204:207], v[188:191], v[20:23]
	v_mfma_f32_16x16x32_bf16 v[16:19], v[212:215], v[188:191], v[16:19]
	v_mfma_f32_16x16x32_bf16 v[4:7], v[204:207], v[196:199], v[4:7]
	v_mfma_f32_16x16x32_bf16 v[0:3], v[212:215], v[196:199], v[0:3]
	v_mfma_f32_16x16x32_bf16 v[52:55], v[208:211], v[174:177], v[52:55]
	v_mfma_f32_16x16x32_bf16 v[48:51], v[216:219], v[174:177], v[48:51]
	v_mfma_f32_16x16x32_bf16 v[36:39], v[208:211], v[184:187], v[36:39]
	v_mfma_f32_16x16x32_bf16 v[32:35], v[216:219], v[184:187], v[32:35]
	v_mfma_f32_16x16x32_bf16 v[20:23], v[208:211], v[192:195], v[20:23]
	v_mfma_f32_16x16x32_bf16 v[16:19], v[216:219], v[192:195], v[16:19]
	v_mfma_f32_16x16x32_bf16 v[4:7], v[208:211], v[200:203], v[4:7]
	v_mfma_f32_16x16x32_bf16 v[0:3], v[216:219], v[200:203], v[0:3]
	s_setprio 0
	s_add_i32 s65, s65, 2
	s_add_u32 s14, s14, 0x100
	s_addc_u32 s15, s15, 0
	s_add_u32 s63, s63, 0x100
	s_addc_u32 s64, s64, 0
	s_cmpk_gt_u32 s65, 0x53
	s_barrier
	s_cbranch_scc0 .LBB0_364
	v_lshl_add_u32 v154, s61, 8, v159
	v_lshl_or_b32 v152, s62, 8, v160
	v_ashrrev_i32_e32 v155, 31, v154
	v_ashrrev_i32_e32 v153, 31, v152
	v_lshlrev_b64 v[128:129], 12, v[154:155]
	v_lshl_add_u64 v[128:129], s[8:9], 0, v[128:129]
	v_lshlrev_b64 v[130:131], 1, v[152:153]
	v_lshl_add_u64 v[184:185], v[128:129], 0, v[130:131]
	v_or_b32_e32 v128, 16, v154
	v_ashrrev_i32_e32 v129, 31, v128
	global_load_dwordx4 v[166:169], v[184:185], off
	global_load_dwordx4 v[170:173], v[184:185], off offset:256
	v_lshlrev_b64 v[128:129], 12, v[128:129]
	v_lshl_add_u64 v[128:129], s[8:9], 0, v[128:129]
	v_lshl_add_u64 v[186:187], v[128:129], 0, v[130:131]
	global_load_dwordx4 v[174:177], v[186:187], off
	global_load_dwordx4 v[180:183], v[186:187], off offset:256
	v_or_b32_e32 v128, 32, v154
	v_ashrrev_i32_e32 v129, 31, v128
	v_lshlrev_b64 v[128:129], 12, v[128:129]
	v_lshl_add_u64 v[128:129], s[8:9], 0, v[128:129]
	v_lshl_add_u64 v[156:157], v[128:129], 0, v[130:131]
	global_load_dwordx4 v[132:135], v[156:157], off
	global_load_dwordx4 v[128:131], v[156:157], off offset:256
	s_waitcnt vmcnt(0)
	v_lshlrev_b32_e32 v188, 16, v166
	v_and_b32_e32 v189, 0xffff0000, v166
	v_lshlrev_b32_e32 v166, 16, v167
	v_and_b32_e32 v167, 0xffff0000, v167
	v_lshlrev_b32_e32 v190, 16, v168
	v_and_b32_e32 v191, 0xffff0000, v168
	v_lshlrev_b32_e32 v168, 16, v169
	v_and_b32_e32 v169, 0xffff0000, v169
	v_lshlrev_b32_e32 v192, 16, v170
	v_and_b32_e32 v193, 0xffff0000, v170
	v_lshlrev_b32_e32 v170, 16, v171
	v_and_b32_e32 v171, 0xffff0000, v171
	v_lshlrev_b32_e32 v194, 16, v172
	v_and_b32_e32 v195, 0xffff0000, v172
	v_lshlrev_b32_e32 v172, 16, v173
	v_and_b32_e32 v173, 0xffff0000, v173
	v_pk_fma_f32 v[126:127], v[126:127], 0.5, v[166:167] op_sel_hi:[1,0,1]
	v_pk_fma_f32 v[124:125], v[124:125], 0.5, v[188:189] op_sel_hi:[1,0,1]
	v_pk_fma_f32 v[122:123], v[122:123], 0.5, v[168:169] op_sel_hi:[1,0,1]
	v_pk_fma_f32 v[166:167], v[120:121], 0.5, v[190:191] op_sel_hi:[1,0,1]
	v_pk_fma_f32 v[168:169], v[118:119], 0.5, v[170:171] op_sel_hi:[1,0,1]
	v_pk_fma_f32 v[170:171], v[116:117], 0.5, v[192:193] op_sel_hi:[1,0,1]
	v_pk_fma_f32 v[172:173], v[114:115], 0.5, v[172:173] op_sel_hi:[1,0,1]
	v_pk_fma_f32 v[188:189], v[112:113], 0.5, v[194:195] op_sel_hi:[1,0,1]
	v_cvt_pk_bf16_f32 v114, v124, v125
	v_cvt_pk_bf16_f32 v115, v126, v127
	v_cvt_pk_bf16_f32 v116, v166, v167
	v_cvt_pk_bf16_f32 v117, v122, v123
	v_mul_f32_e32 v125, v125, v125
	v_mul_f32_e32 v127, v127, v127
	v_mul_f32_e32 v167, v167, v167
	v_mul_f32_e32 v123, v123, v123
	v_cvt_pk_bf16_f32 v118, v170, v171
	v_cvt_pk_bf16_f32 v119, v168, v169
	v_cvt_pk_bf16_f32 v121, v172, v173
	v_mul_f32_e32 v171, v171, v171
	v_mul_f32_e32 v169, v169, v169
	v_mul_f32_e32 v179, v189, v189
	v_mul_f32_e32 v173, v173, v173
	v_lshlrev_b32_e32 v112, 16, v174
	v_and_b32_e32 v113, 0xffff0000, v174
	v_lshlrev_b32_e32 v190, 16, v176
	v_and_b32_e32 v191, 0xffff0000, v176
	v_lshlrev_b32_e32 v176, 16, v177
	v_and_b32_e32 v177, 0xffff0000, v177
	v_fmac_f32_e32 v125, v124, v124
	v_fmac_f32_e32 v127, v126, v126
	v_fmac_f32_e32 v167, v166, v166
	v_fmac_f32_e32 v123, v122, v122
	v_fmac_f32_e32 v171, v170, v170
	v_fmac_f32_e32 v169, v168, v168
	v_fmac_f32_e32 v179, v188, v188
	v_fmac_f32_e32 v173, v172, v172
	v_lshlrev_b32_e32 v174, 16, v175
	v_and_b32_e32 v175, 0xffff0000, v175
	v_pk_fma_f32 v[112:113], v[108:109], 0.5, v[112:113] op_sel_hi:[1,0,1]
	v_pk_fma_f32 v[108:109], v[106:107], 0.5, v[176:177] op_sel_hi:[1,0,1]
	global_store_dwordx4 v[184:185], v[114:117], off
	v_add_f32_e32 v106, v125, v127
	v_add_f32_e32 v107, v167, v123
	v_add_f32_e32 v114, v171, v169
	v_add_f32_e32 v115, v179, v173
	v_pk_fma_f32 v[110:111], v[110:111], 0.5, v[174:175] op_sel_hi:[1,0,1]
	v_add_f32_e32 v106, v106, v107
	v_add_f32_e32 v107, v114, v115
	v_pk_fma_f32 v[114:115], v[104:105], 0.5, v[190:191] op_sel_hi:[1,0,1]
	v_add_f32_e32 v125, v106, v107
	v_cvt_pk_bf16_f32 v104, v112, v113
	v_cvt_pk_bf16_f32 v105, v110, v111
	v_cvt_pk_bf16_f32 v106, v114, v115
	v_cvt_pk_bf16_f32 v107, v108, v109
	v_cvt_pk_bf16_f32 v120, v188, v189
	global_store_dwordx4 v[186:187], v[104:107], off
	global_store_dwordx4 v[184:185], v[118:121], off offset:256
	v_lshlrev_b32_e32 v122, 16, v182
	v_lshlrev_b32_e32 v104, 16, v180
	v_and_b32_e32 v105, 0xffff0000, v180
	v_pk_fma_f32 v[118:119], v[100:101], 0.5, v[104:105] op_sel_hi:[1,0,1]
	v_and_b32_e32 v101, 64, v165
	v_xor_b32_e32 v100, 16, v165
	v_add_u32_e32 v101, 64, v101
	v_cmp_lt_i32_e32 vcc, v100, v101
	v_and_b32_e32 v123, 0xffff0000, v182
	v_pk_fma_f32 v[122:123], v[96:97], 0.5, v[122:123] op_sel_hi:[1,0,1]
	v_cndmask_b32_e32 v100, v165, v100, vcc
	v_lshlrev_b32_e32 v124, 2, v100
	ds_bpermute_b32 v100, v124, v125
	v_xor_b32_e32 v97, 32, v165
	v_cmp_lt_i32_e32 vcc, v97, v101
	v_lshlrev_b32_e32 v106, 16, v181
	v_and_b32_e32 v107, 0xffff0000, v181
	v_cndmask_b32_e32 v97, v165, v97, vcc
	s_waitcnt lgkmcnt(0)
	v_add_f32_e32 v96, v125, v100
	v_lshlrev_b32_e32 v125, 2, v97
	ds_bpermute_b32 v97, v125, v96
	v_lshlrev_b32_e32 v120, 16, v183
	v_and_b32_e32 v121, 0xffff0000, v183
	v_pk_fma_f32 v[116:117], v[102:103], 0.5, v[106:107] op_sel_hi:[1,0,1]
	v_pk_fma_f32 v[120:121], v[98:99], 0.5, v[120:121] op_sel_hi:[1,0,1]
	v_cvt_pk_bf16_f32 v98, v118, v119
	v_cvt_pk_bf16_f32 v99, v116, v117
	v_cvt_pk_bf16_f32 v100, v122, v123
	v_cvt_pk_bf16_f32 v101, v120, v121
	v_lshl_add_u64 v[104:105], v[154:155], 2, s[10:11]
	global_store_dwordx4 v[186:187], v[98:101], off offset:256
	s_and_saveexec_b64 s[14:15], s[2:3]
	s_cbranch_execz .LBB0_367
	s_waitcnt lgkmcnt(0)
	v_add_f32_e32 v96, v96, v97
	global_atomic_add_f32 v[104:105], v96, off

; #define PG8_STAGE(bufoff, gbase, voff) do { _Pragma("unroll") for (int _i = 0; _i < 2; ++_i) \
;         __builtin_amdgcn_global_load_lds((const unsigned*)((const char*)(gbase) + (voff)[_i]), (LAS unsigned*)(lds + (bufoff) + ldsw + _i * 8192), 16, 0, 0); } while (0)
; #define PG8_LDA(dst, b, h) do { _Pragma("unroll") for (int m = 0; m < 4; ++m) _Pragma("unroll") for (int k = 0; k < 2; ++k) dst[m][k] = *(const LAS bf16x8*)(lds + PG8_SA(b, h) + aoff + m * 2048 + k * 1024); } while (0)
; #define PG8_LDB(dst, b, h) do { _Pragma("unroll") for (int n = 0; n < 2; ++n) _Pragma("unroll") for (int k = 0; k < 2; ++k) dst[n][k] = *(const LAS bf16x8*)(lds + PG8_SB(b, h) + boff + n * 2048 + k * 1024); } while (0)
; #define PG8_MMA(ai, bj, At, Bt) do { __builtin_amdgcn_s_setprio(1); _Pragma("unroll") for (int m = 0; m < 4; ++m) _Pragma("unroll") for (int n = 0; n < 2; ++n) _Pragma("unroll") for (int k = 0; k < 2; ++k) \
;         acc[ai][bj][m][n] = __builtin_amdgcn_mfma_f32_16x16x32_bf16(Bt[n][k], At[m][k], acc[ai][bj][m][n], 0, 0, 0); __builtin_amdgcn_s_setprio(0); } while (0)
; #define PG8_WAIT_L(n) asm volatile("s_waitcnt lgkmcnt(" #n ")" ::: "memory")
; #define PG8_BAR __builtin_amdgcn_s_barrier()
; #define PG8_SCHED __builtin_amdgcn_sched_barrier(0)
; template <class Epi>
; __device__ __forceinline__ void gemm_phase(LAS unsigned char* lds, const Gemm g, const StaticOrder& S, const Epi& E) {
;     ...
;             PG8_LDB(B0, 0, 0); PG8_SCHED; PG8_LDA(At, 0, 0); PG8_STAGE(PG8_SA(1, 1), a1 + hstep, voffA);
;             PG8_WAIT_L(8); PG8_BAR; PG8_WAIT_L(0); PG8_MMA(0, 0, At, B0); PG8_BAR; PG8_SCHED;
.LBB0_691:
	ds_read_b128 v[150:153], v167
	ds_read_b128 v[154:157], v167 offset:1024
	ds_read_b128 v[158:161], v167 offset:2048
	ds_read_b128 v[180:183], v167 offset:3072
	s_add_u32 s8, s6, 0xfff80080
	s_addc_u32 s9, s7, -1
	s_cmp_eq_u32 s63, 28
	s_cselect_b32 s11, s1, s9
	s_cselect_b32 s10, s5, s8
	s_cselect_b32 s9, s12, s61
	s_cselect_b32 s8, s13, s33
	v_lshl_add_u64 v[162:163], s[6:7], 0, v[140:141]
	s_add_i32 m0, s74, 0xc000
	ds_read_b128 v[184:187], v168
	ds_read_b128 v[188:191], v168 offset:1024
	ds_read_b128 v[192:195], v168 offset:2048
	ds_read_b128 v[196:199], v168 offset:3072
	ds_read_b128 v[200:203], v168 offset:4096
	ds_read_b128 v[204:207], v168 offset:5120
	ds_read_b128 v[208:211], v168 offset:6144
	ds_read_b128 v[212:215], v168 offset:7168
	global_load_lds_dwordx4 v[162:163], off
	v_lshl_add_u64 v[162:163], s[6:7], 0, v[142:143]
	s_add_i32 m0, s74, 0xe000
	s_nop 0
	global_load_lds_dwordx4 v[162:163], off
	s_waitcnt lgkmcnt(8)
	s_setprio 1
	s_barrier
	s_waitcnt lgkmcnt(0)


; #define PG8_STAGE(bufoff, gbase, voff) do { _Pragma("unroll") for (int _i = 0; _i < 2; ++_i) \
;         __builtin_amdgcn_global_load_lds((const unsigned*)((const char*)(gbase) + (voff)[_i]), (LAS unsigned*)(lds + (bufoff) + ldsw + _i * 8192), 16, 0, 0); } while (0)
; #define PG8_LDB(dst, b, h) do { _Pragma("unroll") for (int n = 0; n < 2; ++n) _Pragma("unroll") for (int k = 0; k < 2; ++k) dst[n][k] = *(const LAS bf16x8*)(lds + PG8_SB(b, h) + boff + n * 2048 + k * 1024); } while (0)
; #define PG8_MMA(ai, bj, At, Bt) do { __builtin_amdgcn_s_setprio(1); _Pragma("unroll") for (int m = 0; m < 4; ++m) _Pragma("unroll") for (int n = 0; n < 2; ++n) _Pragma("unroll") for (int k = 0; k < 2; ++k) \
;         acc[ai][bj][m][n] = __builtin_amdgcn_mfma_f32_16x16x32_bf16(Bt[n][k], At[m][k], acc[ai][bj][m][n], 0, 0, 0); __builtin_amdgcn_s_setprio(0); } while (0)
; #define PG8_WAIT_L(n) asm volatile("s_waitcnt lgkmcnt(" #n ")" ::: "memory")
; #define PG8_BAR __builtin_amdgcn_s_barrier()
; #define PG8_SCHED __builtin_amdgcn_sched_barrier(0)
; template <class Epi>
; __device__ __forceinline__ void gemm_phase(LAS unsigned char* lds, const Gemm g, const StaticOrder& S, const Epi& E) {
;     ...
;             PG8_WAIT_L(8); PG8_BAR; PG8_WAIT_L(0); PG8_MMA(0, 0, At, B0); PG8_BAR; PG8_SCHED;
;             PG8_LDB(B1, 0, 1); PG8_STAGE(PG8_SB(0, 0), b2, voffB);
;             PG8_BAR; PG8_WAIT_L(0); PG8_MMA(0, 1, At, B1); PG8_BAR;
	v_mfma_f32_16x16x32_bf16 v[124:127], v[150:153], v[184:187], v[124:127]
	v_mfma_f32_16x16x32_bf16 v[120:123], v[158:161], v[184:187], v[120:123]
	v_mfma_f32_16x16x32_bf16 v[108:111], v[150:153], v[192:195], v[108:111]
	v_mfma_f32_16x16x32_bf16 v[104:107], v[158:161], v[192:195], v[104:107]
	v_mfma_f32_16x16x32_bf16 v[92:95], v[150:153], v[200:203], v[92:95]
	v_mfma_f32_16x16x32_bf16 v[88:91], v[158:161], v[200:203], v[88:91]
	v_mfma_f32_16x16x32_bf16 v[76:79], v[150:153], v[208:211], v[76:79]
	v_mfma_f32_16x16x32_bf16 v[72:75], v[158:161], v[208:211], v[72:75]
	v_mfma_f32_16x16x32_bf16 v[124:127], v[154:157], v[188:191], v[124:127]
	v_mfma_f32_16x16x32_bf16 v[120:123], v[180:183], v[188:191], v[120:123]
	v_mfma_f32_16x16x32_bf16 v[108:111], v[154:157], v[196:199], v[108:111]
	v_mfma_f32_16x16x32_bf16 v[104:107], v[180:183], v[196:199], v[104:107]
	v_mfma_f32_16x16x32_bf16 v[92:95], v[154:157], v[204:207], v[92:95]
	v_mfma_f32_16x16x32_bf16 v[88:91], v[180:183], v[204:207], v[88:91]
	v_mfma_f32_16x16x32_bf16 v[76:79], v[154:157], v[212:215], v[76:79]
	v_mfma_f32_16x16x32_bf16 v[72:75], v[180:183], v[212:215], v[72:75]
	s_setprio 0
	s_barrier
	s_add_i32 s89, s84, s69
	v_lshl_add_u64 v[162:163], s[8:9], 0, v[130:131]
	s_mov_b32 m0, s89
	ds_read_b128 v[216:219], v169
	ds_read_b128 v[220:223], v169 offset:1024
	ds_read_b128 v[224:227], v169 offset:2048
	ds_read_b128 v[228:231], v169 offset:3072
	global_load_lds_dwordx4 v[162:163], off
	v_lshl_add_u64 v[232:233], s[8:9], 0, v[134:135]
	s_add_i32 m0, s89, 0x2000
	s_nop 0
	global_load_lds_dwordx4 v[232:233], off
	s_waitcnt lgkmcnt(0)
	s_setprio 1
	s_barrier


; #define PG8_STAGE(bufoff, gbase, voff) do { _Pragma("unroll") for (int _i = 0; _i < 2; ++_i) \
;         __builtin_amdgcn_global_load_lds((const unsigned*)((const char*)(gbase) + (voff)[_i]), (LAS unsigned*)(lds + (bufoff) + ldsw + _i * 8192), 16, 0, 0); } while (0)
; #define PG8_LDA(dst, b, h) do { _Pragma("unroll") for (int m = 0; m < 4; ++m) _Pragma("unroll") for (int k = 0; k < 2; ++k) dst[m][k] = *(const LAS bf16x8*)(lds + PG8_SA(b, h) + aoff + m * 2048 + k * 1024); } while (0)
; #define PG8_MMA(ai, bj, At, Bt) do { __builtin_amdgcn_s_setprio(1); _Pragma("unroll") for (int m = 0; m < 4; ++m) _Pragma("unroll") for (int n = 0; n < 2; ++n) _Pragma("unroll") for (int k = 0; k < 2; ++k) \
;         acc[ai][bj][m][n] = __builtin_amdgcn_mfma_f32_16x16x32_bf16(Bt[n][k], At[m][k], acc[ai][bj][m][n], 0, 0, 0); __builtin_amdgcn_s_setprio(0); } while (0)
; #define PG8_WAIT_L(n) asm volatile("s_waitcnt lgkmcnt(" #n ")" ::: "memory")
; #define PG8_BAR __builtin_amdgcn_s_barrier()
; #define PG8_SCHED __builtin_amdgcn_sched_barrier(0)
; template <class Epi>
; __device__ __forceinline__ void gemm_phase(LAS unsigned char* lds, const Gemm g, const StaticOrder& S, const Epi& E) {
;     ...
;             PG8_BAR; PG8_WAIT_L(0); PG8_MMA(0, 1, At, B1); PG8_BAR;
;             PG8_LDA(At, 0, 1); PG8_STAGE(PG8_SA(0, 0), a2, voffA);
;             PG8_BAR; PG8_WAIT_L(0); PG8_MMA(1, 0, At, B0); PG8_BAR; PG8_SCHED;
	v_mfma_f32_16x16x32_bf16 v[116:119], v[216:219], v[184:187], v[116:119]
	v_mfma_f32_16x16x32_bf16 v[112:115], v[224:227], v[184:187], v[112:115]
	v_mfma_f32_16x16x32_bf16 v[100:103], v[216:219], v[192:195], v[100:103]
	v_mfma_f32_16x16x32_bf16 v[96:99], v[224:227], v[192:195], v[96:99]
	v_mfma_f32_16x16x32_bf16 v[84:87], v[216:219], v[200:203], v[84:87]
	v_mfma_f32_16x16x32_bf16 v[80:83], v[224:227], v[200:203], v[80:83]
	v_mfma_f32_16x16x32_bf16 v[68:71], v[216:219], v[208:211], v[68:71]
	v_mfma_f32_16x16x32_bf16 v[64:67], v[224:227], v[208:211], v[64:67]
	v_mfma_f32_16x16x32_bf16 v[116:119], v[220:223], v[188:191], v[116:119]
	v_mfma_f32_16x16x32_bf16 v[112:115], v[228:231], v[188:191], v[112:115]
	v_mfma_f32_16x16x32_bf16 v[100:103], v[220:223], v[196:199], v[100:103]
	v_mfma_f32_16x16x32_bf16 v[96:99], v[228:231], v[196:199], v[96:99]
	v_mfma_f32_16x16x32_bf16 v[84:87], v[220:223], v[204:207], v[84:87]
	v_mfma_f32_16x16x32_bf16 v[80:83], v[228:231], v[204:207], v[80:83]
	v_mfma_f32_16x16x32_bf16 v[68:71], v[220:223], v[212:215], v[68:71]
	v_mfma_f32_16x16x32_bf16 v[64:67], v[228:231], v[212:215], v[64:67]
	s_setprio 0
	s_mov_b32 m0, s74
	v_lshl_add_u64 v[234:235], s[10:11], 0, v[128:129]
	s_barrier
	ds_read_b128 v[184:187], v168 offset:16384
	ds_read_b128 v[188:191], v168 offset:17408
	ds_read_b128 v[192:195], v168 offset:18432
	ds_read_b128 v[196:199], v168 offset:19456
	ds_read_b128 v[200:203], v168 offset:20480
	ds_read_b128 v[204:207], v168 offset:21504
	ds_read_b128 v[208:211], v168 offset:22528
	ds_read_b128 v[212:215], v168 offset:23552
	global_load_lds_dwordx4 v[234:235], off
	v_lshl_add_u64 v[236:237], s[10:11], 0, v[132:133]
	s_mov_b32 m0, s75
	s_nop 0
	global_load_lds_dwordx4 v[236:237], off
	s_waitcnt lgkmcnt(0)
	s_setprio 1
	s_barrier


; #define PG8_STAGE(bufoff, gbase, voff) do { _Pragma("unroll") for (int _i = 0; _i < 2; ++_i) \
;         __builtin_amdgcn_global_load_lds((const unsigned*)((const char*)(gbase) + (voff)[_i]), (LAS unsigned*)(lds + (bufoff) + ldsw + _i * 8192), 16, 0, 0); } while (0)
; #define PG8_MMA(ai, bj, At, Bt) do { __builtin_amdgcn_s_setprio(1); _Pragma("unroll") for (int m = 0; m < 4; ++m) _Pragma("unroll") for (int n = 0; n < 2; ++n) _Pragma("unroll") for (int k = 0; k < 2; ++k) \
;         acc[ai][bj][m][n] = __builtin_amdgcn_mfma_f32_16x16x32_bf16(Bt[n][k], At[m][k], acc[ai][bj][m][n], 0, 0, 0); __builtin_amdgcn_s_setprio(0); } while (0)
; #define PG8_WAIT_V(n) asm volatile("s_waitcnt vmcnt(" #n ")" ::: "memory")
; #define PG8_WAIT_L(n) asm volatile("s_waitcnt lgkmcnt(" #n ")" ::: "memory")
; #define PG8_BAR __builtin_amdgcn_s_barrier()
; #define PG8_SCHED __builtin_amdgcn_sched_barrier(0)
; template <class Epi>
; __device__ __forceinline__ void gemm_phase(LAS unsigned char* lds, const Gemm g, const StaticOrder& S, const Epi& E) {
;     ...
;             PG8_BAR; PG8_WAIT_L(0); PG8_MMA(1, 0, At, B0); PG8_BAR; PG8_SCHED;
;             PG8_STAGE(PG8_SB(0, 1), b2 + hstep, voffB);
;             PG8_WAIT_V(6); PG8_BAR; PG8_MMA(1, 1, At, B1); PG8_BAR;
	v_mfma_f32_16x16x32_bf16 v[60:63], v[150:153], v[184:187], v[60:63]
	v_mfma_f32_16x16x32_bf16 v[56:59], v[158:161], v[184:187], v[56:59]
	v_mfma_f32_16x16x32_bf16 v[44:47], v[150:153], v[192:195], v[44:47]
	v_mfma_f32_16x16x32_bf16 v[40:43], v[158:161], v[192:195], v[40:43]
	v_mfma_f32_16x16x32_bf16 v[28:31], v[150:153], v[200:203], v[28:31]
	v_mfma_f32_16x16x32_bf16 v[24:27], v[158:161], v[200:203], v[24:27]
	v_mfma_f32_16x16x32_bf16 v[12:15], v[150:153], v[208:211], v[12:15]
	v_mfma_f32_16x16x32_bf16 v[8:11], v[158:161], v[208:211], v[8:11]
	v_mfma_f32_16x16x32_bf16 v[60:63], v[154:157], v[188:191], v[60:63]
	v_mfma_f32_16x16x32_bf16 v[56:59], v[180:183], v[188:191], v[56:59]
	v_mfma_f32_16x16x32_bf16 v[44:47], v[154:157], v[196:199], v[44:47]
	v_mfma_f32_16x16x32_bf16 v[40:43], v[180:183], v[196:199], v[40:43]
	v_mfma_f32_16x16x32_bf16 v[28:31], v[154:157], v[204:207], v[28:31]
	v_mfma_f32_16x16x32_bf16 v[24:27], v[180:183], v[204:207], v[24:27]
	v_mfma_f32_16x16x32_bf16 v[12:15], v[154:157], v[212:215], v[12:15]
	v_mfma_f32_16x16x32_bf16 v[8:11], v[180:183], v[212:215], v[8:11]
	s_setprio 0
	s_barrier
	s_add_u32 s90, s8, 0x80000
	s_addc_u32 s91, s9, 0
	s_add_i32 s89, s85, s69
	v_lshl_add_u64 v[150:151], s[90:91], 0, v[130:131]
	s_mov_b32 m0, s89
	s_nop 0
	global_load_lds_dwordx4 v[150:151], off
	v_lshl_add_u64 v[150:151], s[90:91], 0, v[134:135]
	s_add_i32 m0, s89, 0x2000
	s_nop 0
	global_load_lds_dwordx4 v[150:151], off
	s_waitcnt vmcnt(6)
	s_setprio 1
	s_barrier

; #define PG8_STAGE(bufoff, gbase, voff) do { _Pragma("unroll") for (int _i = 0; _i < 2; ++_i) \
;         __builtin_amdgcn_global_load_lds((const unsigned*)((const char*)(gbase) + (voff)[_i]), (LAS unsigned*)(lds + (bufoff) + ldsw + _i * 8192), 16, 0, 0); } while (0)
; #define PG8_LDA(dst, b, h) do { _Pragma("unroll") for (int m = 0; m < 4; ++m) _Pragma("unroll") for (int k = 0; k < 2; ++k) dst[m][k] = *(const LAS bf16x8*)(lds + PG8_SA(b, h) + aoff + m * 2048 + k * 1024); } while (0)
; #define PG8_LDB(dst, b, h) do { _Pragma("unroll") for (int n = 0; n < 2; ++n) _Pragma("unroll") for (int k = 0; k < 2; ++k) dst[n][k] = *(const LAS bf16x8*)(lds + PG8_SB(b, h) + boff + n * 2048 + k * 1024); } while (0)
; #define PG8_MMA(ai, bj, At, Bt) do { __builtin_amdgcn_s_setprio(1); _Pragma("unroll") for (int m = 0; m < 4; ++m) _Pragma("unroll") for (int n = 0; n < 2; ++n) _Pragma("unroll") for (int k = 0; k < 2; ++k) \
;         acc[ai][bj][m][n] = __builtin_amdgcn_mfma_f32_16x16x32_bf16(Bt[n][k], At[m][k], acc[ai][bj][m][n], 0, 0, 0); __builtin_amdgcn_s_setprio(0); } while (0)
; #define PG8_WAIT_V(n) asm volatile("s_waitcnt vmcnt(" #n ")" ::: "memory")
; #define PG8_WAIT_L(n) asm volatile("s_waitcnt lgkmcnt(" #n ")" ::: "memory")
; #define PG8_BAR __builtin_amdgcn_s_barrier()
; #define PG8_SCHED __builtin_amdgcn_sched_barrier(0)
; template <class Epi>
; __device__ __forceinline__ void gemm_phase(LAS unsigned char* lds, const Gemm g, const StaticOrder& S, const Epi& E) {
;     ...
;             PG8_WAIT_V(6); PG8_BAR; PG8_MMA(1, 1, At, B1); PG8_BAR;
;             PG8_LDB(B0, 1, 0); PG8_SCHED; PG8_LDA(At, 1, 0); PG8_STAGE(PG8_SA(0, 1), a2 + hstep, voffA);
;             PG8_WAIT_L(8); PG8_BAR; PG8_WAIT_L(0); PG8_MMA(0, 0, At, B0); PG8_BAR; PG8_SCHED;
	v_mfma_f32_16x16x32_bf16 v[52:55], v[216:219], v[184:187], v[52:55]
	v_mfma_f32_16x16x32_bf16 v[48:51], v[224:227], v[184:187], v[48:51]
	v_mfma_f32_16x16x32_bf16 v[36:39], v[216:219], v[192:195], v[36:39]
	v_mfma_f32_16x16x32_bf16 v[32:35], v[224:227], v[192:195], v[32:35]
	v_mfma_f32_16x16x32_bf16 v[20:23], v[216:219], v[200:203], v[20:23]
	v_mfma_f32_16x16x32_bf16 v[16:19], v[224:227], v[200:203], v[16:19]
	v_mfma_f32_16x16x32_bf16 v[4:7], v[216:219], v[208:211], v[4:7]
	v_mfma_f32_16x16x32_bf16 v[0:3], v[224:227], v[208:211], v[0:3]
	v_mfma_f32_16x16x32_bf16 v[52:55], v[220:223], v[188:191], v[52:55]
	v_mfma_f32_16x16x32_bf16 v[48:51], v[228:231], v[188:191], v[48:51]
	v_mfma_f32_16x16x32_bf16 v[36:39], v[220:223], v[196:199], v[36:39]
	v_mfma_f32_16x16x32_bf16 v[32:35], v[228:231], v[196:199], v[32:35]
	v_mfma_f32_16x16x32_bf16 v[20:23], v[220:223], v[204:207], v[20:23]
	v_mfma_f32_16x16x32_bf16 v[16:19], v[228:231], v[204:207], v[16:19]
	v_mfma_f32_16x16x32_bf16 v[4:7], v[220:223], v[212:215], v[4:7]
	v_mfma_f32_16x16x32_bf16 v[0:3], v[228:231], v[212:215], v[0:3]
	s_setprio 0
	s_add_i32 s89, 0, 0x18000
	v_add_u32_e32 v138, s89, v165
	s_barrier
	ds_read_b128 v[150:153], v138
	ds_read_b128 v[154:157], v138 offset:1024
	ds_read_b128 v[158:161], v138 offset:2048
	ds_read_b128 v[180:183], v138 offset:3072
	s_add_u32 s10, s10, 0x80000
	s_addc_u32 s11, s11, 0
	s_mov_b32 m0, s76
	v_lshl_add_u64 v[216:217], s[10:11], 0, v[128:129]
	ds_read_b128 v[184:187], v168 offset:32768
	ds_read_b128 v[188:191], v168 offset:33792
	ds_read_b128 v[192:195], v168 offset:34816
	ds_read_b128 v[196:199], v168 offset:35840
	ds_read_b128 v[200:203], v168 offset:36864
	ds_read_b128 v[204:207], v168 offset:37888
	ds_read_b128 v[208:211], v168 offset:38912
	ds_read_b128 v[212:215], v168 offset:39936
	global_load_lds_dwordx4 v[216:217], off
	v_lshl_add_u64 v[216:217], s[10:11], 0, v[132:133]
	s_mov_b32 m0, s77
	s_nop 0
	global_load_lds_dwordx4 v[216:217], off
	s_waitcnt lgkmcnt(8)
	s_setprio 1
	s_barrier
	s_waitcnt lgkmcnt(0)


; #define PG8_STAGE(bufoff, gbase, voff) do { _Pragma("unroll") for (int _i = 0; _i < 2; ++_i) \
;         __builtin_amdgcn_global_load_lds((const unsigned*)((const char*)(gbase) + (voff)[_i]), (LAS unsigned*)(lds + (bufoff) + ldsw + _i * 8192), 16, 0, 0); } while (0)
; #define PG8_LDB(dst, b, h) do { _Pragma("unroll") for (int n = 0; n < 2; ++n) _Pragma("unroll") for (int k = 0; k < 2; ++k) dst[n][k] = *(const LAS bf16x8*)(lds + PG8_SB(b, h) + boff + n * 2048 + k * 1024); } while (0)
; #define PG8_MMA(ai, bj, At, Bt) do { __builtin_amdgcn_s_setprio(1); _Pragma("unroll") for (int m = 0; m < 4; ++m) _Pragma("unroll") for (int n = 0; n < 2; ++n) _Pragma("unroll") for (int k = 0; k < 2; ++k) \
;         acc[ai][bj][m][n] = __builtin_amdgcn_mfma_f32_16x16x32_bf16(Bt[n][k], At[m][k], acc[ai][bj][m][n], 0, 0, 0); __builtin_amdgcn_s_setprio(0); } while (0)
; #define PG8_WAIT_L(n) asm volatile("s_waitcnt lgkmcnt(" #n ")" ::: "memory")
; #define PG8_BAR __builtin_amdgcn_s_barrier()
; #define PG8_SCHED __builtin_amdgcn_sched_barrier(0)
; template <class Epi>
; __device__ __forceinline__ void gemm_phase(LAS unsigned char* lds, const Gemm g, const StaticOrder& S, const Epi& E) {
;     ...
;             PG8_WAIT_L(8); PG8_BAR; PG8_WAIT_L(0); PG8_MMA(0, 0, At, B0); PG8_BAR; PG8_SCHED;
;             PG8_LDB(B1, 1, 1); PG8_STAGE(PG8_SB(1, 0), b3, voffB);
;             PG8_BAR; PG8_WAIT_L(0); PG8_MMA(0, 1, At, B1); PG8_BAR;
	v_mfma_f32_16x16x32_bf16 v[124:127], v[150:153], v[184:187], v[124:127]
	v_mfma_f32_16x16x32_bf16 v[120:123], v[158:161], v[184:187], v[120:123]
	v_mfma_f32_16x16x32_bf16 v[108:111], v[150:153], v[192:195], v[108:111]
	v_mfma_f32_16x16x32_bf16 v[104:107], v[158:161], v[192:195], v[104:107]
	v_mfma_f32_16x16x32_bf16 v[92:95], v[150:153], v[200:203], v[92:95]
	v_mfma_f32_16x16x32_bf16 v[88:91], v[158:161], v[200:203], v[88:91]
	v_mfma_f32_16x16x32_bf16 v[76:79], v[150:153], v[208:211], v[76:79]
	v_mfma_f32_16x16x32_bf16 v[72:75], v[158:161], v[208:211], v[72:75]
	v_mfma_f32_16x16x32_bf16 v[124:127], v[154:157], v[188:191], v[124:127]
	v_mfma_f32_16x16x32_bf16 v[120:123], v[180:183], v[188:191], v[120:123]
	v_mfma_f32_16x16x32_bf16 v[108:111], v[154:157], v[196:199], v[108:111]
	v_mfma_f32_16x16x32_bf16 v[104:107], v[180:183], v[196:199], v[104:107]
	v_mfma_f32_16x16x32_bf16 v[92:95], v[154:157], v[204:207], v[92:95]
	v_mfma_f32_16x16x32_bf16 v[88:91], v[180:183], v[204:207], v[88:91]
	v_mfma_f32_16x16x32_bf16 v[76:79], v[154:157], v[212:215], v[76:79]
	v_mfma_f32_16x16x32_bf16 v[72:75], v[180:183], v[212:215], v[72:75]
	s_setprio 0
	s_barrier
	s_add_i32 s10, 0, 0x1c000
	s_add_i32 s11, s89, s69
	v_add_u32_e32 v138, s10, v165
	v_lshl_add_u64 v[162:163], v[162:163], 0, s[34:35]
	s_mov_b32 m0, s11
	ds_read_b128 v[216:219], v138
	ds_read_b128 v[220:223], v138 offset:1024
	ds_read_b128 v[224:227], v138 offset:2048
	ds_read_b128 v[228:231], v138 offset:3072
	global_load_lds_dwordx4 v[162:163], off
	v_lshl_add_u64 v[162:163], v[232:233], 0, s[34:35]
	s_add_i32 m0, s11, 0x2000
	s_nop 0
	global_load_lds_dwordx4 v[162:163], off
	s_waitcnt lgkmcnt(0)
	s_setprio 1
	s_barrier


; #define PG8_STAGE(bufoff, gbase, voff) do { _Pragma("unroll") for (int _i = 0; _i < 2; ++_i) \
;         __builtin_amdgcn_global_load_lds((const unsigned*)((const char*)(gbase) + (voff)[_i]), (LAS unsigned*)(lds + (bufoff) + ldsw + _i * 8192), 16, 0, 0); } while (0)
; #define PG8_LDA(dst, b, h) do { _Pragma("unroll") for (int m = 0; m < 4; ++m) _Pragma("unroll") for (int k = 0; k < 2; ++k) dst[m][k] = *(const LAS bf16x8*)(lds + PG8_SA(b, h) + aoff + m * 2048 + k * 1024); } while (0)
; #define PG8_MMA(ai, bj, At, Bt) do { __builtin_amdgcn_s_setprio(1); _Pragma("unroll") for (int m = 0; m < 4; ++m) _Pragma("unroll") for (int n = 0; n < 2; ++n) _Pragma("unroll") for (int k = 0; k < 2; ++k) \
;         acc[ai][bj][m][n] = __builtin_amdgcn_mfma_f32_16x16x32_bf16(Bt[n][k], At[m][k], acc[ai][bj][m][n], 0, 0, 0); __builtin_amdgcn_s_setprio(0); } while (0)
; #define PG8_WAIT_L(n) asm volatile("s_waitcnt lgkmcnt(" #n ")" ::: "memory")
; #define PG8_BAR __builtin_amdgcn_s_barrier()
; #define PG8_SCHED __builtin_amdgcn_sched_barrier(0)
; template <class Epi>
; __device__ __forceinline__ void gemm_phase(LAS unsigned char* lds, const Gemm g, const StaticOrder& S, const Epi& E) {
;     ...
;             PG8_BAR; PG8_WAIT_L(0); PG8_MMA(0, 1, At, B1); PG8_BAR;
;             PG8_LDA(At, 1, 1); PG8_STAGE(PG8_SA(1, 0), a3, voffA);
;             PG8_BAR; PG8_WAIT_L(0); PG8_MMA(1, 0, At, B0); PG8_BAR; PG8_SCHED;
	v_mfma_f32_16x16x32_bf16 v[116:119], v[216:219], v[184:187], v[116:119]
	v_mfma_f32_16x16x32_bf16 v[112:115], v[224:227], v[184:187], v[112:115]
	v_mfma_f32_16x16x32_bf16 v[100:103], v[216:219], v[192:195], v[100:103]
	v_mfma_f32_16x16x32_bf16 v[96:99], v[224:227], v[192:195], v[96:99]
	v_mfma_f32_16x16x32_bf16 v[84:87], v[216:219], v[200:203], v[84:87]
	v_mfma_f32_16x16x32_bf16 v[80:83], v[224:227], v[200:203], v[80:83]
	v_mfma_f32_16x16x32_bf16 v[68:71], v[216:219], v[208:211], v[68:71]
	v_mfma_f32_16x16x32_bf16 v[64:67], v[224:227], v[208:211], v[64:67]
	v_mfma_f32_16x16x32_bf16 v[116:119], v[220:223], v[188:191], v[116:119]
	v_mfma_f32_16x16x32_bf16 v[112:115], v[228:231], v[188:191], v[112:115]
	v_mfma_f32_16x16x32_bf16 v[100:103], v[220:223], v[196:199], v[100:103]
	v_mfma_f32_16x16x32_bf16 v[96:99], v[228:231], v[196:199], v[96:99]
	v_mfma_f32_16x16x32_bf16 v[84:87], v[220:223], v[204:207], v[84:87]
	v_mfma_f32_16x16x32_bf16 v[80:83], v[228:231], v[204:207], v[80:83]
	v_mfma_f32_16x16x32_bf16 v[68:71], v[220:223], v[212:215], v[68:71]
	v_mfma_f32_16x16x32_bf16 v[64:67], v[228:231], v[212:215], v[64:67]
	s_setprio 0
	s_mov_b32 m0, s79
	v_lshl_add_u64 v[162:163], v[234:235], 0, s[34:35]
	s_barrier
	ds_read_b128 v[184:187], v168 offset:49152
	ds_read_b128 v[188:191], v168 offset:50176
	ds_read_b128 v[192:195], v168 offset:51200
	ds_read_b128 v[196:199], v168 offset:52224
	ds_read_b128 v[200:203], v168 offset:53248
	ds_read_b128 v[204:207], v168 offset:54272
	ds_read_b128 v[208:211], v168 offset:55296
	ds_read_b128 v[212:215], v168 offset:56320
	global_load_lds_dwordx4 v[162:163], off
	v_lshl_add_u64 v[162:163], v[236:237], 0, s[34:35]
	s_mov_b32 m0, s80
	s_nop 0
	global_load_lds_dwordx4 v[162:163], off
	s_waitcnt lgkmcnt(0)
	s_setprio 1
	s_barrier


; #define PG8_STAGE(bufoff, gbase, voff) do { _Pragma("unroll") for (int _i = 0; _i < 2; ++_i) \
;         __builtin_amdgcn_global_load_lds((const unsigned*)((const char*)(gbase) + (voff)[_i]), (LAS unsigned*)(lds + (bufoff) + ldsw + _i * 8192), 16, 0, 0); } while (0)
; #define PG8_MMA(ai, bj, At, Bt) do { __builtin_amdgcn_s_setprio(1); _Pragma("unroll") for (int m = 0; m < 4; ++m) _Pragma("unroll") for (int n = 0; n < 2; ++n) _Pragma("unroll") for (int k = 0; k < 2; ++k) \
;         acc[ai][bj][m][n] = __builtin_amdgcn_mfma_f32_16x16x32_bf16(Bt[n][k], At[m][k], acc[ai][bj][m][n], 0, 0, 0); __builtin_amdgcn_s_setprio(0); } while (0)
; #define PG8_WAIT_V(n) asm volatile("s_waitcnt vmcnt(" #n ")" ::: "memory")
; #define PG8_WAIT_L(n) asm volatile("s_waitcnt lgkmcnt(" #n ")" ::: "memory")
; #define PG8_BAR __builtin_amdgcn_s_barrier()
; #define PG8_SCHED __builtin_amdgcn_sched_barrier(0)
; template <class Epi>
; __device__ __forceinline__ void gemm_phase(LAS unsigned char* lds, const Gemm g, const StaticOrder& S, const Epi& E) {
;     ...
;             PG8_BAR; PG8_WAIT_L(0); PG8_MMA(1, 0, At, B0); PG8_BAR; PG8_SCHED;
;             PG8_STAGE(PG8_SB(1, 1), b3 + hstep, voffB);
;             PG8_WAIT_V(6); PG8_BAR; PG8_MMA(1, 1, At, B1); PG8_BAR;
	v_mfma_f32_16x16x32_bf16 v[60:63], v[150:153], v[184:187], v[60:63]
	v_mfma_f32_16x16x32_bf16 v[56:59], v[158:161], v[184:187], v[56:59]
	v_mfma_f32_16x16x32_bf16 v[44:47], v[150:153], v[192:195], v[44:47]
	v_mfma_f32_16x16x32_bf16 v[40:43], v[158:161], v[192:195], v[40:43]
	v_mfma_f32_16x16x32_bf16 v[28:31], v[150:153], v[200:203], v[28:31]
	v_mfma_f32_16x16x32_bf16 v[24:27], v[158:161], v[200:203], v[24:27]
	v_mfma_f32_16x16x32_bf16 v[12:15], v[150:153], v[208:211], v[12:15]
	v_mfma_f32_16x16x32_bf16 v[8:11], v[158:161], v[208:211], v[8:11]
	v_mfma_f32_16x16x32_bf16 v[60:63], v[154:157], v[188:191], v[60:63]
	v_mfma_f32_16x16x32_bf16 v[56:59], v[180:183], v[188:191], v[56:59]
	v_mfma_f32_16x16x32_bf16 v[44:47], v[154:157], v[196:199], v[44:47]
	v_mfma_f32_16x16x32_bf16 v[40:43], v[180:183], v[196:199], v[40:43]
	v_mfma_f32_16x16x32_bf16 v[28:31], v[154:157], v[204:207], v[28:31]
	v_mfma_f32_16x16x32_bf16 v[24:27], v[180:183], v[204:207], v[24:27]
	v_mfma_f32_16x16x32_bf16 v[12:15], v[154:157], v[212:215], v[12:15]
	v_mfma_f32_16x16x32_bf16 v[8:11], v[180:183], v[212:215], v[8:11]
	s_setprio 0
	s_barrier
	s_add_u32 s8, s8, 0x80080
	s_addc_u32 s9, s9, 0
	s_add_i32 s10, s10, s69
	v_lshl_add_u64 v[150:151], s[8:9], 0, v[130:131]
	s_mov_b32 m0, s10
	s_nop 0
	global_load_lds_dwordx4 v[150:151], off
	v_lshl_add_u64 v[150:151], s[8:9], 0, v[134:135]
	s_add_i32 m0, s10, 0x2000
	s_nop 0
	global_load_lds_dwordx4 v[150:151], off
	s_waitcnt vmcnt(6)
	s_setprio 1
	s_barrier

; __device__ __forceinline__ float sigmoidf_(float x) { return __builtin_amdgcn_rcpf(1.0f + fexp(-x)); }
; #define PG8_MMA(ai, bj, At, Bt) do { __builtin_amdgcn_s_setprio(1); _Pragma("unroll") for (int m = 0; m < 4; ++m) _Pragma("unroll") for (int n = 0; n < 2; ++n) _Pragma("unroll") for (int k = 0; k < 2; ++k) \
;         acc[ai][bj][m][n] = __builtin_amdgcn_mfma_f32_16x16x32_bf16(Bt[n][k], At[m][k], acc[ai][bj][m][n], 0, 0, 0); __builtin_amdgcn_s_setprio(0); } while (0)
; #define PG8_WAIT_V(n) asm volatile("s_waitcnt vmcnt(" #n ")" ::: "memory")
; #define PG8_BAR __builtin_amdgcn_s_barrier()
; template <class Epi>
; __device__ __forceinline__ void gemm_phase(LAS unsigned char* lds, const Gemm g, const StaticOrder& S, const Epi& E) {
;     ...
;             PG8_WAIT_V(6); PG8_BAR; PG8_MMA(1, 1, At, B1); PG8_BAR;
;         }
;     __device__ __forceinline__ void operator()(const f32x4 (&acc)[2][2][4][2], const Unit& u, int wr, int wc, int fr, int fq, const Pre& P) const {
;         const int sec = u.pn >> 3, row0 = ROW_X + u.pm * BM + wr * 64 + fr, colb = (u.pn & 7) * BM + wc * 32 + 8 * fq;
; #pragma unroll
;         for (int ai = 0; ai < 2; ++ai)
; #pragma unroll
;             for (int m = 0; m < 4; ++m) { const int r = row0 + ai * HALF + m * 16; const float rs = __builtin_amdgcn_rsqf(P.rs[ai * 4 + m] * (1.0f / DM) + RMS_EPS);
; #pragma unroll
;                 for (int bj = 0; bj < 2; ++bj) { const int c = colb + bj * HALF; const size_t off = (size_t)r * DM + c; float x[8], y[8];
; #pragma unroll
;                     for (int n = 0; n < 2; ++n)
; #pragma unroll
;                         for (int j = 0; j < 4; ++j) x[n * 4 + j] = acc[ai][bj][m][n][j] * rs;
;                     bf16_t* dst;
;                     if (sec == 0) { dst = QB;
; #pragma unroll
;                         for (int j = 0; j < 8; ++j) y[j] = x[j] * sigmoidf_(x[j]); }
;                     else if (sec == 1) { dst = KB; const f32x4 l0 = *(const f32x4*)(LBv + c), l1 = *(const f32x4*)(LBv + c + 4); float lf[8];
	v_mfma_f32_16x16x32_bf16 v[52:55], v[216:219], v[184:187], v[52:55]
	v_mfma_f32_16x16x32_bf16 v[48:51], v[224:227], v[184:187], v[48:51]
	v_mfma_f32_16x16x32_bf16 v[36:39], v[216:219], v[192:195], v[36:39]
	v_mfma_f32_16x16x32_bf16 v[32:35], v[224:227], v[192:195], v[32:35]
	v_mfma_f32_16x16x32_bf16 v[20:23], v[216:219], v[200:203], v[20:23]
	v_mfma_f32_16x16x32_bf16 v[16:19], v[224:227], v[200:203], v[16:19]
	v_mfma_f32_16x16x32_bf16 v[4:7], v[216:219], v[208:211], v[4:7]
	v_mfma_f32_16x16x32_bf16 v[0:3], v[224:227], v[208:211], v[0:3]
	v_mfma_f32_16x16x32_bf16 v[52:55], v[220:223], v[188:191], v[52:55]
	v_mfma_f32_16x16x32_bf16 v[48:51], v[228:231], v[188:191], v[48:51]
	v_mfma_f32_16x16x32_bf16 v[36:39], v[220:223], v[196:199], v[36:39]
	v_mfma_f32_16x16x32_bf16 v[32:35], v[228:231], v[196:199], v[32:35]
	v_mfma_f32_16x16x32_bf16 v[20:23], v[220:223], v[204:207], v[20:23]
	v_mfma_f32_16x16x32_bf16 v[16:19], v[228:231], v[204:207], v[16:19]
	v_mfma_f32_16x16x32_bf16 v[4:7], v[220:223], v[212:215], v[4:7]
	v_mfma_f32_16x16x32_bf16 v[0:3], v[228:231], v[212:215], v[0:3]
	s_setprio 0
	s_add_i32 s63, s63, 2
	s_add_u32 s6, s6, 0x100
	s_addc_u32 s7, s7, 0
	s_add_u32 s33, s33, 0x100
	s_addc_u32 s61, s61, 0
	s_cmp_gt_u32 s63, 29
	s_barrier
	s_cbranch_scc0 .LBB0_691
	v_fmamk_f32 v149, v149, 0x3a000000, v170
	s_lshl_b32 s1, s0, 8
	v_rsq_f32_e32 v152, v149
	s_ashr_i32 s61, s0, 3
	v_lshl_add_u32 v148, s4, 8, v137
	s_and_b32 s1, s1, 0x700
	s_cmp_gt_u32 s0, 7
	v_ashrrev_i32_e32 v149, 31, v148
	v_or_b32_e32 v138, s1, v166
	v_lshlrev_b32_e32 v254, 2, v138
	global_load_dwordx4 v[238:241], v254, s[24:25]
	global_load_dwordx4 v[242:245], v254, s[24:25] offset:16
	global_load_dwordx4 v[246:249], v254, s[24:25] offset:512
	global_load_dwordx4 v[250:253], v254, s[24:25] offset:528
	s_cselect_b64 s[12:13], -1, 0
	v_lshlrev_b64 v[150:151], 11, v[148:149]
	v_pk_mul_f32 v[124:125], v[152:153], v[124:125] op_sel_hi:[0,1]
	v_pk_mul_f32 v[126:127], v[152:153], v[126:127] op_sel_hi:[0,1]
	v_pk_mul_f32 v[154:155], v[152:153], v[120:121] op_sel_hi:[0,1]
	v_pk_mul_f32 v[122:123], v[152:153], v[122:123] op_sel_hi:[0,1]
	v_or_b32_e32 v120, v150, v138
	v_mov_b32_e32 v121, v151
	s_mov_b64 s[0:1], -1
	s_and_b64 vcc, exec, s[12:13]
	s_cbranch_vccz .LBB0_704
	s_mov_b64 s[6:7], -1
	s_mov_b64 s[0:1], 0
	s_cmp_lt_i32 s61, 2
	s_mov_b64 s[4:5], 0
	s_cbranch_scc1 .LBB0_699
	s_cmp_eq_u32 s61, 2
	s_mov_b64 s[4:5], -1
	s_cbranch_scc0 .LBB0_696
	s_mov_b64 s[4:5], 0
	v_mov_b32_e32 v161, v123
	v_mov_b32_e32 v160, v122
	v_mov_b32_e32 v163, v155
	v_mov_b32_e32 v162, v154
	v_mov_b32_e32 v157, v127
	v_mov_b32_e32 v156, v126
	v_mov_b32_e32 v159, v125
	v_mov_b32_e32 v158, v124

; #define PG8_STAGE(bufoff, gbase, voff) do { _Pragma("unroll") for (int _i = 0; _i < 2; ++_i) \
;         __builtin_amdgcn_global_load_lds((const unsigned*)((const char*)(gbase) + (voff)[_i]), (LAS unsigned*)(lds + (bufoff) + ldsw + _i * 8192), 16, 0, 0); } while (0)
; #define PG8_LDA(dst, b, h) do { _Pragma("unroll") for (int m = 0; m < 4; ++m) _Pragma("unroll") for (int k = 0; k < 2; ++k) dst[m][k] = *(const LAS bf16x8*)(lds + PG8_SA(b, h) + aoff + m * 2048 + k * 1024); } while (0)
; #define PG8_LDB(dst, b, h) do { _Pragma("unroll") for (int n = 0; n < 2; ++n) _Pragma("unroll") for (int k = 0; k < 2; ++k) dst[n][k] = *(const LAS bf16x8*)(lds + PG8_SB(b, h) + boff + n * 2048 + k * 1024); } while (0)
; #define PG8_MMA(ai, bj, At, Bt) do { __builtin_amdgcn_s_setprio(1); _Pragma("unroll") for (int m = 0; m < 4; ++m) _Pragma("unroll") for (int n = 0; n < 2; ++n) _Pragma("unroll") for (int k = 0; k < 2; ++k) \
;         acc[ai][bj][m][n] = __builtin_amdgcn_mfma_f32_16x16x32_bf16(Bt[n][k], At[m][k], acc[ai][bj][m][n], 0, 0, 0); __builtin_amdgcn_s_setprio(0); } while (0)
; #define PG8_WAIT_L(n) asm volatile("s_waitcnt lgkmcnt(" #n ")" ::: "memory")
; #define PG8_BAR __builtin_amdgcn_s_barrier()
; #define PG8_SCHED __builtin_amdgcn_sched_barrier(0)
; template <class Epi>
; __device__ __forceinline__ void gemm_phase(LAS unsigned char* lds, const Gemm g, const StaticOrder& S, const Epi& E) {
;     ...
;             PG8_LDB(B0, 0, 0); PG8_SCHED; PG8_LDA(At, 0, 0); PG8_STAGE(PG8_SA(1, 1), a1 + hstep, voffA);
;             PG8_WAIT_L(8); PG8_BAR; PG8_WAIT_L(0); PG8_MMA(0, 0, At, B0); PG8_BAR; PG8_SCHED;
.LBB0_1220:
	ds_read_b128 v[128:131], v162
	ds_read_b128 v[132:135], v162 offset:1024
	ds_read_b128 v[154:157], v162 offset:2048
	ds_read_b128 v[168:171], v162 offset:3072
	s_add_u32 s24, s22, 0xfff80080
	s_addc_u32 s25, s23, -1
	s_cmp_eq_u32 s67, 28
	s_cselect_b32 s31, s13, s25
	s_cselect_b32 s30, s19, s24
	s_cselect_b32 s25, s11, s66
	s_cselect_b32 s24, s64, s65
	v_lshl_add_u64 v[158:159], s[22:23], 0, v[146:147]
	s_add_i32 m0, s21, 0xc000
	ds_read_b128 v[172:175], v163
	ds_read_b128 v[180:183], v163 offset:1024
	ds_read_b128 v[184:187], v163 offset:2048
	ds_read_b128 v[188:191], v163 offset:3072
	ds_read_b128 v[192:195], v163 offset:4096
	ds_read_b128 v[196:199], v163 offset:5120
	ds_read_b128 v[200:203], v163 offset:6144
	ds_read_b128 v[204:207], v163 offset:7168
	global_load_lds_dwordx4 v[158:159], off
	v_lshl_add_u64 v[158:159], s[22:23], 0, v[148:149]
	s_add_i32 m0, s21, 0xe000
	s_nop 0
	global_load_lds_dwordx4 v[158:159], off
	s_waitcnt lgkmcnt(8)
	s_setprio 1
	s_barrier
	s_waitcnt lgkmcnt(0)


; #define PG8_STAGE(bufoff, gbase, voff) do { _Pragma("unroll") for (int _i = 0; _i < 2; ++_i) \
;         __builtin_amdgcn_global_load_lds((const unsigned*)((const char*)(gbase) + (voff)[_i]), (LAS unsigned*)(lds + (bufoff) + ldsw + _i * 8192), 16, 0, 0); } while (0)
; #define PG8_LDB(dst, b, h) do { _Pragma("unroll") for (int n = 0; n < 2; ++n) _Pragma("unroll") for (int k = 0; k < 2; ++k) dst[n][k] = *(const LAS bf16x8*)(lds + PG8_SB(b, h) + boff + n * 2048 + k * 1024); } while (0)
; #define PG8_MMA(ai, bj, At, Bt) do { __builtin_amdgcn_s_setprio(1); _Pragma("unroll") for (int m = 0; m < 4; ++m) _Pragma("unroll") for (int n = 0; n < 2; ++n) _Pragma("unroll") for (int k = 0; k < 2; ++k) \
;         acc[ai][bj][m][n] = __builtin_amdgcn_mfma_f32_16x16x32_bf16(Bt[n][k], At[m][k], acc[ai][bj][m][n], 0, 0, 0); __builtin_amdgcn_s_setprio(0); } while (0)
; #define PG8_WAIT_L(n) asm volatile("s_waitcnt lgkmcnt(" #n ")" ::: "memory")
; #define PG8_BAR __builtin_amdgcn_s_barrier()
; #define PG8_SCHED __builtin_amdgcn_sched_barrier(0)
; template <class Epi>
; __device__ __forceinline__ void gemm_phase(LAS unsigned char* lds, const Gemm g, const StaticOrder& S, const Epi& E) {
;     ...
;             PG8_WAIT_L(8); PG8_BAR; PG8_WAIT_L(0); PG8_MMA(0, 0, At, B0); PG8_BAR; PG8_SCHED;
;             PG8_LDB(B1, 0, 1); PG8_STAGE(PG8_SB(0, 0), b2, voffB);
;             PG8_BAR; PG8_WAIT_L(0); PG8_MMA(0, 1, At, B1); PG8_BAR;
	v_mfma_f32_16x16x32_bf16 v[124:127], v[128:131], v[172:175], v[124:127]
	v_mfma_f32_16x16x32_bf16 v[120:123], v[154:157], v[172:175], v[120:123]
	v_mfma_f32_16x16x32_bf16 v[108:111], v[128:131], v[184:187], v[108:111]
	v_mfma_f32_16x16x32_bf16 v[104:107], v[154:157], v[184:187], v[104:107]
	v_mfma_f32_16x16x32_bf16 v[92:95], v[128:131], v[192:195], v[92:95]
	v_mfma_f32_16x16x32_bf16 v[88:91], v[154:157], v[192:195], v[88:91]
	v_mfma_f32_16x16x32_bf16 v[76:79], v[128:131], v[200:203], v[76:79]
	v_mfma_f32_16x16x32_bf16 v[72:75], v[154:157], v[200:203], v[72:75]
	v_mfma_f32_16x16x32_bf16 v[124:127], v[132:135], v[180:183], v[124:127]
	v_mfma_f32_16x16x32_bf16 v[120:123], v[168:171], v[180:183], v[120:123]
	v_mfma_f32_16x16x32_bf16 v[108:111], v[132:135], v[188:191], v[108:111]
	v_mfma_f32_16x16x32_bf16 v[104:107], v[168:171], v[188:191], v[104:107]
	v_mfma_f32_16x16x32_bf16 v[92:95], v[132:135], v[196:199], v[92:95]
	v_mfma_f32_16x16x32_bf16 v[88:91], v[168:171], v[196:199], v[88:91]
	v_mfma_f32_16x16x32_bf16 v[76:79], v[132:135], v[204:207], v[76:79]
	v_mfma_f32_16x16x32_bf16 v[72:75], v[168:171], v[204:207], v[72:75]
	s_setprio 0
	s_barrier
	s_add_i32 s68, s62, s36
	v_lshl_add_u64 v[158:159], s[24:25], 0, v[140:141]
	s_mov_b32 m0, s68
	ds_read_b128 v[208:211], v165
	ds_read_b128 v[212:215], v165 offset:1024
	ds_read_b128 v[216:219], v165 offset:2048
	ds_read_b128 v[220:223], v165 offset:3072
	global_load_lds_dwordx4 v[158:159], off
	v_lshl_add_u64 v[176:177], s[24:25], 0, v[144:145]
	s_add_i32 m0, s68, 0x2000
	s_nop 0
	global_load_lds_dwordx4 v[176:177], off
	s_waitcnt lgkmcnt(0)
	s_setprio 1
	s_barrier


; #define PG8_STAGE(bufoff, gbase, voff) do { _Pragma("unroll") for (int _i = 0; _i < 2; ++_i) \
;         __builtin_amdgcn_global_load_lds((const unsigned*)((const char*)(gbase) + (voff)[_i]), (LAS unsigned*)(lds + (bufoff) + ldsw + _i * 8192), 16, 0, 0); } while (0)
; #define PG8_LDA(dst, b, h) do { _Pragma("unroll") for (int m = 0; m < 4; ++m) _Pragma("unroll") for (int k = 0; k < 2; ++k) dst[m][k] = *(const LAS bf16x8*)(lds + PG8_SA(b, h) + aoff + m * 2048 + k * 1024); } while (0)
; #define PG8_MMA(ai, bj, At, Bt) do { __builtin_amdgcn_s_setprio(1); _Pragma("unroll") for (int m = 0; m < 4; ++m) _Pragma("unroll") for (int n = 0; n < 2; ++n) _Pragma("unroll") for (int k = 0; k < 2; ++k) \
;         acc[ai][bj][m][n] = __builtin_amdgcn_mfma_f32_16x16x32_bf16(Bt[n][k], At[m][k], acc[ai][bj][m][n], 0, 0, 0); __builtin_amdgcn_s_setprio(0); } while (0)
; #define PG8_WAIT_L(n) asm volatile("s_waitcnt lgkmcnt(" #n ")" ::: "memory")
; #define PG8_BAR __builtin_amdgcn_s_barrier()
; #define PG8_SCHED __builtin_amdgcn_sched_barrier(0)
; template <class Epi>
; __device__ __forceinline__ void gemm_phase(LAS unsigned char* lds, const Gemm g, const StaticOrder& S, const Epi& E) {
;     ...
;             PG8_BAR; PG8_WAIT_L(0); PG8_MMA(0, 1, At, B1); PG8_BAR;
;             PG8_LDA(At, 0, 1); PG8_STAGE(PG8_SA(0, 0), a2, voffA);
;             PG8_BAR; PG8_WAIT_L(0); PG8_MMA(1, 0, At, B0); PG8_BAR; PG8_SCHED;
	v_mfma_f32_16x16x32_bf16 v[116:119], v[208:211], v[172:175], v[116:119]
	v_mfma_f32_16x16x32_bf16 v[112:115], v[216:219], v[172:175], v[112:115]
	v_mfma_f32_16x16x32_bf16 v[100:103], v[208:211], v[184:187], v[100:103]
	v_mfma_f32_16x16x32_bf16 v[96:99], v[216:219], v[184:187], v[96:99]
	v_mfma_f32_16x16x32_bf16 v[84:87], v[208:211], v[192:195], v[84:87]
	v_mfma_f32_16x16x32_bf16 v[80:83], v[216:219], v[192:195], v[80:83]
	v_mfma_f32_16x16x32_bf16 v[68:71], v[208:211], v[200:203], v[68:71]
	v_mfma_f32_16x16x32_bf16 v[64:67], v[216:219], v[200:203], v[64:67]
	v_mfma_f32_16x16x32_bf16 v[116:119], v[212:215], v[180:183], v[116:119]
	v_mfma_f32_16x16x32_bf16 v[112:115], v[220:223], v[180:183], v[112:115]
	v_mfma_f32_16x16x32_bf16 v[100:103], v[212:215], v[188:191], v[100:103]
	v_mfma_f32_16x16x32_bf16 v[96:99], v[220:223], v[188:191], v[96:99]
	v_mfma_f32_16x16x32_bf16 v[84:87], v[212:215], v[196:199], v[84:87]
	v_mfma_f32_16x16x32_bf16 v[80:83], v[220:223], v[196:199], v[80:83]
	v_mfma_f32_16x16x32_bf16 v[68:71], v[212:215], v[204:207], v[68:71]
	v_mfma_f32_16x16x32_bf16 v[64:67], v[220:223], v[204:207], v[64:67]
	s_setprio 0
	s_mov_b32 m0, s21
	v_lshl_add_u64 v[224:225], s[30:31], 0, v[138:139]
	s_barrier
	ds_read_b128 v[172:175], v163 offset:16384
	ds_read_b128 v[180:183], v163 offset:17408
	ds_read_b128 v[184:187], v163 offset:18432
	ds_read_b128 v[188:191], v163 offset:19456
	ds_read_b128 v[192:195], v163 offset:20480
	ds_read_b128 v[196:199], v163 offset:21504
	ds_read_b128 v[200:203], v163 offset:22528
	ds_read_b128 v[204:207], v163 offset:23552
	global_load_lds_dwordx4 v[224:225], off
	v_lshl_add_u64 v[226:227], s[30:31], 0, v[142:143]
	s_mov_b32 m0, s39
	s_nop 0
	global_load_lds_dwordx4 v[226:227], off
	s_waitcnt lgkmcnt(0)
	s_setprio 1
	s_barrier


; #define PG8_STAGE(bufoff, gbase, voff) do { _Pragma("unroll") for (int _i = 0; _i < 2; ++_i) \
;         __builtin_amdgcn_global_load_lds((const unsigned*)((const char*)(gbase) + (voff)[_i]), (LAS unsigned*)(lds + (bufoff) + ldsw + _i * 8192), 16, 0, 0); } while (0)
; #define PG8_MMA(ai, bj, At, Bt) do { __builtin_amdgcn_s_setprio(1); _Pragma("unroll") for (int m = 0; m < 4; ++m) _Pragma("unroll") for (int n = 0; n < 2; ++n) _Pragma("unroll") for (int k = 0; k < 2; ++k) \
;         acc[ai][bj][m][n] = __builtin_amdgcn_mfma_f32_16x16x32_bf16(Bt[n][k], At[m][k], acc[ai][bj][m][n], 0, 0, 0); __builtin_amdgcn_s_setprio(0); } while (0)
; #define PG8_WAIT_V(n) asm volatile("s_waitcnt vmcnt(" #n ")" ::: "memory")
; #define PG8_WAIT_L(n) asm volatile("s_waitcnt lgkmcnt(" #n ")" ::: "memory")
; #define PG8_BAR __builtin_amdgcn_s_barrier()
; #define PG8_SCHED __builtin_amdgcn_sched_barrier(0)
; template <class Epi>
; __device__ __forceinline__ void gemm_phase(LAS unsigned char* lds, const Gemm g, const StaticOrder& S, const Epi& E) {
;     ...
;             PG8_BAR; PG8_WAIT_L(0); PG8_MMA(1, 0, At, B0); PG8_BAR; PG8_SCHED;
;             PG8_STAGE(PG8_SB(0, 1), b2 + hstep, voffB);
;             PG8_WAIT_V(6); PG8_BAR; PG8_MMA(1, 1, At, B1); PG8_BAR;
	v_mfma_f32_16x16x32_bf16 v[60:63], v[128:131], v[172:175], v[60:63]
	v_mfma_f32_16x16x32_bf16 v[56:59], v[154:157], v[172:175], v[56:59]
	v_mfma_f32_16x16x32_bf16 v[44:47], v[128:131], v[184:187], v[44:47]
	v_mfma_f32_16x16x32_bf16 v[40:43], v[154:157], v[184:187], v[40:43]
	v_mfma_f32_16x16x32_bf16 v[28:31], v[128:131], v[192:195], v[28:31]
	v_mfma_f32_16x16x32_bf16 v[24:27], v[154:157], v[192:195], v[24:27]
	v_mfma_f32_16x16x32_bf16 v[12:15], v[128:131], v[200:203], v[12:15]
	v_mfma_f32_16x16x32_bf16 v[8:11], v[154:157], v[200:203], v[8:11]
	v_mfma_f32_16x16x32_bf16 v[60:63], v[132:135], v[180:183], v[60:63]
	v_mfma_f32_16x16x32_bf16 v[56:59], v[168:171], v[180:183], v[56:59]
	v_mfma_f32_16x16x32_bf16 v[44:47], v[132:135], v[188:191], v[44:47]
	v_mfma_f32_16x16x32_bf16 v[40:43], v[168:171], v[188:191], v[40:43]
	v_mfma_f32_16x16x32_bf16 v[28:31], v[132:135], v[196:199], v[28:31]
	v_mfma_f32_16x16x32_bf16 v[24:27], v[168:171], v[196:199], v[24:27]
	v_mfma_f32_16x16x32_bf16 v[12:15], v[132:135], v[204:207], v[12:15]
	v_mfma_f32_16x16x32_bf16 v[8:11], v[168:171], v[204:207], v[8:11]
	s_setprio 0
	s_barrier
	s_add_u32 s68, s24, 0x80000
	s_addc_u32 s69, s25, 0
	s_add_i32 s70, s63, s36
	v_lshl_add_u64 v[128:129], s[68:69], 0, v[140:141]
	s_mov_b32 m0, s70
	s_nop 0
	global_load_lds_dwordx4 v[128:129], off
	v_lshl_add_u64 v[128:129], s[68:69], 0, v[144:145]
	s_add_i32 m0, s70, 0x2000
	s_nop 0
	global_load_lds_dwordx4 v[128:129], off
	s_waitcnt vmcnt(6)
	s_setprio 1
	s_barrier

; #define PG8_STAGE(bufoff, gbase, voff) do { _Pragma("unroll") for (int _i = 0; _i < 2; ++_i) \
;         __builtin_amdgcn_global_load_lds((const unsigned*)((const char*)(gbase) + (voff)[_i]), (LAS unsigned*)(lds + (bufoff) + ldsw + _i * 8192), 16, 0, 0); } while (0)
; #define PG8_LDA(dst, b, h) do { _Pragma("unroll") for (int m = 0; m < 4; ++m) _Pragma("unroll") for (int k = 0; k < 2; ++k) dst[m][k] = *(const LAS bf16x8*)(lds + PG8_SA(b, h) + aoff + m * 2048 + k * 1024); } while (0)
; #define PG8_LDB(dst, b, h) do { _Pragma("unroll") for (int n = 0; n < 2; ++n) _Pragma("unroll") for (int k = 0; k < 2; ++k) dst[n][k] = *(const LAS bf16x8*)(lds + PG8_SB(b, h) + boff + n * 2048 + k * 1024); } while (0)
; #define PG8_MMA(ai, bj, At, Bt) do { __builtin_amdgcn_s_setprio(1); _Pragma("unroll") for (int m = 0; m < 4; ++m) _Pragma("unroll") for (int n = 0; n < 2; ++n) _Pragma("unroll") for (int k = 0; k < 2; ++k) \
;         acc[ai][bj][m][n] = __builtin_amdgcn_mfma_f32_16x16x32_bf16(Bt[n][k], At[m][k], acc[ai][bj][m][n], 0, 0, 0); __builtin_amdgcn_s_setprio(0); } while (0)
; #define PG8_WAIT_V(n) asm volatile("s_waitcnt vmcnt(" #n ")" ::: "memory")
; #define PG8_WAIT_L(n) asm volatile("s_waitcnt lgkmcnt(" #n ")" ::: "memory")
; #define PG8_BAR __builtin_amdgcn_s_barrier()
; #define PG8_SCHED __builtin_amdgcn_sched_barrier(0)
; template <class Epi>
; __device__ __forceinline__ void gemm_phase(LAS unsigned char* lds, const Gemm g, const StaticOrder& S, const Epi& E) {
;     ...
;             PG8_WAIT_V(6); PG8_BAR; PG8_MMA(1, 1, At, B1); PG8_BAR;
;             PG8_LDB(B0, 1, 0); PG8_SCHED; PG8_LDA(At, 1, 0); PG8_STAGE(PG8_SA(0, 1), a2 + hstep, voffA);
;             PG8_WAIT_L(8); PG8_BAR; PG8_WAIT_L(0); PG8_MMA(0, 0, At, B0); PG8_BAR; PG8_SCHED;
	v_mfma_f32_16x16x32_bf16 v[52:55], v[208:211], v[172:175], v[52:55]
	v_mfma_f32_16x16x32_bf16 v[48:51], v[216:219], v[172:175], v[48:51]
	v_mfma_f32_16x16x32_bf16 v[36:39], v[208:211], v[184:187], v[36:39]
	v_mfma_f32_16x16x32_bf16 v[32:35], v[216:219], v[184:187], v[32:35]
	v_mfma_f32_16x16x32_bf16 v[20:23], v[208:211], v[192:195], v[20:23]
	v_mfma_f32_16x16x32_bf16 v[16:19], v[216:219], v[192:195], v[16:19]
	v_mfma_f32_16x16x32_bf16 v[4:7], v[208:211], v[200:203], v[4:7]
	v_mfma_f32_16x16x32_bf16 v[0:3], v[216:219], v[200:203], v[0:3]
	v_mfma_f32_16x16x32_bf16 v[52:55], v[212:215], v[180:183], v[52:55]
	v_mfma_f32_16x16x32_bf16 v[48:51], v[220:223], v[180:183], v[48:51]
	v_mfma_f32_16x16x32_bf16 v[36:39], v[212:215], v[188:191], v[36:39]
	v_mfma_f32_16x16x32_bf16 v[32:35], v[220:223], v[188:191], v[32:35]
	v_mfma_f32_16x16x32_bf16 v[20:23], v[212:215], v[196:199], v[20:23]
	v_mfma_f32_16x16x32_bf16 v[16:19], v[220:223], v[196:199], v[16:19]
	v_mfma_f32_16x16x32_bf16 v[4:7], v[212:215], v[204:207], v[4:7]
	v_mfma_f32_16x16x32_bf16 v[0:3], v[220:223], v[204:207], v[0:3]
	s_setprio 0
	s_add_i32 s68, 0, 0x18000
	v_add_u32_e32 v167, s68, v137
	s_barrier
	ds_read_b128 v[128:131], v167
	ds_read_b128 v[132:135], v167 offset:1024
	ds_read_b128 v[154:157], v167 offset:2048
	ds_read_b128 v[168:171], v167 offset:3072
	s_add_u32 s30, s30, 0x80000
	s_addc_u32 s31, s31, 0
	s_mov_b32 m0, s42
	v_lshl_add_u64 v[208:209], s[30:31], 0, v[138:139]
	ds_read_b128 v[172:175], v163 offset:32768
	ds_read_b128 v[180:183], v163 offset:33792
	ds_read_b128 v[184:187], v163 offset:34816
	ds_read_b128 v[188:191], v163 offset:35840
	ds_read_b128 v[192:195], v163 offset:36864
	ds_read_b128 v[196:199], v163 offset:37888
	ds_read_b128 v[200:203], v163 offset:38912
	ds_read_b128 v[204:207], v163 offset:39936
	global_load_lds_dwordx4 v[208:209], off
	v_lshl_add_u64 v[208:209], s[30:31], 0, v[142:143]
	s_mov_b32 m0, s43
	s_nop 0
	global_load_lds_dwordx4 v[208:209], off
	s_waitcnt lgkmcnt(8)
	s_setprio 1
	s_barrier
	s_waitcnt lgkmcnt(0)


; #define PG8_STAGE(bufoff, gbase, voff) do { _Pragma("unroll") for (int _i = 0; _i < 2; ++_i) \
;         __builtin_amdgcn_global_load_lds((const unsigned*)((const char*)(gbase) + (voff)[_i]), (LAS unsigned*)(lds + (bufoff) + ldsw + _i * 8192), 16, 0, 0); } while (0)
; #define PG8_LDB(dst, b, h) do { _Pragma("unroll") for (int n = 0; n < 2; ++n) _Pragma("unroll") for (int k = 0; k < 2; ++k) dst[n][k] = *(const LAS bf16x8*)(lds + PG8_SB(b, h) + boff + n * 2048 + k * 1024); } while (0)
; #define PG8_MMA(ai, bj, At, Bt) do { __builtin_amdgcn_s_setprio(1); _Pragma("unroll") for (int m = 0; m < 4; ++m) _Pragma("unroll") for (int n = 0; n < 2; ++n) _Pragma("unroll") for (int k = 0; k < 2; ++k) \
;         acc[ai][bj][m][n] = __builtin_amdgcn_mfma_f32_16x16x32_bf16(Bt[n][k], At[m][k], acc[ai][bj][m][n], 0, 0, 0); __builtin_amdgcn_s_setprio(0); } while (0)
; #define PG8_WAIT_L(n) asm volatile("s_waitcnt lgkmcnt(" #n ")" ::: "memory")
; #define PG8_BAR __builtin_amdgcn_s_barrier()
; #define PG8_SCHED __builtin_amdgcn_sched_barrier(0)
; template <class Epi>
; __device__ __forceinline__ void gemm_phase(LAS unsigned char* lds, const Gemm g, const StaticOrder& S, const Epi& E) {
;     ...
;             PG8_WAIT_L(8); PG8_BAR; PG8_WAIT_L(0); PG8_MMA(0, 0, At, B0); PG8_BAR; PG8_SCHED;
;             PG8_LDB(B1, 1, 1); PG8_STAGE(PG8_SB(1, 0), b3, voffB);
;             PG8_BAR; PG8_WAIT_L(0); PG8_MMA(0, 1, At, B1); PG8_BAR;
	v_mfma_f32_16x16x32_bf16 v[124:127], v[128:131], v[172:175], v[124:127]
	v_mfma_f32_16x16x32_bf16 v[120:123], v[154:157], v[172:175], v[120:123]
	v_mfma_f32_16x16x32_bf16 v[108:111], v[128:131], v[184:187], v[108:111]
	v_mfma_f32_16x16x32_bf16 v[104:107], v[154:157], v[184:187], v[104:107]
	v_mfma_f32_16x16x32_bf16 v[92:95], v[128:131], v[192:195], v[92:95]
	v_mfma_f32_16x16x32_bf16 v[88:91], v[154:157], v[192:195], v[88:91]
	v_mfma_f32_16x16x32_bf16 v[76:79], v[128:131], v[200:203], v[76:79]
	v_mfma_f32_16x16x32_bf16 v[72:75], v[154:157], v[200:203], v[72:75]
	v_mfma_f32_16x16x32_bf16 v[124:127], v[132:135], v[180:183], v[124:127]
	v_mfma_f32_16x16x32_bf16 v[120:123], v[168:171], v[180:183], v[120:123]
	v_mfma_f32_16x16x32_bf16 v[108:111], v[132:135], v[188:191], v[108:111]
	v_mfma_f32_16x16x32_bf16 v[104:107], v[168:171], v[188:191], v[104:107]
	v_mfma_f32_16x16x32_bf16 v[92:95], v[132:135], v[196:199], v[92:95]
	v_mfma_f32_16x16x32_bf16 v[88:91], v[168:171], v[196:199], v[88:91]
	v_mfma_f32_16x16x32_bf16 v[76:79], v[132:135], v[204:207], v[76:79]
	v_mfma_f32_16x16x32_bf16 v[72:75], v[168:171], v[204:207], v[72:75]
	s_setprio 0
	s_barrier
	s_add_i32 s30, 0, 0x1c000
	s_add_i32 s31, s68, s36
	v_add_u32_e32 v167, s30, v137
	v_lshl_add_u64 v[158:159], v[158:159], 0, s[8:9]
	s_mov_b32 m0, s31
	ds_read_b128 v[208:211], v167
	ds_read_b128 v[212:215], v167 offset:1024
	ds_read_b128 v[216:219], v167 offset:2048
	ds_read_b128 v[220:223], v167 offset:3072
	global_load_lds_dwordx4 v[158:159], off
	v_lshl_add_u64 v[158:159], v[176:177], 0, s[8:9]
	s_add_i32 m0, s31, 0x2000
	s_nop 0
	global_load_lds_dwordx4 v[158:159], off
	s_waitcnt lgkmcnt(0)
	s_setprio 1
	s_barrier


; #define PG8_STAGE(bufoff, gbase, voff) do { _Pragma("unroll") for (int _i = 0; _i < 2; ++_i) \
;         __builtin_amdgcn_global_load_lds((const unsigned*)((const char*)(gbase) + (voff)[_i]), (LAS unsigned*)(lds + (bufoff) + ldsw + _i * 8192), 16, 0, 0); } while (0)
; #define PG8_LDA(dst, b, h) do { _Pragma("unroll") for (int m = 0; m < 4; ++m) _Pragma("unroll") for (int k = 0; k < 2; ++k) dst[m][k] = *(const LAS bf16x8*)(lds + PG8_SA(b, h) + aoff + m * 2048 + k * 1024); } while (0)
; #define PG8_MMA(ai, bj, At, Bt) do { __builtin_amdgcn_s_setprio(1); _Pragma("unroll") for (int m = 0; m < 4; ++m) _Pragma("unroll") for (int n = 0; n < 2; ++n) _Pragma("unroll") for (int k = 0; k < 2; ++k) \
;         acc[ai][bj][m][n] = __builtin_amdgcn_mfma_f32_16x16x32_bf16(Bt[n][k], At[m][k], acc[ai][bj][m][n], 0, 0, 0); __builtin_amdgcn_s_setprio(0); } while (0)
; #define PG8_WAIT_L(n) asm volatile("s_waitcnt lgkmcnt(" #n ")" ::: "memory")
; #define PG8_BAR __builtin_amdgcn_s_barrier()
; #define PG8_SCHED __builtin_amdgcn_sched_barrier(0)
; template <class Epi>
; __device__ __forceinline__ void gemm_phase(LAS unsigned char* lds, const Gemm g, const StaticOrder& S, const Epi& E) {
;     ...
;             PG8_BAR; PG8_WAIT_L(0); PG8_MMA(0, 1, At, B1); PG8_BAR;
;             PG8_LDA(At, 1, 1); PG8_STAGE(PG8_SA(1, 0), a3, voffA);
;             PG8_BAR; PG8_WAIT_L(0); PG8_MMA(1, 0, At, B0); PG8_BAR; PG8_SCHED;
	v_mfma_f32_16x16x32_bf16 v[116:119], v[208:211], v[172:175], v[116:119]
	v_mfma_f32_16x16x32_bf16 v[112:115], v[216:219], v[172:175], v[112:115]
	v_mfma_f32_16x16x32_bf16 v[100:103], v[208:211], v[184:187], v[100:103]
	v_mfma_f32_16x16x32_bf16 v[96:99], v[216:219], v[184:187], v[96:99]
	v_mfma_f32_16x16x32_bf16 v[84:87], v[208:211], v[192:195], v[84:87]
	v_mfma_f32_16x16x32_bf16 v[80:83], v[216:219], v[192:195], v[80:83]
	v_mfma_f32_16x16x32_bf16 v[68:71], v[208:211], v[200:203], v[68:71]
	v_mfma_f32_16x16x32_bf16 v[64:67], v[216:219], v[200:203], v[64:67]
	v_mfma_f32_16x16x32_bf16 v[116:119], v[212:215], v[180:183], v[116:119]
	v_mfma_f32_16x16x32_bf16 v[112:115], v[220:223], v[180:183], v[112:115]
	v_mfma_f32_16x16x32_bf16 v[100:103], v[212:215], v[188:191], v[100:103]
	v_mfma_f32_16x16x32_bf16 v[96:99], v[220:223], v[188:191], v[96:99]
	v_mfma_f32_16x16x32_bf16 v[84:87], v[212:215], v[196:199], v[84:87]
	v_mfma_f32_16x16x32_bf16 v[80:83], v[220:223], v[196:199], v[80:83]
	v_mfma_f32_16x16x32_bf16 v[68:71], v[212:215], v[204:207], v[68:71]
	v_mfma_f32_16x16x32_bf16 v[64:67], v[220:223], v[204:207], v[64:67]
	s_setprio 0
	s_mov_b32 m0, s57
	v_lshl_add_u64 v[158:159], v[224:225], 0, s[8:9]
	s_barrier
	ds_read_b128 v[172:175], v163 offset:49152
	ds_read_b128 v[180:183], v163 offset:50176
	ds_read_b128 v[184:187], v163 offset:51200
	ds_read_b128 v[188:191], v163 offset:52224
	ds_read_b128 v[192:195], v163 offset:53248
	ds_read_b128 v[196:199], v163 offset:54272
	ds_read_b128 v[200:203], v163 offset:55296
	ds_read_b128 v[204:207], v163 offset:56320
	global_load_lds_dwordx4 v[158:159], off
	v_lshl_add_u64 v[158:159], v[226:227], 0, s[8:9]
	s_mov_b32 m0, s58
	s_nop 0
	global_load_lds_dwordx4 v[158:159], off
	s_waitcnt lgkmcnt(0)
	s_setprio 1
	s_barrier


; #define PG8_STAGE(bufoff, gbase, voff) do { _Pragma("unroll") for (int _i = 0; _i < 2; ++_i) \
;         __builtin_amdgcn_global_load_lds((const unsigned*)((const char*)(gbase) + (voff)[_i]), (LAS unsigned*)(lds + (bufoff) + ldsw + _i * 8192), 16, 0, 0); } while (0)
; #define PG8_MMA(ai, bj, At, Bt) do { __builtin_amdgcn_s_setprio(1); _Pragma("unroll") for (int m = 0; m < 4; ++m) _Pragma("unroll") for (int n = 0; n < 2; ++n) _Pragma("unroll") for (int k = 0; k < 2; ++k) \
;         acc[ai][bj][m][n] = __builtin_amdgcn_mfma_f32_16x16x32_bf16(Bt[n][k], At[m][k], acc[ai][bj][m][n], 0, 0, 0); __builtin_amdgcn_s_setprio(0); } while (0)
; #define PG8_WAIT_V(n) asm volatile("s_waitcnt vmcnt(" #n ")" ::: "memory")
; #define PG8_WAIT_L(n) asm volatile("s_waitcnt lgkmcnt(" #n ")" ::: "memory")
; #define PG8_BAR __builtin_amdgcn_s_barrier()
; #define PG8_SCHED __builtin_amdgcn_sched_barrier(0)
; template <class Epi>
; __device__ __forceinline__ void gemm_phase(LAS unsigned char* lds, const Gemm g, const StaticOrder& S, const Epi& E) {
;     ...
;             PG8_BAR; PG8_WAIT_L(0); PG8_MMA(1, 0, At, B0); PG8_BAR; PG8_SCHED;
;             PG8_STAGE(PG8_SB(1, 1), b3 + hstep, voffB);
;             PG8_WAIT_V(6); PG8_BAR; PG8_MMA(1, 1, At, B1); PG8_BAR;
	v_mfma_f32_16x16x32_bf16 v[60:63], v[128:131], v[172:175], v[60:63]
	v_mfma_f32_16x16x32_bf16 v[56:59], v[154:157], v[172:175], v[56:59]
	v_mfma_f32_16x16x32_bf16 v[44:47], v[128:131], v[184:187], v[44:47]
	v_mfma_f32_16x16x32_bf16 v[40:43], v[154:157], v[184:187], v[40:43]
	v_mfma_f32_16x16x32_bf16 v[28:31], v[128:131], v[192:195], v[28:31]
	v_mfma_f32_16x16x32_bf16 v[24:27], v[154:157], v[192:195], v[24:27]
	v_mfma_f32_16x16x32_bf16 v[12:15], v[128:131], v[200:203], v[12:15]
	v_mfma_f32_16x16x32_bf16 v[8:11], v[154:157], v[200:203], v[8:11]
	v_mfma_f32_16x16x32_bf16 v[60:63], v[132:135], v[180:183], v[60:63]
	v_mfma_f32_16x16x32_bf16 v[56:59], v[168:171], v[180:183], v[56:59]
	v_mfma_f32_16x16x32_bf16 v[44:47], v[132:135], v[188:191], v[44:47]
	v_mfma_f32_16x16x32_bf16 v[40:43], v[168:171], v[188:191], v[40:43]
	v_mfma_f32_16x16x32_bf16 v[28:31], v[132:135], v[196:199], v[28:31]
	v_mfma_f32_16x16x32_bf16 v[24:27], v[168:171], v[196:199], v[24:27]
	v_mfma_f32_16x16x32_bf16 v[12:15], v[132:135], v[204:207], v[12:15]
	v_mfma_f32_16x16x32_bf16 v[8:11], v[168:171], v[204:207], v[8:11]
	s_setprio 0
	s_barrier
	s_add_u32 s24, s24, 0x80080
	s_addc_u32 s25, s25, 0
	s_add_i32 s30, s30, s36
	v_lshl_add_u64 v[128:129], s[24:25], 0, v[140:141]
	s_mov_b32 m0, s30
	s_nop 0
	global_load_lds_dwordx4 v[128:129], off
	v_lshl_add_u64 v[128:129], s[24:25], 0, v[144:145]
	s_add_i32 m0, s30, 0x2000
	s_nop 0
	global_load_lds_dwordx4 v[128:129], off
	s_waitcnt vmcnt(6)
	s_setprio 1
	s_barrier

; __device__ __forceinline__ float bflo(unsigned w) { return __uint_as_float(w << 16); }
; __device__ __forceinline__ float bfhi(unsigned w) { return __uint_as_float(w & 0xffff0000u); }
; #define PG8_WAIT_V(n) asm volatile("s_waitcnt vmcnt(" #n ")" ::: "memory")
; #define PG8_BAR __builtin_amdgcn_s_barrier()
; template <class Epi>
; __device__ __forceinline__ void gemm_phase(LAS unsigned char* lds, const Gemm g, const StaticOrder& S, const Epi& E) {
;     ...
;             PG8_WAIT_V(6); PG8_BAR; PG8_MMA(1, 1, At, B1); PG8_BAR;
;         }
;     __device__ __forceinline__ void operator()(const f32x4 (&acc)[2][2][4][2], const Unit& u, int wr, int wc, int fr, int fq, const Pre&) const {
;         const int row0 = ROW_X + u.pm * BM + wr * 64 + fr, col0 = u.pn * BM + wc * 32 + 8 * fq;
;         u32x4 hv[2][2]; float sprev = 0.f;
;     ...
;         ER_LOAD(0, 0);
; #pragma unroll
;         for (int g = 0; g < 8; ++g) { const int ai = g >> 2, m = g & 3; const int r = row0 + ai * HALF + m * 16; const size_t off = (size_t)r * DM + col0; float s = 0.f;
;             if (g + 1 < 8) ER_LOAD(g + 1, (g + 1) & 1);
; #pragma unroll
;             for (int bj = 0; bj < 2; ++bj) { const u32x4 w = hv[g & 1][bj];
;                 const f32x4 h0 = {bflo(w.x), bfhi(w.x), bflo(w.y), bfhi(w.y)}, h1 = {bflo(w.z), bfhi(w.z), bflo(w.w), bfhi(w.w)};
;                 const f32x4 o0 = h0 + acc[ai][bj][m][0] * alpha, o1 = h1 + acc[ai][bj][m][1] * alpha;
;                 if (FINAL) { float* op = OUT + (size_t)(r - ROW_X) * DM + col0 + bj * HALF; *(f32x4*)op = o0; *(f32x4*)(op + 4) = o1; }
;                 else { u32x4 q; q.x = cvtpk(o0[0], o0[1]); q.y = cvtpk(o0[2], o0[3]); q.z = cvtpk(o1[0], o1[1]); q.w = cvtpk(o1[2], o1[3]); *(u32x4*)(HB + off + bj * HALF) = q;
;                        s += ((o0[0] * o0[0] + o0[1] * o0[1]) + (o0[2] * o0[2] + o0[3] * o0[3])) + ((o1[0] * o1[0] + o1[1] * o1[1]) + (o1[2] * o1[2] + o1[3] * o1[3])); } }
;             if (!FINAL) { if (g > 0) { float t = sprev; t += __shfl_xor(t, 16); t += __shfl_xor(t, 32);
;                     if (fq == 0) __hip_atomic_fetch_add(ssq_out + row0 + ((g - 1) >> 2) * HALF + ((g - 1) & 3) * 16, t, __ATOMIC_RELAXED, __HIP_MEMORY_SCOPE_AGENT); }
;                 sprev = s; } }
	v_mfma_f32_16x16x32_bf16 v[52:55], v[208:211], v[172:175], v[52:55]
	v_mfma_f32_16x16x32_bf16 v[48:51], v[216:219], v[172:175], v[48:51]
	v_mfma_f32_16x16x32_bf16 v[36:39], v[208:211], v[184:187], v[36:39]
	v_mfma_f32_16x16x32_bf16 v[32:35], v[216:219], v[184:187], v[32:35]
	v_mfma_f32_16x16x32_bf16 v[20:23], v[208:211], v[192:195], v[20:23]
	v_mfma_f32_16x16x32_bf16 v[16:19], v[216:219], v[192:195], v[16:19]
	v_mfma_f32_16x16x32_bf16 v[4:7], v[208:211], v[200:203], v[4:7]
	v_mfma_f32_16x16x32_bf16 v[0:3], v[216:219], v[200:203], v[0:3]
	v_mfma_f32_16x16x32_bf16 v[52:55], v[212:215], v[180:183], v[52:55]
	v_mfma_f32_16x16x32_bf16 v[48:51], v[220:223], v[180:183], v[48:51]
	v_mfma_f32_16x16x32_bf16 v[36:39], v[212:215], v[188:191], v[36:39]
	v_mfma_f32_16x16x32_bf16 v[32:35], v[220:223], v[188:191], v[32:35]
	v_mfma_f32_16x16x32_bf16 v[20:23], v[212:215], v[196:199], v[20:23]
	v_mfma_f32_16x16x32_bf16 v[16:19], v[220:223], v[196:199], v[16:19]
	v_mfma_f32_16x16x32_bf16 v[4:7], v[212:215], v[204:207], v[4:7]
	v_mfma_f32_16x16x32_bf16 v[0:3], v[220:223], v[204:207], v[0:3]
	s_setprio 0
	s_add_i32 s67, s67, 2
	s_add_u32 s22, s22, 0x100
	s_addc_u32 s23, s23, 0
	s_add_u32 s65, s65, 0x100
	s_addc_u32 s66, s66, 0
	s_cmp_gt_u32 s67, 29
	s_barrier
	s_cbranch_scc0 .LBB0_1220
	v_lshl_add_u32 v156, s18, 8, v160
	v_lshl_or_b32 v154, s20, 8, v161
	v_ashrrev_i32_e32 v157, 31, v156
	v_ashrrev_i32_e32 v155, 31, v154
	v_lshlrev_b64 v[128:129], 12, v[156:157]
	v_lshl_add_u64 v[128:129], s[0:1], 0, v[128:129]
	v_lshlrev_b64 v[130:131], 1, v[154:155]
	v_lshl_add_u64 v[176:177], v[128:129], 0, v[130:131]
	v_or_b32_e32 v128, 16, v156
	v_ashrrev_i32_e32 v129, 31, v128
	global_load_dwordx4 v[168:171], v[176:177], off
	global_load_dwordx4 v[172:175], v[176:177], off offset:256
	v_lshlrev_b64 v[128:129], 12, v[128:129]
	v_lshl_add_u64 v[128:129], s[0:1], 0, v[128:129]
	v_lshl_add_u64 v[188:189], v[128:129], 0, v[130:131]
	global_load_dwordx4 v[180:183], v[188:189], off
	global_load_dwordx4 v[184:187], v[188:189], off offset:256
	v_or_b32_e32 v128, 32, v156
	v_ashrrev_i32_e32 v129, 31, v128
	v_lshlrev_b64 v[128:129], 12, v[128:129]
	v_lshl_add_u64 v[128:129], s[0:1], 0, v[128:129]
	v_lshl_add_u64 v[158:159], v[128:129], 0, v[130:131]
	global_load_dwordx4 v[132:135], v[158:159], off
	global_load_dwordx4 v[128:131], v[158:159], off offset:256
	s_waitcnt vmcnt(0)
	v_lshlrev_b32_e32 v190, 16, v168
	v_and_b32_e32 v191, 0xffff0000, v168
	v_lshlrev_b32_e32 v168, 16, v169
	v_and_b32_e32 v169, 0xffff0000, v169
	v_lshlrev_b32_e32 v192, 16, v170
	v_and_b32_e32 v193, 0xffff0000, v170
	v_lshlrev_b32_e32 v170, 16, v171
	v_and_b32_e32 v171, 0xffff0000, v171
	v_lshlrev_b32_e32 v194, 16, v172
	v_and_b32_e32 v195, 0xffff0000, v172
	v_lshlrev_b32_e32 v172, 16, v173
	v_and_b32_e32 v173, 0xffff0000, v173
	v_lshlrev_b32_e32 v196, 16, v174
	v_and_b32_e32 v197, 0xffff0000, v174
	v_lshlrev_b32_e32 v174, 16, v175
	v_and_b32_e32 v175, 0xffff0000, v175
	v_pk_add_f32 v[126:127], v[126:127], v[168:169]
	v_pk_add_f32 v[124:125], v[124:125], v[190:191]
	v_pk_add_f32 v[122:123], v[122:123], v[170:171]
	v_pk_add_f32 v[168:169], v[120:121], v[192:193]
	v_pk_add_f32 v[170:171], v[118:119], v[172:173]
	v_pk_add_f32 v[172:173], v[116:117], v[194:195]
	v_pk_add_f32 v[174:175], v[114:115], v[174:175]
	v_pk_add_f32 v[190:191], v[112:113], v[196:197]
	v_cvt_pk_bf16_f32 v114, v124, v125
	v_cvt_pk_bf16_f32 v115, v126, v127
	v_cvt_pk_bf16_f32 v116, v168, v169
	v_cvt_pk_bf16_f32 v117, v122, v123
	v_mul_f32_e32 v125, v125, v125
	v_mul_f32_e32 v127, v127, v127
	v_mul_f32_e32 v167, v169, v169
	v_mul_f32_e32 v123, v123, v123
	v_cvt_pk_bf16_f32 v118, v172, v173
	v_cvt_pk_bf16_f32 v119, v170, v171
	v_cvt_pk_bf16_f32 v121, v174, v175
	v_mul_f32_e32 v169, v173, v173
	v_mul_f32_e32 v171, v171, v171
	v_mul_f32_e32 v173, v191, v191
	v_mul_f32_e32 v175, v175, v175
	v_lshlrev_b32_e32 v112, 16, v180
	v_and_b32_e32 v113, 0xffff0000, v180
	v_lshlrev_b32_e32 v192, 16, v182
	v_and_b32_e32 v193, 0xffff0000, v182
	v_lshlrev_b32_e32 v182, 16, v183
	v_and_b32_e32 v183, 0xffff0000, v183
	v_fmac_f32_e32 v125, v124, v124
	v_fmac_f32_e32 v127, v126, v126
	v_fmac_f32_e32 v167, v168, v168
	v_fmac_f32_e32 v123, v122, v122
	v_fmac_f32_e32 v169, v172, v172
	v_fmac_f32_e32 v171, v170, v170
	v_fmac_f32_e32 v173, v190, v190
	v_fmac_f32_e32 v175, v174, v174
	v_lshlrev_b32_e32 v180, 16, v181
	v_and_b32_e32 v181, 0xffff0000, v181
	v_pk_add_f32 v[112:113], v[108:109], v[112:113]
	v_pk_add_f32 v[108:109], v[106:107], v[182:183]
	global_store_dwordx4 v[176:177], v[114:117], off
	v_add_f32_e32 v106, v125, v127
	v_add_f32_e32 v107, v167, v123
	v_add_f32_e32 v114, v169, v171
	v_add_f32_e32 v115, v173, v175
	v_pk_add_f32 v[110:111], v[110:111], v[180:181]
	v_add_f32_e32 v106, v106, v107
	v_add_f32_e32 v107, v114, v115
	v_pk_add_f32 v[114:115], v[104:105], v[192:193]
	v_add_f32_e32 v125, v106, v107
	v_cvt_pk_bf16_f32 v104, v112, v113
	v_cvt_pk_bf16_f32 v105, v110, v111
	v_cvt_pk_bf16_f32 v106, v114, v115
	v_cvt_pk_bf16_f32 v107, v108, v109
	v_cvt_pk_bf16_f32 v120, v190, v191
	global_store_dwordx4 v[188:189], v[104:107], off
	global_store_dwordx4 v[176:177], v[118:121], off offset:256
	v_lshlrev_b32_e32 v122, 16, v186
	v_lshlrev_b32_e32 v104, 16, v184
	v_and_b32_e32 v105, 0xffff0000, v184
	v_pk_add_f32 v[118:119], v[100:101], v[104:105]
	v_and_b32_e32 v101, 64, v166
	v_xor_b32_e32 v100, 16, v166
	v_add_u32_e32 v101, 64, v101
	v_cmp_lt_i32_e32 vcc, v100, v101
	v_and_b32_e32 v123, 0xffff0000, v186
	v_pk_add_f32 v[122:123], v[96:97], v[122:123]
	v_cndmask_b32_e32 v100, v166, v100, vcc
	v_lshlrev_b32_e32 v124, 2, v100
	ds_bpermute_b32 v100, v124, v125
	v_xor_b32_e32 v97, 32, v166
	v_cmp_lt_i32_e32 vcc, v97, v101
	v_lshlrev_b32_e32 v106, 16, v185
	v_and_b32_e32 v107, 0xffff0000, v185
	v_cndmask_b32_e32 v97, v166, v97, vcc
	s_waitcnt lgkmcnt(0)
	v_add_f32_e32 v96, v125, v100
	v_lshlrev_b32_e32 v125, 2, v97
	ds_bpermute_b32 v97, v125, v96
	v_lshlrev_b32_e32 v120, 16, v187
	v_and_b32_e32 v121, 0xffff0000, v187
	v_pk_add_f32 v[116:117], v[102:103], v[106:107]
	v_pk_add_f32 v[120:121], v[98:99], v[120:121]
	v_cvt_pk_bf16_f32 v98, v118, v119
	v_cvt_pk_bf16_f32 v99, v116, v117
	v_cvt_pk_bf16_f32 v100, v122, v123
	v_cvt_pk_bf16_f32 v101, v120, v121
	v_lshl_add_u64 v[104:105], v[156:157], 2, s[6:7]
	global_store_dwordx4 v[188:189], v[98:101], off offset:256
	s_and_saveexec_b64 s[18:19], s[2:3]
	s_cbranch_execz .LBB0_1223
	s_waitcnt lgkmcnt(0)
	v_add_f32_e32 v96, v96, v97
	global_atomic_add_f32 v[104:105], v96, off

; #define PG8_STAGE(bufoff, gbase, voff) do { _Pragma("unroll") for (int _i = 0; _i < 2; ++_i) \
;         __builtin_amdgcn_global_load_lds((const unsigned*)((const char*)(gbase) + (voff)[_i]), (LAS unsigned*)(lds + (bufoff) + ldsw + _i * 8192), 16, 0, 0); } while (0)
; #define PG8_LDA(dst, b, h) do { _Pragma("unroll") for (int m = 0; m < 4; ++m) _Pragma("unroll") for (int k = 0; k < 2; ++k) dst[m][k] = *(const LAS bf16x8*)(lds + PG8_SA(b, h) + aoff + m * 2048 + k * 1024); } while (0)
; #define PG8_LDB(dst, b, h) do { _Pragma("unroll") for (int n = 0; n < 2; ++n) _Pragma("unroll") for (int k = 0; k < 2; ++k) dst[n][k] = *(const LAS bf16x8*)(lds + PG8_SB(b, h) + boff + n * 2048 + k * 1024); } while (0)
; #define PG8_MMA(ai, bj, At, Bt) do { __builtin_amdgcn_s_setprio(1); _Pragma("unroll") for (int m = 0; m < 4; ++m) _Pragma("unroll") for (int n = 0; n < 2; ++n) _Pragma("unroll") for (int k = 0; k < 2; ++k) \
;         acc[ai][bj][m][n] = __builtin_amdgcn_mfma_f32_16x16x32_bf16(Bt[n][k], At[m][k], acc[ai][bj][m][n], 0, 0, 0); __builtin_amdgcn_s_setprio(0); } while (0)
; #define PG8_WAIT_L(n) asm volatile("s_waitcnt lgkmcnt(" #n ")" ::: "memory")
; #define PG8_BAR __builtin_amdgcn_s_barrier()
; #define PG8_SCHED __builtin_amdgcn_sched_barrier(0)
; template <class Epi>
; __device__ __forceinline__ void gemm_phase(LAS unsigned char* lds, const Gemm g, const StaticOrder& S, const Epi& E) {
;     ...
;             PG8_LDB(B0, 0, 0); PG8_SCHED; PG8_LDA(At, 0, 0); PG8_STAGE(PG8_SA(1, 1), a1 + hstep, voffA);
;             PG8_WAIT_L(8); PG8_BAR; PG8_WAIT_L(0); PG8_MMA(0, 0, At, B0); PG8_BAR; PG8_SCHED;
.LBB0_1306:
	ds_read_b128 v[166:169], v149
	ds_read_b128 v[170:173], v149 offset:1024
	ds_read_b128 v[174:177], v149 offset:2048
	ds_read_b128 v[180:183], v149 offset:3072
	s_add_u32 s18, s16, 0xfff80080
	s_addc_u32 s19, s17, -1
	s_cmp_eq_u32 s65, 28
	s_cselect_b32 s21, s9, s19
	s_cselect_b32 s20, s61, s18
	s_cselect_b32 s19, s7, s64
	s_cselect_b32 s18, s62, s63
	v_lshl_add_u64 v[162:163], s[16:17], 0, v[138:139]
	s_add_i32 m0, s35, 0xc000
	ds_read_b128 v[184:187], v150
	ds_read_b128 v[188:191], v150 offset:1024
	ds_read_b128 v[192:195], v150 offset:2048
	ds_read_b128 v[196:199], v150 offset:3072
	ds_read_b128 v[200:203], v150 offset:4096
	ds_read_b128 v[204:207], v150 offset:5120
	ds_read_b128 v[208:211], v150 offset:6144
	ds_read_b128 v[212:215], v150 offset:7168
	global_load_lds_dwordx4 v[162:163], off
	v_lshl_add_u64 v[162:163], s[16:17], 0, v[140:141]
	s_add_i32 m0, s35, 0xe000
	s_nop 0
	global_load_lds_dwordx4 v[162:163], off
	s_waitcnt lgkmcnt(8)
	s_setprio 1
	s_barrier
	s_waitcnt lgkmcnt(0)


; #define PG8_STAGE(bufoff, gbase, voff) do { _Pragma("unroll") for (int _i = 0; _i < 2; ++_i) \
;         __builtin_amdgcn_global_load_lds((const unsigned*)((const char*)(gbase) + (voff)[_i]), (LAS unsigned*)(lds + (bufoff) + ldsw + _i * 8192), 16, 0, 0); } while (0)
; #define PG8_LDB(dst, b, h) do { _Pragma("unroll") for (int n = 0; n < 2; ++n) _Pragma("unroll") for (int k = 0; k < 2; ++k) dst[n][k] = *(const LAS bf16x8*)(lds + PG8_SB(b, h) + boff + n * 2048 + k * 1024); } while (0)
; #define PG8_MMA(ai, bj, At, Bt) do { __builtin_amdgcn_s_setprio(1); _Pragma("unroll") for (int m = 0; m < 4; ++m) _Pragma("unroll") for (int n = 0; n < 2; ++n) _Pragma("unroll") for (int k = 0; k < 2; ++k) \
;         acc[ai][bj][m][n] = __builtin_amdgcn_mfma_f32_16x16x32_bf16(Bt[n][k], At[m][k], acc[ai][bj][m][n], 0, 0, 0); __builtin_amdgcn_s_setprio(0); } while (0)
; #define PG8_WAIT_L(n) asm volatile("s_waitcnt lgkmcnt(" #n ")" ::: "memory")
; #define PG8_BAR __builtin_amdgcn_s_barrier()
; #define PG8_SCHED __builtin_amdgcn_sched_barrier(0)
; template <class Epi>
; __device__ __forceinline__ void gemm_phase(LAS unsigned char* lds, const Gemm g, const StaticOrder& S, const Epi& E) {
;     ...
;             PG8_WAIT_L(8); PG8_BAR; PG8_WAIT_L(0); PG8_MMA(0, 0, At, B0); PG8_BAR; PG8_SCHED;
;             PG8_LDB(B1, 0, 1); PG8_STAGE(PG8_SB(0, 0), b2, voffB);
;             PG8_BAR; PG8_WAIT_L(0); PG8_MMA(0, 1, At, B1); PG8_BAR;
	v_mfma_f32_16x16x32_bf16 v[124:127], v[166:169], v[184:187], v[124:127]
	v_mfma_f32_16x16x32_bf16 v[116:119], v[174:177], v[184:187], v[116:119]
	v_mfma_f32_16x16x32_bf16 v[108:111], v[166:169], v[192:195], v[108:111]
	v_mfma_f32_16x16x32_bf16 v[100:103], v[174:177], v[192:195], v[100:103]
	v_mfma_f32_16x16x32_bf16 v[92:95], v[166:169], v[200:203], v[92:95]
	v_mfma_f32_16x16x32_bf16 v[84:87], v[174:177], v[200:203], v[84:87]
	v_mfma_f32_16x16x32_bf16 v[76:79], v[166:169], v[208:211], v[76:79]
	v_mfma_f32_16x16x32_bf16 v[68:71], v[174:177], v[208:211], v[68:71]
	v_mfma_f32_16x16x32_bf16 v[124:127], v[170:173], v[188:191], v[124:127]
	v_mfma_f32_16x16x32_bf16 v[116:119], v[180:183], v[188:191], v[116:119]
	v_mfma_f32_16x16x32_bf16 v[108:111], v[170:173], v[196:199], v[108:111]
	v_mfma_f32_16x16x32_bf16 v[100:103], v[180:183], v[196:199], v[100:103]
	v_mfma_f32_16x16x32_bf16 v[92:95], v[170:173], v[204:207], v[92:95]
	v_mfma_f32_16x16x32_bf16 v[84:87], v[180:183], v[204:207], v[84:87]
	v_mfma_f32_16x16x32_bf16 v[76:79], v[170:173], v[212:215], v[76:79]
	v_mfma_f32_16x16x32_bf16 v[68:71], v[180:183], v[212:215], v[68:71]
	s_setprio 0
	s_barrier
	s_add_i32 s66, s58, s31
	v_lshl_add_u64 v[162:163], s[18:19], 0, v[132:133]
	s_mov_b32 m0, s66
	ds_read_b128 v[216:219], v152
	ds_read_b128 v[220:223], v152 offset:1024
	ds_read_b128 v[224:227], v152 offset:2048
	ds_read_b128 v[228:231], v152 offset:3072
	global_load_lds_dwordx4 v[162:163], off
	v_lshl_add_u64 v[232:233], s[18:19], 0, v[128:129]
	s_add_i32 m0, s66, 0x2000
	s_nop 0
	global_load_lds_dwordx4 v[232:233], off
	s_waitcnt lgkmcnt(0)
	s_setprio 1
	s_barrier


; #define PG8_STAGE(bufoff, gbase, voff) do { _Pragma("unroll") for (int _i = 0; _i < 2; ++_i) \
;         __builtin_amdgcn_global_load_lds((const unsigned*)((const char*)(gbase) + (voff)[_i]), (LAS unsigned*)(lds + (bufoff) + ldsw + _i * 8192), 16, 0, 0); } while (0)
; #define PG8_LDA(dst, b, h) do { _Pragma("unroll") for (int m = 0; m < 4; ++m) _Pragma("unroll") for (int k = 0; k < 2; ++k) dst[m][k] = *(const LAS bf16x8*)(lds + PG8_SA(b, h) + aoff + m * 2048 + k * 1024); } while (0)
; #define PG8_MMA(ai, bj, At, Bt) do { __builtin_amdgcn_s_setprio(1); _Pragma("unroll") for (int m = 0; m < 4; ++m) _Pragma("unroll") for (int n = 0; n < 2; ++n) _Pragma("unroll") for (int k = 0; k < 2; ++k) \
;         acc[ai][bj][m][n] = __builtin_amdgcn_mfma_f32_16x16x32_bf16(Bt[n][k], At[m][k], acc[ai][bj][m][n], 0, 0, 0); __builtin_amdgcn_s_setprio(0); } while (0)
; #define PG8_WAIT_L(n) asm volatile("s_waitcnt lgkmcnt(" #n ")" ::: "memory")
; #define PG8_BAR __builtin_amdgcn_s_barrier()
; #define PG8_SCHED __builtin_amdgcn_sched_barrier(0)
; template <class Epi>
; __device__ __forceinline__ void gemm_phase(LAS unsigned char* lds, const Gemm g, const StaticOrder& S, const Epi& E) {
;     ...
;             PG8_BAR; PG8_WAIT_L(0); PG8_MMA(0, 1, At, B1); PG8_BAR;
;             PG8_LDA(At, 0, 1); PG8_STAGE(PG8_SA(0, 0), a2, voffA);
;             PG8_BAR; PG8_WAIT_L(0); PG8_MMA(1, 0, At, B0); PG8_BAR; PG8_SCHED;
	v_mfma_f32_16x16x32_bf16 v[120:123], v[216:219], v[184:187], v[120:123]
	v_mfma_f32_16x16x32_bf16 v[112:115], v[224:227], v[184:187], v[112:115]
	v_mfma_f32_16x16x32_bf16 v[104:107], v[216:219], v[192:195], v[104:107]
	v_mfma_f32_16x16x32_bf16 v[96:99], v[224:227], v[192:195], v[96:99]
	v_mfma_f32_16x16x32_bf16 v[88:91], v[216:219], v[200:203], v[88:91]
	v_mfma_f32_16x16x32_bf16 v[80:83], v[224:227], v[200:203], v[80:83]
	v_mfma_f32_16x16x32_bf16 v[72:75], v[216:219], v[208:211], v[72:75]
	v_mfma_f32_16x16x32_bf16 v[64:67], v[224:227], v[208:211], v[64:67]
	v_mfma_f32_16x16x32_bf16 v[120:123], v[220:223], v[188:191], v[120:123]
	v_mfma_f32_16x16x32_bf16 v[112:115], v[228:231], v[188:191], v[112:115]
	v_mfma_f32_16x16x32_bf16 v[104:107], v[220:223], v[196:199], v[104:107]
	v_mfma_f32_16x16x32_bf16 v[96:99], v[228:231], v[196:199], v[96:99]
	v_mfma_f32_16x16x32_bf16 v[88:91], v[220:223], v[204:207], v[88:91]
	v_mfma_f32_16x16x32_bf16 v[80:83], v[228:231], v[204:207], v[80:83]
	v_mfma_f32_16x16x32_bf16 v[72:75], v[220:223], v[212:215], v[72:75]
	v_mfma_f32_16x16x32_bf16 v[64:67], v[228:231], v[212:215], v[64:67]
	s_setprio 0
	s_mov_b32 m0, s35
	v_lshl_add_u64 v[234:235], s[20:21], 0, v[134:135]
	s_barrier
	ds_read_b128 v[184:187], v150 offset:16384
	ds_read_b128 v[188:191], v150 offset:17408
	ds_read_b128 v[192:195], v150 offset:18432
	ds_read_b128 v[196:199], v150 offset:19456
	ds_read_b128 v[200:203], v150 offset:20480
	ds_read_b128 v[204:207], v150 offset:21504
	ds_read_b128 v[208:211], v150 offset:22528
	ds_read_b128 v[212:215], v150 offset:23552
	global_load_lds_dwordx4 v[234:235], off
	v_lshl_add_u64 v[236:237], s[20:21], 0, v[130:131]
	s_mov_b32 m0, s36
	s_nop 0
	global_load_lds_dwordx4 v[236:237], off
	s_waitcnt lgkmcnt(0)
	s_setprio 1
	s_barrier


; #define PG8_STAGE(bufoff, gbase, voff) do { _Pragma("unroll") for (int _i = 0; _i < 2; ++_i) \
;         __builtin_amdgcn_global_load_lds((const unsigned*)((const char*)(gbase) + (voff)[_i]), (LAS unsigned*)(lds + (bufoff) + ldsw + _i * 8192), 16, 0, 0); } while (0)
; #define PG8_MMA(ai, bj, At, Bt) do { __builtin_amdgcn_s_setprio(1); _Pragma("unroll") for (int m = 0; m < 4; ++m) _Pragma("unroll") for (int n = 0; n < 2; ++n) _Pragma("unroll") for (int k = 0; k < 2; ++k) \
;         acc[ai][bj][m][n] = __builtin_amdgcn_mfma_f32_16x16x32_bf16(Bt[n][k], At[m][k], acc[ai][bj][m][n], 0, 0, 0); __builtin_amdgcn_s_setprio(0); } while (0)
; #define PG8_WAIT_V(n) asm volatile("s_waitcnt vmcnt(" #n ")" ::: "memory")
; #define PG8_WAIT_L(n) asm volatile("s_waitcnt lgkmcnt(" #n ")" ::: "memory")
; #define PG8_BAR __builtin_amdgcn_s_barrier()
; #define PG8_SCHED __builtin_amdgcn_sched_barrier(0)
; template <class Epi>
; __device__ __forceinline__ void gemm_phase(LAS unsigned char* lds, const Gemm g, const StaticOrder& S, const Epi& E) {
;     ...
;             PG8_BAR; PG8_WAIT_L(0); PG8_MMA(1, 0, At, B0); PG8_BAR; PG8_SCHED;
;             PG8_STAGE(PG8_SB(0, 1), b2 + hstep, voffB);
;             PG8_WAIT_V(6); PG8_BAR; PG8_MMA(1, 1, At, B1); PG8_BAR;
	v_mfma_f32_16x16x32_bf16 v[60:63], v[166:169], v[184:187], v[60:63]
	v_mfma_f32_16x16x32_bf16 v[52:55], v[174:177], v[184:187], v[52:55]
	v_mfma_f32_16x16x32_bf16 v[44:47], v[166:169], v[192:195], v[44:47]
	v_mfma_f32_16x16x32_bf16 v[36:39], v[174:177], v[192:195], v[36:39]
	v_mfma_f32_16x16x32_bf16 v[28:31], v[166:169], v[200:203], v[28:31]
	v_mfma_f32_16x16x32_bf16 v[20:23], v[174:177], v[200:203], v[20:23]
	v_mfma_f32_16x16x32_bf16 v[12:15], v[166:169], v[208:211], v[12:15]
	v_mfma_f32_16x16x32_bf16 v[4:7], v[174:177], v[208:211], v[4:7]
	v_mfma_f32_16x16x32_bf16 v[60:63], v[170:173], v[188:191], v[60:63]
	v_mfma_f32_16x16x32_bf16 v[52:55], v[180:183], v[188:191], v[52:55]
	v_mfma_f32_16x16x32_bf16 v[44:47], v[170:173], v[196:199], v[44:47]
	v_mfma_f32_16x16x32_bf16 v[36:39], v[180:183], v[196:199], v[36:39]
	v_mfma_f32_16x16x32_bf16 v[28:31], v[170:173], v[204:207], v[28:31]
	v_mfma_f32_16x16x32_bf16 v[20:23], v[180:183], v[204:207], v[20:23]
	v_mfma_f32_16x16x32_bf16 v[12:15], v[170:173], v[212:215], v[12:15]
	v_mfma_f32_16x16x32_bf16 v[4:7], v[180:183], v[212:215], v[4:7]
	s_setprio 0
	s_barrier
	s_add_u32 s66, s18, 0x80000
	s_addc_u32 s67, s19, 0
	s_add_i32 s68, s59, s31
	v_lshl_add_u64 v[166:167], s[66:67], 0, v[132:133]
	s_mov_b32 m0, s68
	s_nop 0
	global_load_lds_dwordx4 v[166:167], off
	v_lshl_add_u64 v[166:167], s[66:67], 0, v[128:129]
	s_add_i32 m0, s68, 0x2000
	s_nop 0
	global_load_lds_dwordx4 v[166:167], off
	s_waitcnt vmcnt(6)
	s_setprio 1
	s_barrier

; #define PG8_STAGE(bufoff, gbase, voff) do { _Pragma("unroll") for (int _i = 0; _i < 2; ++_i) \
;         __builtin_amdgcn_global_load_lds((const unsigned*)((const char*)(gbase) + (voff)[_i]), (LAS unsigned*)(lds + (bufoff) + ldsw + _i * 8192), 16, 0, 0); } while (0)
; #define PG8_LDA(dst, b, h) do { _Pragma("unroll") for (int m = 0; m < 4; ++m) _Pragma("unroll") for (int k = 0; k < 2; ++k) dst[m][k] = *(const LAS bf16x8*)(lds + PG8_SA(b, h) + aoff + m * 2048 + k * 1024); } while (0)
; #define PG8_LDB(dst, b, h) do { _Pragma("unroll") for (int n = 0; n < 2; ++n) _Pragma("unroll") for (int k = 0; k < 2; ++k) dst[n][k] = *(const LAS bf16x8*)(lds + PG8_SB(b, h) + boff + n * 2048 + k * 1024); } while (0)
; #define PG8_MMA(ai, bj, At, Bt) do { __builtin_amdgcn_s_setprio(1); _Pragma("unroll") for (int m = 0; m < 4; ++m) _Pragma("unroll") for (int n = 0; n < 2; ++n) _Pragma("unroll") for (int k = 0; k < 2; ++k) \
;         acc[ai][bj][m][n] = __builtin_amdgcn_mfma_f32_16x16x32_bf16(Bt[n][k], At[m][k], acc[ai][bj][m][n], 0, 0, 0); __builtin_amdgcn_s_setprio(0); } while (0)
; #define PG8_WAIT_V(n) asm volatile("s_waitcnt vmcnt(" #n ")" ::: "memory")
; #define PG8_WAIT_L(n) asm volatile("s_waitcnt lgkmcnt(" #n ")" ::: "memory")
; #define PG8_BAR __builtin_amdgcn_s_barrier()
; #define PG8_SCHED __builtin_amdgcn_sched_barrier(0)
; template <class Epi>
; __device__ __forceinline__ void gemm_phase(LAS unsigned char* lds, const Gemm g, const StaticOrder& S, const Epi& E) {
;     ...
;             PG8_WAIT_V(6); PG8_BAR; PG8_MMA(1, 1, At, B1); PG8_BAR;
;             PG8_LDB(B0, 1, 0); PG8_SCHED; PG8_LDA(At, 1, 0); PG8_STAGE(PG8_SA(0, 1), a2 + hstep, voffA);
;             PG8_WAIT_L(8); PG8_BAR; PG8_WAIT_L(0); PG8_MMA(0, 0, At, B0); PG8_BAR; PG8_SCHED;
	v_mfma_f32_16x16x32_bf16 v[56:59], v[216:219], v[184:187], v[56:59]
	v_mfma_f32_16x16x32_bf16 v[48:51], v[224:227], v[184:187], v[48:51]
	v_mfma_f32_16x16x32_bf16 v[40:43], v[216:219], v[192:195], v[40:43]
	v_mfma_f32_16x16x32_bf16 v[32:35], v[224:227], v[192:195], v[32:35]
	v_mfma_f32_16x16x32_bf16 v[24:27], v[216:219], v[200:203], v[24:27]
	v_mfma_f32_16x16x32_bf16 v[16:19], v[224:227], v[200:203], v[16:19]
	v_mfma_f32_16x16x32_bf16 v[8:11], v[216:219], v[208:211], v[8:11]
	v_mfma_f32_16x16x32_bf16 v[0:3], v[224:227], v[208:211], v[0:3]
	v_mfma_f32_16x16x32_bf16 v[56:59], v[220:223], v[188:191], v[56:59]
	v_mfma_f32_16x16x32_bf16 v[48:51], v[228:231], v[188:191], v[48:51]
	v_mfma_f32_16x16x32_bf16 v[40:43], v[220:223], v[196:199], v[40:43]
	v_mfma_f32_16x16x32_bf16 v[32:35], v[228:231], v[196:199], v[32:35]
	v_mfma_f32_16x16x32_bf16 v[24:27], v[220:223], v[204:207], v[24:27]
	v_mfma_f32_16x16x32_bf16 v[16:19], v[228:231], v[204:207], v[16:19]
	v_mfma_f32_16x16x32_bf16 v[8:11], v[220:223], v[212:215], v[8:11]
	v_mfma_f32_16x16x32_bf16 v[0:3], v[228:231], v[212:215], v[0:3]
	s_setprio 0
	s_add_i32 s66, 0, 0x18000
	v_add_u32_e32 v161, s66, v147
	s_barrier
	ds_read_b128 v[166:169], v161
	ds_read_b128 v[170:173], v161 offset:1024
	ds_read_b128 v[174:177], v161 offset:2048
	ds_read_b128 v[180:183], v161 offset:3072
	s_add_u32 s20, s20, 0x80000
	s_addc_u32 s21, s21, 0
	s_mov_b32 m0, s37
	v_lshl_add_u64 v[216:217], s[20:21], 0, v[134:135]
	ds_read_b128 v[184:187], v150 offset:32768
	ds_read_b128 v[188:191], v150 offset:33792
	ds_read_b128 v[192:195], v150 offset:34816
	ds_read_b128 v[196:199], v150 offset:35840
	ds_read_b128 v[200:203], v150 offset:36864
	ds_read_b128 v[204:207], v150 offset:37888
	ds_read_b128 v[208:211], v150 offset:38912
	ds_read_b128 v[212:215], v150 offset:39936
	global_load_lds_dwordx4 v[216:217], off
	v_lshl_add_u64 v[216:217], s[20:21], 0, v[130:131]
	s_mov_b32 m0, s38
	s_nop 0
	global_load_lds_dwordx4 v[216:217], off
	s_waitcnt lgkmcnt(8)
	s_setprio 1
	s_barrier
	s_waitcnt lgkmcnt(0)


; #define PG8_STAGE(bufoff, gbase, voff) do { _Pragma("unroll") for (int _i = 0; _i < 2; ++_i) \
;         __builtin_amdgcn_global_load_lds((const unsigned*)((const char*)(gbase) + (voff)[_i]), (LAS unsigned*)(lds + (bufoff) + ldsw + _i * 8192), 16, 0, 0); } while (0)
; #define PG8_LDB(dst, b, h) do { _Pragma("unroll") for (int n = 0; n < 2; ++n) _Pragma("unroll") for (int k = 0; k < 2; ++k) dst[n][k] = *(const LAS bf16x8*)(lds + PG8_SB(b, h) + boff + n * 2048 + k * 1024); } while (0)
; #define PG8_MMA(ai, bj, At, Bt) do { __builtin_amdgcn_s_setprio(1); _Pragma("unroll") for (int m = 0; m < 4; ++m) _Pragma("unroll") for (int n = 0; n < 2; ++n) _Pragma("unroll") for (int k = 0; k < 2; ++k) \
;         acc[ai][bj][m][n] = __builtin_amdgcn_mfma_f32_16x16x32_bf16(Bt[n][k], At[m][k], acc[ai][bj][m][n], 0, 0, 0); __builtin_amdgcn_s_setprio(0); } while (0)
; #define PG8_WAIT_L(n) asm volatile("s_waitcnt lgkmcnt(" #n ")" ::: "memory")
; #define PG8_BAR __builtin_amdgcn_s_barrier()
; #define PG8_SCHED __builtin_amdgcn_sched_barrier(0)
; template <class Epi>
; __device__ __forceinline__ void gemm_phase(LAS unsigned char* lds, const Gemm g, const StaticOrder& S, const Epi& E) {
;     ...
;             PG8_WAIT_L(8); PG8_BAR; PG8_WAIT_L(0); PG8_MMA(0, 0, At, B0); PG8_BAR; PG8_SCHED;
;             PG8_LDB(B1, 1, 1); PG8_STAGE(PG8_SB(1, 0), b3, voffB);
;             PG8_BAR; PG8_WAIT_L(0); PG8_MMA(0, 1, At, B1); PG8_BAR;
	v_mfma_f32_16x16x32_bf16 v[124:127], v[166:169], v[184:187], v[124:127]
	v_mfma_f32_16x16x32_bf16 v[116:119], v[174:177], v[184:187], v[116:119]
	v_mfma_f32_16x16x32_bf16 v[108:111], v[166:169], v[192:195], v[108:111]
	v_mfma_f32_16x16x32_bf16 v[100:103], v[174:177], v[192:195], v[100:103]
	v_mfma_f32_16x16x32_bf16 v[92:95], v[166:169], v[200:203], v[92:95]
	v_mfma_f32_16x16x32_bf16 v[84:87], v[174:177], v[200:203], v[84:87]
	v_mfma_f32_16x16x32_bf16 v[76:79], v[166:169], v[208:211], v[76:79]
	v_mfma_f32_16x16x32_bf16 v[68:71], v[174:177], v[208:211], v[68:71]
	v_mfma_f32_16x16x32_bf16 v[124:127], v[170:173], v[188:191], v[124:127]
	v_mfma_f32_16x16x32_bf16 v[116:119], v[180:183], v[188:191], v[116:119]
	v_mfma_f32_16x16x32_bf16 v[108:111], v[170:173], v[196:199], v[108:111]
	v_mfma_f32_16x16x32_bf16 v[100:103], v[180:183], v[196:199], v[100:103]
	v_mfma_f32_16x16x32_bf16 v[92:95], v[170:173], v[204:207], v[92:95]
	v_mfma_f32_16x16x32_bf16 v[84:87], v[180:183], v[204:207], v[84:87]
	v_mfma_f32_16x16x32_bf16 v[76:79], v[170:173], v[212:215], v[76:79]
	v_mfma_f32_16x16x32_bf16 v[68:71], v[180:183], v[212:215], v[68:71]
	s_setprio 0
	s_barrier
	s_add_i32 s20, 0, 0x1c000
	s_add_i32 s21, s66, s31
	v_add_u32_e32 v161, s20, v147
	v_lshl_add_u64 v[162:163], v[162:163], 0, s[4:5]
	s_mov_b32 m0, s21
	ds_read_b128 v[216:219], v161
	ds_read_b128 v[220:223], v161 offset:1024
	ds_read_b128 v[224:227], v161 offset:2048
	ds_read_b128 v[228:231], v161 offset:3072
	global_load_lds_dwordx4 v[162:163], off
	v_lshl_add_u64 v[162:163], v[232:233], 0, s[4:5]
	s_add_i32 m0, s21, 0x2000
	s_nop 0
	global_load_lds_dwordx4 v[162:163], off
	s_waitcnt lgkmcnt(0)
	s_setprio 1
	s_barrier


; #define PG8_STAGE(bufoff, gbase, voff) do { _Pragma("unroll") for (int _i = 0; _i < 2; ++_i) \
;         __builtin_amdgcn_global_load_lds((const unsigned*)((const char*)(gbase) + (voff)[_i]), (LAS unsigned*)(lds + (bufoff) + ldsw + _i * 8192), 16, 0, 0); } while (0)
; #define PG8_LDA(dst, b, h) do { _Pragma("unroll") for (int m = 0; m < 4; ++m) _Pragma("unroll") for (int k = 0; k < 2; ++k) dst[m][k] = *(const LAS bf16x8*)(lds + PG8_SA(b, h) + aoff + m * 2048 + k * 1024); } while (0)
; #define PG8_MMA(ai, bj, At, Bt) do { __builtin_amdgcn_s_setprio(1); _Pragma("unroll") for (int m = 0; m < 4; ++m) _Pragma("unroll") for (int n = 0; n < 2; ++n) _Pragma("unroll") for (int k = 0; k < 2; ++k) \
;         acc[ai][bj][m][n] = __builtin_amdgcn_mfma_f32_16x16x32_bf16(Bt[n][k], At[m][k], acc[ai][bj][m][n], 0, 0, 0); __builtin_amdgcn_s_setprio(0); } while (0)
; #define PG8_WAIT_L(n) asm volatile("s_waitcnt lgkmcnt(" #n ")" ::: "memory")
; #define PG8_BAR __builtin_amdgcn_s_barrier()
; #define PG8_SCHED __builtin_amdgcn_sched_barrier(0)
; template <class Epi>
; __device__ __forceinline__ void gemm_phase(LAS unsigned char* lds, const Gemm g, const StaticOrder& S, const Epi& E) {
;     ...
;             PG8_BAR; PG8_WAIT_L(0); PG8_MMA(0, 1, At, B1); PG8_BAR;
;             PG8_LDA(At, 1, 1); PG8_STAGE(PG8_SA(1, 0), a3, voffA);
;             PG8_BAR; PG8_WAIT_L(0); PG8_MMA(1, 0, At, B0); PG8_BAR; PG8_SCHED;
	v_mfma_f32_16x16x32_bf16 v[120:123], v[216:219], v[184:187], v[120:123]
	v_mfma_f32_16x16x32_bf16 v[112:115], v[224:227], v[184:187], v[112:115]
	v_mfma_f32_16x16x32_bf16 v[104:107], v[216:219], v[192:195], v[104:107]
	v_mfma_f32_16x16x32_bf16 v[96:99], v[224:227], v[192:195], v[96:99]
	v_mfma_f32_16x16x32_bf16 v[88:91], v[216:219], v[200:203], v[88:91]
	v_mfma_f32_16x16x32_bf16 v[80:83], v[224:227], v[200:203], v[80:83]
	v_mfma_f32_16x16x32_bf16 v[72:75], v[216:219], v[208:211], v[72:75]
	v_mfma_f32_16x16x32_bf16 v[64:67], v[224:227], v[208:211], v[64:67]
	v_mfma_f32_16x16x32_bf16 v[120:123], v[220:223], v[188:191], v[120:123]
	v_mfma_f32_16x16x32_bf16 v[112:115], v[228:231], v[188:191], v[112:115]
	v_mfma_f32_16x16x32_bf16 v[104:107], v[220:223], v[196:199], v[104:107]
	v_mfma_f32_16x16x32_bf16 v[96:99], v[228:231], v[196:199], v[96:99]
	v_mfma_f32_16x16x32_bf16 v[88:91], v[220:223], v[204:207], v[88:91]
	v_mfma_f32_16x16x32_bf16 v[80:83], v[228:231], v[204:207], v[80:83]
	v_mfma_f32_16x16x32_bf16 v[72:75], v[220:223], v[212:215], v[72:75]
	v_mfma_f32_16x16x32_bf16 v[64:67], v[228:231], v[212:215], v[64:67]
	s_setprio 0
	s_mov_b32 m0, s42
	v_lshl_add_u64 v[162:163], v[234:235], 0, s[4:5]
	s_barrier
	ds_read_b128 v[184:187], v150 offset:49152
	ds_read_b128 v[188:191], v150 offset:50176
	ds_read_b128 v[192:195], v150 offset:51200
	ds_read_b128 v[196:199], v150 offset:52224
	ds_read_b128 v[200:203], v150 offset:53248
	ds_read_b128 v[204:207], v150 offset:54272
	ds_read_b128 v[208:211], v150 offset:55296
	ds_read_b128 v[212:215], v150 offset:56320
	global_load_lds_dwordx4 v[162:163], off
	v_lshl_add_u64 v[162:163], v[236:237], 0, s[4:5]
	s_mov_b32 m0, s43
	s_nop 0
	global_load_lds_dwordx4 v[162:163], off
	s_waitcnt lgkmcnt(0)
	s_setprio 1
	s_barrier


; #define PG8_STAGE(bufoff, gbase, voff) do { _Pragma("unroll") for (int _i = 0; _i < 2; ++_i) \
;         __builtin_amdgcn_global_load_lds((const unsigned*)((const char*)(gbase) + (voff)[_i]), (LAS unsigned*)(lds + (bufoff) + ldsw + _i * 8192), 16, 0, 0); } while (0)
; #define PG8_MMA(ai, bj, At, Bt) do { __builtin_amdgcn_s_setprio(1); _Pragma("unroll") for (int m = 0; m < 4; ++m) _Pragma("unroll") for (int n = 0; n < 2; ++n) _Pragma("unroll") for (int k = 0; k < 2; ++k) \
;         acc[ai][bj][m][n] = __builtin_amdgcn_mfma_f32_16x16x32_bf16(Bt[n][k], At[m][k], acc[ai][bj][m][n], 0, 0, 0); __builtin_amdgcn_s_setprio(0); } while (0)
; #define PG8_WAIT_V(n) asm volatile("s_waitcnt vmcnt(" #n ")" ::: "memory")
; #define PG8_WAIT_L(n) asm volatile("s_waitcnt lgkmcnt(" #n ")" ::: "memory")
; #define PG8_BAR __builtin_amdgcn_s_barrier()
; #define PG8_SCHED __builtin_amdgcn_sched_barrier(0)
; template <class Epi>
; __device__ __forceinline__ void gemm_phase(LAS unsigned char* lds, const Gemm g, const StaticOrder& S, const Epi& E) {
;     ...
;             PG8_BAR; PG8_WAIT_L(0); PG8_MMA(1, 0, At, B0); PG8_BAR; PG8_SCHED;
;             PG8_STAGE(PG8_SB(1, 1), b3 + hstep, voffB);
;             PG8_WAIT_V(6); PG8_BAR; PG8_MMA(1, 1, At, B1); PG8_BAR;
	v_mfma_f32_16x16x32_bf16 v[60:63], v[166:169], v[184:187], v[60:63]
	v_mfma_f32_16x16x32_bf16 v[52:55], v[174:177], v[184:187], v[52:55]
	v_mfma_f32_16x16x32_bf16 v[44:47], v[166:169], v[192:195], v[44:47]
	v_mfma_f32_16x16x32_bf16 v[36:39], v[174:177], v[192:195], v[36:39]
	v_mfma_f32_16x16x32_bf16 v[28:31], v[166:169], v[200:203], v[28:31]
	v_mfma_f32_16x16x32_bf16 v[20:23], v[174:177], v[200:203], v[20:23]
	v_mfma_f32_16x16x32_bf16 v[12:15], v[166:169], v[208:211], v[12:15]
	v_mfma_f32_16x16x32_bf16 v[4:7], v[174:177], v[208:211], v[4:7]
	v_mfma_f32_16x16x32_bf16 v[60:63], v[170:173], v[188:191], v[60:63]
	v_mfma_f32_16x16x32_bf16 v[52:55], v[180:183], v[188:191], v[52:55]
	v_mfma_f32_16x16x32_bf16 v[44:47], v[170:173], v[196:199], v[44:47]
	v_mfma_f32_16x16x32_bf16 v[36:39], v[180:183], v[196:199], v[36:39]
	v_mfma_f32_16x16x32_bf16 v[28:31], v[170:173], v[204:207], v[28:31]
	v_mfma_f32_16x16x32_bf16 v[20:23], v[180:183], v[204:207], v[20:23]
	v_mfma_f32_16x16x32_bf16 v[12:15], v[170:173], v[212:215], v[12:15]
	v_mfma_f32_16x16x32_bf16 v[4:7], v[180:183], v[212:215], v[4:7]
	s_setprio 0
	s_barrier
	s_add_u32 s18, s18, 0x80080
	s_addc_u32 s19, s19, 0
	s_add_i32 s20, s20, s31
	v_lshl_add_u64 v[162:163], s[18:19], 0, v[132:133]
	s_mov_b32 m0, s20
	s_nop 0
	global_load_lds_dwordx4 v[162:163], off
	v_lshl_add_u64 v[162:163], s[18:19], 0, v[128:129]
	s_add_i32 m0, s20, 0x2000
	s_nop 0
	global_load_lds_dwordx4 v[162:163], off
	s_waitcnt vmcnt(6)
	s_setprio 1
	s_barrier

; __device__ __forceinline__ float sigmoidf_(float x) { return __builtin_amdgcn_rcpf(1.0f + fexp(-x)); }
; #define PG8_MMA(ai, bj, At, Bt) do { __builtin_amdgcn_s_setprio(1); _Pragma("unroll") for (int m = 0; m < 4; ++m) _Pragma("unroll") for (int n = 0; n < 2; ++n) _Pragma("unroll") for (int k = 0; k < 2; ++k) \
;         acc[ai][bj][m][n] = __builtin_amdgcn_mfma_f32_16x16x32_bf16(Bt[n][k], At[m][k], acc[ai][bj][m][n], 0, 0, 0); __builtin_amdgcn_s_setprio(0); } while (0)
; #define PG8_WAIT_V(n) asm volatile("s_waitcnt vmcnt(" #n ")" ::: "memory")
; #define PG8_BAR __builtin_amdgcn_s_barrier()
; template <class Epi>
; __device__ __forceinline__ void gemm_phase(LAS unsigned char* lds, const Gemm g, const StaticOrder& S, const Epi& E) {
;     ...
;             PG8_WAIT_V(6); PG8_BAR; PG8_MMA(1, 1, At, B1); PG8_BAR;
;         }
;     __device__ __forceinline__ void operator()(const f32x4 (&acc)[2][2][4][2], const Unit& u, int wr, int wc, int fr, int fq, const Pre& P) const {
;         const int row0 = ROW_X + u.pm * BM + wr * 64 + fr, col0 = u.pn * HALF + wc * 32 + 8 * fq;
; #pragma unroll
;         for (int ai = 0; ai < 2; ++ai)
; #pragma unroll
;             for (int m = 0; m < 4; ++m) { const int r = row0 + ai * HALF + m * 16; const float rs = __builtin_amdgcn_rsqf(P.rs[ai * 4 + m] * (1.0f / DM) + RMS_EPS);
;                 float y[8];
; #pragma unroll
;                 for (int n = 0; n < 2; ++n)
; #pragma unroll
;                     for (int j = 0; j < 4; ++j) { const float a = acc[ai][0][m][n][j] * rs, b = acc[ai][1][m][n][j] * rs; y[n * 4 + j] = a * b * sigmoidf_(a); }
;                 u32x4 w; w.x = cvtpk(y[0], y[1]); w.y = cvtpk(y[2], y[3]); w.z = cvtpk(y[4], y[5]); w.w = cvtpk(y[6], y[7]);
;                 *(u32x4*)(O + (size_t)r * FF + col0) = w; }
	v_mfma_f32_16x16x32_bf16 v[56:59], v[216:219], v[184:187], v[56:59]
	v_mfma_f32_16x16x32_bf16 v[48:51], v[224:227], v[184:187], v[48:51]
	v_mfma_f32_16x16x32_bf16 v[40:43], v[216:219], v[192:195], v[40:43]
	v_mfma_f32_16x16x32_bf16 v[32:35], v[224:227], v[192:195], v[32:35]
	v_mfma_f32_16x16x32_bf16 v[24:27], v[216:219], v[200:203], v[24:27]
	v_mfma_f32_16x16x32_bf16 v[16:19], v[224:227], v[200:203], v[16:19]
	v_mfma_f32_16x16x32_bf16 v[8:11], v[216:219], v[208:211], v[8:11]
	v_mfma_f32_16x16x32_bf16 v[0:3], v[224:227], v[208:211], v[0:3]
	v_mfma_f32_16x16x32_bf16 v[56:59], v[220:223], v[188:191], v[56:59]
	v_mfma_f32_16x16x32_bf16 v[48:51], v[228:231], v[188:191], v[48:51]
	v_mfma_f32_16x16x32_bf16 v[40:43], v[220:223], v[196:199], v[40:43]
	v_mfma_f32_16x16x32_bf16 v[32:35], v[228:231], v[196:199], v[32:35]
	v_mfma_f32_16x16x32_bf16 v[24:27], v[220:223], v[204:207], v[24:27]
	v_mfma_f32_16x16x32_bf16 v[16:19], v[228:231], v[204:207], v[16:19]
	v_mfma_f32_16x16x32_bf16 v[8:11], v[220:223], v[212:215], v[8:11]
	v_mfma_f32_16x16x32_bf16 v[0:3], v[228:231], v[212:215], v[0:3]
	s_setprio 0
	s_add_i32 s65, s65, 2
	s_add_u32 s16, s16, 0x100
	s_addc_u32 s17, s17, 0
	s_add_u32 s63, s63, 0x100
	s_addc_u32 s64, s64, 0
	s_cmp_gt_u32 s65, 29
	s_barrier
	s_cbranch_scc0 .LBB0_1306
	s_waitcnt vmcnt(0)
	v_fmamk_f32 v160, v160, 0x3a000000, v153
	v_rsq_f32_e32 v160, v160
	v_lshl_or_b32 v166, s15, 7, v148
	v_ashrrev_i32_e32 v167, 31, v166
	s_and_b64 vcc, vcc, exec
	v_pk_mul_f32 v[162:163], v[160:161], v[124:125] op_sel_hi:[0,1]
	v_mul_f32_e32 v124, 0xbfb8aa3b, v162
	v_mul_f32_e32 v125, 0xbfb8aa3b, v163
	v_exp_f32_e32 v161, v124
	v_exp_f32_e32 v125, v125
	v_lshl_add_u32 v124, s14, 8, v146
	v_add_f32_e32 v161, 1.0, v161
	v_add_f32_e32 v125, 1.0, v125
	v_rcp_f32_e32 v168, v161
	v_rcp_f32_e32 v169, v125
	v_pk_mul_f32 v[120:121], v[160:161], v[120:121] op_sel_hi:[0,1]
	v_pk_mul_f32 v[120:121], v[162:163], v[120:121]
	v_pk_mul_f32 v[126:127], v[160:161], v[126:127] op_sel_hi:[0,1]
	v_pk_mul_f32 v[120:121], v[168:169], v[120:121]
	v_mul_f32_e32 v125, 0xbfb8aa3b, v126
	v_cvt_pk_bf16_f32 v120, v120, v121
	v_mul_f32_e32 v121, 0xbfb8aa3b, v127
	v_exp_f32_e32 v125, v125
	v_exp_f32_e32 v121, v121
	v_pk_mul_f32 v[122:123], v[160:161], v[122:123] op_sel_hi:[0,1]
	v_pk_mul_f32 v[116:117], v[160:161], v[116:117] op_sel_hi:[0,1]
	v_add_f32_e32 v125, 1.0, v125
	v_add_f32_e32 v121, 1.0, v121
	v_rcp_f32_e32 v162, v125
	v_rcp_f32_e32 v163, v121
	v_pk_mul_f32 v[122:123], v[126:127], v[122:123]
	v_mul_f32_e32 v121, 0xbfb8aa3b, v116
	v_exp_f32_e32 v125, v121
	v_pk_mul_f32 v[122:123], v[162:163], v[122:123]
	v_pk_mul_f32 v[112:113], v[160:161], v[112:113] op_sel_hi:[0,1]
	v_cvt_pk_bf16_f32 v121, v122, v123
	v_mul_f32_e32 v123, 0xbfb8aa3b, v117
	v_exp_f32_e32 v123, v123
	v_add_f32_e32 v122, 1.0, v125
	v_pk_mul_f32 v[112:113], v[116:117], v[112:113]
	v_rcp_f32_e32 v122, v122
	v_add_f32_e32 v116, 1.0, v123
	v_rcp_f32_e32 v123, v116
	v_pk_mul_f32 v[116:117], v[160:161], v[118:119] op_sel_hi:[0,1]
	v_mul_f32_e32 v118, 0xbfb8aa3b, v116
	v_mul_f32_e32 v119, 0xbfb8aa3b, v117
	v_exp_f32_e32 v118, v118
	v_exp_f32_e32 v119, v119
	v_pk_mul_f32 v[112:113], v[122:123], v[112:113]
	v_add_f32_e32 v118, 1.0, v118
	v_cvt_pk_bf16_f32 v122, v112, v113
	v_pk_mul_f32 v[112:113], v[160:161], v[114:115] op_sel_hi:[0,1]
	v_fmamk_f32 v114, v159, 0x3a000000, v153
	v_pk_mul_f32 v[112:113], v[116:117], v[112:113]
	v_rsq_f32_e32 v116, v114
	v_add_f32_e32 v119, 1.0, v119
	v_rcp_f32_e32 v118, v118
	v_rcp_f32_e32 v119, v119
	v_pk_mul_f32 v[108:109], v[116:117], v[108:109] op_sel_hi:[0,1]
	v_mul_f32_e32 v117, 0xbfb8aa3b, v108
	v_exp_f32_e32 v117, v117
	v_mul_f32_e32 v125, 0xbfb8aa3b, v109
	v_pk_mul_f32 v[112:113], v[118:119], v[112:113]
	v_exp_f32_e32 v125, v125
	v_cvt_pk_bf16_f32 v123, v112, v113
	v_mov_b64_e32 v[112:113], s[0:1]
	v_mad_i64_i32 v[118:119], s[14:15], v124, s60, v[112:113]
	v_lshlrev_b64 v[114:115], 1, v[166:167]
	v_lshl_add_u64 v[118:119], v[118:119], 0, v[114:115]
	v_add_f32_e32 v117, 1.0, v117
	global_store_dwordx4 v[118:119], v[120:123], off
	v_rcp_f32_e32 v118, v117
	v_add_f32_e32 v117, 1.0, v125
	v_rcp_f32_e32 v119, v117
	v_or_b32_e32 v117, 16, v124
	v_pk_mul_f32 v[104:105], v[116:117], v[104:105] op_sel_hi:[0,1]
	v_pk_mul_f32 v[104:105], v[108:109], v[104:105]
	v_pk_mul_f32 v[108:109], v[116:117], v[110:111] op_sel_hi:[0,1]
	v_pk_mul_f32 v[104:105], v[118:119], v[104:105]
	v_mul_f32_e32 v110, 0xbfb8aa3b, v108
	v_cvt_pk_bf16_f32 v104, v104, v105
	v_mul_f32_e32 v105, 0xbfb8aa3b, v109
	v_exp_f32_e32 v110, v110
	v_exp_f32_e32 v105, v105
	v_pk_mul_f32 v[106:107], v[116:117], v[106:107] op_sel_hi:[0,1]
	v_pk_mul_f32 v[100:101], v[116:117], v[100:101] op_sel_hi:[0,1]
	v_add_f32_e32 v110, 1.0, v110
	v_add_f32_e32 v105, 1.0, v105
	v_rcp_f32_e32 v110, v110
	v_rcp_f32_e32 v111, v105
	v_pk_mul_f32 v[106:107], v[108:109], v[106:107]
	v_mul_f32_e32 v105, 0xbfb8aa3b, v100
	v_exp_f32_e32 v118, v105
	v_pk_mul_f32 v[106:107], v[110:111], v[106:107]
	v_pk_mul_f32 v[96:97], v[116:117], v[96:97] op_sel_hi:[0,1]
	v_cvt_pk_bf16_f32 v105, v106, v107
	v_mul_f32_e32 v107, 0xbfb8aa3b, v101
	v_exp_f32_e32 v107, v107
	v_pk_mul_f32 v[96:97], v[100:101], v[96:97]
	v_add_f32_e32 v106, 1.0, v118
	v_rcp_f32_e32 v106, v106
	v_add_f32_e32 v100, 1.0, v107
	v_rcp_f32_e32 v107, v100
	v_pk_mul_f32 v[100:101], v[116:117], v[102:103] op_sel_hi:[0,1]
	v_mul_f32_e32 v102, 0xbfb8aa3b, v100
	v_mul_f32_e32 v103, 0xbfb8aa3b, v101
	v_exp_f32_e32 v102, v102
	v_exp_f32_e32 v103, v103
	v_pk_mul_f32 v[96:97], v[106:107], v[96:97]
	v_add_f32_e32 v102, 1.0, v102
	v_add_f32_e32 v103, 1.0, v103
	v_rcp_f32_e32 v102, v102
	v_rcp_f32_e32 v103, v103
; __device__ __forceinline__ float sigmoidf_(float x) { return __builtin_amdgcn_rcpf(1.0f + fexp(-x)); }
;     __device__ __forceinline__ void operator()(const f32x4 (&acc)[2][2][4][2], const Unit& u, int wr, int wc, int fr, int fq, const Pre& P) const {
;         const int row0 = ROW_X + u.pm * BM + wr * 64 + fr, col0 = u.pn * HALF + wc * 32 + 8 * fq;
; #pragma unroll
;         for (int ai = 0; ai < 2; ++ai)
; #pragma unroll
;             for (int m = 0; m < 4; ++m) { const int r = row0 + ai * HALF + m * 16; const float rs = __builtin_amdgcn_rsqf(P.rs[ai * 4 + m] * (1.0f / DM) + RMS_EPS);
;                 float y[8];
; #pragma unroll
;                 for (int n = 0; n < 2; ++n)
; #pragma unroll
;                     for (int j = 0; j < 4; ++j) { const float a = acc[ai][0][m][n][j] * rs, b = acc[ai][1][m][n][j] * rs; y[n * 4 + j] = a * b * sigmoidf_(a); }
;                 u32x4 w; w.x = cvtpk(y[0], y[1]); w.y = cvtpk(y[2], y[3]); w.z = cvtpk(y[4], y[5]); w.w = cvtpk(y[6], y[7]);
;                 *(u32x4*)(O + (size_t)r * FF + col0) = w; }
	v_cvt_pk_bf16_f32 v106, v96, v97
	v_pk_mul_f32 v[96:97], v[116:117], v[98:99] op_sel_hi:[0,1]
	v_pk_mul_f32 v[96:97], v[100:101], v[96:97]
	v_mad_i64_i32 v[98:99], s[14:15], v117, s60, v[112:113]
	v_pk_mul_f32 v[96:97], v[102:103], v[96:97]
	v_lshl_add_u64 v[98:99], v[98:99], 0, v[114:115]
	v_cvt_pk_bf16_f32 v107, v96, v97
	v_fmamk_f32 v96, v158, 0x3a000000, v153
	v_rsq_f32_e32 v96, v96
	global_store_dwordx4 v[98:99], v[104:107], off
	v_pk_mul_f32 v[92:93], v[96:97], v[92:93] op_sel_hi:[0,1]
	v_mul_f32_e32 v97, 0xbfb8aa3b, v92
	v_exp_f32_e32 v97, v97
	v_mul_f32_e32 v100, 0xbfb8aa3b, v93
	v_exp_f32_e32 v100, v100
	v_add_f32_e32 v97, 1.0, v97
	v_rcp_f32_e32 v98, v97
	v_add_f32_e32 v97, 1.0, v100
	v_rcp_f32_e32 v99, v97
	v_or_b32_e32 v97, 32, v124
	v_pk_mul_f32 v[88:89], v[96:97], v[88:89] op_sel_hi:[0,1]
	v_pk_mul_f32 v[88:89], v[92:93], v[88:89]
	v_pk_mul_f32 v[92:93], v[96:97], v[94:95] op_sel_hi:[0,1]
	v_pk_mul_f32 v[88:89], v[98:99], v[88:89]
	v_mul_f32_e32 v94, 0xbfb8aa3b, v92
	v_cvt_pk_bf16_f32 v88, v88, v89
	v_mul_f32_e32 v89, 0xbfb8aa3b, v93
	v_exp_f32_e32 v94, v94
	v_exp_f32_e32 v89, v89
	v_pk_mul_f32 v[90:91], v[96:97], v[90:91] op_sel_hi:[0,1]
	v_pk_mul_f32 v[84:85], v[96:97], v[84:85] op_sel_hi:[0,1]
	v_add_f32_e32 v94, 1.0, v94
	v_add_f32_e32 v89, 1.0, v89
	v_rcp_f32_e32 v94, v94
	v_rcp_f32_e32 v95, v89
	v_pk_mul_f32 v[90:91], v[92:93], v[90:91]
	v_mul_f32_e32 v89, 0xbfb8aa3b, v84
	v_exp_f32_e32 v98, v89
	v_pk_mul_f32 v[90:91], v[94:95], v[90:91]
	v_pk_mul_f32 v[80:81], v[96:97], v[80:81] op_sel_hi:[0,1]
	v_cvt_pk_bf16_f32 v89, v90, v91
	v_mul_f32_e32 v91, 0xbfb8aa3b, v85
	v_exp_f32_e32 v91, v91
	v_pk_mul_f32 v[80:81], v[84:85], v[80:81]
	v_add_f32_e32 v90, 1.0, v98
	v_rcp_f32_e32 v90, v90
	v_add_f32_e32 v84, 1.0, v91
	v_rcp_f32_e32 v91, v84
	v_pk_mul_f32 v[84:85], v[96:97], v[86:87] op_sel_hi:[0,1]
	v_mul_f32_e32 v86, 0xbfb8aa3b, v84
	v_mul_f32_e32 v87, 0xbfb8aa3b, v85
	v_exp_f32_e32 v86, v86
	v_exp_f32_e32 v87, v87
	v_pk_mul_f32 v[80:81], v[90:91], v[80:81]
	v_add_f32_e32 v86, 1.0, v86
	v_add_f32_e32 v87, 1.0, v87
	v_rcp_f32_e32 v86, v86
	v_rcp_f32_e32 v87, v87
	v_cvt_pk_bf16_f32 v90, v80, v81
	v_pk_mul_f32 v[80:81], v[96:97], v[82:83] op_sel_hi:[0,1]
	v_pk_mul_f32 v[80:81], v[84:85], v[80:81]
	v_mad_i64_i32 v[82:83], s[14:15], v97, s60, v[112:113]
	v_pk_mul_f32 v[80:81], v[86:87], v[80:81]
	v_lshl_add_u64 v[82:83], v[82:83], 0, v[114:115]
	v_cvt_pk_bf16_f32 v91, v80, v81
	v_fmamk_f32 v80, v157, 0x3a000000, v153
	v_rsq_f32_e32 v80, v80
	global_store_dwordx4 v[82:83], v[88:91], off
	v_pk_mul_f32 v[76:77], v[80:81], v[76:77] op_sel_hi:[0,1]
	v_mul_f32_e32 v81, 0xbfb8aa3b, v76
	v_exp_f32_e32 v81, v81
	v_mul_f32_e32 v84, 0xbfb8aa3b, v77
	v_exp_f32_e32 v84, v84
	v_add_f32_e32 v81, 1.0, v81
	v_rcp_f32_e32 v82, v81
	v_add_f32_e32 v81, 1.0, v84
	v_rcp_f32_e32 v83, v81
	v_or_b32_e32 v81, 48, v124
	v_pk_mul_f32 v[72:73], v[80:81], v[72:73] op_sel_hi:[0,1]
	v_pk_mul_f32 v[72:73], v[76:77], v[72:73]
	v_pk_mul_f32 v[76:77], v[80:81], v[78:79] op_sel_hi:[0,1]
	v_pk_mul_f32 v[72:73], v[82:83], v[72:73]
	v_mul_f32_e32 v78, 0xbfb8aa3b, v76
	v_cvt_pk_bf16_f32 v72, v72, v73
	v_mul_f32_e32 v73, 0xbfb8aa3b, v77
	v_exp_f32_e32 v78, v78
	v_exp_f32_e32 v73, v73
	v_pk_mul_f32 v[74:75], v[80:81], v[74:75] op_sel_hi:[0,1]
	v_pk_mul_f32 v[68:69], v[80:81], v[68:69] op_sel_hi:[0,1]
	v_add_f32_e32 v78, 1.0, v78
	v_add_f32_e32 v73, 1.0, v73
	v_rcp_f32_e32 v78, v78
	v_rcp_f32_e32 v79, v73
	v_pk_mul_f32 v[74:75], v[76:77], v[74:75]
	v_mul_f32_e32 v73, 0xbfb8aa3b, v68
	v_exp_f32_e32 v82, v73
	v_pk_mul_f32 v[74:75], v[78:79], v[74:75]
	v_pk_mul_f32 v[64:65], v[80:81], v[64:65] op_sel_hi:[0,1]
	v_cvt_pk_bf16_f32 v73, v74, v75
	v_mul_f32_e32 v75, 0xbfb8aa3b, v69
	v_exp_f32_e32 v75, v75
	v_pk_mul_f32 v[64:65], v[68:69], v[64:65]
	v_add_f32_e32 v74, 1.0, v82
	v_rcp_f32_e32 v74, v74
	v_add_f32_e32 v68, 1.0, v75
	v_rcp_f32_e32 v75, v68
	v_pk_mul_f32 v[68:69], v[80:81], v[70:71] op_sel_hi:[0,1]
	v_mul_f32_e32 v70, 0xbfb8aa3b, v68
	v_mul_f32_e32 v71, 0xbfb8aa3b, v69
	v_exp_f32_e32 v70, v70
	v_exp_f32_e32 v71, v71
	v_pk_mul_f32 v[64:65], v[74:75], v[64:65]
	v_add_f32_e32 v70, 1.0, v70
	v_add_f32_e32 v71, 1.0, v71
	v_rcp_f32_e32 v70, v70
	v_rcp_f32_e32 v71, v71
	v_cvt_pk_bf16_f32 v74, v64, v65
	v_pk_mul_f32 v[64:65], v[80:81], v[66:67] op_sel_hi:[0,1]
	v_pk_mul_f32 v[64:65], v[68:69], v[64:65]
	v_mad_i64_i32 v[66:67], s[14:15], v81, s60, v[112:113]
	v_pk_mul_f32 v[64:65], v[70:71], v[64:65]
	v_lshl_add_u64 v[66:67], v[66:67], 0, v[114:115]
	v_cvt_pk_bf16_f32 v75, v64, v65
	v_fmamk_f32 v64, v156, 0x3a000000, v153
	v_rsq_f32_e32 v64, v64
	global_store_dwordx4 v[66:67], v[72:75], off
	v_pk_mul_f32 v[60:61], v[64:65], v[60:61] op_sel_hi:[0,1]
	v_mul_f32_e32 v65, 0xbfb8aa3b, v60
	v_exp_f32_e32 v65, v65
	v_mul_f32_e32 v68, 0xbfb8aa3b, v61
	v_exp_f32_e32 v68, v68
	v_add_f32_e32 v65, 1.0, v65
	v_rcp_f32_e32 v66, v65
	v_add_f32_e32 v65, 1.0, v68
	v_rcp_f32_e32 v67, v65
	v_add_u32_e32 v65, 0x80, v124
	v_pk_mul_f32 v[56:57], v[64:65], v[56:57] op_sel_hi:[0,1]
	v_pk_mul_f32 v[56:57], v[60:61], v[56:57]
	v_pk_mul_f32 v[60:61], v[64:65], v[62:63] op_sel_hi:[0,1]
	v_pk_mul_f32 v[56:57], v[66:67], v[56:57]
	v_mul_f32_e32 v62, 0xbfb8aa3b, v60
	v_cvt_pk_bf16_f32 v56, v56, v57
	v_mul_f32_e32 v57, 0xbfb8aa3b, v61
	v_exp_f32_e32 v62, v62
	v_exp_f32_e32 v57, v57
	v_pk_mul_f32 v[58:59], v[64:65], v[58:59] op_sel_hi:[0,1]
	v_pk_mul_f32 v[52:53], v[64:65], v[52:53] op_sel_hi:[0,1]
	v_add_f32_e32 v62, 1.0, v62
	v_add_f32_e32 v57, 1.0, v57
	v_rcp_f32_e32 v62, v62
	v_rcp_f32_e32 v63, v57
	v_pk_mul_f32 v[58:59], v[60:61], v[58:59]
	v_mul_f32_e32 v57, 0xbfb8aa3b, v52
	v_exp_f32_e32 v66, v57
; __device__ __forceinline__ float sigmoidf_(float x) { return __builtin_amdgcn_rcpf(1.0f + fexp(-x)); }
;     __device__ __forceinline__ void operator()(const f32x4 (&acc)[2][2][4][2], const Unit& u, int wr, int wc, int fr, int fq, const Pre& P) const {
;         const int row0 = ROW_X + u.pm * BM + wr * 64 + fr, col0 = u.pn * HALF + wc * 32 + 8 * fq;
; #pragma unroll
;         for (int ai = 0; ai < 2; ++ai)
; #pragma unroll
;             for (int m = 0; m < 4; ++m) { const int r = row0 + ai * HALF + m * 16; const float rs = __builtin_amdgcn_rsqf(P.rs[ai * 4 + m] * (1.0f / DM) + RMS_EPS);
;                 float y[8];
; #pragma unroll
;                 for (int n = 0; n < 2; ++n)
; #pragma unroll
;                     for (int j = 0; j < 4; ++j) { const float a = acc[ai][0][m][n][j] * rs, b = acc[ai][1][m][n][j] * rs; y[n * 4 + j] = a * b * sigmoidf_(a); }
;                 u32x4 w; w.x = cvtpk(y[0], y[1]); w.y = cvtpk(y[2], y[3]); w.z = cvtpk(y[4], y[5]); w.w = cvtpk(y[6], y[7]);
;                 *(u32x4*)(O + (size_t)r * FF + col0) = w; }
	v_pk_mul_f32 v[58:59], v[62:63], v[58:59]
	v_pk_mul_f32 v[48:49], v[64:65], v[48:49] op_sel_hi:[0,1]
	v_cvt_pk_bf16_f32 v57, v58, v59
	v_mul_f32_e32 v59, 0xbfb8aa3b, v53
	v_exp_f32_e32 v59, v59
	v_pk_mul_f32 v[48:49], v[52:53], v[48:49]
	v_add_f32_e32 v58, 1.0, v66
	v_rcp_f32_e32 v58, v58
	v_add_f32_e32 v52, 1.0, v59
	v_rcp_f32_e32 v59, v52
	v_pk_mul_f32 v[52:53], v[64:65], v[54:55] op_sel_hi:[0,1]
	v_mul_f32_e32 v54, 0xbfb8aa3b, v52
	v_mul_f32_e32 v55, 0xbfb8aa3b, v53
	v_exp_f32_e32 v54, v54
	v_exp_f32_e32 v55, v55
	v_pk_mul_f32 v[48:49], v[58:59], v[48:49]
	v_add_f32_e32 v54, 1.0, v54
	v_add_f32_e32 v55, 1.0, v55
	v_rcp_f32_e32 v54, v54
	v_rcp_f32_e32 v55, v55
	v_cvt_pk_bf16_f32 v58, v48, v49
	v_pk_mul_f32 v[48:49], v[64:65], v[50:51] op_sel_hi:[0,1]
	v_pk_mul_f32 v[48:49], v[52:53], v[48:49]
	v_mad_i64_i32 v[50:51], s[14:15], v65, s60, v[112:113]
	v_pk_mul_f32 v[48:49], v[54:55], v[48:49]
	v_lshl_add_u64 v[50:51], v[50:51], 0, v[114:115]
	v_cvt_pk_bf16_f32 v59, v48, v49
	v_fmamk_f32 v48, v155, 0x3a000000, v153
	v_rsq_f32_e32 v48, v48
	global_store_dwordx4 v[50:51], v[56:59], off
	v_pk_mul_f32 v[44:45], v[48:49], v[44:45] op_sel_hi:[0,1]
	v_mul_f32_e32 v49, 0xbfb8aa3b, v44
	v_exp_f32_e32 v49, v49
	v_mul_f32_e32 v52, 0xbfb8aa3b, v45
	v_exp_f32_e32 v52, v52
	v_add_f32_e32 v49, 1.0, v49
	v_rcp_f32_e32 v50, v49
	v_add_f32_e32 v49, 1.0, v52
	v_rcp_f32_e32 v51, v49
	v_add_u32_e32 v49, 0x90, v124
	v_pk_mul_f32 v[40:41], v[48:49], v[40:41] op_sel_hi:[0,1]
	v_pk_mul_f32 v[40:41], v[44:45], v[40:41]
	v_pk_mul_f32 v[44:45], v[48:49], v[46:47] op_sel_hi:[0,1]
	v_pk_mul_f32 v[40:41], v[50:51], v[40:41]
	v_mul_f32_e32 v46, 0xbfb8aa3b, v44
	v_cvt_pk_bf16_f32 v40, v40, v41
	v_mul_f32_e32 v41, 0xbfb8aa3b, v45
	v_exp_f32_e32 v46, v46
	v_exp_f32_e32 v41, v41
	v_pk_mul_f32 v[42:43], v[48:49], v[42:43] op_sel_hi:[0,1]
	v_pk_mul_f32 v[36:37], v[48:49], v[36:37] op_sel_hi:[0,1]
	v_add_f32_e32 v46, 1.0, v46
	v_add_f32_e32 v41, 1.0, v41
	v_rcp_f32_e32 v46, v46
	v_rcp_f32_e32 v47, v41
	v_pk_mul_f32 v[42:43], v[44:45], v[42:43]
	v_mul_f32_e32 v41, 0xbfb8aa3b, v36
	v_exp_f32_e32 v50, v41
	v_pk_mul_f32 v[42:43], v[46:47], v[42:43]
	v_pk_mul_f32 v[32:33], v[48:49], v[32:33] op_sel_hi:[0,1]
	v_cvt_pk_bf16_f32 v41, v42, v43
	v_mul_f32_e32 v43, 0xbfb8aa3b, v37
	v_exp_f32_e32 v43, v43
	v_pk_mul_f32 v[32:33], v[36:37], v[32:33]
	v_add_f32_e32 v42, 1.0, v50
	v_rcp_f32_e32 v42, v42
	v_add_f32_e32 v36, 1.0, v43
	v_rcp_f32_e32 v43, v36
	v_pk_mul_f32 v[36:37], v[48:49], v[38:39] op_sel_hi:[0,1]
	v_mul_f32_e32 v38, 0xbfb8aa3b, v36
	v_mul_f32_e32 v39, 0xbfb8aa3b, v37
	v_exp_f32_e32 v38, v38
	v_exp_f32_e32 v39, v39
	v_pk_mul_f32 v[32:33], v[42:43], v[32:33]
	v_add_f32_e32 v38, 1.0, v38
	v_add_f32_e32 v39, 1.0, v39
	v_rcp_f32_e32 v38, v38
	v_rcp_f32_e32 v39, v39
	v_cvt_pk_bf16_f32 v42, v32, v33
	v_pk_mul_f32 v[32:33], v[48:49], v[34:35] op_sel_hi:[0,1]
	v_pk_mul_f32 v[32:33], v[36:37], v[32:33]
	v_mad_i64_i32 v[34:35], s[14:15], v49, s60, v[112:113]
	v_pk_mul_f32 v[32:33], v[38:39], v[32:33]
	v_lshl_add_u64 v[34:35], v[34:35], 0, v[114:115]
	v_cvt_pk_bf16_f32 v43, v32, v33
	v_fmamk_f32 v32, v154, 0x3a000000, v153
	v_rsq_f32_e32 v32, v32
	global_store_dwordx4 v[34:35], v[40:43], off
	v_pk_mul_f32 v[28:29], v[32:33], v[28:29] op_sel_hi:[0,1]
	v_mul_f32_e32 v33, 0xbfb8aa3b, v28
	v_exp_f32_e32 v33, v33
	v_mul_f32_e32 v36, 0xbfb8aa3b, v29
	v_exp_f32_e32 v36, v36
	v_add_f32_e32 v33, 1.0, v33
	v_rcp_f32_e32 v34, v33
	v_add_f32_e32 v33, 1.0, v36
	v_rcp_f32_e32 v35, v33
	v_add_u32_e32 v33, 0xa0, v124
	v_pk_mul_f32 v[24:25], v[32:33], v[24:25] op_sel_hi:[0,1]
	v_pk_mul_f32 v[24:25], v[28:29], v[24:25]
	v_pk_mul_f32 v[28:29], v[32:33], v[30:31] op_sel_hi:[0,1]
	v_pk_mul_f32 v[24:25], v[34:35], v[24:25]
	v_mul_f32_e32 v30, 0xbfb8aa3b, v28
	v_cvt_pk_bf16_f32 v24, v24, v25
	v_mul_f32_e32 v25, 0xbfb8aa3b, v29
	v_exp_f32_e32 v30, v30
	v_exp_f32_e32 v25, v25
	v_pk_mul_f32 v[26:27], v[32:33], v[26:27] op_sel_hi:[0,1]
	v_pk_mul_f32 v[20:21], v[32:33], v[20:21] op_sel_hi:[0,1]
	v_add_f32_e32 v30, 1.0, v30
	v_add_f32_e32 v25, 1.0, v25
	v_rcp_f32_e32 v30, v30
	v_rcp_f32_e32 v31, v25
; __device__ __forceinline__ float sigmoidf_(float x) { return __builtin_amdgcn_rcpf(1.0f + fexp(-x)); }
; __device__ __forceinline__ PreRs load_rs(const float* ssq, int pm, int wr, int fr) { PreRs p;
; #pragma unroll
;     for (int ai = 0; ai < 2; ++ai)
; #pragma unroll
;         for (int m = 0; m < 4; ++m) p.rs[ai * 4 + m] = ssq[ROW_X + pm * BM + ai * HALF + wr * 64 + m * 16 + fr];
;     return p; }
;     __device__ __forceinline__ void operator()(const f32x4 (&acc)[2][2][4][2], const Unit& u, int wr, int wc, int fr, int fq, const Pre& P) const {
;     ...
;             for (int m = 0; m < 4; ++m) { const int r = row0 + ai * HALF + m * 16; const float rs = __builtin_amdgcn_rsqf(P.rs[ai * 4 + m] * (1.0f / DM) + RMS_EPS);
;                 float y[8];
; #pragma unroll
;                 for (int n = 0; n < 2; ++n)
; #pragma unroll
;                     for (int j = 0; j < 4; ++j) { const float a = acc[ai][0][m][n][j] * rs, b = acc[ai][1][m][n][j] * rs; y[n * 4 + j] = a * b * sigmoidf_(a); }
;                 u32x4 w; w.x = cvtpk(y[0], y[1]); w.y = cvtpk(y[2], y[3]); w.z = cvtpk(y[4], y[5]); w.w = cvtpk(y[6], y[7]);
;                 *(u32x4*)(O + (size_t)r * FF + col0) = w; }
	v_pk_mul_f32 v[26:27], v[28:29], v[26:27]
	v_mul_f32_e32 v25, 0xbfb8aa3b, v20
	v_exp_f32_e32 v34, v25
	v_pk_mul_f32 v[26:27], v[30:31], v[26:27]
	v_pk_mul_f32 v[16:17], v[32:33], v[16:17] op_sel_hi:[0,1]
	v_cvt_pk_bf16_f32 v25, v26, v27
	v_mul_f32_e32 v27, 0xbfb8aa3b, v21
	v_exp_f32_e32 v27, v27
	v_pk_mul_f32 v[16:17], v[20:21], v[16:17]
	v_add_f32_e32 v26, 1.0, v34
	v_rcp_f32_e32 v26, v26
	v_add_f32_e32 v20, 1.0, v27
	v_rcp_f32_e32 v27, v20
	v_pk_mul_f32 v[20:21], v[32:33], v[22:23] op_sel_hi:[0,1]
	v_mul_f32_e32 v22, 0xbfb8aa3b, v20
	v_mul_f32_e32 v23, 0xbfb8aa3b, v21
	v_exp_f32_e32 v22, v22
	v_exp_f32_e32 v23, v23
	v_pk_mul_f32 v[16:17], v[26:27], v[16:17]
	v_add_f32_e32 v22, 1.0, v22
	v_add_f32_e32 v23, 1.0, v23
	v_rcp_f32_e32 v22, v22
	v_rcp_f32_e32 v23, v23
	v_cvt_pk_bf16_f32 v26, v16, v17
	v_pk_mul_f32 v[16:17], v[32:33], v[18:19] op_sel_hi:[0,1]
	v_pk_mul_f32 v[16:17], v[20:21], v[16:17]
	v_mad_i64_i32 v[18:19], s[14:15], v33, s60, v[112:113]
	v_pk_mul_f32 v[16:17], v[22:23], v[16:17]
	v_lshl_add_u64 v[18:19], v[18:19], 0, v[114:115]
	v_cvt_pk_bf16_f32 v27, v16, v17
	v_fmamk_f32 v16, v151, 0x3a000000, v153
	v_rsq_f32_e32 v16, v16
	global_store_dwordx4 v[18:19], v[24:27], off
	v_pk_mul_f32 v[12:13], v[16:17], v[12:13] op_sel_hi:[0,1]
	v_mul_f32_e32 v17, 0xbfb8aa3b, v12
	v_exp_f32_e32 v17, v17
	v_mul_f32_e32 v20, 0xbfb8aa3b, v13
	v_exp_f32_e32 v20, v20
	v_add_f32_e32 v17, 1.0, v17
	v_rcp_f32_e32 v18, v17
	v_add_f32_e32 v17, 1.0, v20
	v_rcp_f32_e32 v19, v17
	v_add_u32_e32 v17, 0xb0, v124
	v_pk_mul_f32 v[8:9], v[16:17], v[8:9] op_sel_hi:[0,1]
	v_pk_mul_f32 v[8:9], v[12:13], v[8:9]
	v_pk_mul_f32 v[12:13], v[16:17], v[14:15] op_sel_hi:[0,1]
	v_pk_mul_f32 v[8:9], v[18:19], v[8:9]
	v_mul_f32_e32 v14, 0xbfb8aa3b, v12
	v_cvt_pk_bf16_f32 v8, v8, v9
	v_mul_f32_e32 v9, 0xbfb8aa3b, v13
	v_exp_f32_e32 v14, v14
	v_exp_f32_e32 v9, v9
	v_pk_mul_f32 v[10:11], v[16:17], v[10:11] op_sel_hi:[0,1]
	v_pk_mul_f32 v[4:5], v[16:17], v[4:5] op_sel_hi:[0,1]
	v_add_f32_e32 v14, 1.0, v14
	v_add_f32_e32 v9, 1.0, v9
	v_rcp_f32_e32 v14, v14
	v_rcp_f32_e32 v15, v9
	v_pk_mul_f32 v[10:11], v[12:13], v[10:11]
	v_mul_f32_e32 v9, 0xbfb8aa3b, v4
	v_exp_f32_e32 v18, v9
	v_pk_mul_f32 v[10:11], v[14:15], v[10:11]
	v_pk_mul_f32 v[0:1], v[16:17], v[0:1] op_sel_hi:[0,1]
	v_cvt_pk_bf16_f32 v9, v10, v11
	v_mul_f32_e32 v11, 0xbfb8aa3b, v5
	v_exp_f32_e32 v11, v11
	v_pk_mul_f32 v[0:1], v[4:5], v[0:1]
	v_add_f32_e32 v10, 1.0, v18
	v_rcp_f32_e32 v10, v10
	v_add_f32_e32 v4, 1.0, v11
	v_rcp_f32_e32 v11, v4
	v_pk_mul_f32 v[4:5], v[16:17], v[6:7] op_sel_hi:[0,1]
	v_mul_f32_e32 v6, 0xbfb8aa3b, v4
	v_mul_f32_e32 v7, 0xbfb8aa3b, v5
	v_exp_f32_e32 v6, v6
	v_exp_f32_e32 v7, v7
	v_pk_mul_f32 v[0:1], v[10:11], v[0:1]
	v_add_f32_e32 v6, 1.0, v6
	v_add_f32_e32 v7, 1.0, v7
	v_rcp_f32_e32 v6, v6
	v_rcp_f32_e32 v7, v7
	v_cvt_pk_bf16_f32 v10, v0, v1
	v_pk_mul_f32 v[0:1], v[16:17], v[2:3] op_sel_hi:[0,1]
	v_pk_mul_f32 v[0:1], v[4:5], v[0:1]
	s_nop 0
	v_pk_mul_f32 v[0:1], v[6:7], v[0:1]
	s_nop 0
	v_cvt_pk_bf16_f32 v11, v0, v1
	v_mad_i64_i32 v[0:1], s[14:15], v17, s60, v[112:113]
	v_lshl_add_u64 v[0:1], v[0:1], 0, v[114:115]
	s_mov_b64 s[14:15], -1
	global_store_dwordx4 v[0:1], v[8:11], off
	s_cbranch_vccz .LBB0_1302
	v_lshl_add_u32 v0, s8, 8, v146
	v_ashrrev_i32_e32 v1, 31, v0
	v_lshl_add_u64 v[2:3], v[0:1], 2, s[2:3]
	v_add_u32_e32 v4, 0x80, v0
	v_add_u32_e32 v6, 0x90, v0
	v_add_u32_e32 v8, 0xa0, v0
	v_add_u32_e32 v0, 0xb0, v0
	v_ashrrev_i32_e32 v5, 31, v4
	v_ashrrev_i32_e32 v7, 31, v6
	v_ashrrev_i32_e32 v9, 31, v8
	v_ashrrev_i32_e32 v1, 31, v0
	v_lshl_add_u64 v[4:5], v[4:5], 2, s[2:3]
	v_lshl_add_u64 v[6:7], v[6:7], 2, s[2:3]
	v_lshl_add_u64 v[8:9], v[8:9], 2, s[2:3]
	v_lshl_add_u64 v[0:1], v[0:1], 2, s[2:3]
	global_load_dword v160, v[2:3], off
	global_load_dword v159, v[2:3], off offset:64
	global_load_dword v158, v[2:3], off offset:128
	global_load_dword v157, v[2:3], off offset:192
	global_load_dword v156, v[4:5], off
	global_load_dword v155, v[6:7], off
	global_load_dword v154, v[8:9], off
	global_load_dword v151, v[0:1], off
	s_mov_b64 s[14:15], 0
	s_branch .LBB0_1302

; #define PG8_STAGE(bufoff, gbase, voff) do { _Pragma("unroll") for (int _i = 0; _i < 2; ++_i) \
;         __builtin_amdgcn_global_load_lds((const unsigned*)((const char*)(gbase) + (voff)[_i]), (LAS unsigned*)(lds + (bufoff) + ldsw + _i * 8192), 16, 0, 0); } while (0)
; #define PG8_LDA(dst, b, h) do { _Pragma("unroll") for (int m = 0; m < 4; ++m) _Pragma("unroll") for (int k = 0; k < 2; ++k) dst[m][k] = *(const LAS bf16x8*)(lds + PG8_SA(b, h) + aoff + m * 2048 + k * 1024); } while (0)
; #define PG8_LDB(dst, b, h) do { _Pragma("unroll") for (int n = 0; n < 2; ++n) _Pragma("unroll") for (int k = 0; k < 2; ++k) dst[n][k] = *(const LAS bf16x8*)(lds + PG8_SB(b, h) + boff + n * 2048 + k * 1024); } while (0)
; #define PG8_MMA(ai, bj, At, Bt) do { __builtin_amdgcn_s_setprio(1); _Pragma("unroll") for (int m = 0; m < 4; ++m) _Pragma("unroll") for (int n = 0; n < 2; ++n) _Pragma("unroll") for (int k = 0; k < 2; ++k) \
;         acc[ai][bj][m][n] = __builtin_amdgcn_mfma_f32_16x16x32_bf16(Bt[n][k], At[m][k], acc[ai][bj][m][n], 0, 0, 0); __builtin_amdgcn_s_setprio(0); } while (0)
; #define PG8_WAIT_L(n) asm volatile("s_waitcnt lgkmcnt(" #n ")" ::: "memory")
; #define PG8_BAR __builtin_amdgcn_s_barrier()
; #define PG8_SCHED __builtin_amdgcn_sched_barrier(0)
; template <class Epi>
; __device__ __forceinline__ void gemm_phase(LAS unsigned char* lds, const Gemm g, const StaticOrder& S, const Epi& E) {
;     ...
;             const bool last = (t == nt - 2);
;             const char* a1 = cA + (size_t)(t + 1) * kstep;
;             const char* a2 = last ? nA : cA + (size_t)(t + 2) * kstep; const char* b2 = last ? nB : cB + (size_t)(t + 2) * kstep;
;             const char* a3 = a2 + kstep; const char* b3 = b2 + kstep;
;             PG8_LDB(B0, 0, 0); PG8_SCHED; PG8_LDA(At, 0, 0); PG8_STAGE(PG8_SA(1, 1), a1 + hstep, voffA);
;             PG8_WAIT_L(8); PG8_BAR; PG8_WAIT_L(0); PG8_MMA(0, 0, At, B0); PG8_BAR; PG8_SCHED;
.LBB0_1411:
	ds_read_b128 v[128:131], v162
	ds_read_b128 v[132:135], v162 offset:1024
	ds_read_b128 v[154:157], v162 offset:2048
	ds_read_b128 v[168:171], v162 offset:3072
	s_add_u32 s16, s14, 0xffea8080
	s_addc_u32 s17, s15, -1
	s_cmpk_eq_i32 s63, 0x52
	s_cselect_b32 s19, s1, s17
	s_cselect_b32 s18, s0, s16
	s_cselect_b32 s17, s7, s62
	s_cselect_b32 s16, s6, s61
	v_lshl_add_u64 v[158:159], s[14:15], 0, v[146:147]
	s_add_i32 m0, s30, 0xc000
	ds_read_b128 v[172:175], v163
	ds_read_b128 v[180:183], v163 offset:1024
	ds_read_b128 v[184:187], v163 offset:2048
	ds_read_b128 v[188:191], v163 offset:3072
	ds_read_b128 v[192:195], v163 offset:4096
	ds_read_b128 v[196:199], v163 offset:5120
	ds_read_b128 v[200:203], v163 offset:6144
	ds_read_b128 v[204:207], v163 offset:7168
	global_load_lds_dwordx4 v[158:159], off
	v_lshl_add_u64 v[158:159], s[14:15], 0, v[148:149]
	s_add_i32 m0, s30, 0xe000
	s_nop 0
	global_load_lds_dwordx4 v[158:159], off
	s_waitcnt lgkmcnt(8)
	s_setprio 1
	s_barrier
	s_waitcnt lgkmcnt(0)


; #define PG8_STAGE(bufoff, gbase, voff) do { _Pragma("unroll") for (int _i = 0; _i < 2; ++_i) \
;         __builtin_amdgcn_global_load_lds((const unsigned*)((const char*)(gbase) + (voff)[_i]), (LAS unsigned*)(lds + (bufoff) + ldsw + _i * 8192), 16, 0, 0); } while (0)
; #define PG8_LDB(dst, b, h) do { _Pragma("unroll") for (int n = 0; n < 2; ++n) _Pragma("unroll") for (int k = 0; k < 2; ++k) dst[n][k] = *(const LAS bf16x8*)(lds + PG8_SB(b, h) + boff + n * 2048 + k * 1024); } while (0)
; #define PG8_MMA(ai, bj, At, Bt) do { __builtin_amdgcn_s_setprio(1); _Pragma("unroll") for (int m = 0; m < 4; ++m) _Pragma("unroll") for (int n = 0; n < 2; ++n) _Pragma("unroll") for (int k = 0; k < 2; ++k) \
;         acc[ai][bj][m][n] = __builtin_amdgcn_mfma_f32_16x16x32_bf16(Bt[n][k], At[m][k], acc[ai][bj][m][n], 0, 0, 0); __builtin_amdgcn_s_setprio(0); } while (0)
; #define PG8_WAIT_L(n) asm volatile("s_waitcnt lgkmcnt(" #n ")" ::: "memory")
; #define PG8_BAR __builtin_amdgcn_s_barrier()
; #define PG8_SCHED __builtin_amdgcn_sched_barrier(0)
; template <class Epi>
; __device__ __forceinline__ void gemm_phase(LAS unsigned char* lds, const Gemm g, const StaticOrder& S, const Epi& E) {
;     ...
;             PG8_WAIT_L(8); PG8_BAR; PG8_WAIT_L(0); PG8_MMA(0, 0, At, B0); PG8_BAR; PG8_SCHED;
;             PG8_LDB(B1, 0, 1); PG8_STAGE(PG8_SB(0, 0), b2, voffB);
;             PG8_BAR; PG8_WAIT_L(0); PG8_MMA(0, 1, At, B1); PG8_BAR;
	v_mfma_f32_16x16x32_bf16 v[124:127], v[128:131], v[172:175], v[124:127]
	v_mfma_f32_16x16x32_bf16 v[120:123], v[154:157], v[172:175], v[120:123]
	v_mfma_f32_16x16x32_bf16 v[108:111], v[128:131], v[184:187], v[108:111]
	v_mfma_f32_16x16x32_bf16 v[104:107], v[154:157], v[184:187], v[104:107]
	v_mfma_f32_16x16x32_bf16 v[92:95], v[128:131], v[192:195], v[92:95]
	v_mfma_f32_16x16x32_bf16 v[88:91], v[154:157], v[192:195], v[88:91]
	v_mfma_f32_16x16x32_bf16 v[76:79], v[128:131], v[200:203], v[76:79]
	v_mfma_f32_16x16x32_bf16 v[72:75], v[154:157], v[200:203], v[72:75]
	v_mfma_f32_16x16x32_bf16 v[124:127], v[132:135], v[180:183], v[124:127]
	v_mfma_f32_16x16x32_bf16 v[120:123], v[168:171], v[180:183], v[120:123]
	v_mfma_f32_16x16x32_bf16 v[108:111], v[132:135], v[188:191], v[108:111]
	v_mfma_f32_16x16x32_bf16 v[104:107], v[168:171], v[188:191], v[104:107]
	v_mfma_f32_16x16x32_bf16 v[92:95], v[132:135], v[196:199], v[92:95]
	v_mfma_f32_16x16x32_bf16 v[88:91], v[168:171], v[196:199], v[88:91]
	v_mfma_f32_16x16x32_bf16 v[76:79], v[132:135], v[204:207], v[76:79]
	v_mfma_f32_16x16x32_bf16 v[72:75], v[168:171], v[204:207], v[72:75]
	s_setprio 0
	s_barrier
	s_add_i32 s64, s43, s21
	v_lshl_add_u64 v[158:159], s[16:17], 0, v[140:141]
	s_mov_b32 m0, s64
	ds_read_b128 v[208:211], v165
	ds_read_b128 v[212:215], v165 offset:1024
	ds_read_b128 v[216:219], v165 offset:2048
	ds_read_b128 v[220:223], v165 offset:3072
	global_load_lds_dwordx4 v[158:159], off
	v_lshl_add_u64 v[176:177], s[16:17], 0, v[144:145]
	s_add_i32 m0, s64, 0x2000
	s_nop 0
	global_load_lds_dwordx4 v[176:177], off
	s_waitcnt lgkmcnt(0)
	s_setprio 1
	s_barrier


; #define PG8_STAGE(bufoff, gbase, voff) do { _Pragma("unroll") for (int _i = 0; _i < 2; ++_i) \
;         __builtin_amdgcn_global_load_lds((const unsigned*)((const char*)(gbase) + (voff)[_i]), (LAS unsigned*)(lds + (bufoff) + ldsw + _i * 8192), 16, 0, 0); } while (0)
; #define PG8_LDA(dst, b, h) do { _Pragma("unroll") for (int m = 0; m < 4; ++m) _Pragma("unroll") for (int k = 0; k < 2; ++k) dst[m][k] = *(const LAS bf16x8*)(lds + PG8_SA(b, h) + aoff + m * 2048 + k * 1024); } while (0)
; #define PG8_MMA(ai, bj, At, Bt) do { __builtin_amdgcn_s_setprio(1); _Pragma("unroll") for (int m = 0; m < 4; ++m) _Pragma("unroll") for (int n = 0; n < 2; ++n) _Pragma("unroll") for (int k = 0; k < 2; ++k) \
;         acc[ai][bj][m][n] = __builtin_amdgcn_mfma_f32_16x16x32_bf16(Bt[n][k], At[m][k], acc[ai][bj][m][n], 0, 0, 0); __builtin_amdgcn_s_setprio(0); } while (0)
; #define PG8_WAIT_L(n) asm volatile("s_waitcnt lgkmcnt(" #n ")" ::: "memory")
; #define PG8_BAR __builtin_amdgcn_s_barrier()
; #define PG8_SCHED __builtin_amdgcn_sched_barrier(0)
; template <class Epi>
; __device__ __forceinline__ void gemm_phase(LAS unsigned char* lds, const Gemm g, const StaticOrder& S, const Epi& E) {
;     ...
;             PG8_BAR; PG8_WAIT_L(0); PG8_MMA(0, 1, At, B1); PG8_BAR;
;             PG8_LDA(At, 0, 1); PG8_STAGE(PG8_SA(0, 0), a2, voffA);
;             PG8_BAR; PG8_WAIT_L(0); PG8_MMA(1, 0, At, B0); PG8_BAR; PG8_SCHED;
	v_mfma_f32_16x16x32_bf16 v[116:119], v[208:211], v[172:175], v[116:119]
	v_mfma_f32_16x16x32_bf16 v[112:115], v[216:219], v[172:175], v[112:115]
	v_mfma_f32_16x16x32_bf16 v[100:103], v[208:211], v[184:187], v[100:103]
	v_mfma_f32_16x16x32_bf16 v[96:99], v[216:219], v[184:187], v[96:99]
	v_mfma_f32_16x16x32_bf16 v[84:87], v[208:211], v[192:195], v[84:87]
	v_mfma_f32_16x16x32_bf16 v[80:83], v[216:219], v[192:195], v[80:83]
	v_mfma_f32_16x16x32_bf16 v[68:71], v[208:211], v[200:203], v[68:71]
	v_mfma_f32_16x16x32_bf16 v[64:67], v[216:219], v[200:203], v[64:67]
	v_mfma_f32_16x16x32_bf16 v[116:119], v[212:215], v[180:183], v[116:119]
	v_mfma_f32_16x16x32_bf16 v[112:115], v[220:223], v[180:183], v[112:115]
	v_mfma_f32_16x16x32_bf16 v[100:103], v[212:215], v[188:191], v[100:103]
	v_mfma_f32_16x16x32_bf16 v[96:99], v[220:223], v[188:191], v[96:99]
	v_mfma_f32_16x16x32_bf16 v[84:87], v[212:215], v[196:199], v[84:87]
	v_mfma_f32_16x16x32_bf16 v[80:83], v[220:223], v[196:199], v[80:83]
	v_mfma_f32_16x16x32_bf16 v[68:71], v[212:215], v[204:207], v[68:71]
	v_mfma_f32_16x16x32_bf16 v[64:67], v[220:223], v[204:207], v[64:67]
	s_setprio 0
	s_mov_b32 m0, s30
	v_lshl_add_u64 v[224:225], s[18:19], 0, v[138:139]
	s_barrier
	ds_read_b128 v[172:175], v163 offset:16384
	ds_read_b128 v[180:183], v163 offset:17408
	ds_read_b128 v[184:187], v163 offset:18432
	ds_read_b128 v[188:191], v163 offset:19456
	ds_read_b128 v[192:195], v163 offset:20480
	ds_read_b128 v[196:199], v163 offset:21504
	ds_read_b128 v[200:203], v163 offset:22528
	ds_read_b128 v[204:207], v163 offset:23552
	global_load_lds_dwordx4 v[224:225], off
	v_lshl_add_u64 v[226:227], s[18:19], 0, v[142:143]
	s_mov_b32 m0, s31
	s_nop 0
	global_load_lds_dwordx4 v[226:227], off
	s_waitcnt lgkmcnt(0)
	s_setprio 1
	s_barrier


; #define PG8_STAGE(bufoff, gbase, voff) do { _Pragma("unroll") for (int _i = 0; _i < 2; ++_i) \
;         __builtin_amdgcn_global_load_lds((const unsigned*)((const char*)(gbase) + (voff)[_i]), (LAS unsigned*)(lds + (bufoff) + ldsw + _i * 8192), 16, 0, 0); } while (0)
; #define PG8_MMA(ai, bj, At, Bt) do { __builtin_amdgcn_s_setprio(1); _Pragma("unroll") for (int m = 0; m < 4; ++m) _Pragma("unroll") for (int n = 0; n < 2; ++n) _Pragma("unroll") for (int k = 0; k < 2; ++k) \
;         acc[ai][bj][m][n] = __builtin_amdgcn_mfma_f32_16x16x32_bf16(Bt[n][k], At[m][k], acc[ai][bj][m][n], 0, 0, 0); __builtin_amdgcn_s_setprio(0); } while (0)
; #define PG8_WAIT_V(n) asm volatile("s_waitcnt vmcnt(" #n ")" ::: "memory")
; #define PG8_WAIT_L(n) asm volatile("s_waitcnt lgkmcnt(" #n ")" ::: "memory")
; #define PG8_BAR __builtin_amdgcn_s_barrier()
; #define PG8_SCHED __builtin_amdgcn_sched_barrier(0)
; template <class Epi>
; __device__ __forceinline__ void gemm_phase(LAS unsigned char* lds, const Gemm g, const StaticOrder& S, const Epi& E) {
;     ...
;             PG8_BAR; PG8_WAIT_L(0); PG8_MMA(1, 0, At, B0); PG8_BAR; PG8_SCHED;
;             PG8_STAGE(PG8_SB(0, 1), b2 + hstep, voffB);
;             PG8_WAIT_V(6); PG8_BAR; PG8_MMA(1, 1, At, B1); PG8_BAR;
	v_mfma_f32_16x16x32_bf16 v[60:63], v[128:131], v[172:175], v[60:63]
	v_mfma_f32_16x16x32_bf16 v[56:59], v[154:157], v[172:175], v[56:59]
	v_mfma_f32_16x16x32_bf16 v[44:47], v[128:131], v[184:187], v[44:47]
	v_mfma_f32_16x16x32_bf16 v[40:43], v[154:157], v[184:187], v[40:43]
	v_mfma_f32_16x16x32_bf16 v[28:31], v[128:131], v[192:195], v[28:31]
	v_mfma_f32_16x16x32_bf16 v[24:27], v[154:157], v[192:195], v[24:27]
	v_mfma_f32_16x16x32_bf16 v[12:15], v[128:131], v[200:203], v[12:15]
	v_mfma_f32_16x16x32_bf16 v[8:11], v[154:157], v[200:203], v[8:11]
	v_mfma_f32_16x16x32_bf16 v[60:63], v[132:135], v[180:183], v[60:63]
	v_mfma_f32_16x16x32_bf16 v[56:59], v[168:171], v[180:183], v[56:59]
	v_mfma_f32_16x16x32_bf16 v[44:47], v[132:135], v[188:191], v[44:47]
	v_mfma_f32_16x16x32_bf16 v[40:43], v[168:171], v[188:191], v[40:43]
	v_mfma_f32_16x16x32_bf16 v[28:31], v[132:135], v[196:199], v[28:31]
	v_mfma_f32_16x16x32_bf16 v[24:27], v[168:171], v[196:199], v[24:27]
	v_mfma_f32_16x16x32_bf16 v[12:15], v[132:135], v[204:207], v[12:15]
	v_mfma_f32_16x16x32_bf16 v[8:11], v[168:171], v[204:207], v[8:11]
	s_setprio 0
	s_barrier
	s_add_u32 s64, s16, 0x158000
	s_addc_u32 s65, s17, 0
	s_add_i32 s66, s56, s21
	v_lshl_add_u64 v[128:129], s[64:65], 0, v[140:141]
	s_mov_b32 m0, s66
	s_nop 0
	global_load_lds_dwordx4 v[128:129], off
	v_lshl_add_u64 v[128:129], s[64:65], 0, v[144:145]
	s_add_i32 m0, s66, 0x2000
	s_nop 0
	global_load_lds_dwordx4 v[128:129], off
	s_waitcnt vmcnt(6)
	s_setprio 1
	s_barrier

; #define PG8_STAGE(bufoff, gbase, voff) do { _Pragma("unroll") for (int _i = 0; _i < 2; ++_i) \
;         __builtin_amdgcn_global_load_lds((const unsigned*)((const char*)(gbase) + (voff)[_i]), (LAS unsigned*)(lds + (bufoff) + ldsw + _i * 8192), 16, 0, 0); } while (0)
; #define PG8_LDA(dst, b, h) do { _Pragma("unroll") for (int m = 0; m < 4; ++m) _Pragma("unroll") for (int k = 0; k < 2; ++k) dst[m][k] = *(const LAS bf16x8*)(lds + PG8_SA(b, h) + aoff + m * 2048 + k * 1024); } while (0)
; #define PG8_LDB(dst, b, h) do { _Pragma("unroll") for (int n = 0; n < 2; ++n) _Pragma("unroll") for (int k = 0; k < 2; ++k) dst[n][k] = *(const LAS bf16x8*)(lds + PG8_SB(b, h) + boff + n * 2048 + k * 1024); } while (0)
; #define PG8_MMA(ai, bj, At, Bt) do { __builtin_amdgcn_s_setprio(1); _Pragma("unroll") for (int m = 0; m < 4; ++m) _Pragma("unroll") for (int n = 0; n < 2; ++n) _Pragma("unroll") for (int k = 0; k < 2; ++k) \
;         acc[ai][bj][m][n] = __builtin_amdgcn_mfma_f32_16x16x32_bf16(Bt[n][k], At[m][k], acc[ai][bj][m][n], 0, 0, 0); __builtin_amdgcn_s_setprio(0); } while (0)
; #define PG8_WAIT_V(n) asm volatile("s_waitcnt vmcnt(" #n ")" ::: "memory")
; #define PG8_WAIT_L(n) asm volatile("s_waitcnt lgkmcnt(" #n ")" ::: "memory")
; #define PG8_BAR __builtin_amdgcn_s_barrier()
; #define PG8_SCHED __builtin_amdgcn_sched_barrier(0)
; template <class Epi>
; __device__ __forceinline__ void gemm_phase(LAS unsigned char* lds, const Gemm g, const StaticOrder& S, const Epi& E) {
;     ...
;             PG8_WAIT_V(6); PG8_BAR; PG8_MMA(1, 1, At, B1); PG8_BAR;
;             PG8_LDB(B0, 1, 0); PG8_SCHED; PG8_LDA(At, 1, 0); PG8_STAGE(PG8_SA(0, 1), a2 + hstep, voffA);
;             PG8_WAIT_L(8); PG8_BAR; PG8_WAIT_L(0); PG8_MMA(0, 0, At, B0); PG8_BAR; PG8_SCHED;
	v_mfma_f32_16x16x32_bf16 v[52:55], v[208:211], v[172:175], v[52:55]
	v_mfma_f32_16x16x32_bf16 v[48:51], v[216:219], v[172:175], v[48:51]
	v_mfma_f32_16x16x32_bf16 v[36:39], v[208:211], v[184:187], v[36:39]
	v_mfma_f32_16x16x32_bf16 v[32:35], v[216:219], v[184:187], v[32:35]
	v_mfma_f32_16x16x32_bf16 v[20:23], v[208:211], v[192:195], v[20:23]
	v_mfma_f32_16x16x32_bf16 v[16:19], v[216:219], v[192:195], v[16:19]
	v_mfma_f32_16x16x32_bf16 v[4:7], v[208:211], v[200:203], v[4:7]
	v_mfma_f32_16x16x32_bf16 v[0:3], v[216:219], v[200:203], v[0:3]
	v_mfma_f32_16x16x32_bf16 v[52:55], v[212:215], v[180:183], v[52:55]
	v_mfma_f32_16x16x32_bf16 v[48:51], v[220:223], v[180:183], v[48:51]
	v_mfma_f32_16x16x32_bf16 v[36:39], v[212:215], v[188:191], v[36:39]
	v_mfma_f32_16x16x32_bf16 v[32:35], v[220:223], v[188:191], v[32:35]
	v_mfma_f32_16x16x32_bf16 v[20:23], v[212:215], v[196:199], v[20:23]
	v_mfma_f32_16x16x32_bf16 v[16:19], v[220:223], v[196:199], v[16:19]
	v_mfma_f32_16x16x32_bf16 v[4:7], v[212:215], v[204:207], v[4:7]
	v_mfma_f32_16x16x32_bf16 v[0:3], v[220:223], v[204:207], v[0:3]
	s_setprio 0
	s_add_i32 s64, 0, 0x18000
	v_add_u32_e32 v167, s64, v137
	s_barrier
	ds_read_b128 v[128:131], v167
	ds_read_b128 v[132:135], v167 offset:1024
	ds_read_b128 v[154:157], v167 offset:2048
	ds_read_b128 v[168:171], v167 offset:3072
	s_add_u32 s18, s18, 0x158000
	s_addc_u32 s19, s19, 0
	s_mov_b32 m0, s33
	v_lshl_add_u64 v[208:209], s[18:19], 0, v[138:139]
	ds_read_b128 v[172:175], v163 offset:32768
	ds_read_b128 v[180:183], v163 offset:33792
	ds_read_b128 v[184:187], v163 offset:34816
	ds_read_b128 v[188:191], v163 offset:35840
	ds_read_b128 v[192:195], v163 offset:36864
	ds_read_b128 v[196:199], v163 offset:37888
	ds_read_b128 v[200:203], v163 offset:38912
	ds_read_b128 v[204:207], v163 offset:39936
	global_load_lds_dwordx4 v[208:209], off
	v_lshl_add_u64 v[208:209], s[18:19], 0, v[142:143]
	s_mov_b32 m0, s34
	s_nop 0
	global_load_lds_dwordx4 v[208:209], off
	s_waitcnt lgkmcnt(8)
	s_setprio 1
	s_barrier
	s_waitcnt lgkmcnt(0)


; #define PG8_STAGE(bufoff, gbase, voff) do { _Pragma("unroll") for (int _i = 0; _i < 2; ++_i) \
;         __builtin_amdgcn_global_load_lds((const unsigned*)((const char*)(gbase) + (voff)[_i]), (LAS unsigned*)(lds + (bufoff) + ldsw + _i * 8192), 16, 0, 0); } while (0)
; #define PG8_LDB(dst, b, h) do { _Pragma("unroll") for (int n = 0; n < 2; ++n) _Pragma("unroll") for (int k = 0; k < 2; ++k) dst[n][k] = *(const LAS bf16x8*)(lds + PG8_SB(b, h) + boff + n * 2048 + k * 1024); } while (0)
; #define PG8_MMA(ai, bj, At, Bt) do { __builtin_amdgcn_s_setprio(1); _Pragma("unroll") for (int m = 0; m < 4; ++m) _Pragma("unroll") for (int n = 0; n < 2; ++n) _Pragma("unroll") for (int k = 0; k < 2; ++k) \
;         acc[ai][bj][m][n] = __builtin_amdgcn_mfma_f32_16x16x32_bf16(Bt[n][k], At[m][k], acc[ai][bj][m][n], 0, 0, 0); __builtin_amdgcn_s_setprio(0); } while (0)
; #define PG8_WAIT_L(n) asm volatile("s_waitcnt lgkmcnt(" #n ")" ::: "memory")
; #define PG8_BAR __builtin_amdgcn_s_barrier()
; #define PG8_SCHED __builtin_amdgcn_sched_barrier(0)
; template <class Epi>
; __device__ __forceinline__ void gemm_phase(LAS unsigned char* lds, const Gemm g, const StaticOrder& S, const Epi& E) {
;     ...
;             PG8_WAIT_L(8); PG8_BAR; PG8_WAIT_L(0); PG8_MMA(0, 0, At, B0); PG8_BAR; PG8_SCHED;
;             PG8_LDB(B1, 1, 1); PG8_STAGE(PG8_SB(1, 0), b3, voffB);
;             PG8_BAR; PG8_WAIT_L(0); PG8_MMA(0, 1, At, B1); PG8_BAR;
	v_mfma_f32_16x16x32_bf16 v[124:127], v[128:131], v[172:175], v[124:127]
	v_mfma_f32_16x16x32_bf16 v[120:123], v[154:157], v[172:175], v[120:123]
	v_mfma_f32_16x16x32_bf16 v[108:111], v[128:131], v[184:187], v[108:111]
	v_mfma_f32_16x16x32_bf16 v[104:107], v[154:157], v[184:187], v[104:107]
	v_mfma_f32_16x16x32_bf16 v[92:95], v[128:131], v[192:195], v[92:95]
	v_mfma_f32_16x16x32_bf16 v[88:91], v[154:157], v[192:195], v[88:91]
	v_mfma_f32_16x16x32_bf16 v[76:79], v[128:131], v[200:203], v[76:79]
	v_mfma_f32_16x16x32_bf16 v[72:75], v[154:157], v[200:203], v[72:75]
	v_mfma_f32_16x16x32_bf16 v[124:127], v[132:135], v[180:183], v[124:127]
	v_mfma_f32_16x16x32_bf16 v[120:123], v[168:171], v[180:183], v[120:123]
	v_mfma_f32_16x16x32_bf16 v[108:111], v[132:135], v[188:191], v[108:111]
	v_mfma_f32_16x16x32_bf16 v[104:107], v[168:171], v[188:191], v[104:107]
	v_mfma_f32_16x16x32_bf16 v[92:95], v[132:135], v[196:199], v[92:95]
	v_mfma_f32_16x16x32_bf16 v[88:91], v[168:171], v[196:199], v[88:91]
	v_mfma_f32_16x16x32_bf16 v[76:79], v[132:135], v[204:207], v[76:79]
	v_mfma_f32_16x16x32_bf16 v[72:75], v[168:171], v[204:207], v[72:75]
	s_setprio 0
	s_barrier
	s_add_i32 s18, 0, 0x1c000
	s_add_i32 s19, s64, s21
	v_add_u32_e32 v167, s18, v137
	v_lshl_add_u64 v[158:159], v[158:159], 0, s[12:13]
	s_mov_b32 m0, s19
	ds_read_b128 v[208:211], v167
	ds_read_b128 v[212:215], v167 offset:1024
	ds_read_b128 v[216:219], v167 offset:2048
	ds_read_b128 v[220:223], v167 offset:3072
	global_load_lds_dwordx4 v[158:159], off
	v_lshl_add_u64 v[158:159], v[176:177], 0, s[12:13]
	s_add_i32 m0, s19, 0x2000
	s_nop 0
	global_load_lds_dwordx4 v[158:159], off
	s_waitcnt lgkmcnt(0)
	s_setprio 1
	s_barrier


; #define PG8_STAGE(bufoff, gbase, voff) do { _Pragma("unroll") for (int _i = 0; _i < 2; ++_i) \
;         __builtin_amdgcn_global_load_lds((const unsigned*)((const char*)(gbase) + (voff)[_i]), (LAS unsigned*)(lds + (bufoff) + ldsw + _i * 8192), 16, 0, 0); } while (0)
; #define PG8_LDA(dst, b, h) do { _Pragma("unroll") for (int m = 0; m < 4; ++m) _Pragma("unroll") for (int k = 0; k < 2; ++k) dst[m][k] = *(const LAS bf16x8*)(lds + PG8_SA(b, h) + aoff + m * 2048 + k * 1024); } while (0)
; #define PG8_MMA(ai, bj, At, Bt) do { __builtin_amdgcn_s_setprio(1); _Pragma("unroll") for (int m = 0; m < 4; ++m) _Pragma("unroll") for (int n = 0; n < 2; ++n) _Pragma("unroll") for (int k = 0; k < 2; ++k) \
;         acc[ai][bj][m][n] = __builtin_amdgcn_mfma_f32_16x16x32_bf16(Bt[n][k], At[m][k], acc[ai][bj][m][n], 0, 0, 0); __builtin_amdgcn_s_setprio(0); } while (0)
; #define PG8_WAIT_L(n) asm volatile("s_waitcnt lgkmcnt(" #n ")" ::: "memory")
; #define PG8_BAR __builtin_amdgcn_s_barrier()
; #define PG8_SCHED __builtin_amdgcn_sched_barrier(0)
; template <class Epi>
; __device__ __forceinline__ void gemm_phase(LAS unsigned char* lds, const Gemm g, const StaticOrder& S, const Epi& E) {
;     ...
;             PG8_BAR; PG8_WAIT_L(0); PG8_MMA(0, 1, At, B1); PG8_BAR;
;             PG8_LDA(At, 1, 1); PG8_STAGE(PG8_SA(1, 0), a3, voffA);
;             PG8_BAR; PG8_WAIT_L(0); PG8_MMA(1, 0, At, B0); PG8_BAR; PG8_SCHED;
	v_mfma_f32_16x16x32_bf16 v[116:119], v[208:211], v[172:175], v[116:119]
	v_mfma_f32_16x16x32_bf16 v[112:115], v[216:219], v[172:175], v[112:115]
	v_mfma_f32_16x16x32_bf16 v[100:103], v[208:211], v[184:187], v[100:103]
	v_mfma_f32_16x16x32_bf16 v[96:99], v[216:219], v[184:187], v[96:99]
	v_mfma_f32_16x16x32_bf16 v[84:87], v[208:211], v[192:195], v[84:87]
	v_mfma_f32_16x16x32_bf16 v[80:83], v[216:219], v[192:195], v[80:83]
	v_mfma_f32_16x16x32_bf16 v[68:71], v[208:211], v[200:203], v[68:71]
	v_mfma_f32_16x16x32_bf16 v[64:67], v[216:219], v[200:203], v[64:67]
	v_mfma_f32_16x16x32_bf16 v[116:119], v[212:215], v[180:183], v[116:119]
	v_mfma_f32_16x16x32_bf16 v[112:115], v[220:223], v[180:183], v[112:115]
	v_mfma_f32_16x16x32_bf16 v[100:103], v[212:215], v[188:191], v[100:103]
	v_mfma_f32_16x16x32_bf16 v[96:99], v[220:223], v[188:191], v[96:99]
	v_mfma_f32_16x16x32_bf16 v[84:87], v[212:215], v[196:199], v[84:87]
	v_mfma_f32_16x16x32_bf16 v[80:83], v[220:223], v[196:199], v[80:83]
	v_mfma_f32_16x16x32_bf16 v[68:71], v[212:215], v[204:207], v[68:71]
	v_mfma_f32_16x16x32_bf16 v[64:67], v[220:223], v[204:207], v[64:67]
	s_setprio 0
	s_mov_b32 m0, s36
	v_lshl_add_u64 v[158:159], v[224:225], 0, s[12:13]
	s_barrier
	ds_read_b128 v[172:175], v163 offset:49152
	ds_read_b128 v[180:183], v163 offset:50176
	ds_read_b128 v[184:187], v163 offset:51200
	ds_read_b128 v[188:191], v163 offset:52224
	ds_read_b128 v[192:195], v163 offset:53248
	ds_read_b128 v[196:199], v163 offset:54272
	ds_read_b128 v[200:203], v163 offset:55296
	ds_read_b128 v[204:207], v163 offset:56320
	global_load_lds_dwordx4 v[158:159], off
	v_lshl_add_u64 v[158:159], v[226:227], 0, s[12:13]
	s_mov_b32 m0, s37
	s_nop 0
	global_load_lds_dwordx4 v[158:159], off
	s_waitcnt lgkmcnt(0)
	s_setprio 1
	s_barrier


; #define PG8_STAGE(bufoff, gbase, voff) do { _Pragma("unroll") for (int _i = 0; _i < 2; ++_i) \
;         __builtin_amdgcn_global_load_lds((const unsigned*)((const char*)(gbase) + (voff)[_i]), (LAS unsigned*)(lds + (bufoff) + ldsw + _i * 8192), 16, 0, 0); } while (0)
; #define PG8_MMA(ai, bj, At, Bt) do { __builtin_amdgcn_s_setprio(1); _Pragma("unroll") for (int m = 0; m < 4; ++m) _Pragma("unroll") for (int n = 0; n < 2; ++n) _Pragma("unroll") for (int k = 0; k < 2; ++k) \
;         acc[ai][bj][m][n] = __builtin_amdgcn_mfma_f32_16x16x32_bf16(Bt[n][k], At[m][k], acc[ai][bj][m][n], 0, 0, 0); __builtin_amdgcn_s_setprio(0); } while (0)
; #define PG8_WAIT_V(n) asm volatile("s_waitcnt vmcnt(" #n ")" ::: "memory")
; #define PG8_WAIT_L(n) asm volatile("s_waitcnt lgkmcnt(" #n ")" ::: "memory")
; #define PG8_BAR __builtin_amdgcn_s_barrier()
; #define PG8_SCHED __builtin_amdgcn_sched_barrier(0)
; template <class Epi>
; __device__ __forceinline__ void gemm_phase(LAS unsigned char* lds, const Gemm g, const StaticOrder& S, const Epi& E) {
;     ...
;             PG8_BAR; PG8_WAIT_L(0); PG8_MMA(1, 0, At, B0); PG8_BAR; PG8_SCHED;
;             PG8_STAGE(PG8_SB(1, 1), b3 + hstep, voffB);
;             PG8_WAIT_V(6); PG8_BAR; PG8_MMA(1, 1, At, B1); PG8_BAR;
	v_mfma_f32_16x16x32_bf16 v[60:63], v[128:131], v[172:175], v[60:63]
	v_mfma_f32_16x16x32_bf16 v[56:59], v[154:157], v[172:175], v[56:59]
	v_mfma_f32_16x16x32_bf16 v[44:47], v[128:131], v[184:187], v[44:47]
	v_mfma_f32_16x16x32_bf16 v[40:43], v[154:157], v[184:187], v[40:43]
	v_mfma_f32_16x16x32_bf16 v[28:31], v[128:131], v[192:195], v[28:31]
	v_mfma_f32_16x16x32_bf16 v[24:27], v[154:157], v[192:195], v[24:27]
	v_mfma_f32_16x16x32_bf16 v[12:15], v[128:131], v[200:203], v[12:15]
	v_mfma_f32_16x16x32_bf16 v[8:11], v[154:157], v[200:203], v[8:11]
	v_mfma_f32_16x16x32_bf16 v[60:63], v[132:135], v[180:183], v[60:63]
	v_mfma_f32_16x16x32_bf16 v[56:59], v[168:171], v[180:183], v[56:59]
	v_mfma_f32_16x16x32_bf16 v[44:47], v[132:135], v[188:191], v[44:47]
	v_mfma_f32_16x16x32_bf16 v[40:43], v[168:171], v[188:191], v[40:43]
	v_mfma_f32_16x16x32_bf16 v[28:31], v[132:135], v[196:199], v[28:31]
	v_mfma_f32_16x16x32_bf16 v[24:27], v[168:171], v[196:199], v[24:27]
	v_mfma_f32_16x16x32_bf16 v[12:15], v[132:135], v[204:207], v[12:15]
	v_mfma_f32_16x16x32_bf16 v[8:11], v[168:171], v[204:207], v[8:11]
	s_setprio 0
	s_barrier
	s_add_u32 s16, s16, 0x158080
	s_addc_u32 s17, s17, 0
	s_add_i32 s18, s18, s21
	v_lshl_add_u64 v[128:129], s[16:17], 0, v[140:141]
	s_mov_b32 m0, s18
	s_nop 0
	global_load_lds_dwordx4 v[128:129], off
	v_lshl_add_u64 v[128:129], s[16:17], 0, v[144:145]
	s_add_i32 m0, s18, 0x2000
	s_nop 0
	global_load_lds_dwordx4 v[128:129], off
	s_waitcnt vmcnt(6)
	s_setprio 1
	s_barrier

; __device__ __forceinline__ float bflo(unsigned w) { return __uint_as_float(w << 16); }
; __device__ __forceinline__ float bfhi(unsigned w) { return __uint_as_float(w & 0xffff0000u); }
; #define PG8_WAIT_V(n) asm volatile("s_waitcnt vmcnt(" #n ")" ::: "memory")
; #define PG8_BAR __builtin_amdgcn_s_barrier()
; template <class Epi>
; __device__ __forceinline__ void gemm_phase(LAS unsigned char* lds, const Gemm g, const StaticOrder& S, const Epi& E) {
;     ...
;             PG8_WAIT_V(6); PG8_BAR; PG8_MMA(1, 1, At, B1); PG8_BAR;
;         }
;     __device__ __forceinline__ void operator()(const f32x4 (&acc)[2][2][4][2], const Unit& u, int wr, int wc, int fr, int fq, const Pre&) const {
;         const int row0 = ROW_X + u.pm * BM + wr * 64 + fr, col0 = u.pn * BM + wc * 32 + 8 * fq;
;         u32x4 hv[2][2]; float sprev = 0.f;
;     ...
;         ER_LOAD(0, 0);
; #pragma unroll
;         for (int g = 0; g < 8; ++g) { const int ai = g >> 2, m = g & 3; const int r = row0 + ai * HALF + m * 16; const size_t off = (size_t)r * DM + col0; float s = 0.f;
;             if (g + 1 < 8) ER_LOAD(g + 1, (g + 1) & 1);
; #pragma unroll
;             for (int bj = 0; bj < 2; ++bj) { const u32x4 w = hv[g & 1][bj];
;                 const f32x4 h0 = {bflo(w.x), bfhi(w.x), bflo(w.y), bfhi(w.y)}, h1 = {bflo(w.z), bfhi(w.z), bflo(w.w), bfhi(w.w)};
;                 const f32x4 o0 = h0 + acc[ai][bj][m][0] * alpha, o1 = h1 + acc[ai][bj][m][1] * alpha;
;                 if (FINAL) { float* op = OUT + (size_t)(r - ROW_X) * DM + col0 + bj * HALF; *(f32x4*)op = o0; *(f32x4*)(op + 4) = o1; }
;                 else { u32x4 q; q.x = cvtpk(o0[0], o0[1]); q.y = cvtpk(o0[2], o0[3]); q.z = cvtpk(o1[0], o1[1]); q.w = cvtpk(o1[2], o1[3]); *(u32x4*)(HB + off + bj * HALF) = q;
;                        s += ((o0[0] * o0[0] + o0[1] * o0[1]) + (o0[2] * o0[2] + o0[3] * o0[3])) + ((o1[0] * o1[0] + o1[1] * o1[1]) + (o1[2] * o1[2] + o1[3] * o1[3])); } }
;             if (!FINAL) { if (g > 0) { float t = sprev; t += __shfl_xor(t, 16); t += __shfl_xor(t, 32);
;                     if (fq == 0) __hip_atomic_fetch_add(ssq_out + row0 + ((g - 1) >> 2) * HALF + ((g - 1) & 3) * 16, t, __ATOMIC_RELAXED, __HIP_MEMORY_SCOPE_AGENT); }
	v_mfma_f32_16x16x32_bf16 v[52:55], v[208:211], v[172:175], v[52:55]
	v_mfma_f32_16x16x32_bf16 v[48:51], v[216:219], v[172:175], v[48:51]
	v_mfma_f32_16x16x32_bf16 v[36:39], v[208:211], v[184:187], v[36:39]
	v_mfma_f32_16x16x32_bf16 v[32:35], v[216:219], v[184:187], v[32:35]
	v_mfma_f32_16x16x32_bf16 v[20:23], v[208:211], v[192:195], v[20:23]
	v_mfma_f32_16x16x32_bf16 v[16:19], v[216:219], v[192:195], v[16:19]
	v_mfma_f32_16x16x32_bf16 v[4:7], v[208:211], v[200:203], v[4:7]
	v_mfma_f32_16x16x32_bf16 v[0:3], v[216:219], v[200:203], v[0:3]
	v_mfma_f32_16x16x32_bf16 v[52:55], v[212:215], v[180:183], v[52:55]
	v_mfma_f32_16x16x32_bf16 v[48:51], v[220:223], v[180:183], v[48:51]
	v_mfma_f32_16x16x32_bf16 v[36:39], v[212:215], v[188:191], v[36:39]
	v_mfma_f32_16x16x32_bf16 v[32:35], v[220:223], v[188:191], v[32:35]
	v_mfma_f32_16x16x32_bf16 v[20:23], v[212:215], v[196:199], v[20:23]
	v_mfma_f32_16x16x32_bf16 v[16:19], v[220:223], v[196:199], v[16:19]
	v_mfma_f32_16x16x32_bf16 v[4:7], v[212:215], v[204:207], v[4:7]
	v_mfma_f32_16x16x32_bf16 v[0:3], v[220:223], v[204:207], v[0:3]
	s_setprio 0
	s_add_i32 s63, s63, 2
	s_add_u32 s14, s14, 0x100
	s_addc_u32 s15, s15, 0
	s_add_u32 s61, s61, 0x100
	s_addc_u32 s62, s62, 0
	s_cmpk_gt_u32 s63, 0x53
	s_barrier
	s_cbranch_scc0 .LBB0_1411
	v_lshl_add_u32 v156, s59, 8, v160
	v_lshl_or_b32 v154, s60, 8, v161
	v_ashrrev_i32_e32 v157, 31, v156
	v_ashrrev_i32_e32 v155, 31, v154
	v_lshlrev_b64 v[128:129], 12, v[156:157]
	v_lshl_add_u64 v[128:129], s[8:9], 0, v[128:129]
	v_lshlrev_b64 v[130:131], 1, v[154:155]
	v_lshl_add_u64 v[176:177], v[128:129], 0, v[130:131]
	v_or_b32_e32 v128, 16, v156
	v_ashrrev_i32_e32 v129, 31, v128
	global_load_dwordx4 v[168:171], v[176:177], off
	global_load_dwordx4 v[172:175], v[176:177], off offset:256
	v_lshlrev_b64 v[128:129], 12, v[128:129]
	v_lshl_add_u64 v[128:129], s[8:9], 0, v[128:129]
	v_lshl_add_u64 v[188:189], v[128:129], 0, v[130:131]
	global_load_dwordx4 v[180:183], v[188:189], off
	global_load_dwordx4 v[184:187], v[188:189], off offset:256
	v_or_b32_e32 v128, 32, v156
	v_ashrrev_i32_e32 v129, 31, v128
	v_lshlrev_b64 v[128:129], 12, v[128:129]
	v_lshl_add_u64 v[128:129], s[8:9], 0, v[128:129]
	v_lshl_add_u64 v[158:159], v[128:129], 0, v[130:131]
	global_load_dwordx4 v[132:135], v[158:159], off
	global_load_dwordx4 v[128:131], v[158:159], off offset:256
	s_waitcnt vmcnt(0)
	v_lshlrev_b32_e32 v190, 16, v168
	v_and_b32_e32 v191, 0xffff0000, v168
	v_lshlrev_b32_e32 v168, 16, v169
	v_and_b32_e32 v169, 0xffff0000, v169
	v_lshlrev_b32_e32 v192, 16, v170
	v_and_b32_e32 v193, 0xffff0000, v170
	v_lshlrev_b32_e32 v170, 16, v171
	v_and_b32_e32 v171, 0xffff0000, v171
	v_lshlrev_b32_e32 v194, 16, v172
	v_and_b32_e32 v195, 0xffff0000, v172
	v_lshlrev_b32_e32 v172, 16, v173
	v_and_b32_e32 v173, 0xffff0000, v173
	v_lshlrev_b32_e32 v196, 16, v174
	v_and_b32_e32 v197, 0xffff0000, v174
	v_lshlrev_b32_e32 v174, 16, v175
	v_and_b32_e32 v175, 0xffff0000, v175
	v_pk_fma_f32 v[126:127], v[126:127], 0.5, v[168:169] op_sel_hi:[1,0,1]
	v_pk_fma_f32 v[124:125], v[124:125], 0.5, v[190:191] op_sel_hi:[1,0,1]
	v_pk_fma_f32 v[122:123], v[122:123], 0.5, v[170:171] op_sel_hi:[1,0,1]
	v_pk_fma_f32 v[168:169], v[120:121], 0.5, v[192:193] op_sel_hi:[1,0,1]
	v_pk_fma_f32 v[170:171], v[118:119], 0.5, v[172:173] op_sel_hi:[1,0,1]
	v_pk_fma_f32 v[172:173], v[116:117], 0.5, v[194:195] op_sel_hi:[1,0,1]
	v_pk_fma_f32 v[174:175], v[114:115], 0.5, v[174:175] op_sel_hi:[1,0,1]
	v_pk_fma_f32 v[190:191], v[112:113], 0.5, v[196:197] op_sel_hi:[1,0,1]
	v_cvt_pk_bf16_f32 v114, v124, v125
	v_cvt_pk_bf16_f32 v115, v126, v127
	v_cvt_pk_bf16_f32 v116, v168, v169
	v_cvt_pk_bf16_f32 v117, v122, v123
	v_mul_f32_e32 v125, v125, v125
	v_mul_f32_e32 v127, v127, v127
	v_mul_f32_e32 v167, v169, v169
	v_mul_f32_e32 v123, v123, v123
	v_cvt_pk_bf16_f32 v118, v172, v173
	v_cvt_pk_bf16_f32 v119, v170, v171
	v_cvt_pk_bf16_f32 v121, v174, v175
	v_mul_f32_e32 v169, v173, v173
	v_mul_f32_e32 v171, v171, v171
	v_mul_f32_e32 v173, v191, v191
	v_mul_f32_e32 v175, v175, v175
	v_lshlrev_b32_e32 v112, 16, v180
	v_and_b32_e32 v113, 0xffff0000, v180
	v_lshlrev_b32_e32 v192, 16, v182
	v_and_b32_e32 v193, 0xffff0000, v182
	v_lshlrev_b32_e32 v182, 16, v183
	v_and_b32_e32 v183, 0xffff0000, v183
	v_fmac_f32_e32 v125, v124, v124
	v_fmac_f32_e32 v127, v126, v126
	v_fmac_f32_e32 v167, v168, v168
	v_fmac_f32_e32 v123, v122, v122
	v_fmac_f32_e32 v169, v172, v172
	v_fmac_f32_e32 v171, v170, v170
	v_fmac_f32_e32 v173, v190, v190
	v_fmac_f32_e32 v175, v174, v174
	v_lshlrev_b32_e32 v180, 16, v181
	v_and_b32_e32 v181, 0xffff0000, v181
	v_pk_fma_f32 v[112:113], v[108:109], 0.5, v[112:113] op_sel_hi:[1,0,1]
	v_pk_fma_f32 v[108:109], v[106:107], 0.5, v[182:183] op_sel_hi:[1,0,1]
	global_store_dwordx4 v[176:177], v[114:117], off
	v_add_f32_e32 v106, v125, v127
	v_add_f32_e32 v107, v167, v123
	v_add_f32_e32 v114, v169, v171
	v_add_f32_e32 v115, v173, v175
	v_pk_fma_f32 v[110:111], v[110:111], 0.5, v[180:181] op_sel_hi:[1,0,1]
	v_add_f32_e32 v106, v106, v107
	v_add_f32_e32 v107, v114, v115
	v_pk_fma_f32 v[114:115], v[104:105], 0.5, v[192:193] op_sel_hi:[1,0,1]
	v_add_f32_e32 v125, v106, v107
	v_cvt_pk_bf16_f32 v104, v112, v113
	v_cvt_pk_bf16_f32 v105, v110, v111
	v_cvt_pk_bf16_f32 v106, v114, v115
	v_cvt_pk_bf16_f32 v107, v108, v109
	v_cvt_pk_bf16_f32 v120, v190, v191
	global_store_dwordx4 v[188:189], v[104:107], off
	global_store_dwordx4 v[176:177], v[118:121], off offset:256
	v_lshlrev_b32_e32 v122, 16, v186
	v_lshlrev_b32_e32 v104, 16, v184
	v_and_b32_e32 v105, 0xffff0000, v184
	v_pk_fma_f32 v[118:119], v[100:101], 0.5, v[104:105] op_sel_hi:[1,0,1]
	v_and_b32_e32 v101, 64, v166
	v_xor_b32_e32 v100, 16, v166
	v_add_u32_e32 v101, 64, v101
	v_cmp_lt_i32_e32 vcc, v100, v101
	v_and_b32_e32 v123, 0xffff0000, v186
	v_pk_fma_f32 v[122:123], v[96:97], 0.5, v[122:123] op_sel_hi:[1,0,1]
	v_cndmask_b32_e32 v100, v166, v100, vcc
	v_lshlrev_b32_e32 v124, 2, v100
	ds_bpermute_b32 v100, v124, v125
	v_xor_b32_e32 v97, 32, v166
	v_cmp_lt_i32_e32 vcc, v97, v101
	v_lshlrev_b32_e32 v106, 16, v185
	v_and_b32_e32 v107, 0xffff0000, v185
	v_cndmask_b32_e32 v97, v166, v97, vcc
	s_waitcnt lgkmcnt(0)
	v_add_f32_e32 v96, v125, v100
	v_lshlrev_b32_e32 v125, 2, v97
	ds_bpermute_b32 v97, v125, v96
	v_lshlrev_b32_e32 v120, 16, v187
	v_and_b32_e32 v121, 0xffff0000, v187
	v_pk_fma_f32 v[116:117], v[102:103], 0.5, v[106:107] op_sel_hi:[1,0,1]
	v_pk_fma_f32 v[120:121], v[98:99], 0.5, v[120:121] op_sel_hi:[1,0,1]
	v_cvt_pk_bf16_f32 v98, v118, v119
	v_cvt_pk_bf16_f32 v99, v116, v117
	v_cvt_pk_bf16_f32 v100, v122, v123
	v_cvt_pk_bf16_f32 v101, v120, v121
	v_lshl_add_u64 v[104:105], v[156:157], 2, s[10:11]
	global_store_dwordx4 v[188:189], v[98:101], off offset:256
	s_and_saveexec_b64 s[14:15], s[2:3]
	s_cbranch_execz .LBB0_1414
	s_waitcnt lgkmcnt(0)
	v_add_f32_e32 v96, v96, v97
	global_atomic_add_f32 v[104:105], v96, off

; #define PG8_STAGE(bufoff, gbase, voff) do { _Pragma("unroll") for (int _i = 0; _i < 2; ++_i) \
;         __builtin_amdgcn_global_load_lds((const unsigned*)((const char*)(gbase) + (voff)[_i]), (LAS unsigned*)(lds + (bufoff) + ldsw + _i * 8192), 16, 0, 0); } while (0)
; #define PG8_LDA(dst, b, h) do { _Pragma("unroll") for (int m = 0; m < 4; ++m) _Pragma("unroll") for (int k = 0; k < 2; ++k) dst[m][k] = *(const LAS bf16x8*)(lds + PG8_SA(b, h) + aoff + m * 2048 + k * 1024); } while (0)
; #define PG8_LDB(dst, b, h) do { _Pragma("unroll") for (int n = 0; n < 2; ++n) _Pragma("unroll") for (int k = 0; k < 2; ++k) dst[n][k] = *(const LAS bf16x8*)(lds + PG8_SB(b, h) + boff + n * 2048 + k * 1024); } while (0)
; #define PG8_MMA(ai, bj, At, Bt) do { __builtin_amdgcn_s_setprio(1); _Pragma("unroll") for (int m = 0; m < 4; ++m) _Pragma("unroll") for (int n = 0; n < 2; ++n) _Pragma("unroll") for (int k = 0; k < 2; ++k) \
;         acc[ai][bj][m][n] = __builtin_amdgcn_mfma_f32_16x16x32_bf16(Bt[n][k], At[m][k], acc[ai][bj][m][n], 0, 0, 0); __builtin_amdgcn_s_setprio(0); } while (0)
; #define PG8_WAIT_L(n) asm volatile("s_waitcnt lgkmcnt(" #n ")" ::: "memory")
; #define PG8_BAR __builtin_amdgcn_s_barrier()
; #define PG8_SCHED __builtin_amdgcn_sched_barrier(0)
; template <class Epi>
; __device__ __forceinline__ void gemm_phase(LAS unsigned char* lds, const Gemm g, const StaticOrder& S, const Epi& E) {
;     ...
;             const bool last = (t == nt - 2);
;             const char* a1 = cA + (size_t)(t + 1) * kstep;
;             const char* a2 = last ? nA : cA + (size_t)(t + 2) * kstep; const char* b2 = last ? nB : cB + (size_t)(t + 2) * kstep;
;             const char* a3 = a2 + kstep; const char* b3 = b2 + kstep;
;             PG8_LDB(B0, 0, 0); PG8_SCHED; PG8_LDA(At, 0, 0); PG8_STAGE(PG8_SA(1, 1), a1 + hstep, voffA);
;             PG8_WAIT_L(8); PG8_BAR; PG8_WAIT_L(0); PG8_MMA(0, 0, At, B0); PG8_BAR; PG8_SCHED;
.LBB0_1796:
	ds_read_b128 v[172:175], v157
	ds_read_b128 v[180:183], v157 offset:1024
	ds_read_b128 v[184:187], v157 offset:2048
	ds_read_b128 v[188:191], v157 offset:3072
	s_add_u32 s8, s6, 0xfff80080
	s_addc_u32 s9, s7, -1
	s_cmp_eq_u32 s37, 28
	s_cselect_b32 s11, s1, s9
	s_cselect_b32 s10, s5, s8
	s_cselect_b32 s9, s12, s35
	s_cselect_b32 s8, s13, s33
	v_lshl_add_u64 v[152:153], s[6:7], 0, v[142:143]
	s_add_i32 m0, s62, 0xc000
	ds_read_b128 v[192:195], v158
	ds_read_b128 v[196:199], v158 offset:1024
	ds_read_b128 v[200:203], v158 offset:2048
	ds_read_b128 v[204:207], v158 offset:3072
	ds_read_b128 v[208:211], v158 offset:4096
	ds_read_b128 v[212:215], v158 offset:5120
	ds_read_b128 v[216:219], v158 offset:6144
	ds_read_b128 v[220:223], v158 offset:7168
	global_load_lds_dwordx4 v[152:153], off
	v_lshl_add_u64 v[152:153], s[6:7], 0, v[144:145]
	s_add_i32 m0, s62, 0xe000
	s_nop 0
	global_load_lds_dwordx4 v[152:153], off
	s_waitcnt lgkmcnt(8)
	s_setprio 1
	s_barrier
	s_waitcnt lgkmcnt(0)


; #define PG8_STAGE(bufoff, gbase, voff) do { _Pragma("unroll") for (int _i = 0; _i < 2; ++_i) \
;         __builtin_amdgcn_global_load_lds((const unsigned*)((const char*)(gbase) + (voff)[_i]), (LAS unsigned*)(lds + (bufoff) + ldsw + _i * 8192), 16, 0, 0); } while (0)
; #define PG8_LDB(dst, b, h) do { _Pragma("unroll") for (int n = 0; n < 2; ++n) _Pragma("unroll") for (int k = 0; k < 2; ++k) dst[n][k] = *(const LAS bf16x8*)(lds + PG8_SB(b, h) + boff + n * 2048 + k * 1024); } while (0)
; #define PG8_MMA(ai, bj, At, Bt) do { __builtin_amdgcn_s_setprio(1); _Pragma("unroll") for (int m = 0; m < 4; ++m) _Pragma("unroll") for (int n = 0; n < 2; ++n) _Pragma("unroll") for (int k = 0; k < 2; ++k) \
;         acc[ai][bj][m][n] = __builtin_amdgcn_mfma_f32_16x16x32_bf16(Bt[n][k], At[m][k], acc[ai][bj][m][n], 0, 0, 0); __builtin_amdgcn_s_setprio(0); } while (0)
; #define PG8_WAIT_L(n) asm volatile("s_waitcnt lgkmcnt(" #n ")" ::: "memory")
; #define PG8_BAR __builtin_amdgcn_s_barrier()
; #define PG8_SCHED __builtin_amdgcn_sched_barrier(0)
; template <class Epi>
; __device__ __forceinline__ void gemm_phase(LAS unsigned char* lds, const Gemm g, const StaticOrder& S, const Epi& E) {
;     ...
;             PG8_WAIT_L(8); PG8_BAR; PG8_WAIT_L(0); PG8_MMA(0, 0, At, B0); PG8_BAR; PG8_SCHED;
;             PG8_LDB(B1, 0, 1); PG8_STAGE(PG8_SB(0, 0), b2, voffB);
;             PG8_BAR; PG8_WAIT_L(0); PG8_MMA(0, 1, At, B1); PG8_BAR;
	v_mfma_f32_16x16x32_bf16 v[116:119], v[172:175], v[192:195], v[116:119]
	v_mfma_f32_16x16x32_bf16 v[112:115], v[184:187], v[192:195], v[112:115]
	v_mfma_f32_16x16x32_bf16 v[100:103], v[172:175], v[200:203], v[100:103]
	v_mfma_f32_16x16x32_bf16 v[96:99], v[184:187], v[200:203], v[96:99]
	v_mfma_f32_16x16x32_bf16 v[84:87], v[172:175], v[208:211], v[84:87]
	v_mfma_f32_16x16x32_bf16 v[80:83], v[184:187], v[208:211], v[80:83]
	v_mfma_f32_16x16x32_bf16 v[68:71], v[172:175], v[216:219], v[68:71]
	v_mfma_f32_16x16x32_bf16 v[64:67], v[184:187], v[216:219], v[64:67]
	v_mfma_f32_16x16x32_bf16 v[116:119], v[180:183], v[196:199], v[116:119]
	v_mfma_f32_16x16x32_bf16 v[112:115], v[188:191], v[196:199], v[112:115]
	v_mfma_f32_16x16x32_bf16 v[100:103], v[180:183], v[204:207], v[100:103]
	v_mfma_f32_16x16x32_bf16 v[96:99], v[188:191], v[204:207], v[96:99]
	v_mfma_f32_16x16x32_bf16 v[84:87], v[180:183], v[212:215], v[84:87]
	v_mfma_f32_16x16x32_bf16 v[80:83], v[188:191], v[212:215], v[80:83]
	v_mfma_f32_16x16x32_bf16 v[68:71], v[180:183], v[220:223], v[68:71]
	v_mfma_f32_16x16x32_bf16 v[64:67], v[188:191], v[220:223], v[64:67]
	s_setprio 0
	s_barrier
	s_add_i32 s42, s72, s57
	v_lshl_add_u64 v[152:153], s[8:9], 0, v[130:131]
	s_mov_b32 m0, s42
	ds_read_b128 v[224:227], v159
	ds_read_b128 v[228:231], v159 offset:1024
	ds_read_b128 v[232:235], v159 offset:2048
	ds_read_b128 v[236:239], v159 offset:3072
	global_load_lds_dwordx4 v[152:153], off
	v_lshl_add_u64 v[176:177], s[8:9], 0, v[134:135]
	s_add_i32 m0, s42, 0x2000
	s_nop 0
	global_load_lds_dwordx4 v[176:177], off
	s_waitcnt lgkmcnt(0)
	s_setprio 1
	s_barrier


; #define PG8_STAGE(bufoff, gbase, voff) do { _Pragma("unroll") for (int _i = 0; _i < 2; ++_i) \
;         __builtin_amdgcn_global_load_lds((const unsigned*)((const char*)(gbase) + (voff)[_i]), (LAS unsigned*)(lds + (bufoff) + ldsw + _i * 8192), 16, 0, 0); } while (0)
; #define PG8_LDA(dst, b, h) do { _Pragma("unroll") for (int m = 0; m < 4; ++m) _Pragma("unroll") for (int k = 0; k < 2; ++k) dst[m][k] = *(const LAS bf16x8*)(lds + PG8_SA(b, h) + aoff + m * 2048 + k * 1024); } while (0)
; #define PG8_MMA(ai, bj, At, Bt) do { __builtin_amdgcn_s_setprio(1); _Pragma("unroll") for (int m = 0; m < 4; ++m) _Pragma("unroll") for (int n = 0; n < 2; ++n) _Pragma("unroll") for (int k = 0; k < 2; ++k) \
;         acc[ai][bj][m][n] = __builtin_amdgcn_mfma_f32_16x16x32_bf16(Bt[n][k], At[m][k], acc[ai][bj][m][n], 0, 0, 0); __builtin_amdgcn_s_setprio(0); } while (0)
; #define PG8_WAIT_L(n) asm volatile("s_waitcnt lgkmcnt(" #n ")" ::: "memory")
; #define PG8_BAR __builtin_amdgcn_s_barrier()
; #define PG8_SCHED __builtin_amdgcn_sched_barrier(0)
; template <class Epi>
; __device__ __forceinline__ void gemm_phase(LAS unsigned char* lds, const Gemm g, const StaticOrder& S, const Epi& E) {
;     ...
;             PG8_BAR; PG8_WAIT_L(0); PG8_MMA(0, 1, At, B1); PG8_BAR;
;             PG8_LDA(At, 0, 1); PG8_STAGE(PG8_SA(0, 0), a2, voffA);
;             PG8_BAR; PG8_WAIT_L(0); PG8_MMA(1, 0, At, B0); PG8_BAR; PG8_SCHED;
	v_mfma_f32_16x16x32_bf16 v[124:127], v[224:227], v[192:195], v[124:127]
	v_mfma_f32_16x16x32_bf16 v[120:123], v[232:235], v[192:195], v[120:123]
	v_mfma_f32_16x16x32_bf16 v[108:111], v[224:227], v[200:203], v[108:111]
	v_mfma_f32_16x16x32_bf16 v[104:107], v[232:235], v[200:203], v[104:107]
	v_mfma_f32_16x16x32_bf16 v[92:95], v[224:227], v[208:211], v[92:95]
	v_mfma_f32_16x16x32_bf16 v[88:91], v[232:235], v[208:211], v[88:91]
	v_mfma_f32_16x16x32_bf16 v[76:79], v[224:227], v[216:219], v[76:79]
	v_mfma_f32_16x16x32_bf16 v[72:75], v[232:235], v[216:219], v[72:75]
	v_mfma_f32_16x16x32_bf16 v[124:127], v[228:231], v[196:199], v[124:127]
	v_mfma_f32_16x16x32_bf16 v[120:123], v[236:239], v[196:199], v[120:123]
	v_mfma_f32_16x16x32_bf16 v[108:111], v[228:231], v[204:207], v[108:111]
	v_mfma_f32_16x16x32_bf16 v[104:107], v[236:239], v[204:207], v[104:107]
	v_mfma_f32_16x16x32_bf16 v[92:95], v[228:231], v[212:215], v[92:95]
	v_mfma_f32_16x16x32_bf16 v[88:91], v[236:239], v[212:215], v[88:91]
	v_mfma_f32_16x16x32_bf16 v[76:79], v[228:231], v[220:223], v[76:79]
	v_mfma_f32_16x16x32_bf16 v[72:75], v[236:239], v[220:223], v[72:75]
	s_setprio 0
	s_mov_b32 m0, s62
	v_lshl_add_u64 v[240:241], s[10:11], 0, v[128:129]
	s_barrier
	ds_read_b128 v[192:195], v158 offset:16384
	ds_read_b128 v[196:199], v158 offset:17408
	ds_read_b128 v[200:203], v158 offset:18432
	ds_read_b128 v[204:207], v158 offset:19456
	ds_read_b128 v[208:211], v158 offset:20480
	ds_read_b128 v[212:215], v158 offset:21504
	ds_read_b128 v[216:219], v158 offset:22528
	ds_read_b128 v[220:223], v158 offset:23552
	global_load_lds_dwordx4 v[240:241], off
	v_lshl_add_u64 v[242:243], s[10:11], 0, v[132:133]
	s_mov_b32 m0, s63
	s_nop 0
	global_load_lds_dwordx4 v[242:243], off
	s_waitcnt lgkmcnt(0)
	s_setprio 1
	s_barrier


; #define PG8_STAGE(bufoff, gbase, voff) do { _Pragma("unroll") for (int _i = 0; _i < 2; ++_i) \
;         __builtin_amdgcn_global_load_lds((const unsigned*)((const char*)(gbase) + (voff)[_i]), (LAS unsigned*)(lds + (bufoff) + ldsw + _i * 8192), 16, 0, 0); } while (0)
; #define PG8_MMA(ai, bj, At, Bt) do { __builtin_amdgcn_s_setprio(1); _Pragma("unroll") for (int m = 0; m < 4; ++m) _Pragma("unroll") for (int n = 0; n < 2; ++n) _Pragma("unroll") for (int k = 0; k < 2; ++k) \
;         acc[ai][bj][m][n] = __builtin_amdgcn_mfma_f32_16x16x32_bf16(Bt[n][k], At[m][k], acc[ai][bj][m][n], 0, 0, 0); __builtin_amdgcn_s_setprio(0); } while (0)
; #define PG8_WAIT_V(n) asm volatile("s_waitcnt vmcnt(" #n ")" ::: "memory")
; #define PG8_WAIT_L(n) asm volatile("s_waitcnt lgkmcnt(" #n ")" ::: "memory")
; #define PG8_BAR __builtin_amdgcn_s_barrier()
; #define PG8_SCHED __builtin_amdgcn_sched_barrier(0)
; template <class Epi>
; __device__ __forceinline__ void gemm_phase(LAS unsigned char* lds, const Gemm g, const StaticOrder& S, const Epi& E) {
;     ...
;             PG8_BAR; PG8_WAIT_L(0); PG8_MMA(1, 0, At, B0); PG8_BAR; PG8_SCHED;
;             PG8_STAGE(PG8_SB(0, 1), b2 + hstep, voffB);
;             PG8_WAIT_V(6); PG8_BAR; PG8_MMA(1, 1, At, B1); PG8_BAR;
	v_mfma_f32_16x16x32_bf16 v[52:55], v[172:175], v[192:195], v[52:55]
	v_mfma_f32_16x16x32_bf16 v[48:51], v[184:187], v[192:195], v[48:51]
	v_mfma_f32_16x16x32_bf16 v[36:39], v[172:175], v[200:203], v[36:39]
	v_mfma_f32_16x16x32_bf16 v[32:35], v[184:187], v[200:203], v[32:35]
	v_mfma_f32_16x16x32_bf16 v[20:23], v[172:175], v[208:211], v[20:23]
	v_mfma_f32_16x16x32_bf16 v[16:19], v[184:187], v[208:211], v[16:19]
	v_mfma_f32_16x16x32_bf16 v[4:7], v[172:175], v[216:219], v[4:7]
	v_mfma_f32_16x16x32_bf16 v[0:3], v[184:187], v[216:219], v[0:3]
	v_mfma_f32_16x16x32_bf16 v[52:55], v[180:183], v[196:199], v[52:55]
	v_mfma_f32_16x16x32_bf16 v[48:51], v[188:191], v[196:199], v[48:51]
	v_mfma_f32_16x16x32_bf16 v[36:39], v[180:183], v[204:207], v[36:39]
	v_mfma_f32_16x16x32_bf16 v[32:35], v[188:191], v[204:207], v[32:35]
	v_mfma_f32_16x16x32_bf16 v[20:23], v[180:183], v[212:215], v[20:23]
	v_mfma_f32_16x16x32_bf16 v[16:19], v[188:191], v[212:215], v[16:19]
	v_mfma_f32_16x16x32_bf16 v[4:7], v[180:183], v[220:223], v[4:7]
	v_mfma_f32_16x16x32_bf16 v[0:3], v[188:191], v[220:223], v[0:3]
	s_setprio 0
	s_barrier
	s_add_u32 s42, s8, 0x80000
	s_addc_u32 s43, s9, 0
	s_add_i32 s78, s73, s57
	v_lshl_add_u64 v[172:173], s[42:43], 0, v[130:131]
	s_mov_b32 m0, s78
	s_nop 0
	global_load_lds_dwordx4 v[172:173], off
	v_lshl_add_u64 v[172:173], s[42:43], 0, v[134:135]
	s_add_i32 m0, s78, 0x2000
	s_nop 0
	global_load_lds_dwordx4 v[172:173], off
	s_waitcnt vmcnt(6)
	s_setprio 1
	s_barrier

; #define PG8_STAGE(bufoff, gbase, voff) do { _Pragma("unroll") for (int _i = 0; _i < 2; ++_i) \
;         __builtin_amdgcn_global_load_lds((const unsigned*)((const char*)(gbase) + (voff)[_i]), (LAS unsigned*)(lds + (bufoff) + ldsw + _i * 8192), 16, 0, 0); } while (0)
; #define PG8_LDA(dst, b, h) do { _Pragma("unroll") for (int m = 0; m < 4; ++m) _Pragma("unroll") for (int k = 0; k < 2; ++k) dst[m][k] = *(const LAS bf16x8*)(lds + PG8_SA(b, h) + aoff + m * 2048 + k * 1024); } while (0)
; #define PG8_LDB(dst, b, h) do { _Pragma("unroll") for (int n = 0; n < 2; ++n) _Pragma("unroll") for (int k = 0; k < 2; ++k) dst[n][k] = *(const LAS bf16x8*)(lds + PG8_SB(b, h) + boff + n * 2048 + k * 1024); } while (0)
; #define PG8_MMA(ai, bj, At, Bt) do { __builtin_amdgcn_s_setprio(1); _Pragma("unroll") for (int m = 0; m < 4; ++m) _Pragma("unroll") for (int n = 0; n < 2; ++n) _Pragma("unroll") for (int k = 0; k < 2; ++k) \
;         acc[ai][bj][m][n] = __builtin_amdgcn_mfma_f32_16x16x32_bf16(Bt[n][k], At[m][k], acc[ai][bj][m][n], 0, 0, 0); __builtin_amdgcn_s_setprio(0); } while (0)
; #define PG8_WAIT_V(n) asm volatile("s_waitcnt vmcnt(" #n ")" ::: "memory")
; #define PG8_WAIT_L(n) asm volatile("s_waitcnt lgkmcnt(" #n ")" ::: "memory")
; #define PG8_BAR __builtin_amdgcn_s_barrier()
; #define PG8_SCHED __builtin_amdgcn_sched_barrier(0)
; template <class Epi>
; __device__ __forceinline__ void gemm_phase(LAS unsigned char* lds, const Gemm g, const StaticOrder& S, const Epi& E) {
;     ...
;             PG8_WAIT_V(6); PG8_BAR; PG8_MMA(1, 1, At, B1); PG8_BAR;
;             PG8_LDB(B0, 1, 0); PG8_SCHED; PG8_LDA(At, 1, 0); PG8_STAGE(PG8_SA(0, 1), a2 + hstep, voffA);
;             PG8_WAIT_L(8); PG8_BAR; PG8_WAIT_L(0); PG8_MMA(0, 0, At, B0); PG8_BAR; PG8_SCHED;
	v_mfma_f32_16x16x32_bf16 v[60:63], v[224:227], v[192:195], v[60:63]
	v_mfma_f32_16x16x32_bf16 v[56:59], v[232:235], v[192:195], v[56:59]
	v_mfma_f32_16x16x32_bf16 v[44:47], v[224:227], v[200:203], v[44:47]
	v_mfma_f32_16x16x32_bf16 v[40:43], v[232:235], v[200:203], v[40:43]
	v_mfma_f32_16x16x32_bf16 v[28:31], v[224:227], v[208:211], v[28:31]
	v_mfma_f32_16x16x32_bf16 v[24:27], v[232:235], v[208:211], v[24:27]
	v_mfma_f32_16x16x32_bf16 v[12:15], v[224:227], v[216:219], v[12:15]
	v_mfma_f32_16x16x32_bf16 v[8:11], v[232:235], v[216:219], v[8:11]
	v_mfma_f32_16x16x32_bf16 v[60:63], v[228:231], v[196:199], v[60:63]
	v_mfma_f32_16x16x32_bf16 v[56:59], v[236:239], v[196:199], v[56:59]
	v_mfma_f32_16x16x32_bf16 v[44:47], v[228:231], v[204:207], v[44:47]
	v_mfma_f32_16x16x32_bf16 v[40:43], v[236:239], v[204:207], v[40:43]
	v_mfma_f32_16x16x32_bf16 v[28:31], v[228:231], v[212:215], v[28:31]
	v_mfma_f32_16x16x32_bf16 v[24:27], v[236:239], v[212:215], v[24:27]
	v_mfma_f32_16x16x32_bf16 v[12:15], v[228:231], v[220:223], v[12:15]
	v_mfma_f32_16x16x32_bf16 v[8:11], v[236:239], v[220:223], v[8:11]
	s_setprio 0
	s_add_i32 s42, 0, 0x18000
	v_add_u32_e32 v136, s42, v155
	s_barrier
	ds_read_b128 v[172:175], v136
	ds_read_b128 v[180:183], v136 offset:1024
	ds_read_b128 v[184:187], v136 offset:2048
	ds_read_b128 v[188:191], v136 offset:3072
	s_add_u32 s10, s10, 0x80000
	s_addc_u32 s11, s11, 0
	s_mov_b32 m0, s64
	v_lshl_add_u64 v[224:225], s[10:11], 0, v[128:129]
	ds_read_b128 v[192:195], v158 offset:32768
	ds_read_b128 v[196:199], v158 offset:33792
	ds_read_b128 v[200:203], v158 offset:34816
	ds_read_b128 v[204:207], v158 offset:35840
	ds_read_b128 v[208:211], v158 offset:36864
	ds_read_b128 v[212:215], v158 offset:37888
	ds_read_b128 v[216:219], v158 offset:38912
	ds_read_b128 v[220:223], v158 offset:39936
	global_load_lds_dwordx4 v[224:225], off
	v_lshl_add_u64 v[224:225], s[10:11], 0, v[132:133]
	s_mov_b32 m0, s65
	s_nop 0
	global_load_lds_dwordx4 v[224:225], off
	s_waitcnt lgkmcnt(8)
	s_setprio 1
	s_barrier
	s_waitcnt lgkmcnt(0)


; #define PG8_STAGE(bufoff, gbase, voff) do { _Pragma("unroll") for (int _i = 0; _i < 2; ++_i) \
;         __builtin_amdgcn_global_load_lds((const unsigned*)((const char*)(gbase) + (voff)[_i]), (LAS unsigned*)(lds + (bufoff) + ldsw + _i * 8192), 16, 0, 0); } while (0)
; #define PG8_LDB(dst, b, h) do { _Pragma("unroll") for (int n = 0; n < 2; ++n) _Pragma("unroll") for (int k = 0; k < 2; ++k) dst[n][k] = *(const LAS bf16x8*)(lds + PG8_SB(b, h) + boff + n * 2048 + k * 1024); } while (0)
; #define PG8_MMA(ai, bj, At, Bt) do { __builtin_amdgcn_s_setprio(1); _Pragma("unroll") for (int m = 0; m < 4; ++m) _Pragma("unroll") for (int n = 0; n < 2; ++n) _Pragma("unroll") for (int k = 0; k < 2; ++k) \
;         acc[ai][bj][m][n] = __builtin_amdgcn_mfma_f32_16x16x32_bf16(Bt[n][k], At[m][k], acc[ai][bj][m][n], 0, 0, 0); __builtin_amdgcn_s_setprio(0); } while (0)
; #define PG8_WAIT_L(n) asm volatile("s_waitcnt lgkmcnt(" #n ")" ::: "memory")
; #define PG8_BAR __builtin_amdgcn_s_barrier()
; #define PG8_SCHED __builtin_amdgcn_sched_barrier(0)
; template <class Epi>
; __device__ __forceinline__ void gemm_phase(LAS unsigned char* lds, const Gemm g, const StaticOrder& S, const Epi& E) {
;     ...
;             PG8_WAIT_L(8); PG8_BAR; PG8_WAIT_L(0); PG8_MMA(0, 0, At, B0); PG8_BAR; PG8_SCHED;
;             PG8_LDB(B1, 1, 1); PG8_STAGE(PG8_SB(1, 0), b3, voffB);
;             PG8_BAR; PG8_WAIT_L(0); PG8_MMA(0, 1, At, B1); PG8_BAR;
	v_mfma_f32_16x16x32_bf16 v[116:119], v[172:175], v[192:195], v[116:119]
	v_mfma_f32_16x16x32_bf16 v[112:115], v[184:187], v[192:195], v[112:115]
	v_mfma_f32_16x16x32_bf16 v[100:103], v[172:175], v[200:203], v[100:103]
	v_mfma_f32_16x16x32_bf16 v[96:99], v[184:187], v[200:203], v[96:99]
	v_mfma_f32_16x16x32_bf16 v[84:87], v[172:175], v[208:211], v[84:87]
	v_mfma_f32_16x16x32_bf16 v[80:83], v[184:187], v[208:211], v[80:83]
	v_mfma_f32_16x16x32_bf16 v[68:71], v[172:175], v[216:219], v[68:71]
	v_mfma_f32_16x16x32_bf16 v[64:67], v[184:187], v[216:219], v[64:67]
	v_mfma_f32_16x16x32_bf16 v[116:119], v[180:183], v[196:199], v[116:119]
	v_mfma_f32_16x16x32_bf16 v[112:115], v[188:191], v[196:199], v[112:115]
	v_mfma_f32_16x16x32_bf16 v[100:103], v[180:183], v[204:207], v[100:103]
	v_mfma_f32_16x16x32_bf16 v[96:99], v[188:191], v[204:207], v[96:99]
	v_mfma_f32_16x16x32_bf16 v[84:87], v[180:183], v[212:215], v[84:87]
	v_mfma_f32_16x16x32_bf16 v[80:83], v[188:191], v[212:215], v[80:83]
	v_mfma_f32_16x16x32_bf16 v[68:71], v[180:183], v[220:223], v[68:71]
	v_mfma_f32_16x16x32_bf16 v[64:67], v[188:191], v[220:223], v[64:67]
	s_setprio 0
	s_barrier
	s_add_i32 s10, 0, 0x1c000
	s_add_i32 s11, s42, s57
	v_add_u32_e32 v136, s10, v155
	v_lshl_add_u64 v[152:153], v[152:153], 0, s[24:25]
	s_mov_b32 m0, s11
	ds_read_b128 v[224:227], v136
	ds_read_b128 v[228:231], v136 offset:1024
	ds_read_b128 v[232:235], v136 offset:2048
	ds_read_b128 v[236:239], v136 offset:3072
	global_load_lds_dwordx4 v[152:153], off
	v_lshl_add_u64 v[152:153], v[176:177], 0, s[24:25]
	s_add_i32 m0, s11, 0x2000
	s_nop 0
	global_load_lds_dwordx4 v[152:153], off
	s_waitcnt lgkmcnt(0)
	s_setprio 1
	s_barrier


; #define PG8_STAGE(bufoff, gbase, voff) do { _Pragma("unroll") for (int _i = 0; _i < 2; ++_i) \
;         __builtin_amdgcn_global_load_lds((const unsigned*)((const char*)(gbase) + (voff)[_i]), (LAS unsigned*)(lds + (bufoff) + ldsw + _i * 8192), 16, 0, 0); } while (0)
; #define PG8_LDA(dst, b, h) do { _Pragma("unroll") for (int m = 0; m < 4; ++m) _Pragma("unroll") for (int k = 0; k < 2; ++k) dst[m][k] = *(const LAS bf16x8*)(lds + PG8_SA(b, h) + aoff + m * 2048 + k * 1024); } while (0)
; #define PG8_MMA(ai, bj, At, Bt) do { __builtin_amdgcn_s_setprio(1); _Pragma("unroll") for (int m = 0; m < 4; ++m) _Pragma("unroll") for (int n = 0; n < 2; ++n) _Pragma("unroll") for (int k = 0; k < 2; ++k) \
;         acc[ai][bj][m][n] = __builtin_amdgcn_mfma_f32_16x16x32_bf16(Bt[n][k], At[m][k], acc[ai][bj][m][n], 0, 0, 0); __builtin_amdgcn_s_setprio(0); } while (0)
; #define PG8_WAIT_L(n) asm volatile("s_waitcnt lgkmcnt(" #n ")" ::: "memory")
; #define PG8_BAR __builtin_amdgcn_s_barrier()
; #define PG8_SCHED __builtin_amdgcn_sched_barrier(0)
; template <class Epi>
; __device__ __forceinline__ void gemm_phase(LAS unsigned char* lds, const Gemm g, const StaticOrder& S, const Epi& E) {
;     ...
;             PG8_BAR; PG8_WAIT_L(0); PG8_MMA(0, 1, At, B1); PG8_BAR;
;             PG8_LDA(At, 1, 1); PG8_STAGE(PG8_SA(1, 0), a3, voffA);
;             PG8_BAR; PG8_WAIT_L(0); PG8_MMA(1, 0, At, B0); PG8_BAR; PG8_SCHED;
	v_mfma_f32_16x16x32_bf16 v[124:127], v[224:227], v[192:195], v[124:127]
	v_mfma_f32_16x16x32_bf16 v[120:123], v[232:235], v[192:195], v[120:123]
	v_mfma_f32_16x16x32_bf16 v[108:111], v[224:227], v[200:203], v[108:111]
	v_mfma_f32_16x16x32_bf16 v[104:107], v[232:235], v[200:203], v[104:107]
	v_mfma_f32_16x16x32_bf16 v[92:95], v[224:227], v[208:211], v[92:95]
	v_mfma_f32_16x16x32_bf16 v[88:91], v[232:235], v[208:211], v[88:91]
	v_mfma_f32_16x16x32_bf16 v[76:79], v[224:227], v[216:219], v[76:79]
	v_mfma_f32_16x16x32_bf16 v[72:75], v[232:235], v[216:219], v[72:75]
	v_mfma_f32_16x16x32_bf16 v[124:127], v[228:231], v[196:199], v[124:127]
	v_mfma_f32_16x16x32_bf16 v[120:123], v[236:239], v[196:199], v[120:123]
	v_mfma_f32_16x16x32_bf16 v[108:111], v[228:231], v[204:207], v[108:111]
	v_mfma_f32_16x16x32_bf16 v[104:107], v[236:239], v[204:207], v[104:107]
	v_mfma_f32_16x16x32_bf16 v[92:95], v[228:231], v[212:215], v[92:95]
	v_mfma_f32_16x16x32_bf16 v[88:91], v[236:239], v[212:215], v[88:91]
	v_mfma_f32_16x16x32_bf16 v[76:79], v[228:231], v[220:223], v[76:79]
	v_mfma_f32_16x16x32_bf16 v[72:75], v[236:239], v[220:223], v[72:75]
	s_setprio 0
	s_mov_b32 m0, s67
	v_lshl_add_u64 v[152:153], v[240:241], 0, s[24:25]
	s_barrier
	ds_read_b128 v[192:195], v158 offset:49152
	ds_read_b128 v[196:199], v158 offset:50176
	ds_read_b128 v[200:203], v158 offset:51200
	ds_read_b128 v[204:207], v158 offset:52224
	ds_read_b128 v[208:211], v158 offset:53248
	ds_read_b128 v[212:215], v158 offset:54272
	ds_read_b128 v[216:219], v158 offset:55296
	ds_read_b128 v[220:223], v158 offset:56320
	global_load_lds_dwordx4 v[152:153], off
	v_lshl_add_u64 v[152:153], v[242:243], 0, s[24:25]
	s_mov_b32 m0, s68
	s_nop 0
	global_load_lds_dwordx4 v[152:153], off
	s_waitcnt lgkmcnt(0)
	s_setprio 1
	s_barrier


; #define PG8_STAGE(bufoff, gbase, voff) do { _Pragma("unroll") for (int _i = 0; _i < 2; ++_i) \
;         __builtin_amdgcn_global_load_lds((const unsigned*)((const char*)(gbase) + (voff)[_i]), (LAS unsigned*)(lds + (bufoff) + ldsw + _i * 8192), 16, 0, 0); } while (0)
; #define PG8_MMA(ai, bj, At, Bt) do { __builtin_amdgcn_s_setprio(1); _Pragma("unroll") for (int m = 0; m < 4; ++m) _Pragma("unroll") for (int n = 0; n < 2; ++n) _Pragma("unroll") for (int k = 0; k < 2; ++k) \
;         acc[ai][bj][m][n] = __builtin_amdgcn_mfma_f32_16x16x32_bf16(Bt[n][k], At[m][k], acc[ai][bj][m][n], 0, 0, 0); __builtin_amdgcn_s_setprio(0); } while (0)
; #define PG8_WAIT_V(n) asm volatile("s_waitcnt vmcnt(" #n ")" ::: "memory")
; #define PG8_WAIT_L(n) asm volatile("s_waitcnt lgkmcnt(" #n ")" ::: "memory")
; #define PG8_BAR __builtin_amdgcn_s_barrier()
; #define PG8_SCHED __builtin_amdgcn_sched_barrier(0)
; template <class Epi>
; __device__ __forceinline__ void gemm_phase(LAS unsigned char* lds, const Gemm g, const StaticOrder& S, const Epi& E) {
;     ...
;             PG8_BAR; PG8_WAIT_L(0); PG8_MMA(1, 0, At, B0); PG8_BAR; PG8_SCHED;
;             PG8_STAGE(PG8_SB(1, 1), b3 + hstep, voffB);
;             PG8_WAIT_V(6); PG8_BAR; PG8_MMA(1, 1, At, B1); PG8_BAR;
	v_mfma_f32_16x16x32_bf16 v[52:55], v[172:175], v[192:195], v[52:55]
	v_mfma_f32_16x16x32_bf16 v[48:51], v[184:187], v[192:195], v[48:51]
	v_mfma_f32_16x16x32_bf16 v[36:39], v[172:175], v[200:203], v[36:39]
	v_mfma_f32_16x16x32_bf16 v[32:35], v[184:187], v[200:203], v[32:35]
	v_mfma_f32_16x16x32_bf16 v[20:23], v[172:175], v[208:211], v[20:23]
	v_mfma_f32_16x16x32_bf16 v[16:19], v[184:187], v[208:211], v[16:19]
	v_mfma_f32_16x16x32_bf16 v[4:7], v[172:175], v[216:219], v[4:7]
	v_mfma_f32_16x16x32_bf16 v[0:3], v[184:187], v[216:219], v[0:3]
	v_mfma_f32_16x16x32_bf16 v[52:55], v[180:183], v[196:199], v[52:55]
	v_mfma_f32_16x16x32_bf16 v[48:51], v[188:191], v[196:199], v[48:51]
	v_mfma_f32_16x16x32_bf16 v[36:39], v[180:183], v[204:207], v[36:39]
	v_mfma_f32_16x16x32_bf16 v[32:35], v[188:191], v[204:207], v[32:35]
	v_mfma_f32_16x16x32_bf16 v[20:23], v[180:183], v[212:215], v[20:23]
	v_mfma_f32_16x16x32_bf16 v[16:19], v[188:191], v[212:215], v[16:19]
	v_mfma_f32_16x16x32_bf16 v[4:7], v[180:183], v[220:223], v[4:7]
	v_mfma_f32_16x16x32_bf16 v[0:3], v[188:191], v[220:223], v[0:3]
	s_setprio 0
	s_barrier
	s_add_u32 s8, s8, 0x80080
	s_addc_u32 s9, s9, 0
	s_add_i32 s10, s10, s57
	v_lshl_add_u64 v[152:153], s[8:9], 0, v[130:131]
	s_mov_b32 m0, s10
	s_nop 0
	global_load_lds_dwordx4 v[152:153], off
	v_lshl_add_u64 v[152:153], s[8:9], 0, v[134:135]
	s_add_i32 m0, s10, 0x2000
	s_nop 0
	global_load_lds_dwordx4 v[152:153], off
	s_waitcnt vmcnt(6)
	s_setprio 1
	s_barrier

; #define PG8_MMA(ai, bj, At, Bt) do { __builtin_amdgcn_s_setprio(1); _Pragma("unroll") for (int m = 0; m < 4; ++m) _Pragma("unroll") for (int n = 0; n < 2; ++n) _Pragma("unroll") for (int k = 0; k < 2; ++k) \
;         acc[ai][bj][m][n] = __builtin_amdgcn_mfma_f32_16x16x32_bf16(Bt[n][k], At[m][k], acc[ai][bj][m][n], 0, 0, 0); __builtin_amdgcn_s_setprio(0); } while (0)
; #define PG8_WAIT_V(n) asm volatile("s_waitcnt vmcnt(" #n ")" ::: "memory")
; #define PG8_BAR __builtin_amdgcn_s_barrier()
; template <class Epi>
; __device__ __forceinline__ void gemm_phase(LAS unsigned char* lds, const Gemm g, const StaticOrder& S, const Epi& E) {
;     ...
;             PG8_WAIT_V(6); PG8_BAR; PG8_MMA(1, 1, At, B1); PG8_BAR;
;         }
;     __device__ __forceinline__ void operator()(const f32x4 (&acc)[2][2][4][2], const Unit& u, int wr, int wc, int fr, int fq, const Pre& P) const {
;         const int sec = u.pn >> 3, row0 = ROW_X + u.pm * BM + wr * 64 + fr, colb = (u.pn & 7) * BM + wc * 32 + 8 * fq;
; #pragma unroll
;         for (int ai = 0; ai < 2; ++ai)
; #pragma unroll
;             for (int m = 0; m < 4; ++m) { const int r = row0 + ai * HALF + m * 16; const float rs = __builtin_amdgcn_rsqf(P.rs[ai * 4 + m] * (1.0f / DM) + RMS_EPS);
;                 if (sec == 4) {
	v_mfma_f32_16x16x32_bf16 v[60:63], v[224:227], v[192:195], v[60:63]
	v_mfma_f32_16x16x32_bf16 v[56:59], v[232:235], v[192:195], v[56:59]
	v_mfma_f32_16x16x32_bf16 v[44:47], v[224:227], v[200:203], v[44:47]
	v_mfma_f32_16x16x32_bf16 v[40:43], v[232:235], v[200:203], v[40:43]
	v_mfma_f32_16x16x32_bf16 v[28:31], v[224:227], v[208:211], v[28:31]
	v_mfma_f32_16x16x32_bf16 v[24:27], v[232:235], v[208:211], v[24:27]
	v_mfma_f32_16x16x32_bf16 v[12:15], v[224:227], v[216:219], v[12:15]
	v_mfma_f32_16x16x32_bf16 v[8:11], v[232:235], v[216:219], v[8:11]
	v_mfma_f32_16x16x32_bf16 v[60:63], v[228:231], v[196:199], v[60:63]
	v_mfma_f32_16x16x32_bf16 v[56:59], v[236:239], v[196:199], v[56:59]
	v_mfma_f32_16x16x32_bf16 v[44:47], v[228:231], v[204:207], v[44:47]
	v_mfma_f32_16x16x32_bf16 v[40:43], v[236:239], v[204:207], v[40:43]
	v_mfma_f32_16x16x32_bf16 v[28:31], v[228:231], v[212:215], v[28:31]
	v_mfma_f32_16x16x32_bf16 v[24:27], v[236:239], v[212:215], v[24:27]
	v_mfma_f32_16x16x32_bf16 v[12:15], v[228:231], v[220:223], v[12:15]
	v_mfma_f32_16x16x32_bf16 v[8:11], v[236:239], v[220:223], v[8:11]
	s_setprio 0
	s_add_i32 s37, s37, 2
	s_add_u32 s6, s6, 0x100
	s_addc_u32 s7, s7, 0
	s_add_u32 s33, s33, 0x100
	s_addc_u32 s35, s35, 0
	s_cmp_gt_u32 s37, 29
	s_barrier
	s_cbranch_scc0 .LBB0_1796
	s_lshl_b32 s1, s0, 8
	s_ashr_i32 s35, s0, 3
	s_and_b32 s1, s1, 0x700
	s_waitcnt vmcnt(0)
	v_fmamk_f32 v136, v151, 0x3a000000, v160
	s_cmp_lg_u32 s35, 4
	v_rsq_f32_e32 v171, v136
	s_cselect_b64 s[10:11], -1, 0
	s_cmp_eq_u32 s35, 3
	v_lshl_add_u32 v150, s4, 8, v154
	s_cselect_b64 s[4:5], -1, 0
	s_cmp_gt_u32 s0, 7
	v_or_b32_e32 v165, s1, v156
	s_cselect_b64 s[12:13], -1, 0
	s_cmp_eq_u32 s35, 4
	s_mov_b64 s[0:1], -1
	s_cbranch_scc1 .LBB0_1817
	s_and_b64 vcc, exec, s[12:13]
	s_mov_b64 s[0:1], s[14:15]
	s_cbranch_vccz .LBB0_1807
	s_cmp_lt_i32 s35, 2
	s_cbranch_scc1 .LBB0_1803
	s_cmp_eq_u32 s35, 2
	s_mov_b64 s[6:7], -1
	s_cbranch_scc0 .LBB0_1802
	s_mov_b64 s[6:7], 0

; #define PG8_STAGE(bufoff, gbase, voff) do { _Pragma("unroll") for (int _i = 0; _i < 2; ++_i) \
;         __builtin_amdgcn_global_load_lds((const unsigned*)((const char*)(gbase) + (voff)[_i]), (LAS unsigned*)(lds + (bufoff) + ldsw + _i * 8192), 16, 0, 0); } while (0)
; #define PG8_LDA(dst, b, h) do { _Pragma("unroll") for (int m = 0; m < 4; ++m) _Pragma("unroll") for (int k = 0; k < 2; ++k) dst[m][k] = *(const LAS bf16x8*)(lds + PG8_SA(b, h) + aoff + m * 2048 + k * 1024); } while (0)
; #define PG8_LDB(dst, b, h) do { _Pragma("unroll") for (int n = 0; n < 2; ++n) _Pragma("unroll") for (int k = 0; k < 2; ++k) dst[n][k] = *(const LAS bf16x8*)(lds + PG8_SB(b, h) + boff + n * 2048 + k * 1024); } while (0)
; #define PG8_MMA(ai, bj, At, Bt) do { __builtin_amdgcn_s_setprio(1); _Pragma("unroll") for (int m = 0; m < 4; ++m) _Pragma("unroll") for (int n = 0; n < 2; ++n) _Pragma("unroll") for (int k = 0; k < 2; ++k) \
;         acc[ai][bj][m][n] = __builtin_amdgcn_mfma_f32_16x16x32_bf16(Bt[n][k], At[m][k], acc[ai][bj][m][n], 0, 0, 0); __builtin_amdgcn_s_setprio(0); } while (0)
; #define PG8_WAIT_L(n) asm volatile("s_waitcnt lgkmcnt(" #n ")" ::: "memory")
; #define PG8_BAR __builtin_amdgcn_s_barrier()
; #define PG8_SCHED __builtin_amdgcn_sched_barrier(0)
; template <class Epi>
; __device__ __forceinline__ void gemm_phase(LAS unsigned char* lds, const Gemm g, const StaticOrder& S, const Epi& E) {
;     ...
;             const bool last = (t == nt - 2);
;             const char* a1 = cA + (size_t)(t + 1) * kstep;
;             const char* a2 = last ? nA : cA + (size_t)(t + 2) * kstep; const char* b2 = last ? nB : cB + (size_t)(t + 2) * kstep;
;             const char* a3 = a2 + kstep; const char* b3 = b2 + kstep;
;             PG8_LDB(B0, 0, 0); PG8_SCHED; PG8_LDA(At, 0, 0); PG8_STAGE(PG8_SA(1, 1), a1 + hstep, voffA);
;             PG8_WAIT_L(8); PG8_BAR; PG8_WAIT_L(0); PG8_MMA(0, 0, At, B0); PG8_BAR; PG8_SCHED;
.LBB0_2460:
	ds_read_b128 v[128:131], v161
	ds_read_b128 v[132:135], v161 offset:1024
	ds_read_b128 v[152:155], v161 offset:2048
	ds_read_b128 v[166:169], v161 offset:3072
	s_add_u32 s24, s22, 0xfff80080
	s_addc_u32 s25, s23, -1
	s_cmp_eq_u32 s61, 28
	s_cselect_b32 s31, s13, s25
	s_cselect_b32 s30, s19, s24
	s_cselect_b32 s25, s11, s60
	s_cselect_b32 s24, s58, s59
	v_lshl_add_u64 v[156:157], s[22:23], 0, v[144:145]
	s_add_i32 m0, s21, 0xc000
	ds_read_b128 v[170:173], v162
	ds_read_b128 v[174:177], v162 offset:1024
	ds_read_b128 v[180:183], v162 offset:2048
	ds_read_b128 v[184:187], v162 offset:3072
	ds_read_b128 v[188:191], v162 offset:4096
	ds_read_b128 v[192:195], v162 offset:5120
	ds_read_b128 v[196:199], v162 offset:6144
	ds_read_b128 v[200:203], v162 offset:7168
	global_load_lds_dwordx4 v[156:157], off
	v_lshl_add_u64 v[156:157], s[22:23], 0, v[146:147]
	s_add_i32 m0, s21, 0xe000
	s_nop 0
	global_load_lds_dwordx4 v[156:157], off
	s_waitcnt lgkmcnt(8)
	s_setprio 1
	s_barrier
	s_waitcnt lgkmcnt(0)


; #define PG8_STAGE(bufoff, gbase, voff) do { _Pragma("unroll") for (int _i = 0; _i < 2; ++_i) \
;         __builtin_amdgcn_global_load_lds((const unsigned*)((const char*)(gbase) + (voff)[_i]), (LAS unsigned*)(lds + (bufoff) + ldsw + _i * 8192), 16, 0, 0); } while (0)
; #define PG8_LDB(dst, b, h) do { _Pragma("unroll") for (int n = 0; n < 2; ++n) _Pragma("unroll") for (int k = 0; k < 2; ++k) dst[n][k] = *(const LAS bf16x8*)(lds + PG8_SB(b, h) + boff + n * 2048 + k * 1024); } while (0)
; #define PG8_MMA(ai, bj, At, Bt) do { __builtin_amdgcn_s_setprio(1); _Pragma("unroll") for (int m = 0; m < 4; ++m) _Pragma("unroll") for (int n = 0; n < 2; ++n) _Pragma("unroll") for (int k = 0; k < 2; ++k) \
;         acc[ai][bj][m][n] = __builtin_amdgcn_mfma_f32_16x16x32_bf16(Bt[n][k], At[m][k], acc[ai][bj][m][n], 0, 0, 0); __builtin_amdgcn_s_setprio(0); } while (0)
; #define PG8_WAIT_L(n) asm volatile("s_waitcnt lgkmcnt(" #n ")" ::: "memory")
; #define PG8_BAR __builtin_amdgcn_s_barrier()
; #define PG8_SCHED __builtin_amdgcn_sched_barrier(0)
; template <class Epi>
; __device__ __forceinline__ void gemm_phase(LAS unsigned char* lds, const Gemm g, const StaticOrder& S, const Epi& E) {
;     ...
;             PG8_WAIT_L(8); PG8_BAR; PG8_WAIT_L(0); PG8_MMA(0, 0, At, B0); PG8_BAR; PG8_SCHED;
;             PG8_LDB(B1, 0, 1); PG8_STAGE(PG8_SB(0, 0), b2, voffB);
;             PG8_BAR; PG8_WAIT_L(0); PG8_MMA(0, 1, At, B1); PG8_BAR;
	v_mfma_f32_16x16x32_bf16 v[124:127], v[128:131], v[170:173], v[124:127]
	v_mfma_f32_16x16x32_bf16 v[120:123], v[152:155], v[170:173], v[120:123]
	v_mfma_f32_16x16x32_bf16 v[108:111], v[128:131], v[180:183], v[108:111]
	v_mfma_f32_16x16x32_bf16 v[104:107], v[152:155], v[180:183], v[104:107]
	v_mfma_f32_16x16x32_bf16 v[92:95], v[128:131], v[188:191], v[92:95]
	v_mfma_f32_16x16x32_bf16 v[88:91], v[152:155], v[188:191], v[88:91]
	v_mfma_f32_16x16x32_bf16 v[76:79], v[128:131], v[196:199], v[76:79]
	v_mfma_f32_16x16x32_bf16 v[72:75], v[152:155], v[196:199], v[72:75]
	v_mfma_f32_16x16x32_bf16 v[124:127], v[132:135], v[174:177], v[124:127]
	v_mfma_f32_16x16x32_bf16 v[120:123], v[166:169], v[174:177], v[120:123]
	v_mfma_f32_16x16x32_bf16 v[108:111], v[132:135], v[184:187], v[108:111]
	v_mfma_f32_16x16x32_bf16 v[104:107], v[166:169], v[184:187], v[104:107]
	v_mfma_f32_16x16x32_bf16 v[92:95], v[132:135], v[192:195], v[92:95]
	v_mfma_f32_16x16x32_bf16 v[88:91], v[166:169], v[192:195], v[88:91]
	v_mfma_f32_16x16x32_bf16 v[76:79], v[132:135], v[200:203], v[76:79]
	v_mfma_f32_16x16x32_bf16 v[72:75], v[166:169], v[200:203], v[72:75]
	s_setprio 0
	s_barrier
	s_add_i32 s62, s56, s38
	v_lshl_add_u64 v[156:157], s[24:25], 0, v[138:139]
	s_mov_b32 m0, s62
	ds_read_b128 v[204:207], v163
	ds_read_b128 v[208:211], v163 offset:1024
	ds_read_b128 v[212:215], v163 offset:2048
	ds_read_b128 v[216:219], v163 offset:3072
	global_load_lds_dwordx4 v[156:157], off
	v_lshl_add_u64 v[220:221], s[24:25], 0, v[142:143]
	s_add_i32 m0, s62, 0x2000
	s_nop 0
	global_load_lds_dwordx4 v[220:221], off
	s_waitcnt lgkmcnt(0)
	s_setprio 1
	s_barrier


; #define PG8_STAGE(bufoff, gbase, voff) do { _Pragma("unroll") for (int _i = 0; _i < 2; ++_i) \
;         __builtin_amdgcn_global_load_lds((const unsigned*)((const char*)(gbase) + (voff)[_i]), (LAS unsigned*)(lds + (bufoff) + ldsw + _i * 8192), 16, 0, 0); } while (0)
; #define PG8_LDA(dst, b, h) do { _Pragma("unroll") for (int m = 0; m < 4; ++m) _Pragma("unroll") for (int k = 0; k < 2; ++k) dst[m][k] = *(const LAS bf16x8*)(lds + PG8_SA(b, h) + aoff + m * 2048 + k * 1024); } while (0)
; #define PG8_MMA(ai, bj, At, Bt) do { __builtin_amdgcn_s_setprio(1); _Pragma("unroll") for (int m = 0; m < 4; ++m) _Pragma("unroll") for (int n = 0; n < 2; ++n) _Pragma("unroll") for (int k = 0; k < 2; ++k) \
;         acc[ai][bj][m][n] = __builtin_amdgcn_mfma_f32_16x16x32_bf16(Bt[n][k], At[m][k], acc[ai][bj][m][n], 0, 0, 0); __builtin_amdgcn_s_setprio(0); } while (0)
; #define PG8_WAIT_L(n) asm volatile("s_waitcnt lgkmcnt(" #n ")" ::: "memory")
; #define PG8_BAR __builtin_amdgcn_s_barrier()
; #define PG8_SCHED __builtin_amdgcn_sched_barrier(0)
; template <class Epi>
; __device__ __forceinline__ void gemm_phase(LAS unsigned char* lds, const Gemm g, const StaticOrder& S, const Epi& E) {
;     ...
;             PG8_BAR; PG8_WAIT_L(0); PG8_MMA(0, 1, At, B1); PG8_BAR;
;             PG8_LDA(At, 0, 1); PG8_STAGE(PG8_SA(0, 0), a2, voffA);
;             PG8_BAR; PG8_WAIT_L(0); PG8_MMA(1, 0, At, B0); PG8_BAR; PG8_SCHED;
	v_mfma_f32_16x16x32_bf16 v[116:119], v[204:207], v[170:173], v[116:119]
	v_mfma_f32_16x16x32_bf16 v[112:115], v[212:215], v[170:173], v[112:115]
	v_mfma_f32_16x16x32_bf16 v[100:103], v[204:207], v[180:183], v[100:103]
	v_mfma_f32_16x16x32_bf16 v[96:99], v[212:215], v[180:183], v[96:99]
	v_mfma_f32_16x16x32_bf16 v[84:87], v[204:207], v[188:191], v[84:87]
	v_mfma_f32_16x16x32_bf16 v[80:83], v[212:215], v[188:191], v[80:83]
	v_mfma_f32_16x16x32_bf16 v[68:71], v[204:207], v[196:199], v[68:71]
	v_mfma_f32_16x16x32_bf16 v[64:67], v[212:215], v[196:199], v[64:67]
	v_mfma_f32_16x16x32_bf16 v[116:119], v[208:211], v[174:177], v[116:119]
	v_mfma_f32_16x16x32_bf16 v[112:115], v[216:219], v[174:177], v[112:115]
	v_mfma_f32_16x16x32_bf16 v[100:103], v[208:211], v[184:187], v[100:103]
	v_mfma_f32_16x16x32_bf16 v[96:99], v[216:219], v[184:187], v[96:99]
	v_mfma_f32_16x16x32_bf16 v[84:87], v[208:211], v[192:195], v[84:87]
	v_mfma_f32_16x16x32_bf16 v[80:83], v[216:219], v[192:195], v[80:83]
	v_mfma_f32_16x16x32_bf16 v[68:71], v[208:211], v[200:203], v[68:71]
	v_mfma_f32_16x16x32_bf16 v[64:67], v[216:219], v[200:203], v[64:67]
	s_setprio 0
	s_mov_b32 m0, s21
	v_lshl_add_u64 v[222:223], s[30:31], 0, v[136:137]
	s_barrier
	ds_read_b128 v[170:173], v162 offset:16384
	ds_read_b128 v[174:177], v162 offset:17408
	ds_read_b128 v[180:183], v162 offset:18432
	ds_read_b128 v[184:187], v162 offset:19456
	ds_read_b128 v[188:191], v162 offset:20480
	ds_read_b128 v[192:195], v162 offset:21504
	ds_read_b128 v[196:199], v162 offset:22528
	ds_read_b128 v[200:203], v162 offset:23552
	global_load_lds_dwordx4 v[222:223], off
	v_lshl_add_u64 v[224:225], s[30:31], 0, v[140:141]
	s_mov_b32 m0, s39
	s_nop 0
	global_load_lds_dwordx4 v[224:225], off
	s_waitcnt lgkmcnt(0)
	s_setprio 1
	s_barrier


; #define PG8_STAGE(bufoff, gbase, voff) do { _Pragma("unroll") for (int _i = 0; _i < 2; ++_i) \
;         __builtin_amdgcn_global_load_lds((const unsigned*)((const char*)(gbase) + (voff)[_i]), (LAS unsigned*)(lds + (bufoff) + ldsw + _i * 8192), 16, 0, 0); } while (0)
; #define PG8_MMA(ai, bj, At, Bt) do { __builtin_amdgcn_s_setprio(1); _Pragma("unroll") for (int m = 0; m < 4; ++m) _Pragma("unroll") for (int n = 0; n < 2; ++n) _Pragma("unroll") for (int k = 0; k < 2; ++k) \
;         acc[ai][bj][m][n] = __builtin_amdgcn_mfma_f32_16x16x32_bf16(Bt[n][k], At[m][k], acc[ai][bj][m][n], 0, 0, 0); __builtin_amdgcn_s_setprio(0); } while (0)
; #define PG8_WAIT_V(n) asm volatile("s_waitcnt vmcnt(" #n ")" ::: "memory")
; #define PG8_WAIT_L(n) asm volatile("s_waitcnt lgkmcnt(" #n ")" ::: "memory")
; #define PG8_BAR __builtin_amdgcn_s_barrier()
; #define PG8_SCHED __builtin_amdgcn_sched_barrier(0)
; template <class Epi>
; __device__ __forceinline__ void gemm_phase(LAS unsigned char* lds, const Gemm g, const StaticOrder& S, const Epi& E) {
;     ...
;             PG8_BAR; PG8_WAIT_L(0); PG8_MMA(1, 0, At, B0); PG8_BAR; PG8_SCHED;
;             PG8_STAGE(PG8_SB(0, 1), b2 + hstep, voffB);
;             PG8_WAIT_V(6); PG8_BAR; PG8_MMA(1, 1, At, B1); PG8_BAR;
	v_mfma_f32_16x16x32_bf16 v[60:63], v[128:131], v[170:173], v[60:63]
	v_mfma_f32_16x16x32_bf16 v[56:59], v[152:155], v[170:173], v[56:59]
	v_mfma_f32_16x16x32_bf16 v[44:47], v[128:131], v[180:183], v[44:47]
	v_mfma_f32_16x16x32_bf16 v[40:43], v[152:155], v[180:183], v[40:43]
	v_mfma_f32_16x16x32_bf16 v[28:31], v[128:131], v[188:191], v[28:31]
	v_mfma_f32_16x16x32_bf16 v[24:27], v[152:155], v[188:191], v[24:27]
	v_mfma_f32_16x16x32_bf16 v[12:15], v[128:131], v[196:199], v[12:15]
	v_mfma_f32_16x16x32_bf16 v[8:11], v[152:155], v[196:199], v[8:11]
	v_mfma_f32_16x16x32_bf16 v[60:63], v[132:135], v[174:177], v[60:63]
	v_mfma_f32_16x16x32_bf16 v[56:59], v[166:169], v[174:177], v[56:59]
	v_mfma_f32_16x16x32_bf16 v[44:47], v[132:135], v[184:187], v[44:47]
	v_mfma_f32_16x16x32_bf16 v[40:43], v[166:169], v[184:187], v[40:43]
	v_mfma_f32_16x16x32_bf16 v[28:31], v[132:135], v[192:195], v[28:31]
	v_mfma_f32_16x16x32_bf16 v[24:27], v[166:169], v[192:195], v[24:27]
	v_mfma_f32_16x16x32_bf16 v[12:15], v[132:135], v[200:203], v[12:15]
	v_mfma_f32_16x16x32_bf16 v[8:11], v[166:169], v[200:203], v[8:11]
	s_setprio 0
	s_barrier
	s_add_u32 s62, s24, 0x80000
	s_addc_u32 s63, s25, 0
	s_add_i32 s64, s57, s38
	v_lshl_add_u64 v[128:129], s[62:63], 0, v[138:139]
	s_mov_b32 m0, s64
	s_nop 0
	global_load_lds_dwordx4 v[128:129], off
	v_lshl_add_u64 v[128:129], s[62:63], 0, v[142:143]
	s_add_i32 m0, s64, 0x2000
	s_nop 0
	global_load_lds_dwordx4 v[128:129], off
	s_waitcnt vmcnt(6)
	s_setprio 1
	s_barrier

; #define PG8_STAGE(bufoff, gbase, voff) do { _Pragma("unroll") for (int _i = 0; _i < 2; ++_i) \
;         __builtin_amdgcn_global_load_lds((const unsigned*)((const char*)(gbase) + (voff)[_i]), (LAS unsigned*)(lds + (bufoff) + ldsw + _i * 8192), 16, 0, 0); } while (0)
; #define PG8_LDA(dst, b, h) do { _Pragma("unroll") for (int m = 0; m < 4; ++m) _Pragma("unroll") for (int k = 0; k < 2; ++k) dst[m][k] = *(const LAS bf16x8*)(lds + PG8_SA(b, h) + aoff + m * 2048 + k * 1024); } while (0)
; #define PG8_LDB(dst, b, h) do { _Pragma("unroll") for (int n = 0; n < 2; ++n) _Pragma("unroll") for (int k = 0; k < 2; ++k) dst[n][k] = *(const LAS bf16x8*)(lds + PG8_SB(b, h) + boff + n * 2048 + k * 1024); } while (0)
; #define PG8_MMA(ai, bj, At, Bt) do { __builtin_amdgcn_s_setprio(1); _Pragma("unroll") for (int m = 0; m < 4; ++m) _Pragma("unroll") for (int n = 0; n < 2; ++n) _Pragma("unroll") for (int k = 0; k < 2; ++k) \
;         acc[ai][bj][m][n] = __builtin_amdgcn_mfma_f32_16x16x32_bf16(Bt[n][k], At[m][k], acc[ai][bj][m][n], 0, 0, 0); __builtin_amdgcn_s_setprio(0); } while (0)
; #define PG8_WAIT_V(n) asm volatile("s_waitcnt vmcnt(" #n ")" ::: "memory")
; #define PG8_WAIT_L(n) asm volatile("s_waitcnt lgkmcnt(" #n ")" ::: "memory")
; #define PG8_BAR __builtin_amdgcn_s_barrier()
; #define PG8_SCHED __builtin_amdgcn_sched_barrier(0)
; template <class Epi>
; __device__ __forceinline__ void gemm_phase(LAS unsigned char* lds, const Gemm g, const StaticOrder& S, const Epi& E) {
;     ...
;             PG8_WAIT_V(6); PG8_BAR; PG8_MMA(1, 1, At, B1); PG8_BAR;
;             PG8_LDB(B0, 1, 0); PG8_SCHED; PG8_LDA(At, 1, 0); PG8_STAGE(PG8_SA(0, 1), a2 + hstep, voffA);
;             PG8_WAIT_L(8); PG8_BAR; PG8_WAIT_L(0); PG8_MMA(0, 0, At, B0); PG8_BAR; PG8_SCHED;
	v_mfma_f32_16x16x32_bf16 v[52:55], v[204:207], v[170:173], v[52:55]
	v_mfma_f32_16x16x32_bf16 v[48:51], v[212:215], v[170:173], v[48:51]
	v_mfma_f32_16x16x32_bf16 v[36:39], v[204:207], v[180:183], v[36:39]
	v_mfma_f32_16x16x32_bf16 v[32:35], v[212:215], v[180:183], v[32:35]
	v_mfma_f32_16x16x32_bf16 v[20:23], v[204:207], v[188:191], v[20:23]
	v_mfma_f32_16x16x32_bf16 v[16:19], v[212:215], v[188:191], v[16:19]
	v_mfma_f32_16x16x32_bf16 v[4:7], v[204:207], v[196:199], v[4:7]
	v_mfma_f32_16x16x32_bf16 v[0:3], v[212:215], v[196:199], v[0:3]
	v_mfma_f32_16x16x32_bf16 v[52:55], v[208:211], v[174:177], v[52:55]
	v_mfma_f32_16x16x32_bf16 v[48:51], v[216:219], v[174:177], v[48:51]
	v_mfma_f32_16x16x32_bf16 v[36:39], v[208:211], v[184:187], v[36:39]
	v_mfma_f32_16x16x32_bf16 v[32:35], v[216:219], v[184:187], v[32:35]
	v_mfma_f32_16x16x32_bf16 v[20:23], v[208:211], v[192:195], v[20:23]
	v_mfma_f32_16x16x32_bf16 v[16:19], v[216:219], v[192:195], v[16:19]
	v_mfma_f32_16x16x32_bf16 v[4:7], v[208:211], v[200:203], v[4:7]
	v_mfma_f32_16x16x32_bf16 v[0:3], v[216:219], v[200:203], v[0:3]
	s_setprio 0
	s_add_i32 s62, 0, 0x18000
	v_add_u32_e32 v165, s62, v158
	s_barrier
	ds_read_b128 v[128:131], v165
	ds_read_b128 v[132:135], v165 offset:1024
	ds_read_b128 v[152:155], v165 offset:2048
	ds_read_b128 v[166:169], v165 offset:3072
	s_add_u32 s30, s30, 0x80000
	s_addc_u32 s31, s31, 0
	s_mov_b32 m0, s40
	v_lshl_add_u64 v[204:205], s[30:31], 0, v[136:137]
	ds_read_b128 v[170:173], v162 offset:32768
	ds_read_b128 v[174:177], v162 offset:33792
	ds_read_b128 v[180:183], v162 offset:34816
	ds_read_b128 v[184:187], v162 offset:35840
	ds_read_b128 v[188:191], v162 offset:36864
	ds_read_b128 v[192:195], v162 offset:37888
	ds_read_b128 v[196:199], v162 offset:38912
	ds_read_b128 v[200:203], v162 offset:39936
	global_load_lds_dwordx4 v[204:205], off
	v_lshl_add_u64 v[204:205], s[30:31], 0, v[140:141]
	s_mov_b32 m0, s41
	s_nop 0
	global_load_lds_dwordx4 v[204:205], off
	s_waitcnt lgkmcnt(8)
	s_setprio 1
	s_barrier
	s_waitcnt lgkmcnt(0)


; #define PG8_STAGE(bufoff, gbase, voff) do { _Pragma("unroll") for (int _i = 0; _i < 2; ++_i) \
;         __builtin_amdgcn_global_load_lds((const unsigned*)((const char*)(gbase) + (voff)[_i]), (LAS unsigned*)(lds + (bufoff) + ldsw + _i * 8192), 16, 0, 0); } while (0)
; #define PG8_LDB(dst, b, h) do { _Pragma("unroll") for (int n = 0; n < 2; ++n) _Pragma("unroll") for (int k = 0; k < 2; ++k) dst[n][k] = *(const LAS bf16x8*)(lds + PG8_SB(b, h) + boff + n * 2048 + k * 1024); } while (0)
; #define PG8_MMA(ai, bj, At, Bt) do { __builtin_amdgcn_s_setprio(1); _Pragma("unroll") for (int m = 0; m < 4; ++m) _Pragma("unroll") for (int n = 0; n < 2; ++n) _Pragma("unroll") for (int k = 0; k < 2; ++k) \
;         acc[ai][bj][m][n] = __builtin_amdgcn_mfma_f32_16x16x32_bf16(Bt[n][k], At[m][k], acc[ai][bj][m][n], 0, 0, 0); __builtin_amdgcn_s_setprio(0); } while (0)
; #define PG8_WAIT_L(n) asm volatile("s_waitcnt lgkmcnt(" #n ")" ::: "memory")
; #define PG8_BAR __builtin_amdgcn_s_barrier()
; #define PG8_SCHED __builtin_amdgcn_sched_barrier(0)
; template <class Epi>
; __device__ __forceinline__ void gemm_phase(LAS unsigned char* lds, const Gemm g, const StaticOrder& S, const Epi& E) {
;     ...
;             PG8_WAIT_L(8); PG8_BAR; PG8_WAIT_L(0); PG8_MMA(0, 0, At, B0); PG8_BAR; PG8_SCHED;
;             PG8_LDB(B1, 1, 1); PG8_STAGE(PG8_SB(1, 0), b3, voffB);
;             PG8_BAR; PG8_WAIT_L(0); PG8_MMA(0, 1, At, B1); PG8_BAR;
	v_mfma_f32_16x16x32_bf16 v[124:127], v[128:131], v[170:173], v[124:127]
	v_mfma_f32_16x16x32_bf16 v[120:123], v[152:155], v[170:173], v[120:123]
	v_mfma_f32_16x16x32_bf16 v[108:111], v[128:131], v[180:183], v[108:111]
	v_mfma_f32_16x16x32_bf16 v[104:107], v[152:155], v[180:183], v[104:107]
	v_mfma_f32_16x16x32_bf16 v[92:95], v[128:131], v[188:191], v[92:95]
	v_mfma_f32_16x16x32_bf16 v[88:91], v[152:155], v[188:191], v[88:91]
	v_mfma_f32_16x16x32_bf16 v[76:79], v[128:131], v[196:199], v[76:79]
	v_mfma_f32_16x16x32_bf16 v[72:75], v[152:155], v[196:199], v[72:75]
	v_mfma_f32_16x16x32_bf16 v[124:127], v[132:135], v[174:177], v[124:127]
	v_mfma_f32_16x16x32_bf16 v[120:123], v[166:169], v[174:177], v[120:123]
	v_mfma_f32_16x16x32_bf16 v[108:111], v[132:135], v[184:187], v[108:111]
	v_mfma_f32_16x16x32_bf16 v[104:107], v[166:169], v[184:187], v[104:107]
	v_mfma_f32_16x16x32_bf16 v[92:95], v[132:135], v[192:195], v[92:95]
	v_mfma_f32_16x16x32_bf16 v[88:91], v[166:169], v[192:195], v[88:91]
	v_mfma_f32_16x16x32_bf16 v[76:79], v[132:135], v[200:203], v[76:79]
	v_mfma_f32_16x16x32_bf16 v[72:75], v[166:169], v[200:203], v[72:75]
	s_setprio 0
	s_barrier
	s_add_i32 s30, 0, 0x1c000
	s_add_i32 s31, s62, s38
	v_add_u32_e32 v165, s30, v158
	v_lshl_add_u64 v[156:157], v[156:157], 0, s[8:9]
	s_mov_b32 m0, s31
	ds_read_b128 v[204:207], v165
	ds_read_b128 v[208:211], v165 offset:1024
	ds_read_b128 v[212:215], v165 offset:2048
	ds_read_b128 v[216:219], v165 offset:3072
	global_load_lds_dwordx4 v[156:157], off
	v_lshl_add_u64 v[156:157], v[220:221], 0, s[8:9]
	s_add_i32 m0, s31, 0x2000
	s_nop 0
	global_load_lds_dwordx4 v[156:157], off
	s_waitcnt lgkmcnt(0)
	s_setprio 1
	s_barrier


; #define PG8_STAGE(bufoff, gbase, voff) do { _Pragma("unroll") for (int _i = 0; _i < 2; ++_i) \
;         __builtin_amdgcn_global_load_lds((const unsigned*)((const char*)(gbase) + (voff)[_i]), (LAS unsigned*)(lds + (bufoff) + ldsw + _i * 8192), 16, 0, 0); } while (0)
; #define PG8_LDA(dst, b, h) do { _Pragma("unroll") for (int m = 0; m < 4; ++m) _Pragma("unroll") for (int k = 0; k < 2; ++k) dst[m][k] = *(const LAS bf16x8*)(lds + PG8_SA(b, h) + aoff + m * 2048 + k * 1024); } while (0)
; #define PG8_MMA(ai, bj, At, Bt) do { __builtin_amdgcn_s_setprio(1); _Pragma("unroll") for (int m = 0; m < 4; ++m) _Pragma("unroll") for (int n = 0; n < 2; ++n) _Pragma("unroll") for (int k = 0; k < 2; ++k) \
;         acc[ai][bj][m][n] = __builtin_amdgcn_mfma_f32_16x16x32_bf16(Bt[n][k], At[m][k], acc[ai][bj][m][n], 0, 0, 0); __builtin_amdgcn_s_setprio(0); } while (0)
; #define PG8_WAIT_L(n) asm volatile("s_waitcnt lgkmcnt(" #n ")" ::: "memory")
; #define PG8_BAR __builtin_amdgcn_s_barrier()
; #define PG8_SCHED __builtin_amdgcn_sched_barrier(0)
; template <class Epi>
; __device__ __forceinline__ void gemm_phase(LAS unsigned char* lds, const Gemm g, const StaticOrder& S, const Epi& E) {
;     ...
;             PG8_BAR; PG8_WAIT_L(0); PG8_MMA(0, 1, At, B1); PG8_BAR;
;             PG8_LDA(At, 1, 1); PG8_STAGE(PG8_SA(1, 0), a3, voffA);
;             PG8_BAR; PG8_WAIT_L(0); PG8_MMA(1, 0, At, B0); PG8_BAR; PG8_SCHED;
	v_mfma_f32_16x16x32_bf16 v[116:119], v[204:207], v[170:173], v[116:119]
	v_mfma_f32_16x16x32_bf16 v[112:115], v[212:215], v[170:173], v[112:115]
	v_mfma_f32_16x16x32_bf16 v[100:103], v[204:207], v[180:183], v[100:103]
	v_mfma_f32_16x16x32_bf16 v[96:99], v[212:215], v[180:183], v[96:99]
	v_mfma_f32_16x16x32_bf16 v[84:87], v[204:207], v[188:191], v[84:87]
	v_mfma_f32_16x16x32_bf16 v[80:83], v[212:215], v[188:191], v[80:83]
	v_mfma_f32_16x16x32_bf16 v[68:71], v[204:207], v[196:199], v[68:71]
	v_mfma_f32_16x16x32_bf16 v[64:67], v[212:215], v[196:199], v[64:67]
	v_mfma_f32_16x16x32_bf16 v[116:119], v[208:211], v[174:177], v[116:119]
	v_mfma_f32_16x16x32_bf16 v[112:115], v[216:219], v[174:177], v[112:115]
	v_mfma_f32_16x16x32_bf16 v[100:103], v[208:211], v[184:187], v[100:103]
	v_mfma_f32_16x16x32_bf16 v[96:99], v[216:219], v[184:187], v[96:99]
	v_mfma_f32_16x16x32_bf16 v[84:87], v[208:211], v[192:195], v[84:87]
	v_mfma_f32_16x16x32_bf16 v[80:83], v[216:219], v[192:195], v[80:83]
	v_mfma_f32_16x16x32_bf16 v[68:71], v[208:211], v[200:203], v[68:71]
	v_mfma_f32_16x16x32_bf16 v[64:67], v[216:219], v[200:203], v[64:67]
	s_setprio 0
	s_mov_b32 m0, s43
	v_lshl_add_u64 v[156:157], v[222:223], 0, s[8:9]
	s_barrier
	ds_read_b128 v[170:173], v162 offset:49152
	ds_read_b128 v[174:177], v162 offset:50176
	ds_read_b128 v[180:183], v162 offset:51200
	ds_read_b128 v[184:187], v162 offset:52224
	ds_read_b128 v[188:191], v162 offset:53248
	ds_read_b128 v[192:195], v162 offset:54272
	ds_read_b128 v[196:199], v162 offset:55296
	ds_read_b128 v[200:203], v162 offset:56320
	global_load_lds_dwordx4 v[156:157], off
	v_lshl_add_u64 v[156:157], v[224:225], 0, s[8:9]
	s_mov_b32 m0, s44
	s_nop 0
	global_load_lds_dwordx4 v[156:157], off
	s_waitcnt lgkmcnt(0)
	s_setprio 1
	s_barrier


; #define PG8_STAGE(bufoff, gbase, voff) do { _Pragma("unroll") for (int _i = 0; _i < 2; ++_i) \
;         __builtin_amdgcn_global_load_lds((const unsigned*)((const char*)(gbase) + (voff)[_i]), (LAS unsigned*)(lds + (bufoff) + ldsw + _i * 8192), 16, 0, 0); } while (0)
; #define PG8_MMA(ai, bj, At, Bt) do { __builtin_amdgcn_s_setprio(1); _Pragma("unroll") for (int m = 0; m < 4; ++m) _Pragma("unroll") for (int n = 0; n < 2; ++n) _Pragma("unroll") for (int k = 0; k < 2; ++k) \
;         acc[ai][bj][m][n] = __builtin_amdgcn_mfma_f32_16x16x32_bf16(Bt[n][k], At[m][k], acc[ai][bj][m][n], 0, 0, 0); __builtin_amdgcn_s_setprio(0); } while (0)
; #define PG8_WAIT_V(n) asm volatile("s_waitcnt vmcnt(" #n ")" ::: "memory")
; #define PG8_WAIT_L(n) asm volatile("s_waitcnt lgkmcnt(" #n ")" ::: "memory")
; #define PG8_BAR __builtin_amdgcn_s_barrier()
; #define PG8_SCHED __builtin_amdgcn_sched_barrier(0)
; template <class Epi>
; __device__ __forceinline__ void gemm_phase(LAS unsigned char* lds, const Gemm g, const StaticOrder& S, const Epi& E) {
;     ...
;             PG8_BAR; PG8_WAIT_L(0); PG8_MMA(1, 0, At, B0); PG8_BAR; PG8_SCHED;
;             PG8_STAGE(PG8_SB(1, 1), b3 + hstep, voffB);
;             PG8_WAIT_V(6); PG8_BAR; PG8_MMA(1, 1, At, B1); PG8_BAR;
	v_mfma_f32_16x16x32_bf16 v[60:63], v[128:131], v[170:173], v[60:63]
	v_mfma_f32_16x16x32_bf16 v[56:59], v[152:155], v[170:173], v[56:59]
	v_mfma_f32_16x16x32_bf16 v[44:47], v[128:131], v[180:183], v[44:47]
	v_mfma_f32_16x16x32_bf16 v[40:43], v[152:155], v[180:183], v[40:43]
	v_mfma_f32_16x16x32_bf16 v[28:31], v[128:131], v[188:191], v[28:31]
	v_mfma_f32_16x16x32_bf16 v[24:27], v[152:155], v[188:191], v[24:27]
	v_mfma_f32_16x16x32_bf16 v[12:15], v[128:131], v[196:199], v[12:15]
	v_mfma_f32_16x16x32_bf16 v[8:11], v[152:155], v[196:199], v[8:11]
	v_mfma_f32_16x16x32_bf16 v[60:63], v[132:135], v[174:177], v[60:63]
	v_mfma_f32_16x16x32_bf16 v[56:59], v[166:169], v[174:177], v[56:59]
	v_mfma_f32_16x16x32_bf16 v[44:47], v[132:135], v[184:187], v[44:47]
	v_mfma_f32_16x16x32_bf16 v[40:43], v[166:169], v[184:187], v[40:43]
	v_mfma_f32_16x16x32_bf16 v[28:31], v[132:135], v[192:195], v[28:31]
	v_mfma_f32_16x16x32_bf16 v[24:27], v[166:169], v[192:195], v[24:27]
	v_mfma_f32_16x16x32_bf16 v[12:15], v[132:135], v[200:203], v[12:15]
	v_mfma_f32_16x16x32_bf16 v[8:11], v[166:169], v[200:203], v[8:11]
	s_setprio 0
	s_barrier
	s_add_u32 s24, s24, 0x80080
	s_addc_u32 s25, s25, 0
	s_add_i32 s30, s30, s38
	v_lshl_add_u64 v[128:129], s[24:25], 0, v[138:139]
	s_mov_b32 m0, s30
	s_nop 0
	global_load_lds_dwordx4 v[128:129], off
	v_lshl_add_u64 v[128:129], s[24:25], 0, v[142:143]
	s_add_i32 m0, s30, 0x2000
	s_nop 0
	global_load_lds_dwordx4 v[128:129], off
	s_waitcnt vmcnt(6)
	s_setprio 1
	s_barrier

; __device__ __forceinline__ float bflo(unsigned w) { return __uint_as_float(w << 16); }
; __device__ __forceinline__ float bfhi(unsigned w) { return __uint_as_float(w & 0xffff0000u); }
; #define PG8_WAIT_V(n) asm volatile("s_waitcnt vmcnt(" #n ")" ::: "memory")
; #define PG8_BAR __builtin_amdgcn_s_barrier()
; template <class Epi>
; __device__ __forceinline__ void gemm_phase(LAS unsigned char* lds, const Gemm g, const StaticOrder& S, const Epi& E) {
;     ...
;             PG8_WAIT_V(6); PG8_BAR; PG8_MMA(1, 1, At, B1); PG8_BAR;
;         }
;     __device__ __forceinline__ void operator()(const f32x4 (&acc)[2][2][4][2], const Unit& u, int wr, int wc, int fr, int fq, const Pre&) const {
;         const int row0 = ROW_X + u.pm * BM + wr * 64 + fr, col0 = u.pn * BM + wc * 32 + 8 * fq;
;         u32x4 hv[2][2]; float sprev = 0.f;
;     ...
;         ER_LOAD(0, 0);
; #pragma unroll
;         for (int g = 0; g < 8; ++g) { const int ai = g >> 2, m = g & 3; const int r = row0 + ai * HALF + m * 16; const size_t off = (size_t)r * DM + col0; float s = 0.f;
;             if (g + 1 < 8) ER_LOAD(g + 1, (g + 1) & 1);
; #pragma unroll
;             for (int bj = 0; bj < 2; ++bj) { const u32x4 w = hv[g & 1][bj];
;                 const f32x4 h0 = {bflo(w.x), bfhi(w.x), bflo(w.y), bfhi(w.y)}, h1 = {bflo(w.z), bfhi(w.z), bflo(w.w), bfhi(w.w)};
;                 const f32x4 o0 = h0 + acc[ai][bj][m][0] * alpha, o1 = h1 + acc[ai][bj][m][1] * alpha;
;                 if (FINAL) { float* op = OUT + (size_t)(r - ROW_X) * DM + col0 + bj * HALF; *(f32x4*)op = o0; *(f32x4*)(op + 4) = o1; }
;                 else { u32x4 q; q.x = cvtpk(o0[0], o0[1]); q.y = cvtpk(o0[2], o0[3]); q.z = cvtpk(o1[0], o1[1]); q.w = cvtpk(o1[2], o1[3]); *(u32x4*)(HB + off + bj * HALF) = q;
;                        s += ((o0[0] * o0[0] + o0[1] * o0[1]) + (o0[2] * o0[2] + o0[3] * o0[3])) + ((o1[0] * o1[0] + o1[1] * o1[1]) + (o1[2] * o1[2] + o1[3] * o1[3])); } }
;             if (!FINAL) { if (g > 0) { float t = sprev; t += __shfl_xor(t, 16); t += __shfl_xor(t, 32);
;                     if (fq == 0) __hip_atomic_fetch_add(ssq_out + row0 + ((g - 1) >> 2) * HALF + ((g - 1) & 3) * 16, t, __ATOMIC_RELAXED, __HIP_MEMORY_SCOPE_AGENT); }
	v_mfma_f32_16x16x32_bf16 v[52:55], v[204:207], v[170:173], v[52:55]
	v_mfma_f32_16x16x32_bf16 v[48:51], v[212:215], v[170:173], v[48:51]
	v_mfma_f32_16x16x32_bf16 v[36:39], v[204:207], v[180:183], v[36:39]
	v_mfma_f32_16x16x32_bf16 v[32:35], v[212:215], v[180:183], v[32:35]
	v_mfma_f32_16x16x32_bf16 v[20:23], v[204:207], v[188:191], v[20:23]
	v_mfma_f32_16x16x32_bf16 v[16:19], v[212:215], v[188:191], v[16:19]
	v_mfma_f32_16x16x32_bf16 v[4:7], v[204:207], v[196:199], v[4:7]
	v_mfma_f32_16x16x32_bf16 v[0:3], v[212:215], v[196:199], v[0:3]
	v_mfma_f32_16x16x32_bf16 v[52:55], v[208:211], v[174:177], v[52:55]
	v_mfma_f32_16x16x32_bf16 v[48:51], v[216:219], v[174:177], v[48:51]
	v_mfma_f32_16x16x32_bf16 v[36:39], v[208:211], v[184:187], v[36:39]
	v_mfma_f32_16x16x32_bf16 v[32:35], v[216:219], v[184:187], v[32:35]
	v_mfma_f32_16x16x32_bf16 v[20:23], v[208:211], v[192:195], v[20:23]
	v_mfma_f32_16x16x32_bf16 v[16:19], v[216:219], v[192:195], v[16:19]
	v_mfma_f32_16x16x32_bf16 v[4:7], v[208:211], v[200:203], v[4:7]
	v_mfma_f32_16x16x32_bf16 v[0:3], v[216:219], v[200:203], v[0:3]
	s_setprio 0
	s_add_i32 s61, s61, 2
	s_add_u32 s22, s22, 0x100
	s_addc_u32 s23, s23, 0
	s_add_u32 s59, s59, 0x100
	s_addc_u32 s60, s60, 0
	s_cmp_gt_u32 s61, 29
	s_barrier
	s_cbranch_scc0 .LBB0_2460
	v_lshl_add_u32 v154, s18, 8, v159
	v_lshl_or_b32 v152, s20, 8, v160
	v_ashrrev_i32_e32 v155, 31, v154
	v_ashrrev_i32_e32 v153, 31, v152
	v_lshlrev_b64 v[128:129], 12, v[154:155]
	v_lshl_add_u64 v[128:129], s[0:1], 0, v[128:129]
	v_lshlrev_b64 v[130:131], 1, v[152:153]
	v_lshl_add_u64 v[184:185], v[128:129], 0, v[130:131]
	v_or_b32_e32 v128, 16, v154
	v_ashrrev_i32_e32 v129, 31, v128
	global_load_dwordx4 v[166:169], v[184:185], off
	global_load_dwordx4 v[170:173], v[184:185], off offset:256
	v_lshlrev_b64 v[128:129], 12, v[128:129]
	v_lshl_add_u64 v[128:129], s[0:1], 0, v[128:129]
	v_lshl_add_u64 v[186:187], v[128:129], 0, v[130:131]
	global_load_dwordx4 v[174:177], v[186:187], off
	global_load_dwordx4 v[180:183], v[186:187], off offset:256
	v_or_b32_e32 v128, 32, v154
	v_ashrrev_i32_e32 v129, 31, v128
	v_lshlrev_b64 v[128:129], 12, v[128:129]
	v_lshl_add_u64 v[128:129], s[0:1], 0, v[128:129]
	v_lshl_add_u64 v[156:157], v[128:129], 0, v[130:131]
	global_load_dwordx4 v[132:135], v[156:157], off
	global_load_dwordx4 v[128:131], v[156:157], off offset:256
	s_waitcnt vmcnt(0)
	v_lshlrev_b32_e32 v188, 16, v166
	v_and_b32_e32 v189, 0xffff0000, v166
	v_lshlrev_b32_e32 v166, 16, v167
	v_and_b32_e32 v167, 0xffff0000, v167
	v_lshlrev_b32_e32 v190, 16, v168
	v_and_b32_e32 v191, 0xffff0000, v168
	v_lshlrev_b32_e32 v168, 16, v169
	v_and_b32_e32 v169, 0xffff0000, v169
	v_lshlrev_b32_e32 v192, 16, v170
	v_and_b32_e32 v193, 0xffff0000, v170
	v_lshlrev_b32_e32 v170, 16, v171
	v_and_b32_e32 v171, 0xffff0000, v171
	v_lshlrev_b32_e32 v194, 16, v172
	v_and_b32_e32 v195, 0xffff0000, v172
	v_lshlrev_b32_e32 v172, 16, v173
	v_and_b32_e32 v173, 0xffff0000, v173
	v_pk_add_f32 v[126:127], v[126:127], v[166:167]
	v_pk_add_f32 v[124:125], v[124:125], v[188:189]
	v_pk_add_f32 v[122:123], v[122:123], v[168:169]
	v_pk_add_f32 v[166:167], v[120:121], v[190:191]
	v_pk_add_f32 v[168:169], v[118:119], v[170:171]
	v_pk_add_f32 v[170:171], v[116:117], v[192:193]
	v_pk_add_f32 v[172:173], v[114:115], v[172:173]
	v_pk_add_f32 v[188:189], v[112:113], v[194:195]
	v_cvt_pk_bf16_f32 v114, v124, v125
	v_cvt_pk_bf16_f32 v115, v126, v127
	v_cvt_pk_bf16_f32 v116, v166, v167
	v_cvt_pk_bf16_f32 v117, v122, v123
	v_mul_f32_e32 v125, v125, v125
	v_mul_f32_e32 v127, v127, v127
	v_mul_f32_e32 v165, v167, v167
	v_mul_f32_e32 v123, v123, v123
	v_cvt_pk_bf16_f32 v118, v170, v171
	v_cvt_pk_bf16_f32 v119, v168, v169
	v_cvt_pk_bf16_f32 v121, v172, v173
	v_mul_f32_e32 v167, v171, v171
	v_mul_f32_e32 v169, v169, v169
	v_mul_f32_e32 v171, v189, v189
	v_mul_f32_e32 v173, v173, v173
	v_lshlrev_b32_e32 v112, 16, v174
	v_and_b32_e32 v113, 0xffff0000, v174
	v_lshlrev_b32_e32 v190, 16, v176
	v_and_b32_e32 v191, 0xffff0000, v176
	v_lshlrev_b32_e32 v176, 16, v177
	v_and_b32_e32 v177, 0xffff0000, v177
	v_fmac_f32_e32 v125, v124, v124
	v_fmac_f32_e32 v127, v126, v126
	v_fmac_f32_e32 v165, v166, v166
	v_fmac_f32_e32 v123, v122, v122
	v_fmac_f32_e32 v167, v170, v170
	v_fmac_f32_e32 v169, v168, v168
	v_fmac_f32_e32 v171, v188, v188
	v_fmac_f32_e32 v173, v172, v172
	v_lshlrev_b32_e32 v174, 16, v175
	v_and_b32_e32 v175, 0xffff0000, v175
	v_pk_add_f32 v[112:113], v[108:109], v[112:113]
	v_pk_add_f32 v[108:109], v[106:107], v[176:177]
	global_store_dwordx4 v[184:185], v[114:117], off
	v_add_f32_e32 v106, v125, v127
	v_add_f32_e32 v107, v165, v123
	v_add_f32_e32 v114, v167, v169
	v_add_f32_e32 v115, v171, v173
	v_pk_add_f32 v[110:111], v[110:111], v[174:175]
	v_add_f32_e32 v106, v106, v107
	v_add_f32_e32 v107, v114, v115
	v_pk_add_f32 v[114:115], v[104:105], v[190:191]
	v_add_f32_e32 v125, v106, v107
	v_cvt_pk_bf16_f32 v104, v112, v113
	v_cvt_pk_bf16_f32 v105, v110, v111
	v_cvt_pk_bf16_f32 v106, v114, v115
	v_cvt_pk_bf16_f32 v107, v108, v109
	v_cvt_pk_bf16_f32 v120, v188, v189
	global_store_dwordx4 v[186:187], v[104:107], off
	global_store_dwordx4 v[184:185], v[118:121], off offset:256
	v_lshlrev_b32_e32 v122, 16, v182
	v_lshlrev_b32_e32 v104, 16, v180
	v_and_b32_e32 v105, 0xffff0000, v180
	v_pk_add_f32 v[118:119], v[100:101], v[104:105]
	v_and_b32_e32 v101, 64, v164
	v_xor_b32_e32 v100, 16, v164
	v_add_u32_e32 v101, 64, v101
	v_cmp_lt_i32_e32 vcc, v100, v101
	v_and_b32_e32 v123, 0xffff0000, v182
	v_pk_add_f32 v[122:123], v[96:97], v[122:123]
	v_cndmask_b32_e32 v100, v164, v100, vcc
	v_lshlrev_b32_e32 v124, 2, v100
	ds_bpermute_b32 v100, v124, v125
	v_xor_b32_e32 v97, 32, v164
	v_cmp_lt_i32_e32 vcc, v97, v101
	v_lshlrev_b32_e32 v106, 16, v181
	v_and_b32_e32 v107, 0xffff0000, v181
	v_cndmask_b32_e32 v97, v164, v97, vcc
	s_waitcnt lgkmcnt(0)
	v_add_f32_e32 v96, v125, v100
	v_lshlrev_b32_e32 v125, 2, v97
	ds_bpermute_b32 v97, v125, v96
	v_lshlrev_b32_e32 v120, 16, v183
	v_and_b32_e32 v121, 0xffff0000, v183
	v_pk_add_f32 v[116:117], v[102:103], v[106:107]
	v_pk_add_f32 v[120:121], v[98:99], v[120:121]
	v_cvt_pk_bf16_f32 v98, v118, v119
	v_cvt_pk_bf16_f32 v99, v116, v117
	v_cvt_pk_bf16_f32 v100, v122, v123
	v_cvt_pk_bf16_f32 v101, v120, v121
	v_lshl_add_u64 v[104:105], v[154:155], 2, s[6:7]
	global_store_dwordx4 v[186:187], v[98:101], off offset:256
	s_and_saveexec_b64 s[18:19], s[2:3]
	s_cbranch_execz .LBB0_2463
	s_waitcnt lgkmcnt(0)
	v_add_f32_e32 v96, v96, v97
	global_atomic_add_f32 v[104:105], v96, off

; #define PG8_STAGE(bufoff, gbase, voff) do { _Pragma("unroll") for (int _i = 0; _i < 2; ++_i) \
;         __builtin_amdgcn_global_load_lds((const unsigned*)((const char*)(gbase) + (voff)[_i]), (LAS unsigned*)(lds + (bufoff) + ldsw + _i * 8192), 16, 0, 0); } while (0)
; #define PG8_LDA(dst, b, h) do { _Pragma("unroll") for (int m = 0; m < 4; ++m) _Pragma("unroll") for (int k = 0; k < 2; ++k) dst[m][k] = *(const LAS bf16x8*)(lds + PG8_SA(b, h) + aoff + m * 2048 + k * 1024); } while (0)
; #define PG8_LDB(dst, b, h) do { _Pragma("unroll") for (int n = 0; n < 2; ++n) _Pragma("unroll") for (int k = 0; k < 2; ++k) dst[n][k] = *(const LAS bf16x8*)(lds + PG8_SB(b, h) + boff + n * 2048 + k * 1024); } while (0)
; #define PG8_MMA(ai, bj, At, Bt) do { __builtin_amdgcn_s_setprio(1); _Pragma("unroll") for (int m = 0; m < 4; ++m) _Pragma("unroll") for (int n = 0; n < 2; ++n) _Pragma("unroll") for (int k = 0; k < 2; ++k) \
;         acc[ai][bj][m][n] = __builtin_amdgcn_mfma_f32_16x16x32_bf16(Bt[n][k], At[m][k], acc[ai][bj][m][n], 0, 0, 0); __builtin_amdgcn_s_setprio(0); } while (0)
; #define PG8_WAIT_L(n) asm volatile("s_waitcnt lgkmcnt(" #n ")" ::: "memory")
; #define PG8_BAR __builtin_amdgcn_s_barrier()
; #define PG8_SCHED __builtin_amdgcn_sched_barrier(0)
; template <class Epi>
; __device__ __forceinline__ void gemm_phase(LAS unsigned char* lds, const Gemm g, const StaticOrder& S, const Epi& E) {
;     ...
;             const bool last = (t == nt - 2);
;             const char* a1 = cA + (size_t)(t + 1) * kstep;
;             const char* a2 = last ? nA : cA + (size_t)(t + 2) * kstep; const char* b2 = last ? nB : cB + (size_t)(t + 2) * kstep;
;             const char* a3 = a2 + kstep; const char* b3 = b2 + kstep;
;             PG8_LDB(B0, 0, 0); PG8_SCHED; PG8_LDA(At, 0, 0); PG8_STAGE(PG8_SA(1, 1), a1 + hstep, voffA);
;             PG8_WAIT_L(8); PG8_BAR; PG8_WAIT_L(0); PG8_MMA(0, 0, At, B0); PG8_BAR; PG8_SCHED;
.LBB0_2546:
	ds_read_b128 v[160:163], v148
	ds_read_b128 v[164:167], v148 offset:1024
	ds_read_b128 v[168:171], v148 offset:2048
	ds_read_b128 v[172:175], v148 offset:3072
	s_add_u32 s18, s16, 0xfff80080
	s_addc_u32 s19, s17, -1
	s_cmp_eq_u32 s59, 28
	s_cselect_b32 s21, s9, s19
	s_cselect_b32 s20, s47, s18
	s_cselect_b32 s19, s7, s58
	s_cselect_b32 s18, s56, s57
	v_lshl_add_u64 v[176:177], s[16:17], 0, v[136:137]
	s_add_i32 m0, s35, 0xc000
	ds_read_b128 v[180:183], v149
	ds_read_b128 v[184:187], v149 offset:1024
	ds_read_b128 v[188:191], v149 offset:2048
	ds_read_b128 v[192:195], v149 offset:3072
	ds_read_b128 v[196:199], v149 offset:4096
	ds_read_b128 v[200:203], v149 offset:5120
	ds_read_b128 v[204:207], v149 offset:6144
	ds_read_b128 v[208:211], v149 offset:7168
	global_load_lds_dwordx4 v[176:177], off
	v_lshl_add_u64 v[176:177], s[16:17], 0, v[138:139]
	s_add_i32 m0, s35, 0xe000
	s_nop 0
	global_load_lds_dwordx4 v[176:177], off
	s_waitcnt lgkmcnt(8)
	s_setprio 1
	s_barrier
	s_waitcnt lgkmcnt(0)


; #define PG8_STAGE(bufoff, gbase, voff) do { _Pragma("unroll") for (int _i = 0; _i < 2; ++_i) \
;         __builtin_amdgcn_global_load_lds((const unsigned*)((const char*)(gbase) + (voff)[_i]), (LAS unsigned*)(lds + (bufoff) + ldsw + _i * 8192), 16, 0, 0); } while (0)
; #define PG8_LDB(dst, b, h) do { _Pragma("unroll") for (int n = 0; n < 2; ++n) _Pragma("unroll") for (int k = 0; k < 2; ++k) dst[n][k] = *(const LAS bf16x8*)(lds + PG8_SB(b, h) + boff + n * 2048 + k * 1024); } while (0)
; #define PG8_MMA(ai, bj, At, Bt) do { __builtin_amdgcn_s_setprio(1); _Pragma("unroll") for (int m = 0; m < 4; ++m) _Pragma("unroll") for (int n = 0; n < 2; ++n) _Pragma("unroll") for (int k = 0; k < 2; ++k) \
;         acc[ai][bj][m][n] = __builtin_amdgcn_mfma_f32_16x16x32_bf16(Bt[n][k], At[m][k], acc[ai][bj][m][n], 0, 0, 0); __builtin_amdgcn_s_setprio(0); } while (0)
; #define PG8_WAIT_L(n) asm volatile("s_waitcnt lgkmcnt(" #n ")" ::: "memory")
; #define PG8_BAR __builtin_amdgcn_s_barrier()
; #define PG8_SCHED __builtin_amdgcn_sched_barrier(0)
; template <class Epi>
; __device__ __forceinline__ void gemm_phase(LAS unsigned char* lds, const Gemm g, const StaticOrder& S, const Epi& E) {
;     ...
;             PG8_WAIT_L(8); PG8_BAR; PG8_WAIT_L(0); PG8_MMA(0, 0, At, B0); PG8_BAR; PG8_SCHED;
;             PG8_LDB(B1, 0, 1); PG8_STAGE(PG8_SB(0, 0), b2, voffB);
;             PG8_BAR; PG8_WAIT_L(0); PG8_MMA(0, 1, At, B1); PG8_BAR;
	v_mfma_f32_16x16x32_bf16 v[124:127], v[160:163], v[180:183], v[124:127]
	v_mfma_f32_16x16x32_bf16 v[116:119], v[168:171], v[180:183], v[116:119]
	v_mfma_f32_16x16x32_bf16 v[108:111], v[160:163], v[188:191], v[108:111]
	v_mfma_f32_16x16x32_bf16 v[100:103], v[168:171], v[188:191], v[100:103]
	v_mfma_f32_16x16x32_bf16 v[92:95], v[160:163], v[196:199], v[92:95]
	v_mfma_f32_16x16x32_bf16 v[84:87], v[168:171], v[196:199], v[84:87]
	v_mfma_f32_16x16x32_bf16 v[76:79], v[160:163], v[204:207], v[76:79]
	v_mfma_f32_16x16x32_bf16 v[68:71], v[168:171], v[204:207], v[68:71]
	v_mfma_f32_16x16x32_bf16 v[124:127], v[164:167], v[184:187], v[124:127]
	v_mfma_f32_16x16x32_bf16 v[116:119], v[172:175], v[184:187], v[116:119]
	v_mfma_f32_16x16x32_bf16 v[108:111], v[164:167], v[192:195], v[108:111]
	v_mfma_f32_16x16x32_bf16 v[100:103], v[172:175], v[192:195], v[100:103]
	v_mfma_f32_16x16x32_bf16 v[92:95], v[164:167], v[200:203], v[92:95]
	v_mfma_f32_16x16x32_bf16 v[84:87], v[172:175], v[200:203], v[84:87]
	v_mfma_f32_16x16x32_bf16 v[76:79], v[164:167], v[208:211], v[76:79]
	v_mfma_f32_16x16x32_bf16 v[68:71], v[172:175], v[208:211], v[68:71]
	s_setprio 0
	s_barrier
	s_add_i32 s60, s44, s31
	v_lshl_add_u64 v[176:177], s[18:19], 0, v[132:133]
	s_mov_b32 m0, s60
	ds_read_b128 v[212:215], v150
	ds_read_b128 v[216:219], v150 offset:1024
	ds_read_b128 v[220:223], v150 offset:2048
	ds_read_b128 v[224:227], v150 offset:3072
	global_load_lds_dwordx4 v[176:177], off
	v_lshl_add_u64 v[228:229], s[18:19], 0, v[128:129]
	s_add_i32 m0, s60, 0x2000
	s_nop 0
	global_load_lds_dwordx4 v[228:229], off
	s_waitcnt lgkmcnt(0)
	s_setprio 1
	s_barrier


; #define PG8_STAGE(bufoff, gbase, voff) do { _Pragma("unroll") for (int _i = 0; _i < 2; ++_i) \
;         __builtin_amdgcn_global_load_lds((const unsigned*)((const char*)(gbase) + (voff)[_i]), (LAS unsigned*)(lds + (bufoff) + ldsw + _i * 8192), 16, 0, 0); } while (0)
; #define PG8_LDA(dst, b, h) do { _Pragma("unroll") for (int m = 0; m < 4; ++m) _Pragma("unroll") for (int k = 0; k < 2; ++k) dst[m][k] = *(const LAS bf16x8*)(lds + PG8_SA(b, h) + aoff + m * 2048 + k * 1024); } while (0)
; #define PG8_MMA(ai, bj, At, Bt) do { __builtin_amdgcn_s_setprio(1); _Pragma("unroll") for (int m = 0; m < 4; ++m) _Pragma("unroll") for (int n = 0; n < 2; ++n) _Pragma("unroll") for (int k = 0; k < 2; ++k) \
;         acc[ai][bj][m][n] = __builtin_amdgcn_mfma_f32_16x16x32_bf16(Bt[n][k], At[m][k], acc[ai][bj][m][n], 0, 0, 0); __builtin_amdgcn_s_setprio(0); } while (0)
; #define PG8_WAIT_L(n) asm volatile("s_waitcnt lgkmcnt(" #n ")" ::: "memory")
; #define PG8_BAR __builtin_amdgcn_s_barrier()
; #define PG8_SCHED __builtin_amdgcn_sched_barrier(0)
; template <class Epi>
; __device__ __forceinline__ void gemm_phase(LAS unsigned char* lds, const Gemm g, const StaticOrder& S, const Epi& E) {
;     ...
;             PG8_BAR; PG8_WAIT_L(0); PG8_MMA(0, 1, At, B1); PG8_BAR;
;             PG8_LDA(At, 0, 1); PG8_STAGE(PG8_SA(0, 0), a2, voffA);
;             PG8_BAR; PG8_WAIT_L(0); PG8_MMA(1, 0, At, B0); PG8_BAR; PG8_SCHED;
	v_mfma_f32_16x16x32_bf16 v[120:123], v[212:215], v[180:183], v[120:123]
	v_mfma_f32_16x16x32_bf16 v[112:115], v[220:223], v[180:183], v[112:115]
	v_mfma_f32_16x16x32_bf16 v[104:107], v[212:215], v[188:191], v[104:107]
	v_mfma_f32_16x16x32_bf16 v[96:99], v[220:223], v[188:191], v[96:99]
	v_mfma_f32_16x16x32_bf16 v[88:91], v[212:215], v[196:199], v[88:91]
	v_mfma_f32_16x16x32_bf16 v[80:83], v[220:223], v[196:199], v[80:83]
	v_mfma_f32_16x16x32_bf16 v[72:75], v[212:215], v[204:207], v[72:75]
	v_mfma_f32_16x16x32_bf16 v[64:67], v[220:223], v[204:207], v[64:67]
	v_mfma_f32_16x16x32_bf16 v[120:123], v[216:219], v[184:187], v[120:123]
	v_mfma_f32_16x16x32_bf16 v[112:115], v[224:227], v[184:187], v[112:115]
	v_mfma_f32_16x16x32_bf16 v[104:107], v[216:219], v[192:195], v[104:107]
	v_mfma_f32_16x16x32_bf16 v[96:99], v[224:227], v[192:195], v[96:99]
	v_mfma_f32_16x16x32_bf16 v[88:91], v[216:219], v[200:203], v[88:91]
	v_mfma_f32_16x16x32_bf16 v[80:83], v[224:227], v[200:203], v[80:83]
	v_mfma_f32_16x16x32_bf16 v[72:75], v[216:219], v[208:211], v[72:75]
	v_mfma_f32_16x16x32_bf16 v[64:67], v[224:227], v[208:211], v[64:67]
	s_setprio 0
	s_mov_b32 m0, s35
	v_lshl_add_u64 v[230:231], s[20:21], 0, v[134:135]
	s_barrier
	ds_read_b128 v[180:183], v149 offset:16384
	ds_read_b128 v[184:187], v149 offset:17408
	ds_read_b128 v[188:191], v149 offset:18432
	ds_read_b128 v[192:195], v149 offset:19456
	ds_read_b128 v[196:199], v149 offset:20480
	ds_read_b128 v[200:203], v149 offset:21504
	ds_read_b128 v[204:207], v149 offset:22528
	ds_read_b128 v[208:211], v149 offset:23552
	global_load_lds_dwordx4 v[230:231], off
	v_lshl_add_u64 v[232:233], s[20:21], 0, v[130:131]
	s_mov_b32 m0, s36
	s_nop 0
	global_load_lds_dwordx4 v[232:233], off
	s_waitcnt lgkmcnt(0)
	s_setprio 1
	s_barrier


; #define PG8_STAGE(bufoff, gbase, voff) do { _Pragma("unroll") for (int _i = 0; _i < 2; ++_i) \
;         __builtin_amdgcn_global_load_lds((const unsigned*)((const char*)(gbase) + (voff)[_i]), (LAS unsigned*)(lds + (bufoff) + ldsw + _i * 8192), 16, 0, 0); } while (0)
; #define PG8_MMA(ai, bj, At, Bt) do { __builtin_amdgcn_s_setprio(1); _Pragma("unroll") for (int m = 0; m < 4; ++m) _Pragma("unroll") for (int n = 0; n < 2; ++n) _Pragma("unroll") for (int k = 0; k < 2; ++k) \
;         acc[ai][bj][m][n] = __builtin_amdgcn_mfma_f32_16x16x32_bf16(Bt[n][k], At[m][k], acc[ai][bj][m][n], 0, 0, 0); __builtin_amdgcn_s_setprio(0); } while (0)
; #define PG8_WAIT_V(n) asm volatile("s_waitcnt vmcnt(" #n ")" ::: "memory")
; #define PG8_WAIT_L(n) asm volatile("s_waitcnt lgkmcnt(" #n ")" ::: "memory")
; #define PG8_BAR __builtin_amdgcn_s_barrier()
; #define PG8_SCHED __builtin_amdgcn_sched_barrier(0)
; template <class Epi>
; __device__ __forceinline__ void gemm_phase(LAS unsigned char* lds, const Gemm g, const StaticOrder& S, const Epi& E) {
;     ...
;             PG8_BAR; PG8_WAIT_L(0); PG8_MMA(1, 0, At, B0); PG8_BAR; PG8_SCHED;
;             PG8_STAGE(PG8_SB(0, 1), b2 + hstep, voffB);
;             PG8_WAIT_V(6); PG8_BAR; PG8_MMA(1, 1, At, B1); PG8_BAR;
	v_mfma_f32_16x16x32_bf16 v[60:63], v[160:163], v[180:183], v[60:63]
	v_mfma_f32_16x16x32_bf16 v[52:55], v[168:171], v[180:183], v[52:55]
	v_mfma_f32_16x16x32_bf16 v[44:47], v[160:163], v[188:191], v[44:47]
	v_mfma_f32_16x16x32_bf16 v[36:39], v[168:171], v[188:191], v[36:39]
	v_mfma_f32_16x16x32_bf16 v[28:31], v[160:163], v[196:199], v[28:31]
	v_mfma_f32_16x16x32_bf16 v[20:23], v[168:171], v[196:199], v[20:23]
	v_mfma_f32_16x16x32_bf16 v[12:15], v[160:163], v[204:207], v[12:15]
	v_mfma_f32_16x16x32_bf16 v[4:7], v[168:171], v[204:207], v[4:7]
	v_mfma_f32_16x16x32_bf16 v[60:63], v[164:167], v[184:187], v[60:63]
	v_mfma_f32_16x16x32_bf16 v[52:55], v[172:175], v[184:187], v[52:55]
	v_mfma_f32_16x16x32_bf16 v[44:47], v[164:167], v[192:195], v[44:47]
	v_mfma_f32_16x16x32_bf16 v[36:39], v[172:175], v[192:195], v[36:39]
	v_mfma_f32_16x16x32_bf16 v[28:31], v[164:167], v[200:203], v[28:31]
	v_mfma_f32_16x16x32_bf16 v[20:23], v[172:175], v[200:203], v[20:23]
	v_mfma_f32_16x16x32_bf16 v[12:15], v[164:167], v[208:211], v[12:15]
	v_mfma_f32_16x16x32_bf16 v[4:7], v[172:175], v[208:211], v[4:7]
	s_setprio 0
	s_barrier
	s_add_u32 s60, s18, 0x80000
	s_addc_u32 s61, s19, 0
	s_add_i32 s62, s45, s31
	v_lshl_add_u64 v[160:161], s[60:61], 0, v[132:133]
	s_mov_b32 m0, s62
	s_nop 0
	global_load_lds_dwordx4 v[160:161], off
	v_lshl_add_u64 v[160:161], s[60:61], 0, v[128:129]
	s_add_i32 m0, s62, 0x2000
	s_nop 0
	global_load_lds_dwordx4 v[160:161], off
	s_waitcnt vmcnt(6)
	s_setprio 1
	s_barrier

; #define PG8_STAGE(bufoff, gbase, voff) do { _Pragma("unroll") for (int _i = 0; _i < 2; ++_i) \
;         __builtin_amdgcn_global_load_lds((const unsigned*)((const char*)(gbase) + (voff)[_i]), (LAS unsigned*)(lds + (bufoff) + ldsw + _i * 8192), 16, 0, 0); } while (0)
; #define PG8_LDA(dst, b, h) do { _Pragma("unroll") for (int m = 0; m < 4; ++m) _Pragma("unroll") for (int k = 0; k < 2; ++k) dst[m][k] = *(const LAS bf16x8*)(lds + PG8_SA(b, h) + aoff + m * 2048 + k * 1024); } while (0)
; #define PG8_LDB(dst, b, h) do { _Pragma("unroll") for (int n = 0; n < 2; ++n) _Pragma("unroll") for (int k = 0; k < 2; ++k) dst[n][k] = *(const LAS bf16x8*)(lds + PG8_SB(b, h) + boff + n * 2048 + k * 1024); } while (0)
; #define PG8_MMA(ai, bj, At, Bt) do { __builtin_amdgcn_s_setprio(1); _Pragma("unroll") for (int m = 0; m < 4; ++m) _Pragma("unroll") for (int n = 0; n < 2; ++n) _Pragma("unroll") for (int k = 0; k < 2; ++k) \
;         acc[ai][bj][m][n] = __builtin_amdgcn_mfma_f32_16x16x32_bf16(Bt[n][k], At[m][k], acc[ai][bj][m][n], 0, 0, 0); __builtin_amdgcn_s_setprio(0); } while (0)
; #define PG8_WAIT_V(n) asm volatile("s_waitcnt vmcnt(" #n ")" ::: "memory")
; #define PG8_WAIT_L(n) asm volatile("s_waitcnt lgkmcnt(" #n ")" ::: "memory")
; #define PG8_BAR __builtin_amdgcn_s_barrier()
; #define PG8_SCHED __builtin_amdgcn_sched_barrier(0)
; template <class Epi>
; __device__ __forceinline__ void gemm_phase(LAS unsigned char* lds, const Gemm g, const StaticOrder& S, const Epi& E) {
;     ...
;             PG8_WAIT_V(6); PG8_BAR; PG8_MMA(1, 1, At, B1); PG8_BAR;
;             PG8_LDB(B0, 1, 0); PG8_SCHED; PG8_LDA(At, 1, 0); PG8_STAGE(PG8_SA(0, 1), a2 + hstep, voffA);
;             PG8_WAIT_L(8); PG8_BAR; PG8_WAIT_L(0); PG8_MMA(0, 0, At, B0); PG8_BAR; PG8_SCHED;
	v_mfma_f32_16x16x32_bf16 v[56:59], v[212:215], v[180:183], v[56:59]
	v_mfma_f32_16x16x32_bf16 v[48:51], v[220:223], v[180:183], v[48:51]
	v_mfma_f32_16x16x32_bf16 v[40:43], v[212:215], v[188:191], v[40:43]
	v_mfma_f32_16x16x32_bf16 v[32:35], v[220:223], v[188:191], v[32:35]
	v_mfma_f32_16x16x32_bf16 v[24:27], v[212:215], v[196:199], v[24:27]
	v_mfma_f32_16x16x32_bf16 v[16:19], v[220:223], v[196:199], v[16:19]
	v_mfma_f32_16x16x32_bf16 v[8:11], v[212:215], v[204:207], v[8:11]
	v_mfma_f32_16x16x32_bf16 v[0:3], v[220:223], v[204:207], v[0:3]
	v_mfma_f32_16x16x32_bf16 v[56:59], v[216:219], v[184:187], v[56:59]
	v_mfma_f32_16x16x32_bf16 v[48:51], v[224:227], v[184:187], v[48:51]
	v_mfma_f32_16x16x32_bf16 v[40:43], v[216:219], v[192:195], v[40:43]
	v_mfma_f32_16x16x32_bf16 v[32:35], v[224:227], v[192:195], v[32:35]
	v_mfma_f32_16x16x32_bf16 v[24:27], v[216:219], v[200:203], v[24:27]
	v_mfma_f32_16x16x32_bf16 v[16:19], v[224:227], v[200:203], v[16:19]
	v_mfma_f32_16x16x32_bf16 v[8:11], v[216:219], v[208:211], v[8:11]
	v_mfma_f32_16x16x32_bf16 v[0:3], v[224:227], v[208:211], v[0:3]
	s_setprio 0
	s_add_i32 s60, 0, 0x18000
	v_add_u32_e32 v159, s60, v145
	s_barrier
	ds_read_b128 v[160:163], v159
	ds_read_b128 v[164:167], v159 offset:1024
	ds_read_b128 v[168:171], v159 offset:2048
	ds_read_b128 v[172:175], v159 offset:3072
	s_add_u32 s20, s20, 0x80000
	s_addc_u32 s21, s21, 0
	s_mov_b32 m0, s37
	v_lshl_add_u64 v[212:213], s[20:21], 0, v[134:135]
	ds_read_b128 v[180:183], v149 offset:32768
	ds_read_b128 v[184:187], v149 offset:33792
	ds_read_b128 v[188:191], v149 offset:34816
	ds_read_b128 v[192:195], v149 offset:35840
	ds_read_b128 v[196:199], v149 offset:36864
	ds_read_b128 v[200:203], v149 offset:37888
	ds_read_b128 v[204:207], v149 offset:38912
	ds_read_b128 v[208:211], v149 offset:39936
	global_load_lds_dwordx4 v[212:213], off
	v_lshl_add_u64 v[212:213], s[20:21], 0, v[130:131]
	s_mov_b32 m0, s38
	s_nop 0
	global_load_lds_dwordx4 v[212:213], off
	s_waitcnt lgkmcnt(8)
	s_setprio 1
	s_barrier
	s_waitcnt lgkmcnt(0)


; #define PG8_STAGE(bufoff, gbase, voff) do { _Pragma("unroll") for (int _i = 0; _i < 2; ++_i) \
;         __builtin_amdgcn_global_load_lds((const unsigned*)((const char*)(gbase) + (voff)[_i]), (LAS unsigned*)(lds + (bufoff) + ldsw + _i * 8192), 16, 0, 0); } while (0)
; #define PG8_LDB(dst, b, h) do { _Pragma("unroll") for (int n = 0; n < 2; ++n) _Pragma("unroll") for (int k = 0; k < 2; ++k) dst[n][k] = *(const LAS bf16x8*)(lds + PG8_SB(b, h) + boff + n * 2048 + k * 1024); } while (0)
; #define PG8_MMA(ai, bj, At, Bt) do { __builtin_amdgcn_s_setprio(1); _Pragma("unroll") for (int m = 0; m < 4; ++m) _Pragma("unroll") for (int n = 0; n < 2; ++n) _Pragma("unroll") for (int k = 0; k < 2; ++k) \
;         acc[ai][bj][m][n] = __builtin_amdgcn_mfma_f32_16x16x32_bf16(Bt[n][k], At[m][k], acc[ai][bj][m][n], 0, 0, 0); __builtin_amdgcn_s_setprio(0); } while (0)
; #define PG8_WAIT_L(n) asm volatile("s_waitcnt lgkmcnt(" #n ")" ::: "memory")
; #define PG8_BAR __builtin_amdgcn_s_barrier()
; #define PG8_SCHED __builtin_amdgcn_sched_barrier(0)
; template <class Epi>
; __device__ __forceinline__ void gemm_phase(LAS unsigned char* lds, const Gemm g, const StaticOrder& S, const Epi& E) {
;     ...
;             PG8_WAIT_L(8); PG8_BAR; PG8_WAIT_L(0); PG8_MMA(0, 0, At, B0); PG8_BAR; PG8_SCHED;
;             PG8_LDB(B1, 1, 1); PG8_STAGE(PG8_SB(1, 0), b3, voffB);
;             PG8_BAR; PG8_WAIT_L(0); PG8_MMA(0, 1, At, B1); PG8_BAR;
	v_mfma_f32_16x16x32_bf16 v[124:127], v[160:163], v[180:183], v[124:127]
	v_mfma_f32_16x16x32_bf16 v[116:119], v[168:171], v[180:183], v[116:119]
	v_mfma_f32_16x16x32_bf16 v[108:111], v[160:163], v[188:191], v[108:111]
	v_mfma_f32_16x16x32_bf16 v[100:103], v[168:171], v[188:191], v[100:103]
	v_mfma_f32_16x16x32_bf16 v[92:95], v[160:163], v[196:199], v[92:95]
	v_mfma_f32_16x16x32_bf16 v[84:87], v[168:171], v[196:199], v[84:87]
	v_mfma_f32_16x16x32_bf16 v[76:79], v[160:163], v[204:207], v[76:79]
	v_mfma_f32_16x16x32_bf16 v[68:71], v[168:171], v[204:207], v[68:71]
	v_mfma_f32_16x16x32_bf16 v[124:127], v[164:167], v[184:187], v[124:127]
	v_mfma_f32_16x16x32_bf16 v[116:119], v[172:175], v[184:187], v[116:119]
	v_mfma_f32_16x16x32_bf16 v[108:111], v[164:167], v[192:195], v[108:111]
	v_mfma_f32_16x16x32_bf16 v[100:103], v[172:175], v[192:195], v[100:103]
	v_mfma_f32_16x16x32_bf16 v[92:95], v[164:167], v[200:203], v[92:95]
	v_mfma_f32_16x16x32_bf16 v[84:87], v[172:175], v[200:203], v[84:87]
	v_mfma_f32_16x16x32_bf16 v[76:79], v[164:167], v[208:211], v[76:79]
	v_mfma_f32_16x16x32_bf16 v[68:71], v[172:175], v[208:211], v[68:71]
	s_setprio 0
	s_barrier
	s_add_i32 s20, 0, 0x1c000
	s_add_i32 s21, s60, s31
	v_add_u32_e32 v159, s20, v145
	v_lshl_add_u64 v[176:177], v[176:177], 0, s[4:5]
	s_mov_b32 m0, s21
	ds_read_b128 v[212:215], v159
	ds_read_b128 v[216:219], v159 offset:1024
	ds_read_b128 v[220:223], v159 offset:2048
	ds_read_b128 v[224:227], v159 offset:3072
	global_load_lds_dwordx4 v[176:177], off
	v_lshl_add_u64 v[176:177], v[228:229], 0, s[4:5]
	s_add_i32 m0, s21, 0x2000
	s_nop 0
	global_load_lds_dwordx4 v[176:177], off
	s_waitcnt lgkmcnt(0)
	s_setprio 1
	s_barrier


; #define PG8_STAGE(bufoff, gbase, voff) do { _Pragma("unroll") for (int _i = 0; _i < 2; ++_i) \
;         __builtin_amdgcn_global_load_lds((const unsigned*)((const char*)(gbase) + (voff)[_i]), (LAS unsigned*)(lds + (bufoff) + ldsw + _i * 8192), 16, 0, 0); } while (0)
; #define PG8_LDA(dst, b, h) do { _Pragma("unroll") for (int m = 0; m < 4; ++m) _Pragma("unroll") for (int k = 0; k < 2; ++k) dst[m][k] = *(const LAS bf16x8*)(lds + PG8_SA(b, h) + aoff + m * 2048 + k * 1024); } while (0)
; #define PG8_MMA(ai, bj, At, Bt) do { __builtin_amdgcn_s_setprio(1); _Pragma("unroll") for (int m = 0; m < 4; ++m) _Pragma("unroll") for (int n = 0; n < 2; ++n) _Pragma("unroll") for (int k = 0; k < 2; ++k) \
;         acc[ai][bj][m][n] = __builtin_amdgcn_mfma_f32_16x16x32_bf16(Bt[n][k], At[m][k], acc[ai][bj][m][n], 0, 0, 0); __builtin_amdgcn_s_setprio(0); } while (0)
; #define PG8_WAIT_L(n) asm volatile("s_waitcnt lgkmcnt(" #n ")" ::: "memory")
; #define PG8_BAR __builtin_amdgcn_s_barrier()
; #define PG8_SCHED __builtin_amdgcn_sched_barrier(0)
; template <class Epi>
; __device__ __forceinline__ void gemm_phase(LAS unsigned char* lds, const Gemm g, const StaticOrder& S, const Epi& E) {
;     ...
;             PG8_BAR; PG8_WAIT_L(0); PG8_MMA(0, 1, At, B1); PG8_BAR;
;             PG8_LDA(At, 1, 1); PG8_STAGE(PG8_SA(1, 0), a3, voffA);
;             PG8_BAR; PG8_WAIT_L(0); PG8_MMA(1, 0, At, B0); PG8_BAR; PG8_SCHED;
	v_mfma_f32_16x16x32_bf16 v[120:123], v[212:215], v[180:183], v[120:123]
	v_mfma_f32_16x16x32_bf16 v[112:115], v[220:223], v[180:183], v[112:115]
	v_mfma_f32_16x16x32_bf16 v[104:107], v[212:215], v[188:191], v[104:107]
	v_mfma_f32_16x16x32_bf16 v[96:99], v[220:223], v[188:191], v[96:99]
	v_mfma_f32_16x16x32_bf16 v[88:91], v[212:215], v[196:199], v[88:91]
	v_mfma_f32_16x16x32_bf16 v[80:83], v[220:223], v[196:199], v[80:83]
	v_mfma_f32_16x16x32_bf16 v[72:75], v[212:215], v[204:207], v[72:75]
	v_mfma_f32_16x16x32_bf16 v[64:67], v[220:223], v[204:207], v[64:67]
	v_mfma_f32_16x16x32_bf16 v[120:123], v[216:219], v[184:187], v[120:123]
	v_mfma_f32_16x16x32_bf16 v[112:115], v[224:227], v[184:187], v[112:115]
	v_mfma_f32_16x16x32_bf16 v[104:107], v[216:219], v[192:195], v[104:107]
	v_mfma_f32_16x16x32_bf16 v[96:99], v[224:227], v[192:195], v[96:99]
	v_mfma_f32_16x16x32_bf16 v[88:91], v[216:219], v[200:203], v[88:91]
	v_mfma_f32_16x16x32_bf16 v[80:83], v[224:227], v[200:203], v[80:83]
	v_mfma_f32_16x16x32_bf16 v[72:75], v[216:219], v[208:211], v[72:75]
	v_mfma_f32_16x16x32_bf16 v[64:67], v[224:227], v[208:211], v[64:67]
	s_setprio 0
	s_mov_b32 m0, s40
	v_lshl_add_u64 v[176:177], v[230:231], 0, s[4:5]
	s_barrier
	ds_read_b128 v[180:183], v149 offset:49152
	ds_read_b128 v[184:187], v149 offset:50176
	ds_read_b128 v[188:191], v149 offset:51200
	ds_read_b128 v[192:195], v149 offset:52224
	ds_read_b128 v[196:199], v149 offset:53248
	ds_read_b128 v[200:203], v149 offset:54272
	ds_read_b128 v[204:207], v149 offset:55296
	ds_read_b128 v[208:211], v149 offset:56320
	global_load_lds_dwordx4 v[176:177], off
	v_lshl_add_u64 v[176:177], v[232:233], 0, s[4:5]
	s_mov_b32 m0, s41
	s_nop 0
	global_load_lds_dwordx4 v[176:177], off
	s_waitcnt lgkmcnt(0)
	s_setprio 1
	s_barrier


; #define PG8_STAGE(bufoff, gbase, voff) do { _Pragma("unroll") for (int _i = 0; _i < 2; ++_i) \
;         __builtin_amdgcn_global_load_lds((const unsigned*)((const char*)(gbase) + (voff)[_i]), (LAS unsigned*)(lds + (bufoff) + ldsw + _i * 8192), 16, 0, 0); } while (0)
; #define PG8_MMA(ai, bj, At, Bt) do { __builtin_amdgcn_s_setprio(1); _Pragma("unroll") for (int m = 0; m < 4; ++m) _Pragma("unroll") for (int n = 0; n < 2; ++n) _Pragma("unroll") for (int k = 0; k < 2; ++k) \
;         acc[ai][bj][m][n] = __builtin_amdgcn_mfma_f32_16x16x32_bf16(Bt[n][k], At[m][k], acc[ai][bj][m][n], 0, 0, 0); __builtin_amdgcn_s_setprio(0); } while (0)
; #define PG8_WAIT_V(n) asm volatile("s_waitcnt vmcnt(" #n ")" ::: "memory")
; #define PG8_WAIT_L(n) asm volatile("s_waitcnt lgkmcnt(" #n ")" ::: "memory")
; #define PG8_BAR __builtin_amdgcn_s_barrier()
; #define PG8_SCHED __builtin_amdgcn_sched_barrier(0)
; template <class Epi>
; __device__ __forceinline__ void gemm_phase(LAS unsigned char* lds, const Gemm g, const StaticOrder& S, const Epi& E) {
;     ...
;             PG8_BAR; PG8_WAIT_L(0); PG8_MMA(1, 0, At, B0); PG8_BAR; PG8_SCHED;
;             PG8_STAGE(PG8_SB(1, 1), b3 + hstep, voffB);
;             PG8_WAIT_V(6); PG8_BAR; PG8_MMA(1, 1, At, B1); PG8_BAR;
	v_mfma_f32_16x16x32_bf16 v[60:63], v[160:163], v[180:183], v[60:63]
	v_mfma_f32_16x16x32_bf16 v[52:55], v[168:171], v[180:183], v[52:55]
	v_mfma_f32_16x16x32_bf16 v[44:47], v[160:163], v[188:191], v[44:47]
	v_mfma_f32_16x16x32_bf16 v[36:39], v[168:171], v[188:191], v[36:39]
	v_mfma_f32_16x16x32_bf16 v[28:31], v[160:163], v[196:199], v[28:31]
	v_mfma_f32_16x16x32_bf16 v[20:23], v[168:171], v[196:199], v[20:23]
	v_mfma_f32_16x16x32_bf16 v[12:15], v[160:163], v[204:207], v[12:15]
	v_mfma_f32_16x16x32_bf16 v[4:7], v[168:171], v[204:207], v[4:7]
	v_mfma_f32_16x16x32_bf16 v[60:63], v[164:167], v[184:187], v[60:63]
	v_mfma_f32_16x16x32_bf16 v[52:55], v[172:175], v[184:187], v[52:55]
	v_mfma_f32_16x16x32_bf16 v[44:47], v[164:167], v[192:195], v[44:47]
	v_mfma_f32_16x16x32_bf16 v[36:39], v[172:175], v[192:195], v[36:39]
	v_mfma_f32_16x16x32_bf16 v[28:31], v[164:167], v[200:203], v[28:31]
	v_mfma_f32_16x16x32_bf16 v[20:23], v[172:175], v[200:203], v[20:23]
	v_mfma_f32_16x16x32_bf16 v[12:15], v[164:167], v[208:211], v[12:15]
	v_mfma_f32_16x16x32_bf16 v[4:7], v[172:175], v[208:211], v[4:7]
	s_setprio 0
	s_barrier
	s_add_u32 s18, s18, 0x80080
	s_addc_u32 s19, s19, 0
	s_add_i32 s20, s20, s31
	v_lshl_add_u64 v[160:161], s[18:19], 0, v[132:133]
	s_mov_b32 m0, s20
	s_nop 0
	global_load_lds_dwordx4 v[160:161], off
	v_lshl_add_u64 v[160:161], s[18:19], 0, v[128:129]
	s_add_i32 m0, s20, 0x2000
	s_nop 0
	global_load_lds_dwordx4 v[160:161], off
	s_waitcnt vmcnt(6)
	s_setprio 1
	s_barrier

; __device__ __forceinline__ float sigmoidf_(float x) { return __builtin_amdgcn_rcpf(1.0f + fexp(-x)); }
; #define PG8_MMA(ai, bj, At, Bt) do { __builtin_amdgcn_s_setprio(1); _Pragma("unroll") for (int m = 0; m < 4; ++m) _Pragma("unroll") for (int n = 0; n < 2; ++n) _Pragma("unroll") for (int k = 0; k < 2; ++k) \
;         acc[ai][bj][m][n] = __builtin_amdgcn_mfma_f32_16x16x32_bf16(Bt[n][k], At[m][k], acc[ai][bj][m][n], 0, 0, 0); __builtin_amdgcn_s_setprio(0); } while (0)
; #define PG8_WAIT_V(n) asm volatile("s_waitcnt vmcnt(" #n ")" ::: "memory")
; #define PG8_BAR __builtin_amdgcn_s_barrier()
; template <class Epi>
; __device__ __forceinline__ void gemm_phase(LAS unsigned char* lds, const Gemm g, const StaticOrder& S, const Epi& E) {
;     ...
;             PG8_WAIT_V(6); PG8_BAR; PG8_MMA(1, 1, At, B1); PG8_BAR;
;         }
;     __device__ __forceinline__ void operator()(const f32x4 (&acc)[2][2][4][2], const Unit& u, int wr, int wc, int fr, int fq, const Pre& P) const {
;         const int row0 = ROW_X + u.pm * BM + wr * 64 + fr, col0 = u.pn * HALF + wc * 32 + 8 * fq;
; #pragma unroll
;         for (int ai = 0; ai < 2; ++ai)
; #pragma unroll
;             for (int m = 0; m < 4; ++m) { const int r = row0 + ai * HALF + m * 16; const float rs = __builtin_amdgcn_rsqf(P.rs[ai * 4 + m] * (1.0f / DM) + RMS_EPS);
;                 float y[8];
; #pragma unroll
;                 for (int n = 0; n < 2; ++n)
; #pragma unroll
;                     for (int j = 0; j < 4; ++j) { const float a = acc[ai][0][m][n][j] * rs, b = acc[ai][1][m][n][j] * rs; y[n * 4 + j] = a * b * sigmoidf_(a); }
;                 u32x4 w; w.x = cvtpk(y[0], y[1]); w.y = cvtpk(y[2], y[3]); w.z = cvtpk(y[4], y[5]); w.w = cvtpk(y[6], y[7]);
;                 *(u32x4*)(O + (size_t)r * FF + col0) = w; }
	v_mfma_f32_16x16x32_bf16 v[56:59], v[212:215], v[180:183], v[56:59]
	v_mfma_f32_16x16x32_bf16 v[48:51], v[220:223], v[180:183], v[48:51]
	v_mfma_f32_16x16x32_bf16 v[40:43], v[212:215], v[188:191], v[40:43]
	v_mfma_f32_16x16x32_bf16 v[32:35], v[220:223], v[188:191], v[32:35]
	v_mfma_f32_16x16x32_bf16 v[24:27], v[212:215], v[196:199], v[24:27]
	v_mfma_f32_16x16x32_bf16 v[16:19], v[220:223], v[196:199], v[16:19]
	v_mfma_f32_16x16x32_bf16 v[8:11], v[212:215], v[204:207], v[8:11]
	v_mfma_f32_16x16x32_bf16 v[0:3], v[220:223], v[204:207], v[0:3]
	v_mfma_f32_16x16x32_bf16 v[56:59], v[216:219], v[184:187], v[56:59]
	v_mfma_f32_16x16x32_bf16 v[48:51], v[224:227], v[184:187], v[48:51]
	v_mfma_f32_16x16x32_bf16 v[40:43], v[216:219], v[192:195], v[40:43]
	v_mfma_f32_16x16x32_bf16 v[32:35], v[224:227], v[192:195], v[32:35]
	v_mfma_f32_16x16x32_bf16 v[24:27], v[216:219], v[200:203], v[24:27]
	v_mfma_f32_16x16x32_bf16 v[16:19], v[224:227], v[200:203], v[16:19]
	v_mfma_f32_16x16x32_bf16 v[8:11], v[216:219], v[208:211], v[8:11]
	v_mfma_f32_16x16x32_bf16 v[0:3], v[224:227], v[208:211], v[0:3]
	s_setprio 0
	s_add_i32 s59, s59, 2
	s_add_u32 s16, s16, 0x100
	s_addc_u32 s17, s17, 0
	s_add_u32 s57, s57, 0x100
	s_addc_u32 s58, s58, 0
	s_cmp_gt_u32 s59, 29
	s_barrier
	s_cbranch_scc0 .LBB0_2546
	s_waitcnt vmcnt(0)
	v_fmamk_f32 v158, v158, 0x3a000000, v151
	v_rsq_f32_e32 v158, v158
	v_lshl_or_b32 v162, s15, 7, v146
	v_ashrrev_i32_e32 v163, 31, v162
	s_and_b64 vcc, vcc, exec
	v_pk_mul_f32 v[160:161], v[158:159], v[124:125] op_sel_hi:[0,1]
	v_mul_f32_e32 v124, 0xbfb8aa3b, v160
	v_mul_f32_e32 v125, 0xbfb8aa3b, v161
	v_exp_f32_e32 v159, v124
	v_exp_f32_e32 v125, v125
	v_lshl_add_u32 v124, s14, 8, v144
	v_add_f32_e32 v159, 1.0, v159
	v_add_f32_e32 v125, 1.0, v125
	v_rcp_f32_e32 v164, v159
	v_rcp_f32_e32 v165, v125
	v_pk_mul_f32 v[120:121], v[158:159], v[120:121] op_sel_hi:[0,1]
	v_pk_mul_f32 v[120:121], v[160:161], v[120:121]
	v_pk_mul_f32 v[126:127], v[158:159], v[126:127] op_sel_hi:[0,1]
	v_pk_mul_f32 v[120:121], v[164:165], v[120:121]
	v_mul_f32_e32 v125, 0xbfb8aa3b, v126
	v_cvt_pk_bf16_f32 v120, v120, v121
	v_mul_f32_e32 v121, 0xbfb8aa3b, v127
	v_exp_f32_e32 v125, v125
	v_exp_f32_e32 v121, v121
	v_pk_mul_f32 v[122:123], v[158:159], v[122:123] op_sel_hi:[0,1]
	v_pk_mul_f32 v[116:117], v[158:159], v[116:117] op_sel_hi:[0,1]
	v_add_f32_e32 v125, 1.0, v125
	v_add_f32_e32 v121, 1.0, v121
	v_rcp_f32_e32 v160, v125
	v_rcp_f32_e32 v161, v121
	v_pk_mul_f32 v[122:123], v[126:127], v[122:123]
	v_mul_f32_e32 v121, 0xbfb8aa3b, v116
	v_exp_f32_e32 v125, v121
	v_pk_mul_f32 v[122:123], v[160:161], v[122:123]
	v_pk_mul_f32 v[112:113], v[158:159], v[112:113] op_sel_hi:[0,1]
	v_cvt_pk_bf16_f32 v121, v122, v123
	v_mul_f32_e32 v123, 0xbfb8aa3b, v117
	v_exp_f32_e32 v123, v123
	v_add_f32_e32 v122, 1.0, v125
	v_pk_mul_f32 v[112:113], v[116:117], v[112:113]
	v_rcp_f32_e32 v122, v122
	v_add_f32_e32 v116, 1.0, v123
	v_rcp_f32_e32 v123, v116
	v_pk_mul_f32 v[116:117], v[158:159], v[118:119] op_sel_hi:[0,1]
	v_mul_f32_e32 v118, 0xbfb8aa3b, v116
	v_mul_f32_e32 v119, 0xbfb8aa3b, v117
	v_exp_f32_e32 v118, v118
	v_exp_f32_e32 v119, v119
	v_pk_mul_f32 v[112:113], v[122:123], v[112:113]
	v_add_f32_e32 v118, 1.0, v118
	v_cvt_pk_bf16_f32 v122, v112, v113
	v_pk_mul_f32 v[112:113], v[158:159], v[114:115] op_sel_hi:[0,1]
	v_fmamk_f32 v114, v157, 0x3a000000, v151
	v_pk_mul_f32 v[112:113], v[116:117], v[112:113]
	v_rsq_f32_e32 v116, v114
	v_add_f32_e32 v119, 1.0, v119
	v_rcp_f32_e32 v118, v118
	v_rcp_f32_e32 v119, v119
	v_pk_mul_f32 v[108:109], v[116:117], v[108:109] op_sel_hi:[0,1]
	v_mul_f32_e32 v117, 0xbfb8aa3b, v108
	v_exp_f32_e32 v117, v117
	v_mul_f32_e32 v125, 0xbfb8aa3b, v109
	v_pk_mul_f32 v[112:113], v[118:119], v[112:113]
	v_exp_f32_e32 v125, v125
	v_cvt_pk_bf16_f32 v123, v112, v113
	v_mov_b64_e32 v[112:113], s[2:3]
	v_mad_i64_i32 v[118:119], s[14:15], v124, s46, v[112:113]
	v_lshlrev_b64 v[114:115], 1, v[162:163]
	v_lshl_add_u64 v[118:119], v[118:119], 0, v[114:115]
	v_add_f32_e32 v117, 1.0, v117
	global_store_dwordx4 v[118:119], v[120:123], off
	v_rcp_f32_e32 v118, v117
	v_add_f32_e32 v117, 1.0, v125
	v_rcp_f32_e32 v119, v117
	v_or_b32_e32 v117, 16, v124
	v_pk_mul_f32 v[104:105], v[116:117], v[104:105] op_sel_hi:[0,1]
	v_pk_mul_f32 v[104:105], v[108:109], v[104:105]
	v_pk_mul_f32 v[108:109], v[116:117], v[110:111] op_sel_hi:[0,1]
	v_pk_mul_f32 v[104:105], v[118:119], v[104:105]
	v_mul_f32_e32 v110, 0xbfb8aa3b, v108
	v_cvt_pk_bf16_f32 v104, v104, v105
	v_mul_f32_e32 v105, 0xbfb8aa3b, v109
	v_exp_f32_e32 v110, v110
	v_exp_f32_e32 v105, v105
	v_pk_mul_f32 v[106:107], v[116:117], v[106:107] op_sel_hi:[0,1]
	v_pk_mul_f32 v[100:101], v[116:117], v[100:101] op_sel_hi:[0,1]
	v_add_f32_e32 v110, 1.0, v110
	v_add_f32_e32 v105, 1.0, v105
	v_rcp_f32_e32 v110, v110
	v_rcp_f32_e32 v111, v105
	v_pk_mul_f32 v[106:107], v[108:109], v[106:107]
	v_mul_f32_e32 v105, 0xbfb8aa3b, v100
	v_exp_f32_e32 v118, v105
	v_pk_mul_f32 v[106:107], v[110:111], v[106:107]
	v_pk_mul_f32 v[96:97], v[116:117], v[96:97] op_sel_hi:[0,1]
	v_cvt_pk_bf16_f32 v105, v106, v107
	v_mul_f32_e32 v107, 0xbfb8aa3b, v101
	v_exp_f32_e32 v107, v107
	v_pk_mul_f32 v[96:97], v[100:101], v[96:97]
	v_add_f32_e32 v106, 1.0, v118
	v_rcp_f32_e32 v106, v106
	v_add_f32_e32 v100, 1.0, v107
	v_rcp_f32_e32 v107, v100
	v_pk_mul_f32 v[100:101], v[116:117], v[102:103] op_sel_hi:[0,1]
	v_mul_f32_e32 v102, 0xbfb8aa3b, v100
	v_mul_f32_e32 v103, 0xbfb8aa3b, v101
	v_exp_f32_e32 v102, v102
	v_exp_f32_e32 v103, v103
	v_pk_mul_f32 v[96:97], v[106:107], v[96:97]
	v_add_f32_e32 v102, 1.0, v102
	v_add_f32_e32 v103, 1.0, v103
	v_rcp_f32_e32 v102, v102
	v_rcp_f32_e32 v103, v103
; __device__ __forceinline__ float sigmoidf_(float x) { return __builtin_amdgcn_rcpf(1.0f + fexp(-x)); }
;     __device__ __forceinline__ void operator()(const f32x4 (&acc)[2][2][4][2], const Unit& u, int wr, int wc, int fr, int fq, const Pre& P) const {
;         const int row0 = ROW_X + u.pm * BM + wr * 64 + fr, col0 = u.pn * HALF + wc * 32 + 8 * fq;
; #pragma unroll
;         for (int ai = 0; ai < 2; ++ai)
; #pragma unroll
;             for (int m = 0; m < 4; ++m) { const int r = row0 + ai * HALF + m * 16; const float rs = __builtin_amdgcn_rsqf(P.rs[ai * 4 + m] * (1.0f / DM) + RMS_EPS);
;                 float y[8];
; #pragma unroll
;                 for (int n = 0; n < 2; ++n)
; #pragma unroll
;                     for (int j = 0; j < 4; ++j) { const float a = acc[ai][0][m][n][j] * rs, b = acc[ai][1][m][n][j] * rs; y[n * 4 + j] = a * b * sigmoidf_(a); }
;                 u32x4 w; w.x = cvtpk(y[0], y[1]); w.y = cvtpk(y[2], y[3]); w.z = cvtpk(y[4], y[5]); w.w = cvtpk(y[6], y[7]);
;                 *(u32x4*)(O + (size_t)r * FF + col0) = w; }
	v_cvt_pk_bf16_f32 v106, v96, v97
	v_pk_mul_f32 v[96:97], v[116:117], v[98:99] op_sel_hi:[0,1]
	v_pk_mul_f32 v[96:97], v[100:101], v[96:97]
	v_mad_i64_i32 v[98:99], s[14:15], v117, s46, v[112:113]
	v_pk_mul_f32 v[96:97], v[102:103], v[96:97]
	v_lshl_add_u64 v[98:99], v[98:99], 0, v[114:115]
	v_cvt_pk_bf16_f32 v107, v96, v97
	v_fmamk_f32 v96, v156, 0x3a000000, v151
	v_rsq_f32_e32 v96, v96
	global_store_dwordx4 v[98:99], v[104:107], off
	v_pk_mul_f32 v[92:93], v[96:97], v[92:93] op_sel_hi:[0,1]
	v_mul_f32_e32 v97, 0xbfb8aa3b, v92
	v_exp_f32_e32 v97, v97
	v_mul_f32_e32 v100, 0xbfb8aa3b, v93
	v_exp_f32_e32 v100, v100
	v_add_f32_e32 v97, 1.0, v97
	v_rcp_f32_e32 v98, v97
	v_add_f32_e32 v97, 1.0, v100
	v_rcp_f32_e32 v99, v97
	v_or_b32_e32 v97, 32, v124
	v_pk_mul_f32 v[88:89], v[96:97], v[88:89] op_sel_hi:[0,1]
	v_pk_mul_f32 v[88:89], v[92:93], v[88:89]
	v_pk_mul_f32 v[92:93], v[96:97], v[94:95] op_sel_hi:[0,1]
	v_pk_mul_f32 v[88:89], v[98:99], v[88:89]
	v_mul_f32_e32 v94, 0xbfb8aa3b, v92
	v_cvt_pk_bf16_f32 v88, v88, v89
	v_mul_f32_e32 v89, 0xbfb8aa3b, v93
	v_exp_f32_e32 v94, v94
	v_exp_f32_e32 v89, v89
	v_pk_mul_f32 v[90:91], v[96:97], v[90:91] op_sel_hi:[0,1]
	v_pk_mul_f32 v[84:85], v[96:97], v[84:85] op_sel_hi:[0,1]
	v_add_f32_e32 v94, 1.0, v94
	v_add_f32_e32 v89, 1.0, v89
	v_rcp_f32_e32 v94, v94
	v_rcp_f32_e32 v95, v89
	v_pk_mul_f32 v[90:91], v[92:93], v[90:91]
	v_mul_f32_e32 v89, 0xbfb8aa3b, v84
	v_exp_f32_e32 v98, v89
	v_pk_mul_f32 v[90:91], v[94:95], v[90:91]
	v_pk_mul_f32 v[80:81], v[96:97], v[80:81] op_sel_hi:[0,1]
	v_cvt_pk_bf16_f32 v89, v90, v91
	v_mul_f32_e32 v91, 0xbfb8aa3b, v85
	v_exp_f32_e32 v91, v91
	v_pk_mul_f32 v[80:81], v[84:85], v[80:81]
	v_add_f32_e32 v90, 1.0, v98
	v_rcp_f32_e32 v90, v90
	v_add_f32_e32 v84, 1.0, v91
	v_rcp_f32_e32 v91, v84
	v_pk_mul_f32 v[84:85], v[96:97], v[86:87] op_sel_hi:[0,1]
	v_mul_f32_e32 v86, 0xbfb8aa3b, v84
	v_mul_f32_e32 v87, 0xbfb8aa3b, v85
	v_exp_f32_e32 v86, v86
	v_exp_f32_e32 v87, v87
	v_pk_mul_f32 v[80:81], v[90:91], v[80:81]
	v_add_f32_e32 v86, 1.0, v86
	v_add_f32_e32 v87, 1.0, v87
	v_rcp_f32_e32 v86, v86
	v_rcp_f32_e32 v87, v87
	v_cvt_pk_bf16_f32 v90, v80, v81
	v_pk_mul_f32 v[80:81], v[96:97], v[82:83] op_sel_hi:[0,1]
	v_pk_mul_f32 v[80:81], v[84:85], v[80:81]
	v_mad_i64_i32 v[82:83], s[14:15], v97, s46, v[112:113]
	v_pk_mul_f32 v[80:81], v[86:87], v[80:81]
	v_lshl_add_u64 v[82:83], v[82:83], 0, v[114:115]
	v_cvt_pk_bf16_f32 v91, v80, v81
	v_fmamk_f32 v80, v155, 0x3a000000, v151
	v_rsq_f32_e32 v80, v80
	global_store_dwordx4 v[82:83], v[88:91], off
	v_pk_mul_f32 v[76:77], v[80:81], v[76:77] op_sel_hi:[0,1]
	v_mul_f32_e32 v81, 0xbfb8aa3b, v76
	v_exp_f32_e32 v81, v81
	v_mul_f32_e32 v84, 0xbfb8aa3b, v77
	v_exp_f32_e32 v84, v84
	v_add_f32_e32 v81, 1.0, v81
	v_rcp_f32_e32 v82, v81
	v_add_f32_e32 v81, 1.0, v84
	v_rcp_f32_e32 v83, v81
	v_or_b32_e32 v81, 48, v124
	v_pk_mul_f32 v[72:73], v[80:81], v[72:73] op_sel_hi:[0,1]
	v_pk_mul_f32 v[72:73], v[76:77], v[72:73]
	v_pk_mul_f32 v[76:77], v[80:81], v[78:79] op_sel_hi:[0,1]
	v_pk_mul_f32 v[72:73], v[82:83], v[72:73]
	v_mul_f32_e32 v78, 0xbfb8aa3b, v76
	v_cvt_pk_bf16_f32 v72, v72, v73
	v_mul_f32_e32 v73, 0xbfb8aa3b, v77
	v_exp_f32_e32 v78, v78
	v_exp_f32_e32 v73, v73
	v_pk_mul_f32 v[74:75], v[80:81], v[74:75] op_sel_hi:[0,1]
	v_pk_mul_f32 v[68:69], v[80:81], v[68:69] op_sel_hi:[0,1]
	v_add_f32_e32 v78, 1.0, v78
	v_add_f32_e32 v73, 1.0, v73
	v_rcp_f32_e32 v78, v78
	v_rcp_f32_e32 v79, v73
	v_pk_mul_f32 v[74:75], v[76:77], v[74:75]
	v_mul_f32_e32 v73, 0xbfb8aa3b, v68
	v_exp_f32_e32 v82, v73
	v_pk_mul_f32 v[74:75], v[78:79], v[74:75]
	v_pk_mul_f32 v[64:65], v[80:81], v[64:65] op_sel_hi:[0,1]
	v_cvt_pk_bf16_f32 v73, v74, v75
	v_mul_f32_e32 v75, 0xbfb8aa3b, v69
	v_exp_f32_e32 v75, v75
	v_pk_mul_f32 v[64:65], v[68:69], v[64:65]
	v_add_f32_e32 v74, 1.0, v82
	v_rcp_f32_e32 v74, v74
	v_add_f32_e32 v68, 1.0, v75
	v_rcp_f32_e32 v75, v68
	v_pk_mul_f32 v[68:69], v[80:81], v[70:71] op_sel_hi:[0,1]
	v_mul_f32_e32 v70, 0xbfb8aa3b, v68
	v_mul_f32_e32 v71, 0xbfb8aa3b, v69
	v_exp_f32_e32 v70, v70
	v_exp_f32_e32 v71, v71
	v_pk_mul_f32 v[64:65], v[74:75], v[64:65]
	v_add_f32_e32 v70, 1.0, v70
	v_add_f32_e32 v71, 1.0, v71
	v_rcp_f32_e32 v70, v70
	v_rcp_f32_e32 v71, v71
	v_cvt_pk_bf16_f32 v74, v64, v65
	v_pk_mul_f32 v[64:65], v[80:81], v[66:67] op_sel_hi:[0,1]
	v_pk_mul_f32 v[64:65], v[68:69], v[64:65]
	v_mad_i64_i32 v[66:67], s[14:15], v81, s46, v[112:113]
	v_pk_mul_f32 v[64:65], v[70:71], v[64:65]
	v_lshl_add_u64 v[66:67], v[66:67], 0, v[114:115]
	v_cvt_pk_bf16_f32 v75, v64, v65
	v_fmamk_f32 v64, v154, 0x3a000000, v151
	v_rsq_f32_e32 v64, v64
	global_store_dwordx4 v[66:67], v[72:75], off
	v_pk_mul_f32 v[60:61], v[64:65], v[60:61] op_sel_hi:[0,1]
	v_mul_f32_e32 v65, 0xbfb8aa3b, v60
	v_exp_f32_e32 v65, v65
	v_mul_f32_e32 v68, 0xbfb8aa3b, v61
	v_exp_f32_e32 v68, v68
	v_add_f32_e32 v65, 1.0, v65
	v_rcp_f32_e32 v66, v65
	v_add_f32_e32 v65, 1.0, v68
	v_rcp_f32_e32 v67, v65
	v_add_u32_e32 v65, 0x80, v124
	v_pk_mul_f32 v[56:57], v[64:65], v[56:57] op_sel_hi:[0,1]
	v_pk_mul_f32 v[56:57], v[60:61], v[56:57]
	v_pk_mul_f32 v[60:61], v[64:65], v[62:63] op_sel_hi:[0,1]
	v_pk_mul_f32 v[56:57], v[66:67], v[56:57]
	v_mul_f32_e32 v62, 0xbfb8aa3b, v60
	v_cvt_pk_bf16_f32 v56, v56, v57
	v_mul_f32_e32 v57, 0xbfb8aa3b, v61
	v_exp_f32_e32 v62, v62
	v_exp_f32_e32 v57, v57
	v_pk_mul_f32 v[58:59], v[64:65], v[58:59] op_sel_hi:[0,1]
	v_pk_mul_f32 v[52:53], v[64:65], v[52:53] op_sel_hi:[0,1]
	v_add_f32_e32 v62, 1.0, v62
	v_add_f32_e32 v57, 1.0, v57
	v_rcp_f32_e32 v62, v62
	v_rcp_f32_e32 v63, v57
	v_pk_mul_f32 v[58:59], v[60:61], v[58:59]
	v_mul_f32_e32 v57, 0xbfb8aa3b, v52
	v_exp_f32_e32 v66, v57
; __device__ __forceinline__ float sigmoidf_(float x) { return __builtin_amdgcn_rcpf(1.0f + fexp(-x)); }
;     __device__ __forceinline__ void operator()(const f32x4 (&acc)[2][2][4][2], const Unit& u, int wr, int wc, int fr, int fq, const Pre& P) const {
;         const int row0 = ROW_X + u.pm * BM + wr * 64 + fr, col0 = u.pn * HALF + wc * 32 + 8 * fq;
; #pragma unroll
;         for (int ai = 0; ai < 2; ++ai)
; #pragma unroll
;             for (int m = 0; m < 4; ++m) { const int r = row0 + ai * HALF + m * 16; const float rs = __builtin_amdgcn_rsqf(P.rs[ai * 4 + m] * (1.0f / DM) + RMS_EPS);
;                 float y[8];
; #pragma unroll
;                 for (int n = 0; n < 2; ++n)
; #pragma unroll
;                     for (int j = 0; j < 4; ++j) { const float a = acc[ai][0][m][n][j] * rs, b = acc[ai][1][m][n][j] * rs; y[n * 4 + j] = a * b * sigmoidf_(a); }
;                 u32x4 w; w.x = cvtpk(y[0], y[1]); w.y = cvtpk(y[2], y[3]); w.z = cvtpk(y[4], y[5]); w.w = cvtpk(y[6], y[7]);
;                 *(u32x4*)(O + (size_t)r * FF + col0) = w; }
	v_pk_mul_f32 v[58:59], v[62:63], v[58:59]
	v_pk_mul_f32 v[48:49], v[64:65], v[48:49] op_sel_hi:[0,1]
	v_cvt_pk_bf16_f32 v57, v58, v59
	v_mul_f32_e32 v59, 0xbfb8aa3b, v53
	v_exp_f32_e32 v59, v59
	v_pk_mul_f32 v[48:49], v[52:53], v[48:49]
	v_add_f32_e32 v58, 1.0, v66
	v_rcp_f32_e32 v58, v58
	v_add_f32_e32 v52, 1.0, v59
	v_rcp_f32_e32 v59, v52
	v_pk_mul_f32 v[52:53], v[64:65], v[54:55] op_sel_hi:[0,1]
	v_mul_f32_e32 v54, 0xbfb8aa3b, v52
	v_mul_f32_e32 v55, 0xbfb8aa3b, v53
	v_exp_f32_e32 v54, v54
	v_exp_f32_e32 v55, v55
	v_pk_mul_f32 v[48:49], v[58:59], v[48:49]
	v_add_f32_e32 v54, 1.0, v54
	v_add_f32_e32 v55, 1.0, v55
	v_rcp_f32_e32 v54, v54
	v_rcp_f32_e32 v55, v55
	v_cvt_pk_bf16_f32 v58, v48, v49
	v_pk_mul_f32 v[48:49], v[64:65], v[50:51] op_sel_hi:[0,1]
	v_pk_mul_f32 v[48:49], v[52:53], v[48:49]
	v_mad_i64_i32 v[50:51], s[14:15], v65, s46, v[112:113]
	v_pk_mul_f32 v[48:49], v[54:55], v[48:49]
	v_lshl_add_u64 v[50:51], v[50:51], 0, v[114:115]
	v_cvt_pk_bf16_f32 v59, v48, v49
	v_fmamk_f32 v48, v153, 0x3a000000, v151
	v_rsq_f32_e32 v48, v48
	global_store_dwordx4 v[50:51], v[56:59], off
	v_pk_mul_f32 v[44:45], v[48:49], v[44:45] op_sel_hi:[0,1]
	v_mul_f32_e32 v49, 0xbfb8aa3b, v44
	v_exp_f32_e32 v49, v49
	v_mul_f32_e32 v52, 0xbfb8aa3b, v45
	v_exp_f32_e32 v52, v52
	v_add_f32_e32 v49, 1.0, v49
	v_rcp_f32_e32 v50, v49
	v_add_f32_e32 v49, 1.0, v52
	v_rcp_f32_e32 v51, v49
	v_add_u32_e32 v49, 0x90, v124
	v_pk_mul_f32 v[40:41], v[48:49], v[40:41] op_sel_hi:[0,1]
	v_pk_mul_f32 v[40:41], v[44:45], v[40:41]
	v_pk_mul_f32 v[44:45], v[48:49], v[46:47] op_sel_hi:[0,1]
	v_pk_mul_f32 v[40:41], v[50:51], v[40:41]
	v_mul_f32_e32 v46, 0xbfb8aa3b, v44
	v_cvt_pk_bf16_f32 v40, v40, v41
	v_mul_f32_e32 v41, 0xbfb8aa3b, v45
	v_exp_f32_e32 v46, v46
	v_exp_f32_e32 v41, v41
	v_pk_mul_f32 v[42:43], v[48:49], v[42:43] op_sel_hi:[0,1]
	v_pk_mul_f32 v[36:37], v[48:49], v[36:37] op_sel_hi:[0,1]
	v_add_f32_e32 v46, 1.0, v46
	v_add_f32_e32 v41, 1.0, v41
	v_rcp_f32_e32 v46, v46
	v_rcp_f32_e32 v47, v41
	v_pk_mul_f32 v[42:43], v[44:45], v[42:43]
	v_mul_f32_e32 v41, 0xbfb8aa3b, v36
	v_exp_f32_e32 v50, v41
	v_pk_mul_f32 v[42:43], v[46:47], v[42:43]
	v_pk_mul_f32 v[32:33], v[48:49], v[32:33] op_sel_hi:[0,1]
	v_cvt_pk_bf16_f32 v41, v42, v43
	v_mul_f32_e32 v43, 0xbfb8aa3b, v37
	v_exp_f32_e32 v43, v43
	v_pk_mul_f32 v[32:33], v[36:37], v[32:33]
	v_add_f32_e32 v42, 1.0, v50
	v_rcp_f32_e32 v42, v42
	v_add_f32_e32 v36, 1.0, v43
	v_rcp_f32_e32 v43, v36
	v_pk_mul_f32 v[36:37], v[48:49], v[38:39] op_sel_hi:[0,1]
	v_mul_f32_e32 v38, 0xbfb8aa3b, v36
	v_mul_f32_e32 v39, 0xbfb8aa3b, v37
	v_exp_f32_e32 v38, v38
	v_exp_f32_e32 v39, v39
	v_pk_mul_f32 v[32:33], v[42:43], v[32:33]
	v_add_f32_e32 v38, 1.0, v38
	v_add_f32_e32 v39, 1.0, v39
	v_rcp_f32_e32 v38, v38
	v_rcp_f32_e32 v39, v39
	v_cvt_pk_bf16_f32 v42, v32, v33
	v_pk_mul_f32 v[32:33], v[48:49], v[34:35] op_sel_hi:[0,1]
	v_pk_mul_f32 v[32:33], v[36:37], v[32:33]
	v_mad_i64_i32 v[34:35], s[14:15], v49, s46, v[112:113]
	v_pk_mul_f32 v[32:33], v[38:39], v[32:33]
	v_lshl_add_u64 v[34:35], v[34:35], 0, v[114:115]
	v_cvt_pk_bf16_f32 v43, v32, v33
	v_fmamk_f32 v32, v152, 0x3a000000, v151
	v_rsq_f32_e32 v32, v32
	global_store_dwordx4 v[34:35], v[40:43], off
	v_pk_mul_f32 v[28:29], v[32:33], v[28:29] op_sel_hi:[0,1]
	v_mul_f32_e32 v33, 0xbfb8aa3b, v28
	v_exp_f32_e32 v33, v33
	v_mul_f32_e32 v36, 0xbfb8aa3b, v29
	v_exp_f32_e32 v36, v36
	v_add_f32_e32 v33, 1.0, v33
	v_rcp_f32_e32 v34, v33
	v_add_f32_e32 v33, 1.0, v36
	v_rcp_f32_e32 v35, v33
	v_add_u32_e32 v33, 0xa0, v124
	v_pk_mul_f32 v[24:25], v[32:33], v[24:25] op_sel_hi:[0,1]
	v_pk_mul_f32 v[24:25], v[28:29], v[24:25]
	v_pk_mul_f32 v[28:29], v[32:33], v[30:31] op_sel_hi:[0,1]
	v_pk_mul_f32 v[24:25], v[34:35], v[24:25]
	v_mul_f32_e32 v30, 0xbfb8aa3b, v28
	v_cvt_pk_bf16_f32 v24, v24, v25
	v_mul_f32_e32 v25, 0xbfb8aa3b, v29
	v_exp_f32_e32 v30, v30
	v_exp_f32_e32 v25, v25
	v_pk_mul_f32 v[26:27], v[32:33], v[26:27] op_sel_hi:[0,1]
	v_pk_mul_f32 v[20:21], v[32:33], v[20:21] op_sel_hi:[0,1]
	v_add_f32_e32 v30, 1.0, v30
	v_add_f32_e32 v25, 1.0, v25
	v_rcp_f32_e32 v30, v30
	v_rcp_f32_e32 v31, v25
; __device__ __forceinline__ float sigmoidf_(float x) { return __builtin_amdgcn_rcpf(1.0f + fexp(-x)); }
; __device__ __forceinline__ PreRs load_rs(const float* ssq, int pm, int wr, int fr) { PreRs p;
; #pragma unroll
;     for (int ai = 0; ai < 2; ++ai)
; #pragma unroll
;         for (int m = 0; m < 4; ++m) p.rs[ai * 4 + m] = ssq[ROW_X + pm * BM + ai * HALF + wr * 64 + m * 16 + fr];
;     return p; }
;     __device__ __forceinline__ void operator()(const f32x4 (&acc)[2][2][4][2], const Unit& u, int wr, int wc, int fr, int fq, const Pre& P) const {
;         const int row0 = ROW_X + u.pm * BM + wr * 64 + fr, col0 = u.pn * HALF + wc * 32 + 8 * fq;
; #pragma unroll
;         for (int ai = 0; ai < 2; ++ai)
; #pragma unroll
;             for (int m = 0; m < 4; ++m) { const int r = row0 + ai * HALF + m * 16; const float rs = __builtin_amdgcn_rsqf(P.rs[ai * 4 + m] * (1.0f / DM) + RMS_EPS);
;                 float y[8];
; #pragma unroll
;                 for (int n = 0; n < 2; ++n)
; #pragma unroll
;                     for (int j = 0; j < 4; ++j) { const float a = acc[ai][0][m][n][j] * rs, b = acc[ai][1][m][n][j] * rs; y[n * 4 + j] = a * b * sigmoidf_(a); }
;                 u32x4 w; w.x = cvtpk(y[0], y[1]); w.y = cvtpk(y[2], y[3]); w.z = cvtpk(y[4], y[5]); w.w = cvtpk(y[6], y[7]);
;                 *(u32x4*)(O + (size_t)r * FF + col0) = w; }
	v_pk_mul_f32 v[26:27], v[28:29], v[26:27]
	v_mul_f32_e32 v25, 0xbfb8aa3b, v20
	v_exp_f32_e32 v34, v25
	v_pk_mul_f32 v[26:27], v[30:31], v[26:27]
	v_pk_mul_f32 v[16:17], v[32:33], v[16:17] op_sel_hi:[0,1]
	v_cvt_pk_bf16_f32 v25, v26, v27
	v_mul_f32_e32 v27, 0xbfb8aa3b, v21
	v_exp_f32_e32 v27, v27
	v_pk_mul_f32 v[16:17], v[20:21], v[16:17]
	v_add_f32_e32 v26, 1.0, v34
	v_rcp_f32_e32 v26, v26
	v_add_f32_e32 v20, 1.0, v27
	v_rcp_f32_e32 v27, v20
	v_pk_mul_f32 v[20:21], v[32:33], v[22:23] op_sel_hi:[0,1]
	v_mul_f32_e32 v22, 0xbfb8aa3b, v20
	v_mul_f32_e32 v23, 0xbfb8aa3b, v21
	v_exp_f32_e32 v22, v22
	v_exp_f32_e32 v23, v23
	v_pk_mul_f32 v[16:17], v[26:27], v[16:17]
	v_add_f32_e32 v22, 1.0, v22
	v_add_f32_e32 v23, 1.0, v23
	v_rcp_f32_e32 v22, v22
	v_rcp_f32_e32 v23, v23
	v_cvt_pk_bf16_f32 v26, v16, v17
	v_pk_mul_f32 v[16:17], v[32:33], v[18:19] op_sel_hi:[0,1]
	v_pk_mul_f32 v[16:17], v[20:21], v[16:17]
	v_mad_i64_i32 v[18:19], s[14:15], v33, s46, v[112:113]
	v_pk_mul_f32 v[16:17], v[22:23], v[16:17]
	v_lshl_add_u64 v[18:19], v[18:19], 0, v[114:115]
	v_cvt_pk_bf16_f32 v27, v16, v17
	v_fmamk_f32 v16, v147, 0x3a000000, v151
	v_rsq_f32_e32 v16, v16
	global_store_dwordx4 v[18:19], v[24:27], off
	v_pk_mul_f32 v[12:13], v[16:17], v[12:13] op_sel_hi:[0,1]
	v_mul_f32_e32 v17, 0xbfb8aa3b, v12
	v_exp_f32_e32 v17, v17
	v_mul_f32_e32 v20, 0xbfb8aa3b, v13
	v_exp_f32_e32 v20, v20
	v_add_f32_e32 v17, 1.0, v17
	v_rcp_f32_e32 v18, v17
	v_add_f32_e32 v17, 1.0, v20
	v_rcp_f32_e32 v19, v17
	v_add_u32_e32 v17, 0xb0, v124
	v_pk_mul_f32 v[8:9], v[16:17], v[8:9] op_sel_hi:[0,1]
	v_pk_mul_f32 v[8:9], v[12:13], v[8:9]
	v_pk_mul_f32 v[12:13], v[16:17], v[14:15] op_sel_hi:[0,1]
	v_pk_mul_f32 v[8:9], v[18:19], v[8:9]
	v_mul_f32_e32 v14, 0xbfb8aa3b, v12
	v_cvt_pk_bf16_f32 v8, v8, v9
	v_mul_f32_e32 v9, 0xbfb8aa3b, v13
	v_exp_f32_e32 v14, v14
	v_exp_f32_e32 v9, v9
	v_pk_mul_f32 v[10:11], v[16:17], v[10:11] op_sel_hi:[0,1]
	v_pk_mul_f32 v[4:5], v[16:17], v[4:5] op_sel_hi:[0,1]
	v_add_f32_e32 v14, 1.0, v14
	v_add_f32_e32 v9, 1.0, v9
	v_rcp_f32_e32 v14, v14
	v_rcp_f32_e32 v15, v9
	v_pk_mul_f32 v[10:11], v[12:13], v[10:11]
	v_mul_f32_e32 v9, 0xbfb8aa3b, v4
	v_exp_f32_e32 v18, v9
	v_pk_mul_f32 v[10:11], v[14:15], v[10:11]
	v_pk_mul_f32 v[0:1], v[16:17], v[0:1] op_sel_hi:[0,1]
	v_cvt_pk_bf16_f32 v9, v10, v11
	v_mul_f32_e32 v11, 0xbfb8aa3b, v5
	v_exp_f32_e32 v11, v11
	v_pk_mul_f32 v[0:1], v[4:5], v[0:1]
	v_add_f32_e32 v10, 1.0, v18
	v_rcp_f32_e32 v10, v10
	v_add_f32_e32 v4, 1.0, v11
	v_rcp_f32_e32 v11, v4
	v_pk_mul_f32 v[4:5], v[16:17], v[6:7] op_sel_hi:[0,1]
	v_mul_f32_e32 v6, 0xbfb8aa3b, v4
	v_mul_f32_e32 v7, 0xbfb8aa3b, v5
	v_exp_f32_e32 v6, v6
	v_exp_f32_e32 v7, v7
	v_pk_mul_f32 v[0:1], v[10:11], v[0:1]
	v_add_f32_e32 v6, 1.0, v6
	v_add_f32_e32 v7, 1.0, v7
	v_rcp_f32_e32 v6, v6
	v_rcp_f32_e32 v7, v7
	v_cvt_pk_bf16_f32 v10, v0, v1
	v_pk_mul_f32 v[0:1], v[16:17], v[2:3] op_sel_hi:[0,1]
	v_pk_mul_f32 v[0:1], v[4:5], v[0:1]
	s_nop 0
	v_pk_mul_f32 v[0:1], v[6:7], v[0:1]
	s_nop 0
	v_cvt_pk_bf16_f32 v11, v0, v1
	v_mad_i64_i32 v[0:1], s[14:15], v17, s46, v[112:113]
	v_lshl_add_u64 v[0:1], v[0:1], 0, v[114:115]
	s_mov_b64 s[14:15], -1
	global_store_dwordx4 v[0:1], v[8:11], off
	s_cbranch_vccz .LBB0_2542
	v_lshl_add_u32 v0, s8, 8, v144
	v_ashrrev_i32_e32 v1, 31, v0
	v_lshl_add_u64 v[2:3], v[0:1], 2, s[0:1]
	v_add_u32_e32 v4, 0x80, v0
	v_add_u32_e32 v6, 0x90, v0
	v_add_u32_e32 v8, 0xa0, v0
	v_add_u32_e32 v0, 0xb0, v0
	v_ashrrev_i32_e32 v5, 31, v4
	v_ashrrev_i32_e32 v7, 31, v6
	v_ashrrev_i32_e32 v9, 31, v8
	v_ashrrev_i32_e32 v1, 31, v0
	v_lshl_add_u64 v[4:5], v[4:5], 2, s[0:1]
	v_lshl_add_u64 v[6:7], v[6:7], 2, s[0:1]
	v_lshl_add_u64 v[8:9], v[8:9], 2, s[0:1]
	v_lshl_add_u64 v[0:1], v[0:1], 2, s[0:1]
	global_load_dword v158, v[2:3], off
	global_load_dword v157, v[2:3], off offset:64
	global_load_dword v156, v[2:3], off offset:128
	global_load_dword v155, v[2:3], off offset:192
	global_load_dword v154, v[4:5], off
	global_load_dword v153, v[6:7], off
	global_load_dword v152, v[8:9], off
	global_load_dword v147, v[0:1], off
	s_mov_b64 s[14:15], 0
	s_branch .LBB0_2542

; #define PG8_STAGE(bufoff, gbase, voff) do { _Pragma("unroll") for (int _i = 0; _i < 2; ++_i) \
;         __builtin_amdgcn_global_load_lds((const unsigned*)((const char*)(gbase) + (voff)[_i]), (LAS unsigned*)(lds + (bufoff) + ldsw + _i * 8192), 16, 0, 0); } while (0)
; #define PG8_LDA(dst, b, h) do { _Pragma("unroll") for (int m = 0; m < 4; ++m) _Pragma("unroll") for (int k = 0; k < 2; ++k) dst[m][k] = *(const LAS bf16x8*)(lds + PG8_SA(b, h) + aoff + m * 2048 + k * 1024); } while (0)
; #define PG8_LDB(dst, b, h) do { _Pragma("unroll") for (int n = 0; n < 2; ++n) _Pragma("unroll") for (int k = 0; k < 2; ++k) dst[n][k] = *(const LAS bf16x8*)(lds + PG8_SB(b, h) + boff + n * 2048 + k * 1024); } while (0)
; #define PG8_MMA(ai, bj, At, Bt) do { __builtin_amdgcn_s_setprio(1); _Pragma("unroll") for (int m = 0; m < 4; ++m) _Pragma("unroll") for (int n = 0; n < 2; ++n) _Pragma("unroll") for (int k = 0; k < 2; ++k) \
;         acc[ai][bj][m][n] = __builtin_amdgcn_mfma_f32_16x16x32_bf16(Bt[n][k], At[m][k], acc[ai][bj][m][n], 0, 0, 0); __builtin_amdgcn_s_setprio(0); } while (0)
; #define PG8_WAIT_L(n) asm volatile("s_waitcnt lgkmcnt(" #n ")" ::: "memory")
; #define PG8_BAR __builtin_amdgcn_s_barrier()
; #define PG8_SCHED __builtin_amdgcn_sched_barrier(0)
; template <class Epi>
; __device__ __forceinline__ void gemm_phase(LAS unsigned char* lds, const Gemm g, const StaticOrder& S, const Epi& E) {
;     ...
;             const bool last = (t == nt - 2);
;             const char* a1 = cA + (size_t)(t + 1) * kstep;
;             const char* a2 = last ? nA : cA + (size_t)(t + 2) * kstep; const char* b2 = last ? nB : cB + (size_t)(t + 2) * kstep;
;             const char* a3 = a2 + kstep; const char* b3 = b2 + kstep;
;             PG8_LDB(B0, 0, 0); PG8_SCHED; PG8_LDA(At, 0, 0); PG8_STAGE(PG8_SA(1, 1), a1 + hstep, voffA);
;             PG8_WAIT_L(8); PG8_BAR; PG8_WAIT_L(0); PG8_MMA(0, 0, At, B0); PG8_BAR; PG8_SCHED;
.LBB0_2626:
	ds_read_b128 v[144:147], v153
	ds_read_b128 v[156:159], v153 offset:1024
	ds_read_b128 v[160:163], v153 offset:2048
	ds_read_b128 v[164:167], v153 offset:3072
	s_add_u32 s20, s18, 0xffea8080
	s_addc_u32 s21, s19, -1
	s_cmpk_eq_i32 s64, 0x52
	s_cselect_b32 s23, s1, s21
	s_cselect_b32 s22, s0, s20
	s_cselect_b32 s21, s5, s63
	s_cselect_b32 s20, s4, s62
	v_lshl_add_u64 v[148:149], s[18:19], 0, v[136:137]
	s_add_i32 m0, s36, 0xc000
	ds_read_b128 v[168:171], v154
	ds_read_b128 v[172:175], v154 offset:1024
	ds_read_b128 v[176:179], v154 offset:2048
	ds_read_b128 v[180:183], v154 offset:3072
	ds_read_b128 v[184:187], v154 offset:4096
	ds_read_b128 v[188:191], v154 offset:5120
	ds_read_b128 v[192:195], v154 offset:6144
	ds_read_b128 v[196:199], v154 offset:7168
	global_load_lds_dwordx4 v[148:149], off
	v_lshl_add_u64 v[148:149], s[18:19], 0, v[138:139]
	s_add_i32 m0, s36, 0xe000
	s_nop 0
	global_load_lds_dwordx4 v[148:149], off
	s_waitcnt lgkmcnt(8)
	s_setprio 1
	s_barrier
	s_waitcnt lgkmcnt(0)


; #define PG8_STAGE(bufoff, gbase, voff) do { _Pragma("unroll") for (int _i = 0; _i < 2; ++_i) \
;         __builtin_amdgcn_global_load_lds((const unsigned*)((const char*)(gbase) + (voff)[_i]), (LAS unsigned*)(lds + (bufoff) + ldsw + _i * 8192), 16, 0, 0); } while (0)
; #define PG8_LDB(dst, b, h) do { _Pragma("unroll") for (int n = 0; n < 2; ++n) _Pragma("unroll") for (int k = 0; k < 2; ++k) dst[n][k] = *(const LAS bf16x8*)(lds + PG8_SB(b, h) + boff + n * 2048 + k * 1024); } while (0)
; #define PG8_MMA(ai, bj, At, Bt) do { __builtin_amdgcn_s_setprio(1); _Pragma("unroll") for (int m = 0; m < 4; ++m) _Pragma("unroll") for (int n = 0; n < 2; ++n) _Pragma("unroll") for (int k = 0; k < 2; ++k) \
;         acc[ai][bj][m][n] = __builtin_amdgcn_mfma_f32_16x16x32_bf16(Bt[n][k], At[m][k], acc[ai][bj][m][n], 0, 0, 0); __builtin_amdgcn_s_setprio(0); } while (0)
; #define PG8_WAIT_L(n) asm volatile("s_waitcnt lgkmcnt(" #n ")" ::: "memory")
; #define PG8_BAR __builtin_amdgcn_s_barrier()
; #define PG8_SCHED __builtin_amdgcn_sched_barrier(0)
; template <class Epi>
; __device__ __forceinline__ void gemm_phase(LAS unsigned char* lds, const Gemm g, const StaticOrder& S, const Epi& E) {
;     ...
;             PG8_WAIT_L(8); PG8_BAR; PG8_WAIT_L(0); PG8_MMA(0, 0, At, B0); PG8_BAR; PG8_SCHED;
;             PG8_LDB(B1, 0, 1); PG8_STAGE(PG8_SB(0, 0), b2, voffB);
;             PG8_BAR; PG8_WAIT_L(0); PG8_MMA(0, 1, At, B1); PG8_BAR;
	v_mfma_f32_16x16x32_bf16 v[124:127], v[144:147], v[168:171], v[124:127]
	v_mfma_f32_16x16x32_bf16 v[120:123], v[160:163], v[168:171], v[120:123]
	v_mfma_f32_16x16x32_bf16 v[112:115], v[144:147], v[176:179], v[112:115]
	v_mfma_f32_16x16x32_bf16 v[104:107], v[160:163], v[176:179], v[104:107]
	v_mfma_f32_16x16x32_bf16 v[92:95], v[144:147], v[184:187], v[92:95]
	v_mfma_f32_16x16x32_bf16 v[88:91], v[160:163], v[184:187], v[88:91]
	v_mfma_f32_16x16x32_bf16 v[80:83], v[144:147], v[192:195], v[80:83]
	v_mfma_f32_16x16x32_bf16 v[72:75], v[160:163], v[192:195], v[72:75]
	v_mfma_f32_16x16x32_bf16 v[124:127], v[156:159], v[172:175], v[124:127]
	v_mfma_f32_16x16x32_bf16 v[120:123], v[164:167], v[172:175], v[120:123]
	v_mfma_f32_16x16x32_bf16 v[112:115], v[156:159], v[180:183], v[112:115]
	v_mfma_f32_16x16x32_bf16 v[104:107], v[164:167], v[180:183], v[104:107]
	v_mfma_f32_16x16x32_bf16 v[92:95], v[156:159], v[188:191], v[92:95]
	v_mfma_f32_16x16x32_bf16 v[88:91], v[164:167], v[188:191], v[88:91]
	v_mfma_f32_16x16x32_bf16 v[80:83], v[156:159], v[196:199], v[80:83]
	v_mfma_f32_16x16x32_bf16 v[72:75], v[164:167], v[196:199], v[72:75]
	s_setprio 0
	s_barrier
	s_add_i32 s65, s45, s35
	v_lshl_add_u64 v[148:149], s[20:21], 0, v[130:131]
	s_mov_b32 m0, s65
	ds_read_b128 v[200:203], v155
	ds_read_b128 v[204:207], v155 offset:1024
	ds_read_b128 v[208:211], v155 offset:2048
	ds_read_b128 v[212:215], v155 offset:3072
	global_load_lds_dwordx4 v[148:149], off
	v_lshl_add_u64 v[216:217], s[20:21], 0, v[134:135]
	s_add_i32 m0, s65, 0x2000
	s_nop 0
	global_load_lds_dwordx4 v[216:217], off
	s_waitcnt lgkmcnt(0)
	s_setprio 1
	s_barrier


; #define PG8_STAGE(bufoff, gbase, voff) do { _Pragma("unroll") for (int _i = 0; _i < 2; ++_i) \
;         __builtin_amdgcn_global_load_lds((const unsigned*)((const char*)(gbase) + (voff)[_i]), (LAS unsigned*)(lds + (bufoff) + ldsw + _i * 8192), 16, 0, 0); } while (0)
; #define PG8_LDA(dst, b, h) do { _Pragma("unroll") for (int m = 0; m < 4; ++m) _Pragma("unroll") for (int k = 0; k < 2; ++k) dst[m][k] = *(const LAS bf16x8*)(lds + PG8_SA(b, h) + aoff + m * 2048 + k * 1024); } while (0)
; #define PG8_MMA(ai, bj, At, Bt) do { __builtin_amdgcn_s_setprio(1); _Pragma("unroll") for (int m = 0; m < 4; ++m) _Pragma("unroll") for (int n = 0; n < 2; ++n) _Pragma("unroll") for (int k = 0; k < 2; ++k) \
;         acc[ai][bj][m][n] = __builtin_amdgcn_mfma_f32_16x16x32_bf16(Bt[n][k], At[m][k], acc[ai][bj][m][n], 0, 0, 0); __builtin_amdgcn_s_setprio(0); } while (0)
; #define PG8_WAIT_L(n) asm volatile("s_waitcnt lgkmcnt(" #n ")" ::: "memory")
; #define PG8_BAR __builtin_amdgcn_s_barrier()
; #define PG8_SCHED __builtin_amdgcn_sched_barrier(0)
; template <class Epi>
; __device__ __forceinline__ void gemm_phase(LAS unsigned char* lds, const Gemm g, const StaticOrder& S, const Epi& E) {
;     ...
;             PG8_BAR; PG8_WAIT_L(0); PG8_MMA(0, 1, At, B1); PG8_BAR;
;             PG8_LDA(At, 0, 1); PG8_STAGE(PG8_SA(0, 0), a2, voffA);
;             PG8_BAR; PG8_WAIT_L(0); PG8_MMA(1, 0, At, B0); PG8_BAR; PG8_SCHED;
	v_mfma_f32_16x16x32_bf16 v[116:119], v[200:203], v[168:171], v[116:119]
	v_mfma_f32_16x16x32_bf16 v[108:111], v[208:211], v[168:171], v[108:111]
	v_mfma_f32_16x16x32_bf16 v[100:103], v[200:203], v[176:179], v[100:103]
	v_mfma_f32_16x16x32_bf16 v[96:99], v[208:211], v[176:179], v[96:99]
	v_mfma_f32_16x16x32_bf16 v[84:87], v[200:203], v[184:187], v[84:87]
	v_mfma_f32_16x16x32_bf16 v[76:79], v[208:211], v[184:187], v[76:79]
	v_mfma_f32_16x16x32_bf16 v[68:71], v[200:203], v[192:195], v[68:71]
	v_mfma_f32_16x16x32_bf16 v[64:67], v[208:211], v[192:195], v[64:67]
	v_mfma_f32_16x16x32_bf16 v[116:119], v[204:207], v[172:175], v[116:119]
	v_mfma_f32_16x16x32_bf16 v[108:111], v[212:215], v[172:175], v[108:111]
	v_mfma_f32_16x16x32_bf16 v[100:103], v[204:207], v[180:183], v[100:103]
	v_mfma_f32_16x16x32_bf16 v[96:99], v[212:215], v[180:183], v[96:99]
	v_mfma_f32_16x16x32_bf16 v[84:87], v[204:207], v[188:191], v[84:87]
	v_mfma_f32_16x16x32_bf16 v[76:79], v[212:215], v[188:191], v[76:79]
	v_mfma_f32_16x16x32_bf16 v[68:71], v[204:207], v[196:199], v[68:71]
	v_mfma_f32_16x16x32_bf16 v[64:67], v[212:215], v[196:199], v[64:67]
	s_setprio 0
	s_mov_b32 m0, s36
	v_lshl_add_u64 v[218:219], s[22:23], 0, v[128:129]
	s_barrier
	ds_read_b128 v[168:171], v154 offset:16384
	ds_read_b128 v[172:175], v154 offset:17408
	ds_read_b128 v[176:179], v154 offset:18432
	ds_read_b128 v[180:183], v154 offset:19456
	ds_read_b128 v[184:187], v154 offset:20480
	ds_read_b128 v[188:191], v154 offset:21504
	ds_read_b128 v[192:195], v154 offset:22528
	ds_read_b128 v[196:199], v154 offset:23552
	global_load_lds_dwordx4 v[218:219], off
	v_lshl_add_u64 v[220:221], s[22:23], 0, v[132:133]
	s_mov_b32 m0, s37
	s_nop 0
	global_load_lds_dwordx4 v[220:221], off
	s_waitcnt lgkmcnt(0)
	s_setprio 1
	s_barrier


; #define PG8_STAGE(bufoff, gbase, voff) do { _Pragma("unroll") for (int _i = 0; _i < 2; ++_i) \
;         __builtin_amdgcn_global_load_lds((const unsigned*)((const char*)(gbase) + (voff)[_i]), (LAS unsigned*)(lds + (bufoff) + ldsw + _i * 8192), 16, 0, 0); } while (0)
; #define PG8_MMA(ai, bj, At, Bt) do { __builtin_amdgcn_s_setprio(1); _Pragma("unroll") for (int m = 0; m < 4; ++m) _Pragma("unroll") for (int n = 0; n < 2; ++n) _Pragma("unroll") for (int k = 0; k < 2; ++k) \
;         acc[ai][bj][m][n] = __builtin_amdgcn_mfma_f32_16x16x32_bf16(Bt[n][k], At[m][k], acc[ai][bj][m][n], 0, 0, 0); __builtin_amdgcn_s_setprio(0); } while (0)
; #define PG8_WAIT_V(n) asm volatile("s_waitcnt vmcnt(" #n ")" ::: "memory")
; #define PG8_WAIT_L(n) asm volatile("s_waitcnt lgkmcnt(" #n ")" ::: "memory")
; #define PG8_BAR __builtin_amdgcn_s_barrier()
; #define PG8_SCHED __builtin_amdgcn_sched_barrier(0)
; template <class Epi>
; __device__ __forceinline__ void gemm_phase(LAS unsigned char* lds, const Gemm g, const StaticOrder& S, const Epi& E) {
;     ...
;             PG8_BAR; PG8_WAIT_L(0); PG8_MMA(1, 0, At, B0); PG8_BAR; PG8_SCHED;
;             PG8_STAGE(PG8_SB(0, 1), b2 + hstep, voffB);
;             PG8_WAIT_V(6); PG8_BAR; PG8_MMA(1, 1, At, B1); PG8_BAR;
	v_mfma_f32_16x16x32_bf16 v[60:63], v[144:147], v[168:171], v[60:63]
	v_mfma_f32_16x16x32_bf16 v[56:59], v[160:163], v[168:171], v[56:59]
	v_mfma_f32_16x16x32_bf16 v[48:51], v[144:147], v[176:179], v[48:51]
	v_mfma_f32_16x16x32_bf16 v[40:43], v[160:163], v[176:179], v[40:43]
	v_mfma_f32_16x16x32_bf16 v[28:31], v[144:147], v[184:187], v[28:31]
	v_mfma_f32_16x16x32_bf16 v[24:27], v[160:163], v[184:187], v[24:27]
	v_mfma_f32_16x16x32_bf16 v[20:23], v[144:147], v[192:195], v[20:23]
	v_mfma_f32_16x16x32_bf16 v[12:15], v[160:163], v[192:195], v[12:15]
	v_mfma_f32_16x16x32_bf16 v[60:63], v[156:159], v[172:175], v[60:63]
	v_mfma_f32_16x16x32_bf16 v[56:59], v[164:167], v[172:175], v[56:59]
	v_mfma_f32_16x16x32_bf16 v[48:51], v[156:159], v[180:183], v[48:51]
	v_mfma_f32_16x16x32_bf16 v[40:43], v[164:167], v[180:183], v[40:43]
	v_mfma_f32_16x16x32_bf16 v[28:31], v[156:159], v[188:191], v[28:31]
	v_mfma_f32_16x16x32_bf16 v[24:27], v[164:167], v[188:191], v[24:27]
	v_mfma_f32_16x16x32_bf16 v[20:23], v[156:159], v[196:199], v[20:23]
	v_mfma_f32_16x16x32_bf16 v[12:15], v[164:167], v[196:199], v[12:15]
	s_setprio 0
	s_barrier
	s_add_u32 s66, s20, 0x158000
	s_addc_u32 s67, s21, 0
	s_add_i32 s65, s46, s35
	v_lshl_add_u64 v[144:145], s[66:67], 0, v[130:131]
	s_mov_b32 m0, s65
	s_nop 0
	global_load_lds_dwordx4 v[144:145], off
	v_lshl_add_u64 v[144:145], s[66:67], 0, v[134:135]
	s_add_i32 m0, s65, 0x2000
	s_nop 0
	global_load_lds_dwordx4 v[144:145], off
	s_waitcnt vmcnt(6)
	s_setprio 1
	s_barrier

; #define PG8_STAGE(bufoff, gbase, voff) do { _Pragma("unroll") for (int _i = 0; _i < 2; ++_i) \
;         __builtin_amdgcn_global_load_lds((const unsigned*)((const char*)(gbase) + (voff)[_i]), (LAS unsigned*)(lds + (bufoff) + ldsw + _i * 8192), 16, 0, 0); } while (0)
; #define PG8_LDA(dst, b, h) do { _Pragma("unroll") for (int m = 0; m < 4; ++m) _Pragma("unroll") for (int k = 0; k < 2; ++k) dst[m][k] = *(const LAS bf16x8*)(lds + PG8_SA(b, h) + aoff + m * 2048 + k * 1024); } while (0)
; #define PG8_LDB(dst, b, h) do { _Pragma("unroll") for (int n = 0; n < 2; ++n) _Pragma("unroll") for (int k = 0; k < 2; ++k) dst[n][k] = *(const LAS bf16x8*)(lds + PG8_SB(b, h) + boff + n * 2048 + k * 1024); } while (0)
; #define PG8_MMA(ai, bj, At, Bt) do { __builtin_amdgcn_s_setprio(1); _Pragma("unroll") for (int m = 0; m < 4; ++m) _Pragma("unroll") for (int n = 0; n < 2; ++n) _Pragma("unroll") for (int k = 0; k < 2; ++k) \
;         acc[ai][bj][m][n] = __builtin_amdgcn_mfma_f32_16x16x32_bf16(Bt[n][k], At[m][k], acc[ai][bj][m][n], 0, 0, 0); __builtin_amdgcn_s_setprio(0); } while (0)
; #define PG8_WAIT_V(n) asm volatile("s_waitcnt vmcnt(" #n ")" ::: "memory")
; #define PG8_WAIT_L(n) asm volatile("s_waitcnt lgkmcnt(" #n ")" ::: "memory")
; #define PG8_BAR __builtin_amdgcn_s_barrier()
; #define PG8_SCHED __builtin_amdgcn_sched_barrier(0)
; template <class Epi>
; __device__ __forceinline__ void gemm_phase(LAS unsigned char* lds, const Gemm g, const StaticOrder& S, const Epi& E) {
;     ...
;             PG8_WAIT_V(6); PG8_BAR; PG8_MMA(1, 1, At, B1); PG8_BAR;
;             PG8_LDB(B0, 1, 0); PG8_SCHED; PG8_LDA(At, 1, 0); PG8_STAGE(PG8_SA(0, 1), a2 + hstep, voffA);
;             PG8_WAIT_L(8); PG8_BAR; PG8_WAIT_L(0); PG8_MMA(0, 0, At, B0); PG8_BAR; PG8_SCHED;
	v_mfma_f32_16x16x32_bf16 v[52:55], v[200:203], v[168:171], v[52:55]
	v_mfma_f32_16x16x32_bf16 v[44:47], v[208:211], v[168:171], v[44:47]
	v_mfma_f32_16x16x32_bf16 v[36:39], v[200:203], v[176:179], v[36:39]
	v_mfma_f32_16x16x32_bf16 v[32:35], v[208:211], v[176:179], v[32:35]
	v_mfma_f32_16x16x32_bf16 v[16:19], v[200:203], v[184:187], v[16:19]
	v_mfma_f32_16x16x32_bf16 v[8:11], v[208:211], v[184:187], v[8:11]
	v_mfma_f32_16x16x32_bf16 v[4:7], v[200:203], v[192:195], v[4:7]
	v_mfma_f32_16x16x32_bf16 v[0:3], v[208:211], v[192:195], v[0:3]
	v_mfma_f32_16x16x32_bf16 v[52:55], v[204:207], v[172:175], v[52:55]
	v_mfma_f32_16x16x32_bf16 v[44:47], v[212:215], v[172:175], v[44:47]
	v_mfma_f32_16x16x32_bf16 v[36:39], v[204:207], v[180:183], v[36:39]
	v_mfma_f32_16x16x32_bf16 v[32:35], v[212:215], v[180:183], v[32:35]
	v_mfma_f32_16x16x32_bf16 v[16:19], v[204:207], v[188:191], v[16:19]
	v_mfma_f32_16x16x32_bf16 v[8:11], v[212:215], v[188:191], v[8:11]
	v_mfma_f32_16x16x32_bf16 v[4:7], v[204:207], v[196:199], v[4:7]
	v_mfma_f32_16x16x32_bf16 v[0:3], v[212:215], v[196:199], v[0:3]
	s_setprio 0
	s_add_i32 s65, 0, 0x18000
	v_add_u32_e32 v164, s65, v150
	s_barrier
	ds_read_b128 v[144:147], v164
	ds_read_b128 v[156:159], v164 offset:1024
	ds_read_b128 v[160:163], v164 offset:2048
	ds_read_b128 v[164:167], v164 offset:3072
	s_add_u32 s22, s22, 0x158000
	s_addc_u32 s23, s23, 0
	s_mov_b32 m0, s38
	v_lshl_add_u64 v[200:201], s[22:23], 0, v[128:129]
	ds_read_b128 v[168:171], v154 offset:32768
	ds_read_b128 v[172:175], v154 offset:33792
	ds_read_b128 v[176:179], v154 offset:34816
	ds_read_b128 v[180:183], v154 offset:35840
	ds_read_b128 v[184:187], v154 offset:36864
	ds_read_b128 v[188:191], v154 offset:37888
	ds_read_b128 v[192:195], v154 offset:38912
	ds_read_b128 v[196:199], v154 offset:39936
	global_load_lds_dwordx4 v[200:201], off
	v_lshl_add_u64 v[200:201], s[22:23], 0, v[132:133]
	s_mov_b32 m0, s39
	s_nop 0
	global_load_lds_dwordx4 v[200:201], off
	s_waitcnt lgkmcnt(8)
	s_setprio 1
	s_barrier
	s_waitcnt lgkmcnt(0)


; #define PG8_STAGE(bufoff, gbase, voff) do { _Pragma("unroll") for (int _i = 0; _i < 2; ++_i) \
;         __builtin_amdgcn_global_load_lds((const unsigned*)((const char*)(gbase) + (voff)[_i]), (LAS unsigned*)(lds + (bufoff) + ldsw + _i * 8192), 16, 0, 0); } while (0)
; #define PG8_LDB(dst, b, h) do { _Pragma("unroll") for (int n = 0; n < 2; ++n) _Pragma("unroll") for (int k = 0; k < 2; ++k) dst[n][k] = *(const LAS bf16x8*)(lds + PG8_SB(b, h) + boff + n * 2048 + k * 1024); } while (0)
; #define PG8_MMA(ai, bj, At, Bt) do { __builtin_amdgcn_s_setprio(1); _Pragma("unroll") for (int m = 0; m < 4; ++m) _Pragma("unroll") for (int n = 0; n < 2; ++n) _Pragma("unroll") for (int k = 0; k < 2; ++k) \
;         acc[ai][bj][m][n] = __builtin_amdgcn_mfma_f32_16x16x32_bf16(Bt[n][k], At[m][k], acc[ai][bj][m][n], 0, 0, 0); __builtin_amdgcn_s_setprio(0); } while (0)
; #define PG8_WAIT_L(n) asm volatile("s_waitcnt lgkmcnt(" #n ")" ::: "memory")
; #define PG8_BAR __builtin_amdgcn_s_barrier()
; #define PG8_SCHED __builtin_amdgcn_sched_barrier(0)
; template <class Epi>
; __device__ __forceinline__ void gemm_phase(LAS unsigned char* lds, const Gemm g, const StaticOrder& S, const Epi& E) {
;     ...
;             PG8_WAIT_L(8); PG8_BAR; PG8_WAIT_L(0); PG8_MMA(0, 0, At, B0); PG8_BAR; PG8_SCHED;
;             PG8_LDB(B1, 1, 1); PG8_STAGE(PG8_SB(1, 0), b3, voffB);
;             PG8_BAR; PG8_WAIT_L(0); PG8_MMA(0, 1, At, B1); PG8_BAR;
	v_mfma_f32_16x16x32_bf16 v[124:127], v[144:147], v[168:171], v[124:127]
	v_mfma_f32_16x16x32_bf16 v[120:123], v[160:163], v[168:171], v[120:123]
	v_mfma_f32_16x16x32_bf16 v[112:115], v[144:147], v[176:179], v[112:115]
	v_mfma_f32_16x16x32_bf16 v[104:107], v[160:163], v[176:179], v[104:107]
	v_mfma_f32_16x16x32_bf16 v[92:95], v[144:147], v[184:187], v[92:95]
	v_mfma_f32_16x16x32_bf16 v[88:91], v[160:163], v[184:187], v[88:91]
	v_mfma_f32_16x16x32_bf16 v[80:83], v[144:147], v[192:195], v[80:83]
	v_mfma_f32_16x16x32_bf16 v[72:75], v[160:163], v[192:195], v[72:75]
	v_mfma_f32_16x16x32_bf16 v[124:127], v[156:159], v[172:175], v[124:127]
	v_mfma_f32_16x16x32_bf16 v[120:123], v[164:167], v[172:175], v[120:123]
	v_mfma_f32_16x16x32_bf16 v[112:115], v[156:159], v[180:183], v[112:115]
	v_mfma_f32_16x16x32_bf16 v[104:107], v[164:167], v[180:183], v[104:107]
	v_mfma_f32_16x16x32_bf16 v[92:95], v[156:159], v[188:191], v[92:95]
	v_mfma_f32_16x16x32_bf16 v[88:91], v[164:167], v[188:191], v[88:91]
	v_mfma_f32_16x16x32_bf16 v[80:83], v[156:159], v[196:199], v[80:83]
	v_mfma_f32_16x16x32_bf16 v[72:75], v[164:167], v[196:199], v[72:75]
	s_setprio 0
	s_barrier
	s_add_i32 s22, 0, 0x1c000
	s_add_i32 s23, s65, s35
	v_add_u32_e32 v212, s22, v150
	v_lshl_add_u64 v[148:149], v[148:149], 0, s[8:9]
	s_mov_b32 m0, s23
	ds_read_b128 v[200:203], v212
	ds_read_b128 v[204:207], v212 offset:1024
	ds_read_b128 v[208:211], v212 offset:2048
	ds_read_b128 v[212:215], v212 offset:3072
	global_load_lds_dwordx4 v[148:149], off
	v_lshl_add_u64 v[148:149], v[216:217], 0, s[8:9]
	s_add_i32 m0, s23, 0x2000
	s_nop 0
	global_load_lds_dwordx4 v[148:149], off
	s_waitcnt lgkmcnt(0)
	s_setprio 1
	s_barrier


; #define PG8_STAGE(bufoff, gbase, voff) do { _Pragma("unroll") for (int _i = 0; _i < 2; ++_i) \
;         __builtin_amdgcn_global_load_lds((const unsigned*)((const char*)(gbase) + (voff)[_i]), (LAS unsigned*)(lds + (bufoff) + ldsw + _i * 8192), 16, 0, 0); } while (0)
; #define PG8_LDA(dst, b, h) do { _Pragma("unroll") for (int m = 0; m < 4; ++m) _Pragma("unroll") for (int k = 0; k < 2; ++k) dst[m][k] = *(const LAS bf16x8*)(lds + PG8_SA(b, h) + aoff + m * 2048 + k * 1024); } while (0)
; #define PG8_MMA(ai, bj, At, Bt) do { __builtin_amdgcn_s_setprio(1); _Pragma("unroll") for (int m = 0; m < 4; ++m) _Pragma("unroll") for (int n = 0; n < 2; ++n) _Pragma("unroll") for (int k = 0; k < 2; ++k) \
;         acc[ai][bj][m][n] = __builtin_amdgcn_mfma_f32_16x16x32_bf16(Bt[n][k], At[m][k], acc[ai][bj][m][n], 0, 0, 0); __builtin_amdgcn_s_setprio(0); } while (0)
; #define PG8_WAIT_L(n) asm volatile("s_waitcnt lgkmcnt(" #n ")" ::: "memory")
; #define PG8_BAR __builtin_amdgcn_s_barrier()
; #define PG8_SCHED __builtin_amdgcn_sched_barrier(0)
; template <class Epi>
; __device__ __forceinline__ void gemm_phase(LAS unsigned char* lds, const Gemm g, const StaticOrder& S, const Epi& E) {
;     ...
;             PG8_BAR; PG8_WAIT_L(0); PG8_MMA(0, 1, At, B1); PG8_BAR;
;             PG8_LDA(At, 1, 1); PG8_STAGE(PG8_SA(1, 0), a3, voffA);
;             PG8_BAR; PG8_WAIT_L(0); PG8_MMA(1, 0, At, B0); PG8_BAR; PG8_SCHED;
	v_mfma_f32_16x16x32_bf16 v[116:119], v[200:203], v[168:171], v[116:119]
	v_mfma_f32_16x16x32_bf16 v[108:111], v[208:211], v[168:171], v[108:111]
	v_mfma_f32_16x16x32_bf16 v[100:103], v[200:203], v[176:179], v[100:103]
	v_mfma_f32_16x16x32_bf16 v[96:99], v[208:211], v[176:179], v[96:99]
	v_mfma_f32_16x16x32_bf16 v[84:87], v[200:203], v[184:187], v[84:87]
	v_mfma_f32_16x16x32_bf16 v[76:79], v[208:211], v[184:187], v[76:79]
	v_mfma_f32_16x16x32_bf16 v[68:71], v[200:203], v[192:195], v[68:71]
	v_mfma_f32_16x16x32_bf16 v[64:67], v[208:211], v[192:195], v[64:67]
	v_mfma_f32_16x16x32_bf16 v[116:119], v[204:207], v[172:175], v[116:119]
	v_mfma_f32_16x16x32_bf16 v[108:111], v[212:215], v[172:175], v[108:111]
	v_mfma_f32_16x16x32_bf16 v[100:103], v[204:207], v[180:183], v[100:103]
	v_mfma_f32_16x16x32_bf16 v[96:99], v[212:215], v[180:183], v[96:99]
	v_mfma_f32_16x16x32_bf16 v[84:87], v[204:207], v[188:191], v[84:87]
	v_mfma_f32_16x16x32_bf16 v[76:79], v[212:215], v[188:191], v[76:79]
	v_mfma_f32_16x16x32_bf16 v[68:71], v[204:207], v[196:199], v[68:71]
	v_mfma_f32_16x16x32_bf16 v[64:67], v[212:215], v[196:199], v[64:67]
	s_setprio 0
	s_mov_b32 m0, s41
	v_lshl_add_u64 v[148:149], v[218:219], 0, s[8:9]
	s_barrier
	ds_read_b128 v[168:171], v154 offset:49152
	ds_read_b128 v[172:175], v154 offset:50176
	ds_read_b128 v[176:179], v154 offset:51200
	ds_read_b128 v[180:183], v154 offset:52224
	ds_read_b128 v[184:187], v154 offset:53248
	ds_read_b128 v[188:191], v154 offset:54272
	ds_read_b128 v[192:195], v154 offset:55296
	ds_read_b128 v[196:199], v154 offset:56320
	global_load_lds_dwordx4 v[148:149], off
	v_lshl_add_u64 v[148:149], v[220:221], 0, s[8:9]
	s_mov_b32 m0, s42
	s_nop 0
	global_load_lds_dwordx4 v[148:149], off
	s_waitcnt lgkmcnt(0)
	s_setprio 1
	s_barrier


; #define PG8_STAGE(bufoff, gbase, voff) do { _Pragma("unroll") for (int _i = 0; _i < 2; ++_i) \
;         __builtin_amdgcn_global_load_lds((const unsigned*)((const char*)(gbase) + (voff)[_i]), (LAS unsigned*)(lds + (bufoff) + ldsw + _i * 8192), 16, 0, 0); } while (0)
; #define PG8_MMA(ai, bj, At, Bt) do { __builtin_amdgcn_s_setprio(1); _Pragma("unroll") for (int m = 0; m < 4; ++m) _Pragma("unroll") for (int n = 0; n < 2; ++n) _Pragma("unroll") for (int k = 0; k < 2; ++k) \
;         acc[ai][bj][m][n] = __builtin_amdgcn_mfma_f32_16x16x32_bf16(Bt[n][k], At[m][k], acc[ai][bj][m][n], 0, 0, 0); __builtin_amdgcn_s_setprio(0); } while (0)
; #define PG8_WAIT_V(n) asm volatile("s_waitcnt vmcnt(" #n ")" ::: "memory")
; #define PG8_WAIT_L(n) asm volatile("s_waitcnt lgkmcnt(" #n ")" ::: "memory")
; #define PG8_BAR __builtin_amdgcn_s_barrier()
; #define PG8_SCHED __builtin_amdgcn_sched_barrier(0)
; template <class Epi>
; __device__ __forceinline__ void gemm_phase(LAS unsigned char* lds, const Gemm g, const StaticOrder& S, const Epi& E) {
;     ...
;             PG8_BAR; PG8_WAIT_L(0); PG8_MMA(1, 0, At, B0); PG8_BAR; PG8_SCHED;
;             PG8_STAGE(PG8_SB(1, 1), b3 + hstep, voffB);
;             PG8_WAIT_V(6); PG8_BAR; PG8_MMA(1, 1, At, B1); PG8_BAR;
	v_mfma_f32_16x16x32_bf16 v[60:63], v[144:147], v[168:171], v[60:63]
	v_mfma_f32_16x16x32_bf16 v[56:59], v[160:163], v[168:171], v[56:59]
	v_mfma_f32_16x16x32_bf16 v[48:51], v[144:147], v[176:179], v[48:51]
	v_mfma_f32_16x16x32_bf16 v[40:43], v[160:163], v[176:179], v[40:43]
	v_mfma_f32_16x16x32_bf16 v[28:31], v[144:147], v[184:187], v[28:31]
	v_mfma_f32_16x16x32_bf16 v[24:27], v[160:163], v[184:187], v[24:27]
	v_mfma_f32_16x16x32_bf16 v[20:23], v[144:147], v[192:195], v[20:23]
	v_mfma_f32_16x16x32_bf16 v[12:15], v[160:163], v[192:195], v[12:15]
	v_mfma_f32_16x16x32_bf16 v[60:63], v[156:159], v[172:175], v[60:63]
	v_mfma_f32_16x16x32_bf16 v[56:59], v[164:167], v[172:175], v[56:59]
	v_mfma_f32_16x16x32_bf16 v[48:51], v[156:159], v[180:183], v[48:51]
	v_mfma_f32_16x16x32_bf16 v[40:43], v[164:167], v[180:183], v[40:43]
	v_mfma_f32_16x16x32_bf16 v[28:31], v[156:159], v[188:191], v[28:31]
	v_mfma_f32_16x16x32_bf16 v[24:27], v[164:167], v[188:191], v[24:27]
	v_mfma_f32_16x16x32_bf16 v[20:23], v[156:159], v[196:199], v[20:23]
	v_mfma_f32_16x16x32_bf16 v[12:15], v[164:167], v[196:199], v[12:15]
	s_setprio 0
	s_barrier
	s_add_u32 s20, s20, 0x158080
	s_addc_u32 s21, s21, 0
	s_add_i32 s22, s22, s35
	v_lshl_add_u64 v[144:145], s[20:21], 0, v[130:131]
	s_mov_b32 m0, s22
	s_nop 0
	global_load_lds_dwordx4 v[144:145], off
	v_lshl_add_u64 v[144:145], s[20:21], 0, v[134:135]
	s_add_i32 m0, s22, 0x2000
	s_nop 0
	global_load_lds_dwordx4 v[144:145], off
	s_waitcnt vmcnt(6)
	s_setprio 1
	s_barrier

; __device__ __forceinline__ float bflo(unsigned w) { return __uint_as_float(w << 16); }
; __device__ __forceinline__ float bfhi(unsigned w) { return __uint_as_float(w & 0xffff0000u); }
; #define PG8_MMA(ai, bj, At, Bt) do { __builtin_amdgcn_s_setprio(1); _Pragma("unroll") for (int m = 0; m < 4; ++m) _Pragma("unroll") for (int n = 0; n < 2; ++n) _Pragma("unroll") for (int k = 0; k < 2; ++k) \
;         acc[ai][bj][m][n] = __builtin_amdgcn_mfma_f32_16x16x32_bf16(Bt[n][k], At[m][k], acc[ai][bj][m][n], 0, 0, 0); __builtin_amdgcn_s_setprio(0); } while (0)
; #define PG8_WAIT_V(n) asm volatile("s_waitcnt vmcnt(" #n ")" ::: "memory")
; #define PG8_BAR __builtin_amdgcn_s_barrier()
; #define ER_LOAD(g_, set_) do { const size_t off_ = (size_t)(row0 + ((g_) >> 2) * HALF + ((g_) & 3) * 16) * DM + col0; \
;         hv[set_][0] = *(const u32x4*)(HB + off_); hv[set_][1] = *(const u32x4*)(HB + off_ + HALF); } while (0)
; template <class Epi>
; __device__ __forceinline__ void gemm_phase(LAS unsigned char* lds, const Gemm g, const StaticOrder& S, const Epi& E) {
;     ...
;             PG8_WAIT_V(6); PG8_BAR; PG8_MMA(1, 1, At, B1); PG8_BAR;
;         }
;     __device__ __forceinline__ void operator()(const f32x4 (&acc)[2][2][4][2], const Unit& u, int wr, int wc, int fr, int fq, const Pre&) const {
;         const int row0 = ROW_X + u.pm * BM + wr * 64 + fr, col0 = u.pn * BM + wc * 32 + 8 * fq;
;         u32x4 hv[2][2]; float sprev = 0.f;
;     ...
;         ER_LOAD(0, 0);
; #pragma unroll
;         for (int g = 0; g < 8; ++g) { const int ai = g >> 2, m = g & 3; const int r = row0 + ai * HALF + m * 16; const size_t off = (size_t)r * DM + col0; float s = 0.f;
;             if (g + 1 < 8) ER_LOAD(g + 1, (g + 1) & 1);
; #pragma unroll
;             for (int bj = 0; bj < 2; ++bj) { const u32x4 w = hv[g & 1][bj];
;                 const f32x4 h0 = {bflo(w.x), bfhi(w.x), bflo(w.y), bfhi(w.y)}, h1 = {bflo(w.z), bfhi(w.z), bflo(w.w), bfhi(w.w)};
;                 const f32x4 o0 = h0 + acc[ai][bj][m][0] * alpha, o1 = h1 + acc[ai][bj][m][1] * alpha;
;                 if (FINAL) { float* op = OUT + (size_t)(r - ROW_X) * DM + col0 + bj * HALF; *(f32x4*)op = o0; *(f32x4*)(op + 4) = o1; }
	v_mfma_f32_16x16x32_bf16 v[52:55], v[200:203], v[168:171], v[52:55]
	v_mfma_f32_16x16x32_bf16 v[44:47], v[208:211], v[168:171], v[44:47]
	v_mfma_f32_16x16x32_bf16 v[36:39], v[200:203], v[176:179], v[36:39]
	v_mfma_f32_16x16x32_bf16 v[32:35], v[208:211], v[176:179], v[32:35]
	v_mfma_f32_16x16x32_bf16 v[16:19], v[200:203], v[184:187], v[16:19]
	v_mfma_f32_16x16x32_bf16 v[8:11], v[208:211], v[184:187], v[8:11]
	v_mfma_f32_16x16x32_bf16 v[4:7], v[200:203], v[192:195], v[4:7]
	v_mfma_f32_16x16x32_bf16 v[0:3], v[208:211], v[192:195], v[0:3]
	v_mfma_f32_16x16x32_bf16 v[52:55], v[204:207], v[172:175], v[52:55]
	v_mfma_f32_16x16x32_bf16 v[44:47], v[212:215], v[172:175], v[44:47]
	v_mfma_f32_16x16x32_bf16 v[36:39], v[204:207], v[180:183], v[36:39]
	v_mfma_f32_16x16x32_bf16 v[32:35], v[212:215], v[180:183], v[32:35]
	v_mfma_f32_16x16x32_bf16 v[16:19], v[204:207], v[188:191], v[16:19]
	v_mfma_f32_16x16x32_bf16 v[8:11], v[212:215], v[188:191], v[8:11]
	v_mfma_f32_16x16x32_bf16 v[4:7], v[204:207], v[196:199], v[4:7]
	v_mfma_f32_16x16x32_bf16 v[0:3], v[212:215], v[196:199], v[0:3]
	s_setprio 0
	s_add_i32 s64, s64, 2
	s_add_u32 s18, s18, 0x100
	s_addc_u32 s19, s19, 0
	s_add_u32 s62, s62, 0x100
	s_addc_u32 s63, s63, 0
	s_cmpk_gt_u32 s64, 0x53
	s_barrier
	s_cbranch_scc0 .LBB0_2626
	v_lshl_add_u32 v144, s60, 8, v151
	v_lshl_or_b32 v148, s61, 8, v152
	v_ashrrev_i32_e32 v145, 31, v144
	v_ashrrev_i32_e32 v149, 31, v148
	v_lshlrev_b64 v[146:147], 12, v[144:145]
	v_or_b32_e32 v164, 16, v144
	v_lshl_add_u64 v[146:147], s[6:7], 0, v[146:147]
	v_lshlrev_b64 v[172:173], 1, v[148:149]
	v_ashrrev_i32_e32 v165, 31, v164
	v_lshl_add_u64 v[146:147], v[146:147], 0, v[172:173]
	v_lshlrev_b64 v[164:165], 12, v[164:165]
	global_load_dwordx4 v[156:159], v[146:147], off
	global_load_dwordx4 v[160:163], v[146:147], off offset:256
	v_lshl_add_u64 v[164:165], s[6:7], 0, v[164:165]
	v_lshl_add_u64 v[168:169], v[164:165], 0, v[172:173]
	global_load_dwordx4 v[164:167], v[168:169], off
	s_nop 0
	global_load_dwordx4 v[168:171], v[168:169], off offset:256
	v_or_b32_e32 v176, 32, v144
	v_or_b32_e32 v180, 48, v144
	v_add_u32_e32 v174, 0xffffff00, v144
	v_ashrrev_i32_e32 v177, 31, v176
	v_ashrrev_i32_e32 v181, 31, v180
	v_ashrrev_i32_e32 v175, 31, v174
	v_lshlrev_b64 v[176:177], 12, v[176:177]
	v_lshlrev_b64 v[180:181], 12, v[180:181]
	v_add_u32_e32 v178, 0xffffff10, v144
	v_lshlrev_b64 v[174:175], 13, v[174:175]
	v_lshl_add_u64 v[176:177], s[6:7], 0, v[176:177]
	v_lshl_add_u64 v[180:181], s[6:7], 0, v[180:181]
	v_lshlrev_b64 v[148:149], 2, v[148:149]
	v_ashrrev_i32_e32 v179, 31, v178
	v_lshl_add_u64 v[174:175], s[48:49], 0, v[174:175]
	v_lshl_add_u64 v[176:177], v[176:177], 0, v[172:173]
	v_lshl_add_u64 v[172:173], v[180:181], 0, v[172:173]
	v_lshlrev_b64 v[178:179], 13, v[178:179]
	v_lshl_add_u64 v[174:175], v[174:175], 0, v[148:149]
	v_lshl_add_u64 v[178:179], s[48:49], 0, v[178:179]
	v_lshl_add_u64 v[178:179], v[178:179], 0, v[148:149]
	s_mov_b32 s60, s59
	s_mov_b32 s61, s58
	s_mov_b64 s[20:21], s[4:5]
	s_mov_b64 s[18:19], s[0:1]
	s_waitcnt vmcnt(0)
	v_lshlrev_b32_e32 v180, 16, v156
	v_and_b32_e32 v181, 0xffff0000, v156
	v_lshlrev_b32_e32 v156, 16, v157
	v_and_b32_e32 v157, 0xffff0000, v157
	v_lshlrev_b32_e32 v182, 16, v158
	v_and_b32_e32 v183, 0xffff0000, v158
	v_lshlrev_b32_e32 v158, 16, v159
	v_and_b32_e32 v159, 0xffff0000, v159
	v_lshlrev_b32_e32 v184, 16, v160
	v_and_b32_e32 v185, 0xffff0000, v160
	v_lshlrev_b32_e32 v160, 16, v161
	v_and_b32_e32 v161, 0xffff0000, v161
	v_lshlrev_b32_e32 v186, 16, v162
	v_and_b32_e32 v187, 0xffff0000, v162
	v_lshlrev_b32_e32 v162, 16, v163
	v_and_b32_e32 v163, 0xffff0000, v163
	v_pk_fma_f32 v[126:127], v[126:127], 0.5, v[156:157] op_sel_hi:[1,0,1]
	v_pk_fma_f32 v[124:125], v[124:125], 0.5, v[180:181] op_sel_hi:[1,0,1]
	v_pk_fma_f32 v[122:123], v[122:123], 0.5, v[158:159] op_sel_hi:[1,0,1]
	v_pk_fma_f32 v[120:121], v[120:121], 0.5, v[182:183] op_sel_hi:[1,0,1]
	v_pk_fma_f32 v[118:119], v[118:119], 0.5, v[160:161] op_sel_hi:[1,0,1]
	v_pk_fma_f32 v[116:117], v[116:117], 0.5, v[184:185] op_sel_hi:[1,0,1]
	v_pk_fma_f32 v[110:111], v[110:111], 0.5, v[162:163] op_sel_hi:[1,0,1]
	v_pk_fma_f32 v[108:109], v[108:109], 0.5, v[186:187] op_sel_hi:[1,0,1]
	v_lshlrev_b32_e32 v156, 16, v164
	v_and_b32_e32 v157, 0xffff0000, v164
	v_lshlrev_b32_e32 v158, 16, v165
	v_and_b32_e32 v159, 0xffff0000, v165
	global_store_dwordx4 v[174:175], v[124:127], off
	global_store_dwordx4 v[174:175], v[120:123], off offset:16
	global_store_dwordx4 v[174:175], v[116:119], off offset:512
	global_store_dwordx4 v[174:175], v[108:111], off offset:528
	v_lshlrev_b32_e32 v160, 16, v166
	v_and_b32_e32 v161, 0xffff0000, v166
	global_load_dwordx4 v[108:111], v[176:177], off
	global_load_dwordx4 v[116:119], v[176:177], off offset:256
	v_lshlrev_b32_e32 v120, 16, v167
	v_and_b32_e32 v121, 0xffff0000, v167
	v_lshlrev_b32_e32 v122, 16, v168
	v_and_b32_e32 v123, 0xffff0000, v168
	v_lshlrev_b32_e32 v124, 16, v169
	v_and_b32_e32 v125, 0xffff0000, v169
	v_lshlrev_b32_e32 v126, 16, v170
	v_and_b32_e32 v127, 0xffff0000, v170
	v_lshlrev_b32_e32 v162, 16, v171
	v_and_b32_e32 v163, 0xffff0000, v171
	v_pk_fma_f32 v[114:115], v[114:115], 0.5, v[158:159] op_sel_hi:[1,0,1]
	v_pk_fma_f32 v[112:113], v[112:113], 0.5, v[156:157] op_sel_hi:[1,0,1]
	v_pk_fma_f32 v[106:107], v[106:107], 0.5, v[120:121] op_sel_hi:[1,0,1]
	v_pk_fma_f32 v[104:105], v[104:105], 0.5, v[160:161] op_sel_hi:[1,0,1]
	v_pk_fma_f32 v[102:103], v[102:103], 0.5, v[124:125] op_sel_hi:[1,0,1]
	v_pk_fma_f32 v[100:101], v[100:101], 0.5, v[122:123] op_sel_hi:[1,0,1]
	v_pk_fma_f32 v[98:99], v[98:99], 0.5, v[162:163] op_sel_hi:[1,0,1]
	v_pk_fma_f32 v[96:97], v[96:97], 0.5, v[126:127] op_sel_hi:[1,0,1]
	global_store_dwordx4 v[178:179], v[112:115], off
	global_store_dwordx4 v[178:179], v[104:107], off offset:16
	global_store_dwordx4 v[178:179], v[100:103], off offset:512
	global_store_dwordx4 v[178:179], v[96:99], off offset:528
	global_load_dwordx4 v[96:99], v[172:173], off
	s_nop 0
	global_load_dwordx4 v[100:103], v[172:173], off offset:256
	v_add_u32_e32 v104, 0xffffff20, v144
	v_add_u32_e32 v106, 0xffffff30, v144
	v_ashrrev_i32_e32 v105, 31, v104
	v_ashrrev_i32_e32 v107, 31, v106
	v_lshlrev_b64 v[104:105], 13, v[104:105]
	v_lshlrev_b64 v[106:107], 13, v[106:107]
	v_lshl_add_u64 v[104:105], s[48:49], 0, v[104:105]
	v_add_co_u32_e32 v114, vcc, s47, v146
	v_lshl_add_u64 v[106:107], s[48:49], 0, v[106:107]
	v_lshl_add_u64 v[104:105], v[104:105], 0, v[148:149]
	v_addc_co_u32_e32 v115, vcc, 0, v147, vcc
	v_lshl_add_u64 v[112:113], v[146:147], 0, s[10:11]
	v_lshl_add_u64 v[106:107], v[106:107], 0, v[148:149]
	v_add_co_u32_e32 v120, vcc, s52, v146
	s_waitcnt vmcnt(0)
; __device__ __forceinline__ float bflo(unsigned w) { return __uint_as_float(w << 16); }
; __device__ __forceinline__ float bfhi(unsigned w) { return __uint_as_float(w & 0xffff0000u); }
; #define ER_LOAD(g_, set_) do { const size_t off_ = (size_t)(row0 + ((g_) >> 2) * HALF + ((g_) & 3) * 16) * DM + col0; \
;         hv[set_][0] = *(const u32x4*)(HB + off_); hv[set_][1] = *(const u32x4*)(HB + off_ + HALF); } while (0)
;     __device__ __forceinline__ void operator()(const f32x4 (&acc)[2][2][4][2], const Unit& u, int wr, int wc, int fr, int fq, const Pre&) const {
;         const int row0 = ROW_X + u.pm * BM + wr * 64 + fr, col0 = u.pn * BM + wc * 32 + 8 * fq;
;         u32x4 hv[2][2]; float sprev = 0.f;
;     ...
;         ER_LOAD(0, 0);
; #pragma unroll
;         for (int g = 0; g < 8; ++g) { const int ai = g >> 2, m = g & 3; const int r = row0 + ai * HALF + m * 16; const size_t off = (size_t)r * DM + col0; float s = 0.f;
;             if (g + 1 < 8) ER_LOAD(g + 1, (g + 1) & 1);
; #pragma unroll
;             for (int bj = 0; bj < 2; ++bj) { const u32x4 w = hv[g & 1][bj];
;                 const f32x4 h0 = {bflo(w.x), bfhi(w.x), bflo(w.y), bfhi(w.y)}, h1 = {bflo(w.z), bfhi(w.z), bflo(w.w), bfhi(w.w)};
;                 const f32x4 o0 = h0 + acc[ai][bj][m][0] * alpha, o1 = h1 + acc[ai][bj][m][1] * alpha;
;                 if (FINAL) { float* op = OUT + (size_t)(r - ROW_X) * DM + col0 + bj * HALF; *(f32x4*)op = o0; *(f32x4*)(op + 4) = o1; }
	v_lshlrev_b32_e32 v122, 16, v108
	v_and_b32_e32 v123, 0xffff0000, v108
	v_lshlrev_b32_e32 v108, 16, v109
	v_and_b32_e32 v109, 0xffff0000, v109
	v_lshlrev_b32_e32 v124, 16, v110
	v_and_b32_e32 v125, 0xffff0000, v110
	v_lshlrev_b32_e32 v110, 16, v111
	v_and_b32_e32 v111, 0xffff0000, v111
	v_lshlrev_b32_e32 v126, 16, v116
	v_and_b32_e32 v127, 0xffff0000, v116
	v_lshlrev_b32_e32 v116, 16, v117
	v_and_b32_e32 v117, 0xffff0000, v117
	v_lshlrev_b32_e32 v156, 16, v118
	v_and_b32_e32 v157, 0xffff0000, v118
	v_lshlrev_b32_e32 v118, 16, v119
	v_and_b32_e32 v119, 0xffff0000, v119
	v_pk_fma_f32 v[94:95], v[94:95], 0.5, v[108:109] op_sel_hi:[1,0,1]
	v_pk_fma_f32 v[92:93], v[92:93], 0.5, v[122:123] op_sel_hi:[1,0,1]
	v_pk_fma_f32 v[90:91], v[90:91], 0.5, v[110:111] op_sel_hi:[1,0,1]
	v_pk_fma_f32 v[88:89], v[88:89], 0.5, v[124:125] op_sel_hi:[1,0,1]
	v_lshlrev_b32_e32 v108, 16, v96
	v_and_b32_e32 v109, 0xffff0000, v96
	v_lshlrev_b32_e32 v96, 16, v97
	v_and_b32_e32 v97, 0xffff0000, v97
	v_pk_fma_f32 v[86:87], v[86:87], 0.5, v[116:117] op_sel_hi:[1,0,1]
	v_pk_fma_f32 v[84:85], v[84:85], 0.5, v[126:127] op_sel_hi:[1,0,1]
	v_pk_fma_f32 v[78:79], v[78:79], 0.5, v[118:119] op_sel_hi:[1,0,1]
	v_pk_fma_f32 v[76:77], v[76:77], 0.5, v[156:157] op_sel_hi:[1,0,1]
	v_lshlrev_b32_e32 v110, 16, v98
	v_and_b32_e32 v111, 0xffff0000, v98
	global_store_dwordx4 v[104:105], v[92:95], off
	global_store_dwordx4 v[104:105], v[88:91], off offset:16
	global_store_dwordx4 v[104:105], v[84:87], off offset:512
	global_store_dwordx4 v[104:105], v[76:79], off offset:528
	v_lshlrev_b32_e32 v88, 16, v99
	v_and_b32_e32 v89, 0xffff0000, v99
	v_lshlrev_b32_e32 v90, 16, v100
	v_and_b32_e32 v91, 0xffff0000, v100
	v_lshlrev_b32_e32 v92, 16, v101
	v_and_b32_e32 v93, 0xffff0000, v101
	v_lshlrev_b32_e32 v94, 16, v102
	v_and_b32_e32 v95, 0xffff0000, v102
	v_lshlrev_b32_e32 v98, 16, v103
	v_and_b32_e32 v99, 0xffff0000, v103
	v_pk_fma_f32 v[82:83], v[82:83], 0.5, v[96:97] op_sel_hi:[1,0,1]
	v_pk_fma_f32 v[80:81], v[80:81], 0.5, v[108:109] op_sel_hi:[1,0,1]
	v_addc_co_u32_e32 v121, vcc, 0, v147, vcc
	global_load_dwordx4 v[76:79], v[114:115], off
	global_load_dwordx4 v[84:87], v[112:113], off offset:256
	v_pk_fma_f32 v[74:75], v[74:75], 0.5, v[88:89] op_sel_hi:[1,0,1]
	v_pk_fma_f32 v[72:73], v[72:73], 0.5, v[110:111] op_sel_hi:[1,0,1]
	v_pk_fma_f32 v[70:71], v[70:71], 0.5, v[92:93] op_sel_hi:[1,0,1]
	v_pk_fma_f32 v[68:69], v[68:69], 0.5, v[90:91] op_sel_hi:[1,0,1]
	v_pk_fma_f32 v[66:67], v[66:67], 0.5, v[98:99] op_sel_hi:[1,0,1]
	v_pk_fma_f32 v[64:65], v[64:65], 0.5, v[94:95] op_sel_hi:[1,0,1]
	global_store_dwordx4 v[106:107], v[80:83], off
	global_store_dwordx4 v[106:107], v[72:75], off offset:16
	global_store_dwordx4 v[106:107], v[68:71], off offset:512
	global_store_dwordx4 v[106:107], v[64:67], off offset:528
	global_load_dwordx4 v[64:67], v[120:121], off
	v_lshl_add_u64 v[68:69], v[146:147], 0, s[12:13]
	global_load_dwordx4 v[68:71], v[68:69], off offset:256
	v_add_u32_e32 v72, 0xffffff80, v144
	v_add_u32_e32 v74, 0xffffff90, v144
	v_ashrrev_i32_e32 v73, 31, v72
	v_ashrrev_i32_e32 v75, 31, v74
	v_lshlrev_b64 v[72:73], 13, v[72:73]
	v_lshlrev_b64 v[74:75], 13, v[74:75]
	v_lshl_add_u64 v[72:73], s[48:49], 0, v[72:73]
	v_add_co_u32_e32 v82, vcc, s56, v146
	v_lshl_add_u64 v[74:75], s[48:49], 0, v[74:75]
	v_lshl_add_u64 v[72:73], v[72:73], 0, v[148:149]
	v_addc_co_u32_e32 v83, vcc, 0, v147, vcc
	v_lshl_add_u64 v[80:81], v[146:147], 0, s[14:15]
	v_lshl_add_u64 v[74:75], v[74:75], 0, v[148:149]
	v_add_co_u32_e32 v88, vcc, s57, v146
	s_waitcnt vmcnt(0)
; __device__ __forceinline__ float bflo(unsigned w) { return __uint_as_float(w << 16); }
; __device__ __forceinline__ float bfhi(unsigned w) { return __uint_as_float(w & 0xffff0000u); }
; #define PG8_WAIT_V(n) asm volatile("s_waitcnt vmcnt(" #n ")" ::: "memory")
; #define PG8_BAR __builtin_amdgcn_s_barrier()
; #define ER_LOAD(g_, set_) do { const size_t off_ = (size_t)(row0 + ((g_) >> 2) * HALF + ((g_) & 3) * 16) * DM + col0; \
;         hv[set_][0] = *(const u32x4*)(HB + off_); hv[set_][1] = *(const u32x4*)(HB + off_ + HALF); } while (0)
; template <class Epi>
; __device__ __forceinline__ void gemm_phase(LAS unsigned char* lds, const Gemm g, const StaticOrder& S, const Epi& E) {
;     ...
;     PG8_WAIT_V(0);
;     if (wr == 0) PG8_BAR;
;     PG8_BAR;
;     __device__ __forceinline__ void operator()(const f32x4 (&acc)[2][2][4][2], const Unit& u, int wr, int wc, int fr, int fq, const Pre&) const {
;         const int row0 = ROW_X + u.pm * BM + wr * 64 + fr, col0 = u.pn * BM + wc * 32 + 8 * fq;
;         u32x4 hv[2][2]; float sprev = 0.f;
;     ...
;         ER_LOAD(0, 0);
; #pragma unroll
;         for (int g = 0; g < 8; ++g) { const int ai = g >> 2, m = g & 3; const int r = row0 + ai * HALF + m * 16; const size_t off = (size_t)r * DM + col0; float s = 0.f;
;             if (g + 1 < 8) ER_LOAD(g + 1, (g + 1) & 1);
; #pragma unroll
;             for (int bj = 0; bj < 2; ++bj) { const u32x4 w = hv[g & 1][bj];
;                 const f32x4 h0 = {bflo(w.x), bfhi(w.x), bflo(w.y), bfhi(w.y)}, h1 = {bflo(w.z), bfhi(w.z), bflo(w.w), bfhi(w.w)};
;                 const f32x4 o0 = h0 + acc[ai][bj][m][0] * alpha, o1 = h1 + acc[ai][bj][m][1] * alpha;
;                 if (FINAL) { float* op = OUT + (size_t)(r - ROW_X) * DM + col0 + bj * HALF; *(f32x4*)op = o0; *(f32x4*)(op + 4) = o1; }
	v_lshlrev_b32_e32 v90, 16, v76
	v_and_b32_e32 v91, 0xffff0000, v76
	v_lshlrev_b32_e32 v76, 16, v77
	v_and_b32_e32 v77, 0xffff0000, v77
	v_lshlrev_b32_e32 v92, 16, v78
	v_and_b32_e32 v93, 0xffff0000, v78
	v_lshlrev_b32_e32 v78, 16, v79
	v_and_b32_e32 v79, 0xffff0000, v79
	v_lshlrev_b32_e32 v94, 16, v84
	v_and_b32_e32 v95, 0xffff0000, v84
	v_lshlrev_b32_e32 v84, 16, v85
	v_and_b32_e32 v85, 0xffff0000, v85
	v_lshlrev_b32_e32 v96, 16, v86
	v_and_b32_e32 v97, 0xffff0000, v86
	v_lshlrev_b32_e32 v86, 16, v87
	v_and_b32_e32 v87, 0xffff0000, v87
	v_pk_fma_f32 v[62:63], v[62:63], 0.5, v[76:77] op_sel_hi:[1,0,1]
	v_pk_fma_f32 v[60:61], v[60:61], 0.5, v[90:91] op_sel_hi:[1,0,1]
	v_pk_fma_f32 v[58:59], v[58:59], 0.5, v[78:79] op_sel_hi:[1,0,1]
	v_pk_fma_f32 v[56:57], v[56:57], 0.5, v[92:93] op_sel_hi:[1,0,1]
	v_lshlrev_b32_e32 v76, 16, v64
	v_and_b32_e32 v77, 0xffff0000, v64
	v_lshlrev_b32_e32 v64, 16, v65
	v_and_b32_e32 v65, 0xffff0000, v65
	v_pk_fma_f32 v[54:55], v[54:55], 0.5, v[84:85] op_sel_hi:[1,0,1]
	v_pk_fma_f32 v[52:53], v[52:53], 0.5, v[94:95] op_sel_hi:[1,0,1]
	v_pk_fma_f32 v[46:47], v[46:47], 0.5, v[86:87] op_sel_hi:[1,0,1]
	v_pk_fma_f32 v[44:45], v[44:45], 0.5, v[96:97] op_sel_hi:[1,0,1]
	v_lshlrev_b32_e32 v78, 16, v66
	v_and_b32_e32 v79, 0xffff0000, v66
	global_store_dwordx4 v[72:73], v[60:63], off
	global_store_dwordx4 v[72:73], v[56:59], off offset:16
	global_store_dwordx4 v[72:73], v[52:55], off offset:512
	global_store_dwordx4 v[72:73], v[44:47], off offset:528
	v_lshlrev_b32_e32 v56, 16, v67
	v_and_b32_e32 v57, 0xffff0000, v67
	v_lshlrev_b32_e32 v58, 16, v68
	v_and_b32_e32 v59, 0xffff0000, v68
	v_lshlrev_b32_e32 v60, 16, v69
	v_and_b32_e32 v61, 0xffff0000, v69
	v_lshlrev_b32_e32 v62, 16, v70
	v_and_b32_e32 v63, 0xffff0000, v70
	v_lshlrev_b32_e32 v66, 16, v71
	v_and_b32_e32 v67, 0xffff0000, v71
	v_pk_fma_f32 v[50:51], v[50:51], 0.5, v[64:65] op_sel_hi:[1,0,1]
	v_pk_fma_f32 v[48:49], v[48:49], 0.5, v[76:77] op_sel_hi:[1,0,1]
	v_addc_co_u32_e32 v89, vcc, 0, v147, vcc
	global_load_dwordx4 v[44:47], v[82:83], off
	global_load_dwordx4 v[52:55], v[80:81], off offset:256
	v_pk_fma_f32 v[42:43], v[42:43], 0.5, v[56:57] op_sel_hi:[1,0,1]
	v_pk_fma_f32 v[40:41], v[40:41], 0.5, v[78:79] op_sel_hi:[1,0,1]
	v_pk_fma_f32 v[38:39], v[38:39], 0.5, v[60:61] op_sel_hi:[1,0,1]
	v_pk_fma_f32 v[36:37], v[36:37], 0.5, v[58:59] op_sel_hi:[1,0,1]
	v_pk_fma_f32 v[34:35], v[34:35], 0.5, v[66:67] op_sel_hi:[1,0,1]
	v_pk_fma_f32 v[32:33], v[32:33], 0.5, v[62:63] op_sel_hi:[1,0,1]
	global_store_dwordx4 v[74:75], v[48:51], off
	global_store_dwordx4 v[74:75], v[40:43], off offset:16
	global_store_dwordx4 v[74:75], v[36:39], off offset:512
	global_store_dwordx4 v[74:75], v[32:35], off offset:528
	global_load_dwordx4 v[32:35], v[88:89], off
	v_lshl_add_u64 v[36:37], v[146:147], 0, s[16:17]
	global_load_dwordx4 v[36:39], v[36:37], off offset:256
	v_add_u32_e32 v40, 0xffffffa0, v144
	v_add_u32_e32 v42, 0xffffffb0, v144
	v_ashrrev_i32_e32 v41, 31, v40
	v_ashrrev_i32_e32 v43, 31, v42
	v_lshlrev_b64 v[40:41], 13, v[40:41]
	v_lshlrev_b64 v[42:43], 13, v[42:43]
	v_lshl_add_u64 v[40:41], s[48:49], 0, v[40:41]
	v_lshl_add_u64 v[42:43], s[48:49], 0, v[42:43]
	v_lshl_add_u64 v[40:41], v[40:41], 0, v[148:149]
	s_and_b64 vcc, exec, s[2:3]
	v_lshl_add_u64 v[42:43], v[42:43], 0, v[148:149]
	s_waitcnt vmcnt(0)
	v_lshlrev_b32_e32 v48, 16, v44
	v_and_b32_e32 v49, 0xffff0000, v44
	v_lshlrev_b32_e32 v44, 16, v45
	v_and_b32_e32 v45, 0xffff0000, v45
	v_lshlrev_b32_e32 v58, 16, v54
	v_and_b32_e32 v59, 0xffff0000, v54
	v_lshlrev_b32_e32 v54, 16, v55
	v_and_b32_e32 v55, 0xffff0000, v55
	v_lshlrev_b32_e32 v50, 16, v46
	v_and_b32_e32 v51, 0xffff0000, v46
	v_lshlrev_b32_e32 v46, 16, v47
	v_and_b32_e32 v47, 0xffff0000, v47
	v_lshlrev_b32_e32 v56, 16, v52
	v_and_b32_e32 v57, 0xffff0000, v52
	v_lshlrev_b32_e32 v52, 16, v53
	v_and_b32_e32 v53, 0xffff0000, v53
	v_pk_fma_f32 v[30:31], v[30:31], 0.5, v[44:45] op_sel_hi:[1,0,1]
	v_pk_fma_f32 v[28:29], v[28:29], 0.5, v[48:49] op_sel_hi:[1,0,1]
	v_pk_fma_f32 v[10:11], v[10:11], 0.5, v[54:55] op_sel_hi:[1,0,1]
	v_pk_fma_f32 v[8:9], v[8:9], 0.5, v[58:59] op_sel_hi:[1,0,1]
	v_lshlrev_b32_e32 v44, 16, v32
	v_and_b32_e32 v45, 0xffff0000, v32
	v_lshlrev_b32_e32 v32, 16, v33
	v_and_b32_e32 v33, 0xffff0000, v33
	v_pk_fma_f32 v[26:27], v[26:27], 0.5, v[46:47] op_sel_hi:[1,0,1]
	v_pk_fma_f32 v[24:25], v[24:25], 0.5, v[50:51] op_sel_hi:[1,0,1]
	v_pk_fma_f32 v[18:19], v[18:19], 0.5, v[52:53] op_sel_hi:[1,0,1]
	v_pk_fma_f32 v[16:17], v[16:17], 0.5, v[56:57] op_sel_hi:[1,0,1]
	v_lshlrev_b32_e32 v46, 16, v34
	v_and_b32_e32 v47, 0xffff0000, v34
	v_lshlrev_b32_e32 v34, 16, v35
	v_and_b32_e32 v35, 0xffff0000, v35
	v_lshlrev_b32_e32 v48, 16, v36
	v_and_b32_e32 v49, 0xffff0000, v36
	v_lshlrev_b32_e32 v36, 16, v37
	v_and_b32_e32 v37, 0xffff0000, v37
	v_lshlrev_b32_e32 v50, 16, v38
	v_and_b32_e32 v51, 0xffff0000, v38
	v_lshlrev_b32_e32 v38, 16, v39
	v_and_b32_e32 v39, 0xffff0000, v39
	global_store_dwordx4 v[40:41], v[28:31], off
	global_store_dwordx4 v[40:41], v[24:27], off offset:16
	global_store_dwordx4 v[40:41], v[16:19], off offset:512
	global_store_dwordx4 v[40:41], v[8:11], off offset:528
	v_pk_fma_f32 v[14:15], v[14:15], 0.5, v[34:35] op_sel_hi:[1,0,1]
	v_pk_fma_f32 v[12:13], v[12:13], 0.5, v[46:47] op_sel_hi:[1,0,1]
	v_pk_fma_f32 v[10:11], v[22:23], 0.5, v[32:33] op_sel_hi:[1,0,1]
	v_pk_fma_f32 v[8:9], v[20:21], 0.5, v[44:45] op_sel_hi:[1,0,1]
	v_pk_fma_f32 v[6:7], v[6:7], 0.5, v[36:37] op_sel_hi:[1,0,1]
	v_pk_fma_f32 v[4:5], v[4:5], 0.5, v[48:49] op_sel_hi:[1,0,1]
	v_pk_fma_f32 v[2:3], v[2:3], 0.5, v[38:39] op_sel_hi:[1,0,1]
	v_pk_fma_f32 v[0:1], v[0:1], 0.5, v[50:51] op_sel_hi:[1,0,1]
	global_store_dwordx4 v[42:43], v[8:11], off
	global_store_dwordx4 v[42:43], v[12:15], off offset:16
	global_store_dwordx4 v[42:43], v[4:7], off offset:512
	global_store_dwordx4 v[42:43], v[0:3], off offset:528
	s_cbranch_vccz .LBB0_2615
	s_waitcnt vmcnt(0)
	s_cmpk_gt_u32 s24, 0xff
	s_cbranch_scc1 .LBB0_2630
	s_barrier
